# gather: per-expert dot results gathered into a lane vector through a wave-private LDS row (two-lane ds_write + one ds_read) instead of 8 readlane + 8 writelane per batch
# speedup vs baseline: 1.0039x; 1.0039x over previous
; DEV int opaque_tid() { int t = (int)threadIdx.x; asm volatile("" : "+v"(t)); return t; }
; __device__ void peer_gather_phase(const Params& P, int l, bool do_store) {
;   const int lane = opaque_tid() & 63, w = opaque_tid() >> 6;
;   const unsigned char* U = P.U8 + (size_t)l * 16384 * 768 + (lane & 31) * 24;
;   const unsigned char* V = P.V8 + (size_t)l * 16384 * 512 + lane * 8;
;   const float* SU = P.SU + l * 16384;
;   const float* SV = P.SV + l * 16384;
;   int nev0, nev1; float ngv0, ngv1; uint4 nxa, nxc;
;   {
;     const int t = blockIdx.x * 4 + w;
;     nev0 = P.EXP[(size_t)t * 128 + lane]; nev1 = P.EXP[(size_t)t * 128 + 64 + lane];
;     ngv0 = P.GATE[(size_t)t * 128 + lane]; ngv1 = P.GATE[(size_t)t * 128 + 64 + lane];
;     const bf16_t* xb = P.XB + (size_t)t * 1024 + lane * 16;
;     nxa = *(const uint4*)xb; nxc = *(const uint4*)(xb + 8);
;   }
;   for (int r4 = blockIdx.x; r4 < T_TOK / 4; r4 += gridDim.x) {
;     const int t = r4 * 4 + w;
;     f32x2 xf[8];
;     const int ev0 = nev0, ev1 = nev1; const float gv0 = ngv0, gv1 = ngv1;
;     ...
;         const float da = __builtin_bit_cast(float, __builtin_amdgcn_readlane(__builtin_bit_cast(int, hs), 31));
;         const float db = __builtin_bit_cast(float, __builtin_amdgcn_readlane(__builtin_bit_cast(int, hs), 63));
;         dvec = (lane == kb + 2 * pr) ? da : dvec;
;         dvec = (lane == kb + 2 * pr + 1) ? db : dvec;
.LBB0_14:
	v_readlane_b32 s4, v248, 27
	s_add_i32 s4, s4, 1
	v_readlane_b32 s2, v249, 37
	s_cmp_eq_u32 s4, s2
	v_writelane_b32 v248, s4, 27
	s_cselect_b64 s[4:5], -1, 0
	v_writelane_b32 v248, s4, 32
	s_mov_b64 s[0:1], -1
	s_nop 0
	v_writelane_b32 v248, s5, 33
	v_readlane_b32 s4, v249, 38
	v_readlane_b32 s5, v249, 39
	s_and_b64 vcc, exec, s[4:5]
	s_cbranch_vccz .LBB0_310
	v_readlane_b32 s0, v251, 58
	v_readlane_b32 s1, v251, 59
	s_load_dword s0, s[0:1], 0x0
	s_waitcnt lgkmcnt(0)
	v_writelane_b32 v248, s0, 34
	s_nop 1
	v_writelane_b32 v248, s1, 35
	v_readlane_b32 s0, v249, 40
	s_cmp_lt_i32 s0, 4
	s_mov_b64 s[0:1], -1
	s_cbranch_scc1 .LBB0_65
	v_readlane_b32 s0, v249, 40
	s_cmp_lt_i32 s0, 6
	s_mov_b64 s[0:1], -1
	s_cbranch_scc1 .LBB0_39
	v_readlane_b32 s0, v249, 40
	s_cmp_gt_i32 s0, 6
	s_cbranch_scc0 .LBB0_38
	v_readlane_b32 s0, v251, 60
	v_readlane_b32 s1, v251, 61
	v_mov_b32_e32 v0, v202
	v_mov_b32_e32 v1, v202
	s_andn2_b64 vcc, exec, s[0:1]
	s_cbranch_vccnz .LBB0_38
	v_ashrrev_i32_e32 v73, 6, v1
	v_and_b32_e32 v1, 31, v0
	v_readlane_b32 s0, v249, 41
	v_mul_u32_u24_e32 v176, 24, v1
	v_readlane_b32 s1, v249, 42
	v_and_b32_e32 v72, 63, v0
	v_readlane_b32 s4, v251, 2
	v_lshl_add_u64 v[74:75], s[0:1], 0, v[176:177]
	v_readlane_b32 s0, v249, 43
	v_lshlrev_b32_e32 v176, 3, v72
	v_readlane_b32 s1, v249, 44
	v_readlane_b32 s5, v251, 3
	v_readlane_b32 s6, v251, 4
	v_lshl_add_u64 v[76:77], s[0:1], 0, v[176:177]
	v_readlane_b32 s0, v251, 62
	v_lshlrev_b32_e32 v176, 5, v72
	v_readlane_b32 s7, v251, 5
	v_add_u32_e32 v2, s0, v73
	v_ashrrev_i32_e32 v3, 31, v2
	v_lshlrev_b64 v[4:5], 11, v[2:3]
	v_lshl_add_u64 v[4:5], s[28:29], 0, v[4:5]
	v_lshlrev_b64 v[2:3], 9, v[2:3]
	v_lshl_add_u64 v[4:5], v[4:5], 0, v[176:177]
	v_lshl_or_b32 v2, v72, 2, v2
	global_load_dwordx4 v[64:67], v[4:5], off offset:16
	global_load_dwordx4 v[68:71], v[4:5], off
	v_lshl_add_u64 v[4:5], s[4:5], 0, v[2:3]
	v_lshl_add_u64 v[2:3], s[6:7], 0, v[2:3]
	global_load_dword v93, v[4:5], off offset:256
	global_load_dword v91, v[4:5], off
	global_load_dword v188, v[2:3], off offset:256
	global_load_dword v179, v[2:3], off
	v_readlane_b32 s0, v249, 49
	v_readlane_b32 s4, v248, 32
	v_readlane_b32 s1, v249, 50
	v_readlane_b32 s5, v248, 33
	s_and_b64 s[38:39], s[0:1], s[4:5]
	v_readlane_b32 s0, v248, 1
	v_readlane_b32 s1, v248, 2
	s_and_b64 s[0:1], s[0:1], s[4:5]
	s_xor_b64 s[0:1], s[0:1], -1
	v_writelane_b32 v248, s0, 45
	v_lshl_add_u64 v[78:79], s[28:29], 0, v[176:177]
	v_lshlrev_b32_e32 v176, 6, v72
	v_writelane_b32 v248, s1, 46
	v_readlane_b32 s0, v249, 54
	v_readlane_b32 s1, v249, 55
	v_lshlrev_b32_e32 v0, 5, v0
	v_readlane_b32 s44, v252, 12
	v_lshl_add_u64 v[82:83], s[0:1], 0, v[176:177]
	v_readlane_b32 s0, v249, 56
	v_readlane_b32 s1, v249, 57
	v_lshlrev_b32_e32 v2, 4, v72
	v_and_b32_e32 v0, 0x3e0, v0
	v_readlane_b32 s58, v252, 26
	v_readlane_b32 s59, v252, 27
	v_lshl_add_u64 v[84:85], s[0:1], 0, v[176:177]
	v_readlane_b32 s0, v249, 5
	v_cmp_lt_u32_e64 s[40:41], 31, v72
	v_lshl_add_u64 v[80:81], s[58:59], 0, v[176:177]
	v_lshlrev_b32_e32 v86, 1, v0
	v_lshlrev_b32_e32 v176, 1, v2
	v_mov_b32_e32 v87, v177
	s_mov_b32 s2, s0
	s_movk_i32 s33, 0x300
	v_readlane_b32 s45, v252, 13
	v_readlane_b32 s46, v252, 14
	v_readlane_b32 s47, v252, 15
	v_readlane_b32 s48, v252, 16
	v_readlane_b32 s49, v252, 17
	v_readlane_b32 s50, v252, 18
	v_readlane_b32 s51, v252, 19
	v_readlane_b32 s52, v252, 20
	v_readlane_b32 s53, v252, 21
	v_readlane_b32 s54, v252, 22
	v_readlane_b32 s55, v252, 23
	v_readlane_b32 s56, v252, 24
	v_readlane_b32 s57, v252, 25
	v_readlane_b32 s1, v249, 6
	v_lshrrev_b32_e32 v74, 5, v72
	v_lshlrev_b32_e32 v74, 2, v74
	v_lshl_add_u32 v74, v73, 9, v74
	v_lshlrev_b32_e32 v75, 2, v72
	v_lshl_add_u32 v75, v73, 9, v75
	s_branch .LBB0_21

; __device__ void peer_gather_phase(const Params& P, int l, bool do_store) {
;     ...
;         const int ea = __builtin_amdgcn_readlane(evs, kb + 2 * pr), eb = __builtin_amdgcn_readlane(evs, kb + 2 * pr + 1);
;         const uint2* up = (const uint2*)(U + (size_t)(uphi ? eb : ea) * 768);
;         u6[3 * pr] = up[0]; u6[3 * pr + 1] = up[1]; u6[3 * pr + 2] = up[2];
;         v8[2 * pr] = *(const uint2*)(V + (size_t)ea * 512);
;         v8[2 * pr + 1] = *(const uint2*)(V + (size_t)eb * 512);
;       }
;     };
;     auto compute_batch = [&](const uint2 (&u6)[12], const uint2 (&v8)[8], int bt) {
;       const int kb = (bt & 7) * 8;
;       float dvec = 0.f;
; #pragma unroll
;       for (int pr = 0; pr < 4; ++pr) {
;         v6u_t qv; qv[0] = u6[3 * pr].x; qv[1] = u6[3 * pr].y; qv[2] = u6[3 * pr + 1].x; qv[3] = u6[3 * pr + 1].y; qv[4] = u6[3 * pr + 2].x; qv[5] = u6[3 * pr + 2].y;
;         const v32f_t wv = __builtin_amdgcn_cvt_scalef32_pk32_f32_fp6(qv, 1.0f);
;         f32x2 a2 = f32x2{0.f, 0.f};
; #pragma unroll
;         for (int i = 0; i < 16; ++i) a2 += f32x2{wv[2 * i], wv[2 * i + 1]} * xu[i];
;         float hs = a2.x + a2.y;
.LBB0_22:
	v_readlane_b32 s54, v92, 16
	v_readlane_b32 s55, v92, 17
	s_mul_i32 s0, s54, 0x300
	s_mul_i32 s1, s55, 0x300
	v_add_u32_e32 v167, s0, v195
	s_and_saveexec_b64 s[98:99], s[40:41]
	v_add_u32_e32 v167, s1, v195
	s_mov_b64 exec, s[98:99]
	s_waitcnt vmcnt(32)
	v_cvt_scalef32_pk32_f32_fp6 v[0:31], v[50:55], 1.0
	global_load_dwordx2 v[54:55], v167, s[62:63] offset:16
	global_load_dwordx4 v[50:53], v167, s[62:63]
	v_pk_mul_f32 v[246:247], v[0:1], v[96:97]
	v_pk_mul_f32 v[254:255], v[2:3], v[98:99]
	v_pk_mul_f32 v[160:161], v[4:5], v[100:101]
	v_pk_fma_f32 v[246:247], v[6:7], v[102:103], v[246:247]
	v_pk_fma_f32 v[254:255], v[8:9], v[104:105], v[254:255]
	v_pk_fma_f32 v[160:161], v[10:11], v[106:107], v[160:161]
	v_pk_fma_f32 v[246:247], v[12:13], v[108:109], v[246:247]
	v_pk_fma_f32 v[254:255], v[14:15], v[110:111], v[254:255]
	v_pk_fma_f32 v[160:161], v[16:17], v[112:113], v[160:161]
	v_pk_fma_f32 v[246:247], v[18:19], v[114:115], v[246:247]
	v_pk_fma_f32 v[254:255], v[20:21], v[116:117], v[254:255]
	v_pk_fma_f32 v[160:161], v[22:23], v[118:119], v[160:161]
	v_pk_fma_f32 v[246:247], v[24:25], v[120:121], v[246:247]
	v_pk_fma_f32 v[254:255], v[26:27], v[122:123], v[254:255]
	v_pk_fma_f32 v[160:161], v[28:29], v[124:125], v[160:161]
	v_pk_fma_f32 v[246:247], v[30:31], v[126:127], v[246:247]
	v_pk_add_f32 v[254:255], v[254:255], v[160:161]
	s_nop 0
	v_pk_add_f32 v[246:247], v[246:247], v[254:255]
	s_nop 0
	v_add_f32_e32 v162, v246, v247
	v_readlane_b32 s54, v92, 18
	v_readlane_b32 s55, v92, 19
	s_mul_i32 s0, s54, 0x300
	s_mul_i32 s1, s55, 0x300
	v_add_u32_e32 v167, s0, v195
	s_and_saveexec_b64 s[98:99], s[40:41]
	v_add_u32_e32 v167, s1, v195
	s_mov_b64 exec, s[98:99]
	s_waitcnt vmcnt(32)
	v_cvt_scalef32_pk32_f32_fp6 v[0:31], v[44:49], 1.0
	global_load_dwordx2 v[48:49], v167, s[62:63] offset:16
	global_load_dwordx4 v[44:47], v167, s[62:63]
	v_pk_mul_f32 v[246:247], v[0:1], v[96:97]
	v_pk_mul_f32 v[254:255], v[2:3], v[98:99]
	v_pk_mul_f32 v[160:161], v[4:5], v[100:101]
	v_pk_fma_f32 v[246:247], v[6:7], v[102:103], v[246:247]
	v_pk_fma_f32 v[254:255], v[8:9], v[104:105], v[254:255]
	v_pk_fma_f32 v[160:161], v[10:11], v[106:107], v[160:161]
	v_pk_fma_f32 v[246:247], v[12:13], v[108:109], v[246:247]
	v_pk_fma_f32 v[254:255], v[14:15], v[110:111], v[254:255]
	v_pk_fma_f32 v[160:161], v[16:17], v[112:113], v[160:161]
	v_pk_fma_f32 v[246:247], v[18:19], v[114:115], v[246:247]
	v_pk_fma_f32 v[254:255], v[20:21], v[116:117], v[254:255]
	v_pk_fma_f32 v[160:161], v[22:23], v[118:119], v[160:161]
	v_pk_fma_f32 v[246:247], v[24:25], v[120:121], v[246:247]
	v_pk_fma_f32 v[254:255], v[26:27], v[122:123], v[254:255]
	v_pk_fma_f32 v[160:161], v[28:29], v[124:125], v[160:161]
	v_pk_fma_f32 v[246:247], v[30:31], v[126:127], v[246:247]
	v_pk_add_f32 v[254:255], v[254:255], v[160:161]
	s_nop 0
	v_pk_add_f32 v[246:247], v[246:247], v[254:255]
	s_nop 0
	v_add_f32_e32 v163, v246, v247
	v_readlane_b32 s54, v92, 20
	v_readlane_b32 s55, v92, 21
	s_mul_i32 s0, s54, 0x300
	s_mul_i32 s1, s55, 0x300
	v_add_u32_e32 v167, s0, v195
	s_and_saveexec_b64 s[98:99], s[40:41]
	v_add_u32_e32 v167, s1, v195
	s_mov_b64 exec, s[98:99]
	s_waitcnt vmcnt(32)
	v_cvt_scalef32_pk32_f32_fp6 v[0:31], v[38:43], 1.0
	global_load_dwordx2 v[42:43], v167, s[62:63] offset:16
	global_load_dwordx4 v[38:41], v167, s[62:63]
	v_pk_mul_f32 v[246:247], v[0:1], v[96:97]
	v_pk_mul_f32 v[254:255], v[2:3], v[98:99]
	v_pk_mul_f32 v[160:161], v[4:5], v[100:101]
	v_pk_fma_f32 v[246:247], v[6:7], v[102:103], v[246:247]
	v_pk_fma_f32 v[254:255], v[8:9], v[104:105], v[254:255]
	v_pk_fma_f32 v[160:161], v[10:11], v[106:107], v[160:161]
	v_pk_fma_f32 v[246:247], v[12:13], v[108:109], v[246:247]
	v_pk_fma_f32 v[254:255], v[14:15], v[110:111], v[254:255]
	v_pk_fma_f32 v[160:161], v[16:17], v[112:113], v[160:161]
	v_pk_fma_f32 v[246:247], v[18:19], v[114:115], v[246:247]
	v_pk_fma_f32 v[254:255], v[20:21], v[116:117], v[254:255]
	v_pk_fma_f32 v[160:161], v[22:23], v[118:119], v[160:161]
	v_pk_fma_f32 v[246:247], v[24:25], v[120:121], v[246:247]
	v_pk_fma_f32 v[254:255], v[26:27], v[122:123], v[254:255]
	v_pk_fma_f32 v[160:161], v[28:29], v[124:125], v[160:161]
	v_pk_fma_f32 v[246:247], v[30:31], v[126:127], v[246:247]
	v_pk_add_f32 v[254:255], v[254:255], v[160:161]
	s_nop 0
	v_pk_add_f32 v[246:247], v[246:247], v[254:255]
	s_nop 0
	v_add_f32_e32 v164, v246, v247
	v_readlane_b32 s54, v92, 22
	v_readlane_b32 s55, v92, 23
	s_mul_i32 s0, s54, 0x300
	s_mul_i32 s1, s55, 0x300
	v_add_u32_e32 v167, s0, v195
	s_and_saveexec_b64 s[98:99], s[40:41]
	v_add_u32_e32 v167, s1, v195
	s_mov_b64 exec, s[98:99]
	s_waitcnt vmcnt(32)
; __device__ void peer_gather_phase(const Params& P, int l, bool do_store) {
;     ...
;       for (int pr = 0; pr < 4; ++pr) {
;         v6u_t qv; qv[0] = u6[3 * pr].x; qv[1] = u6[3 * pr].y; qv[2] = u6[3 * pr + 1].x; qv[3] = u6[3 * pr + 1].y; qv[4] = u6[3 * pr + 2].x; qv[5] = u6[3 * pr + 2].y;
;         const v32f_t wv = __builtin_amdgcn_cvt_scalef32_pk32_f32_fp6(qv, 1.0f);
;         f32x2 a2 = f32x2{0.f, 0.f};
; #pragma unroll
;         for (int i = 0; i < 16; ++i) a2 += f32x2{wv[2 * i], wv[2 * i + 1]} * xu[i];
;         float hs = a2.x + a2.y;
;         hs += dpp_row_shr(hs, 1); hs += dpp_row_shr(hs, 2); hs += dpp_row_shr(hs, 4); hs += dpp_row_shr(hs, 8);
;         hs += __builtin_bit_cast(float, __builtin_amdgcn_update_dpp(0, __builtin_bit_cast(int, hs), 0x142, 0xa, 0xf, false));
;         const float da = __builtin_bit_cast(float, __builtin_amdgcn_readlane(__builtin_bit_cast(int, hs), 31));
;         const float db = __builtin_bit_cast(float, __builtin_amdgcn_readlane(__builtin_bit_cast(int, hs), 63));
;         dvec = (lane == kb + 2 * pr) ? da : dvec;
;         dvec = (lane == kb + 2 * pr + 1) ? db : dvec;
	v_cvt_scalef32_pk32_f32_fp6 v[0:31], v[32:37], 1.0
	global_load_dwordx2 v[36:37], v167, s[62:63] offset:16
	global_load_dwordx4 v[32:35], v167, s[62:63]
	v_pk_mul_f32 v[246:247], v[0:1], v[96:97]
	v_pk_mul_f32 v[254:255], v[2:3], v[98:99]
	v_pk_mul_f32 v[160:161], v[4:5], v[100:101]
	v_pk_fma_f32 v[246:247], v[6:7], v[102:103], v[246:247]
	v_pk_fma_f32 v[254:255], v[8:9], v[104:105], v[254:255]
	v_pk_fma_f32 v[160:161], v[10:11], v[106:107], v[160:161]
	v_pk_fma_f32 v[246:247], v[12:13], v[108:109], v[246:247]
	v_pk_fma_f32 v[254:255], v[14:15], v[110:111], v[254:255]
	v_pk_fma_f32 v[160:161], v[16:17], v[112:113], v[160:161]
	v_pk_fma_f32 v[246:247], v[18:19], v[114:115], v[246:247]
	v_pk_fma_f32 v[254:255], v[20:21], v[116:117], v[254:255]
	v_pk_fma_f32 v[160:161], v[22:23], v[118:119], v[160:161]
	v_pk_fma_f32 v[246:247], v[24:25], v[120:121], v[246:247]
	v_pk_fma_f32 v[254:255], v[26:27], v[122:123], v[254:255]
	v_pk_fma_f32 v[160:161], v[28:29], v[124:125], v[160:161]
	v_pk_fma_f32 v[246:247], v[30:31], v[126:127], v[246:247]
	v_pk_add_f32 v[254:255], v[254:255], v[160:161]
	s_nop 0
	v_pk_add_f32 v[246:247], v[246:247], v[254:255]
	s_nop 0
	v_add_f32_e32 v165, v246, v247
	v_add_f32_dpp v162, v162, v162 row_shr:1 row_mask:0xf bank_mask:0xf bound_ctrl:1
	v_add_f32_dpp v163, v163, v163 row_shr:1 row_mask:0xf bank_mask:0xf bound_ctrl:1
	v_add_f32_dpp v164, v164, v164 row_shr:1 row_mask:0xf bank_mask:0xf bound_ctrl:1
	v_add_f32_dpp v165, v165, v165 row_shr:1 row_mask:0xf bank_mask:0xf bound_ctrl:1
	v_add_f32_dpp v162, v162, v162 row_shr:2 row_mask:0xf bank_mask:0xf bound_ctrl:1
	v_add_f32_dpp v163, v163, v163 row_shr:2 row_mask:0xf bank_mask:0xf bound_ctrl:1
	v_add_f32_dpp v164, v164, v164 row_shr:2 row_mask:0xf bank_mask:0xf bound_ctrl:1
	v_add_f32_dpp v165, v165, v165 row_shr:2 row_mask:0xf bank_mask:0xf bound_ctrl:1
	v_add_f32_dpp v162, v162, v162 row_shr:4 row_mask:0xf bank_mask:0xf bound_ctrl:1
	v_add_f32_dpp v163, v163, v163 row_shr:4 row_mask:0xf bank_mask:0xf bound_ctrl:1
	v_add_f32_dpp v164, v164, v164 row_shr:4 row_mask:0xf bank_mask:0xf bound_ctrl:1
	v_add_f32_dpp v165, v165, v165 row_shr:4 row_mask:0xf bank_mask:0xf bound_ctrl:1
	v_add_f32_dpp v162, v162, v162 row_shr:8 row_mask:0xf bank_mask:0xf bound_ctrl:1
	v_add_f32_dpp v163, v163, v163 row_shr:8 row_mask:0xf bank_mask:0xf bound_ctrl:1
	v_add_f32_dpp v164, v164, v164 row_shr:8 row_mask:0xf bank_mask:0xf bound_ctrl:1
	v_add_f32_dpp v165, v165, v165 row_shr:8 row_mask:0xf bank_mask:0xf bound_ctrl:1
	v_add_f32_dpp v162, v162, v162 row_bcast:15 row_mask:0xa bank_mask:0xf
	v_add_f32_dpp v163, v163, v163 row_bcast:15 row_mask:0xa bank_mask:0xf
	v_add_f32_dpp v164, v164, v164 row_bcast:15 row_mask:0xa bank_mask:0xf
	v_add_f32_dpp v165, v165, v165 row_bcast:15 row_mask:0xa bank_mask:0xf
	s_mov_b64 s[98:99], exec
	s_mov_b32 exec_lo, 0x80000000
	s_mov_b32 exec_hi, 0x80000000
	ds_write_b32 v74, v162
	ds_write_b32 v74, v163 offset:8
	ds_write_b32 v74, v164 offset:16
	ds_write_b32 v74, v165 offset:24
	s_mov_b64 exec, s[98:99]
	v_readlane_b32 s54, v92, 24
	v_readlane_b32 s55, v92, 25
	s_mul_i32 s0, s54, 0x300
	s_mul_i32 s1, s55, 0x300
	v_add_u32_e32 v167, s0, v195
	s_and_saveexec_b64 s[98:99], s[40:41]
	v_add_u32_e32 v167, s1, v195
	s_mov_b64 exec, s[98:99]
	s_waitcnt vmcnt(32)
	v_cvt_scalef32_pk32_f32_fp6 v[0:31], v[196:201], 1.0
	global_load_dwordx2 v[200:201], v167, s[62:63] offset:16
	global_load_dwordx4 v[196:199], v167, s[62:63]
	v_pk_mul_f32 v[246:247], v[0:1], v[96:97]
	v_pk_mul_f32 v[254:255], v[2:3], v[98:99]
	v_pk_mul_f32 v[160:161], v[4:5], v[100:101]
	v_pk_fma_f32 v[246:247], v[6:7], v[102:103], v[246:247]
	v_pk_fma_f32 v[254:255], v[8:9], v[104:105], v[254:255]
	v_pk_fma_f32 v[160:161], v[10:11], v[106:107], v[160:161]
	v_pk_fma_f32 v[246:247], v[12:13], v[108:109], v[246:247]
	v_pk_fma_f32 v[254:255], v[14:15], v[110:111], v[254:255]
	v_pk_fma_f32 v[160:161], v[16:17], v[112:113], v[160:161]
	v_pk_fma_f32 v[246:247], v[18:19], v[114:115], v[246:247]
	v_pk_fma_f32 v[254:255], v[20:21], v[116:117], v[254:255]
	v_pk_fma_f32 v[160:161], v[22:23], v[118:119], v[160:161]
	v_pk_fma_f32 v[246:247], v[24:25], v[120:121], v[246:247]
	v_pk_fma_f32 v[254:255], v[26:27], v[122:123], v[254:255]
	v_pk_fma_f32 v[160:161], v[28:29], v[124:125], v[160:161]
	v_pk_fma_f32 v[246:247], v[30:31], v[126:127], v[246:247]
	v_pk_add_f32 v[254:255], v[254:255], v[160:161]
	s_nop 0
	v_pk_add_f32 v[246:247], v[246:247], v[254:255]
	s_nop 0
	v_add_f32_e32 v162, v246, v247
	v_readlane_b32 s54, v92, 26
	v_readlane_b32 s55, v92, 27
	s_mul_i32 s0, s54, 0x300
	s_mul_i32 s1, s55, 0x300
	v_add_u32_e32 v167, s0, v195
	s_and_saveexec_b64 s[98:99], s[40:41]
	v_add_u32_e32 v167, s1, v195
	s_mov_b64 exec, s[98:99]
	s_waitcnt vmcnt(32)
	v_cvt_scalef32_pk32_f32_fp6 v[0:31], v[228:233], 1.0
	global_load_dwordx2 v[232:233], v167, s[62:63] offset:16
	global_load_dwordx4 v[228:231], v167, s[62:63]
	v_pk_mul_f32 v[246:247], v[0:1], v[96:97]
	v_pk_mul_f32 v[254:255], v[2:3], v[98:99]
	v_pk_mul_f32 v[160:161], v[4:5], v[100:101]
	v_pk_fma_f32 v[246:247], v[6:7], v[102:103], v[246:247]
	v_pk_fma_f32 v[254:255], v[8:9], v[104:105], v[254:255]
	v_pk_fma_f32 v[160:161], v[10:11], v[106:107], v[160:161]
	v_pk_fma_f32 v[246:247], v[12:13], v[108:109], v[246:247]
	v_pk_fma_f32 v[254:255], v[14:15], v[110:111], v[254:255]
	v_pk_fma_f32 v[160:161], v[16:17], v[112:113], v[160:161]
	v_pk_fma_f32 v[246:247], v[18:19], v[114:115], v[246:247]
	v_pk_fma_f32 v[254:255], v[20:21], v[116:117], v[254:255]
	v_pk_fma_f32 v[160:161], v[22:23], v[118:119], v[160:161]
	v_pk_fma_f32 v[246:247], v[24:25], v[120:121], v[246:247]
	v_pk_fma_f32 v[254:255], v[26:27], v[122:123], v[254:255]
	v_pk_fma_f32 v[160:161], v[28:29], v[124:125], v[160:161]
	v_pk_fma_f32 v[246:247], v[30:31], v[126:127], v[246:247]
	v_pk_add_f32 v[254:255], v[254:255], v[160:161]
	s_nop 0
	v_pk_add_f32 v[246:247], v[246:247], v[254:255]
	s_nop 0
	v_add_f32_e32 v163, v246, v247
	v_readlane_b32 s54, v92, 28
	v_readlane_b32 s55, v92, 29
	s_mul_i32 s0, s54, 0x300
	s_mul_i32 s1, s55, 0x300
	v_add_u32_e32 v167, s0, v195
	s_and_saveexec_b64 s[98:99], s[40:41]
	v_add_u32_e32 v167, s1, v195
	s_mov_b64 exec, s[98:99]
	s_waitcnt vmcnt(32)
; __device__ void peer_gather_phase(const Params& P, int l, bool do_store) {
;     ...
;       for (int pr = 0; pr < 4; ++pr) {
;         v6u_t qv; qv[0] = u6[3 * pr].x; qv[1] = u6[3 * pr].y; qv[2] = u6[3 * pr + 1].x; qv[3] = u6[3 * pr + 1].y; qv[4] = u6[3 * pr + 2].x; qv[5] = u6[3 * pr + 2].y;
;         const v32f_t wv = __builtin_amdgcn_cvt_scalef32_pk32_f32_fp6(qv, 1.0f);
;         f32x2 a2 = f32x2{0.f, 0.f};
; #pragma unroll
;         for (int i = 0; i < 16; ++i) a2 += f32x2{wv[2 * i], wv[2 * i + 1]} * xu[i];
;         float hs = a2.x + a2.y;
;         hs += dpp_row_shr(hs, 1); hs += dpp_row_shr(hs, 2); hs += dpp_row_shr(hs, 4); hs += dpp_row_shr(hs, 8);
;         hs += __builtin_bit_cast(float, __builtin_amdgcn_update_dpp(0, __builtin_bit_cast(int, hs), 0x142, 0xa, 0xf, false));
;         const float da = __builtin_bit_cast(float, __builtin_amdgcn_readlane(__builtin_bit_cast(int, hs), 31));
;         const float db = __builtin_bit_cast(float, __builtin_amdgcn_readlane(__builtin_bit_cast(int, hs), 63));
;         dvec = (lane == kb + 2 * pr) ? da : dvec;
;         dvec = (lane == kb + 2 * pr + 1) ? db : dvec;
	v_cvt_scalef32_pk32_f32_fp6 v[0:31], v[234:239], 1.0
	global_load_dwordx2 v[238:239], v167, s[62:63] offset:16
	global_load_dwordx4 v[234:237], v167, s[62:63]
	v_pk_mul_f32 v[246:247], v[0:1], v[96:97]
	v_pk_mul_f32 v[254:255], v[2:3], v[98:99]
	v_pk_mul_f32 v[160:161], v[4:5], v[100:101]
	v_pk_fma_f32 v[246:247], v[6:7], v[102:103], v[246:247]
	v_pk_fma_f32 v[254:255], v[8:9], v[104:105], v[254:255]
	v_pk_fma_f32 v[160:161], v[10:11], v[106:107], v[160:161]
	v_pk_fma_f32 v[246:247], v[12:13], v[108:109], v[246:247]
	v_pk_fma_f32 v[254:255], v[14:15], v[110:111], v[254:255]
	v_pk_fma_f32 v[160:161], v[16:17], v[112:113], v[160:161]
	v_pk_fma_f32 v[246:247], v[18:19], v[114:115], v[246:247]
	v_pk_fma_f32 v[254:255], v[20:21], v[116:117], v[254:255]
	v_pk_fma_f32 v[160:161], v[22:23], v[118:119], v[160:161]
	v_pk_fma_f32 v[246:247], v[24:25], v[120:121], v[246:247]
	v_pk_fma_f32 v[254:255], v[26:27], v[122:123], v[254:255]
	v_pk_fma_f32 v[160:161], v[28:29], v[124:125], v[160:161]
	v_pk_fma_f32 v[246:247], v[30:31], v[126:127], v[246:247]
	v_pk_add_f32 v[254:255], v[254:255], v[160:161]
	s_nop 0
	v_pk_add_f32 v[246:247], v[246:247], v[254:255]
	s_nop 0
	v_add_f32_e32 v164, v246, v247
	v_readlane_b32 s54, v92, 30
	v_readlane_b32 s55, v92, 31
	s_mul_i32 s0, s54, 0x300
	s_mul_i32 s1, s55, 0x300
	v_add_u32_e32 v167, s0, v195
	s_and_saveexec_b64 s[98:99], s[40:41]
	v_add_u32_e32 v167, s1, v195
	s_mov_b64 exec, s[98:99]
	s_waitcnt vmcnt(32)
	v_cvt_scalef32_pk32_f32_fp6 v[0:31], v[240:245], 1.0
	global_load_dwordx2 v[244:245], v167, s[62:63] offset:16
	global_load_dwordx4 v[240:243], v167, s[62:63]
	v_pk_mul_f32 v[246:247], v[0:1], v[96:97]
	v_pk_mul_f32 v[254:255], v[2:3], v[98:99]
	v_pk_mul_f32 v[160:161], v[4:5], v[100:101]
	v_pk_fma_f32 v[246:247], v[6:7], v[102:103], v[246:247]
	v_pk_fma_f32 v[254:255], v[8:9], v[104:105], v[254:255]
	v_pk_fma_f32 v[160:161], v[10:11], v[106:107], v[160:161]
	v_pk_fma_f32 v[246:247], v[12:13], v[108:109], v[246:247]
	v_pk_fma_f32 v[254:255], v[14:15], v[110:111], v[254:255]
	v_pk_fma_f32 v[160:161], v[16:17], v[112:113], v[160:161]
	v_pk_fma_f32 v[246:247], v[18:19], v[114:115], v[246:247]
	v_pk_fma_f32 v[254:255], v[20:21], v[116:117], v[254:255]
	v_pk_fma_f32 v[160:161], v[22:23], v[118:119], v[160:161]
	v_pk_fma_f32 v[246:247], v[24:25], v[120:121], v[246:247]
	v_pk_fma_f32 v[254:255], v[26:27], v[122:123], v[254:255]
	v_pk_fma_f32 v[160:161], v[28:29], v[124:125], v[160:161]
	v_pk_fma_f32 v[246:247], v[30:31], v[126:127], v[246:247]
	v_pk_add_f32 v[254:255], v[254:255], v[160:161]
	s_nop 0
	v_pk_add_f32 v[246:247], v[246:247], v[254:255]
	s_nop 0
	v_add_f32_e32 v165, v246, v247
	v_add_f32_dpp v162, v162, v162 row_shr:1 row_mask:0xf bank_mask:0xf bound_ctrl:1
	v_add_f32_dpp v163, v163, v163 row_shr:1 row_mask:0xf bank_mask:0xf bound_ctrl:1
	v_add_f32_dpp v164, v164, v164 row_shr:1 row_mask:0xf bank_mask:0xf bound_ctrl:1
	v_add_f32_dpp v165, v165, v165 row_shr:1 row_mask:0xf bank_mask:0xf bound_ctrl:1
	v_add_f32_dpp v162, v162, v162 row_shr:2 row_mask:0xf bank_mask:0xf bound_ctrl:1
	v_add_f32_dpp v163, v163, v163 row_shr:2 row_mask:0xf bank_mask:0xf bound_ctrl:1
	v_add_f32_dpp v164, v164, v164 row_shr:2 row_mask:0xf bank_mask:0xf bound_ctrl:1
	v_add_f32_dpp v165, v165, v165 row_shr:2 row_mask:0xf bank_mask:0xf bound_ctrl:1
	v_add_f32_dpp v162, v162, v162 row_shr:4 row_mask:0xf bank_mask:0xf bound_ctrl:1
	v_add_f32_dpp v163, v163, v163 row_shr:4 row_mask:0xf bank_mask:0xf bound_ctrl:1
	v_add_f32_dpp v164, v164, v164 row_shr:4 row_mask:0xf bank_mask:0xf bound_ctrl:1
	v_add_f32_dpp v165, v165, v165 row_shr:4 row_mask:0xf bank_mask:0xf bound_ctrl:1
	v_add_f32_dpp v162, v162, v162 row_shr:8 row_mask:0xf bank_mask:0xf bound_ctrl:1
	v_add_f32_dpp v163, v163, v163 row_shr:8 row_mask:0xf bank_mask:0xf bound_ctrl:1
	v_add_f32_dpp v164, v164, v164 row_shr:8 row_mask:0xf bank_mask:0xf bound_ctrl:1
	v_add_f32_dpp v165, v165, v165 row_shr:8 row_mask:0xf bank_mask:0xf bound_ctrl:1
	v_add_f32_dpp v162, v162, v162 row_bcast:15 row_mask:0xa bank_mask:0xf
	v_add_f32_dpp v163, v163, v163 row_bcast:15 row_mask:0xa bank_mask:0xf
	v_add_f32_dpp v164, v164, v164 row_bcast:15 row_mask:0xa bank_mask:0xf
	v_add_f32_dpp v165, v165, v165 row_bcast:15 row_mask:0xa bank_mask:0xf
	s_mov_b64 s[98:99], exec
	s_mov_b32 exec_lo, 0x80000000
	s_mov_b32 exec_hi, 0x80000000
	ds_write_b32 v74, v162 offset:32
	ds_write_b32 v74, v163 offset:40
	ds_write_b32 v74, v164 offset:48
	ds_write_b32 v74, v165 offset:56
	s_mov_b64 exec, s[98:99]
	v_readlane_b32 s54, v92, 32
	v_readlane_b32 s55, v92, 33
	s_mul_i32 s0, s54, 0x300
	s_mul_i32 s1, s55, 0x300
	v_add_u32_e32 v167, s0, v195
	s_and_saveexec_b64 s[98:99], s[40:41]
	v_add_u32_e32 v167, s1, v195
	s_mov_b64 exec, s[98:99]
	s_waitcnt vmcnt(14)
	v_cvt_scalef32_pk32_f32_fp6 v[0:31], v[50:55], 1.0
	global_load_dwordx2 v[54:55], v167, s[62:63] offset:16
	global_load_dwordx4 v[50:53], v167, s[62:63]
	v_pk_mul_f32 v[246:247], v[0:1], v[96:97]
	v_pk_mul_f32 v[254:255], v[2:3], v[98:99]
	v_pk_mul_f32 v[160:161], v[4:5], v[100:101]
	v_pk_fma_f32 v[246:247], v[6:7], v[102:103], v[246:247]
	v_pk_fma_f32 v[254:255], v[8:9], v[104:105], v[254:255]
	v_pk_fma_f32 v[160:161], v[10:11], v[106:107], v[160:161]
	v_pk_fma_f32 v[246:247], v[12:13], v[108:109], v[246:247]
	v_pk_fma_f32 v[254:255], v[14:15], v[110:111], v[254:255]
	v_pk_fma_f32 v[160:161], v[16:17], v[112:113], v[160:161]
	v_pk_fma_f32 v[246:247], v[18:19], v[114:115], v[246:247]
	v_pk_fma_f32 v[254:255], v[20:21], v[116:117], v[254:255]
	v_pk_fma_f32 v[160:161], v[22:23], v[118:119], v[160:161]
	v_pk_fma_f32 v[246:247], v[24:25], v[120:121], v[246:247]
	v_pk_fma_f32 v[254:255], v[26:27], v[122:123], v[254:255]
	v_pk_fma_f32 v[160:161], v[28:29], v[124:125], v[160:161]
	v_pk_fma_f32 v[246:247], v[30:31], v[126:127], v[246:247]
	v_pk_add_f32 v[254:255], v[254:255], v[160:161]
	s_nop 0
	v_pk_add_f32 v[246:247], v[246:247], v[254:255]
	s_nop 0
	v_add_f32_e32 v162, v246, v247
	v_readlane_b32 s54, v92, 34
	v_readlane_b32 s55, v92, 35
	s_mul_i32 s0, s54, 0x300
	s_mul_i32 s1, s55, 0x300
	v_add_u32_e32 v167, s0, v195
	s_and_saveexec_b64 s[98:99], s[40:41]
	v_add_u32_e32 v167, s1, v195
	s_mov_b64 exec, s[98:99]
	s_waitcnt vmcnt(14)
; __device__ void peer_gather_phase(const Params& P, int l, bool do_store) {
;     ...
;       for (int pr = 0; pr < 4; ++pr) {
;         v6u_t qv; qv[0] = u6[3 * pr].x; qv[1] = u6[3 * pr].y; qv[2] = u6[3 * pr + 1].x; qv[3] = u6[3 * pr + 1].y; qv[4] = u6[3 * pr + 2].x; qv[5] = u6[3 * pr + 2].y;
;         const v32f_t wv = __builtin_amdgcn_cvt_scalef32_pk32_f32_fp6(qv, 1.0f);
;         f32x2 a2 = f32x2{0.f, 0.f};
; #pragma unroll
;         for (int i = 0; i < 16; ++i) a2 += f32x2{wv[2 * i], wv[2 * i + 1]} * xu[i];
;         float hs = a2.x + a2.y;
;         hs += dpp_row_shr(hs, 1); hs += dpp_row_shr(hs, 2); hs += dpp_row_shr(hs, 4); hs += dpp_row_shr(hs, 8);
;         hs += __builtin_bit_cast(float, __builtin_amdgcn_update_dpp(0, __builtin_bit_cast(int, hs), 0x142, 0xa, 0xf, false));
;         const float da = __builtin_bit_cast(float, __builtin_amdgcn_readlane(__builtin_bit_cast(int, hs), 31));
;         const float db = __builtin_bit_cast(float, __builtin_amdgcn_readlane(__builtin_bit_cast(int, hs), 63));
;         dvec = (lane == kb + 2 * pr) ? da : dvec;
;         dvec = (lane == kb + 2 * pr + 1) ? db : dvec;
	v_cvt_scalef32_pk32_f32_fp6 v[0:31], v[44:49], 1.0
	global_load_dwordx2 v[48:49], v167, s[62:63] offset:16
	global_load_dwordx4 v[44:47], v167, s[62:63]
	v_pk_mul_f32 v[246:247], v[0:1], v[96:97]
	v_pk_mul_f32 v[254:255], v[2:3], v[98:99]
	v_pk_mul_f32 v[160:161], v[4:5], v[100:101]
	v_pk_fma_f32 v[246:247], v[6:7], v[102:103], v[246:247]
	v_pk_fma_f32 v[254:255], v[8:9], v[104:105], v[254:255]
	v_pk_fma_f32 v[160:161], v[10:11], v[106:107], v[160:161]
	v_pk_fma_f32 v[246:247], v[12:13], v[108:109], v[246:247]
	v_pk_fma_f32 v[254:255], v[14:15], v[110:111], v[254:255]
	v_pk_fma_f32 v[160:161], v[16:17], v[112:113], v[160:161]
	v_pk_fma_f32 v[246:247], v[18:19], v[114:115], v[246:247]
	v_pk_fma_f32 v[254:255], v[20:21], v[116:117], v[254:255]
	v_pk_fma_f32 v[160:161], v[22:23], v[118:119], v[160:161]
	v_pk_fma_f32 v[246:247], v[24:25], v[120:121], v[246:247]
	v_pk_fma_f32 v[254:255], v[26:27], v[122:123], v[254:255]
	v_pk_fma_f32 v[160:161], v[28:29], v[124:125], v[160:161]
	v_pk_fma_f32 v[246:247], v[30:31], v[126:127], v[246:247]
	v_pk_add_f32 v[254:255], v[254:255], v[160:161]
	s_nop 0
	v_pk_add_f32 v[246:247], v[246:247], v[254:255]
	s_nop 0
	v_add_f32_e32 v163, v246, v247
	v_readlane_b32 s54, v92, 36
	v_readlane_b32 s55, v92, 37
	s_mul_i32 s0, s54, 0x300
	s_mul_i32 s1, s55, 0x300
	v_add_u32_e32 v167, s0, v195
	s_and_saveexec_b64 s[98:99], s[40:41]
	v_add_u32_e32 v167, s1, v195
	s_mov_b64 exec, s[98:99]
	s_waitcnt vmcnt(14)
	v_cvt_scalef32_pk32_f32_fp6 v[0:31], v[38:43], 1.0
	global_load_dwordx2 v[42:43], v167, s[62:63] offset:16
	global_load_dwordx4 v[38:41], v167, s[62:63]
	v_pk_mul_f32 v[246:247], v[0:1], v[96:97]
	v_pk_mul_f32 v[254:255], v[2:3], v[98:99]
	v_pk_mul_f32 v[160:161], v[4:5], v[100:101]
	v_pk_fma_f32 v[246:247], v[6:7], v[102:103], v[246:247]
	v_pk_fma_f32 v[254:255], v[8:9], v[104:105], v[254:255]
	v_pk_fma_f32 v[160:161], v[10:11], v[106:107], v[160:161]
	v_pk_fma_f32 v[246:247], v[12:13], v[108:109], v[246:247]
	v_pk_fma_f32 v[254:255], v[14:15], v[110:111], v[254:255]
	v_pk_fma_f32 v[160:161], v[16:17], v[112:113], v[160:161]
	v_pk_fma_f32 v[246:247], v[18:19], v[114:115], v[246:247]
	v_pk_fma_f32 v[254:255], v[20:21], v[116:117], v[254:255]
	v_pk_fma_f32 v[160:161], v[22:23], v[118:119], v[160:161]
	v_pk_fma_f32 v[246:247], v[24:25], v[120:121], v[246:247]
	v_pk_fma_f32 v[254:255], v[26:27], v[122:123], v[254:255]
	v_pk_fma_f32 v[160:161], v[28:29], v[124:125], v[160:161]
	v_pk_fma_f32 v[246:247], v[30:31], v[126:127], v[246:247]
	v_pk_add_f32 v[254:255], v[254:255], v[160:161]
	s_nop 0
	v_pk_add_f32 v[246:247], v[246:247], v[254:255]
	s_nop 0
	v_add_f32_e32 v164, v246, v247
	v_readlane_b32 s54, v92, 38
	v_readlane_b32 s55, v92, 39
	s_mul_i32 s0, s54, 0x300
	s_mul_i32 s1, s55, 0x300
	v_add_u32_e32 v167, s0, v195
	s_and_saveexec_b64 s[98:99], s[40:41]
	v_add_u32_e32 v167, s1, v195
	s_mov_b64 exec, s[98:99]
	s_waitcnt vmcnt(14)
	v_cvt_scalef32_pk32_f32_fp6 v[0:31], v[32:37], 1.0
	global_load_dwordx2 v[36:37], v167, s[62:63] offset:16
	global_load_dwordx4 v[32:35], v167, s[62:63]
	v_pk_mul_f32 v[246:247], v[0:1], v[96:97]
	v_pk_mul_f32 v[254:255], v[2:3], v[98:99]
	v_pk_mul_f32 v[160:161], v[4:5], v[100:101]
	v_pk_fma_f32 v[246:247], v[6:7], v[102:103], v[246:247]
	v_pk_fma_f32 v[254:255], v[8:9], v[104:105], v[254:255]
	v_pk_fma_f32 v[160:161], v[10:11], v[106:107], v[160:161]
	v_pk_fma_f32 v[246:247], v[12:13], v[108:109], v[246:247]
	v_pk_fma_f32 v[254:255], v[14:15], v[110:111], v[254:255]
	v_pk_fma_f32 v[160:161], v[16:17], v[112:113], v[160:161]
	v_pk_fma_f32 v[246:247], v[18:19], v[114:115], v[246:247]
	v_pk_fma_f32 v[254:255], v[20:21], v[116:117], v[254:255]
	v_pk_fma_f32 v[160:161], v[22:23], v[118:119], v[160:161]
	v_pk_fma_f32 v[246:247], v[24:25], v[120:121], v[246:247]
	v_pk_fma_f32 v[254:255], v[26:27], v[122:123], v[254:255]
	v_pk_fma_f32 v[160:161], v[28:29], v[124:125], v[160:161]
	v_pk_fma_f32 v[246:247], v[30:31], v[126:127], v[246:247]
	v_pk_add_f32 v[254:255], v[254:255], v[160:161]
	s_nop 0
	v_pk_add_f32 v[246:247], v[246:247], v[254:255]
	s_nop 0
	v_add_f32_e32 v165, v246, v247
	v_add_f32_dpp v162, v162, v162 row_shr:1 row_mask:0xf bank_mask:0xf bound_ctrl:1
	v_add_f32_dpp v163, v163, v163 row_shr:1 row_mask:0xf bank_mask:0xf bound_ctrl:1
	v_add_f32_dpp v164, v164, v164 row_shr:1 row_mask:0xf bank_mask:0xf bound_ctrl:1
	v_add_f32_dpp v165, v165, v165 row_shr:1 row_mask:0xf bank_mask:0xf bound_ctrl:1
	v_add_f32_dpp v162, v162, v162 row_shr:2 row_mask:0xf bank_mask:0xf bound_ctrl:1
	v_add_f32_dpp v163, v163, v163 row_shr:2 row_mask:0xf bank_mask:0xf bound_ctrl:1
	v_add_f32_dpp v164, v164, v164 row_shr:2 row_mask:0xf bank_mask:0xf bound_ctrl:1
	v_add_f32_dpp v165, v165, v165 row_shr:2 row_mask:0xf bank_mask:0xf bound_ctrl:1
	v_add_f32_dpp v162, v162, v162 row_shr:4 row_mask:0xf bank_mask:0xf bound_ctrl:1
	v_add_f32_dpp v163, v163, v163 row_shr:4 row_mask:0xf bank_mask:0xf bound_ctrl:1
	v_add_f32_dpp v164, v164, v164 row_shr:4 row_mask:0xf bank_mask:0xf bound_ctrl:1
	v_add_f32_dpp v165, v165, v165 row_shr:4 row_mask:0xf bank_mask:0xf bound_ctrl:1
	v_add_f32_dpp v162, v162, v162 row_shr:8 row_mask:0xf bank_mask:0xf bound_ctrl:1
	v_add_f32_dpp v163, v163, v163 row_shr:8 row_mask:0xf bank_mask:0xf bound_ctrl:1
	v_add_f32_dpp v164, v164, v164 row_shr:8 row_mask:0xf bank_mask:0xf bound_ctrl:1
	v_add_f32_dpp v165, v165, v165 row_shr:8 row_mask:0xf bank_mask:0xf bound_ctrl:1
	v_add_f32_dpp v162, v162, v162 row_bcast:15 row_mask:0xa bank_mask:0xf
	v_add_f32_dpp v163, v163, v163 row_bcast:15 row_mask:0xa bank_mask:0xf
	v_add_f32_dpp v164, v164, v164 row_bcast:15 row_mask:0xa bank_mask:0xf
	v_add_f32_dpp v165, v165, v165 row_bcast:15 row_mask:0xa bank_mask:0xf
	s_mov_b64 s[98:99], exec
	s_mov_b32 exec_lo, 0x80000000
	s_mov_b32 exec_hi, 0x80000000
	ds_write_b32 v74, v162 offset:64
	ds_write_b32 v74, v163 offset:72
	ds_write_b32 v74, v164 offset:80
	ds_write_b32 v74, v165 offset:88
	s_mov_b64 exec, s[98:99]
	v_readlane_b32 s54, v92, 40
	v_readlane_b32 s55, v92, 41
	s_mul_i32 s0, s54, 0x300
	s_mul_i32 s1, s55, 0x300
	v_add_u32_e32 v167, s0, v195
	s_and_saveexec_b64 s[98:99], s[40:41]
	v_add_u32_e32 v167, s1, v195
	s_mov_b64 exec, s[98:99]
	s_waitcnt vmcnt(14)
; __device__ void peer_gather_phase(const Params& P, int l, bool do_store) {
;     ...
;         const int ea = __builtin_amdgcn_readlane(evs, kb + 2 * pr), eb = __builtin_amdgcn_readlane(evs, kb + 2 * pr + 1);
;         const uint2* up = (const uint2*)(U + (size_t)(uphi ? eb : ea) * 768);
;         u6[3 * pr] = up[0]; u6[3 * pr + 1] = up[1]; u6[3 * pr + 2] = up[2];
;         v8[2 * pr] = *(const uint2*)(V + (size_t)ea * 512);
;         v8[2 * pr + 1] = *(const uint2*)(V + (size_t)eb * 512);
;       }
;     };
;     auto compute_batch = [&](const uint2 (&u6)[12], const uint2 (&v8)[8], int bt) {
;       const int kb = (bt & 7) * 8;
;       float dvec = 0.f;
; #pragma unroll
;       for (int pr = 0; pr < 4; ++pr) {
;         v6u_t qv; qv[0] = u6[3 * pr].x; qv[1] = u6[3 * pr].y; qv[2] = u6[3 * pr + 1].x; qv[3] = u6[3 * pr + 1].y; qv[4] = u6[3 * pr + 2].x; qv[5] = u6[3 * pr + 2].y;
;         const v32f_t wv = __builtin_amdgcn_cvt_scalef32_pk32_f32_fp6(qv, 1.0f);
;         f32x2 a2 = f32x2{0.f, 0.f};
; #pragma unroll
;         for (int i = 0; i < 16; ++i) a2 += f32x2{wv[2 * i], wv[2 * i + 1]} * xu[i];
;         float hs = a2.x + a2.y;
	v_cvt_scalef32_pk32_f32_fp6 v[0:31], v[196:201], 1.0
	global_load_dwordx2 v[200:201], v167, s[62:63] offset:16
	global_load_dwordx4 v[196:199], v167, s[62:63]
	v_pk_mul_f32 v[246:247], v[0:1], v[96:97]
	v_pk_mul_f32 v[254:255], v[2:3], v[98:99]
	v_pk_mul_f32 v[160:161], v[4:5], v[100:101]
	v_pk_fma_f32 v[246:247], v[6:7], v[102:103], v[246:247]
	v_pk_fma_f32 v[254:255], v[8:9], v[104:105], v[254:255]
	v_pk_fma_f32 v[160:161], v[10:11], v[106:107], v[160:161]
	v_pk_fma_f32 v[246:247], v[12:13], v[108:109], v[246:247]
	v_pk_fma_f32 v[254:255], v[14:15], v[110:111], v[254:255]
	v_pk_fma_f32 v[160:161], v[16:17], v[112:113], v[160:161]
	v_pk_fma_f32 v[246:247], v[18:19], v[114:115], v[246:247]
	v_pk_fma_f32 v[254:255], v[20:21], v[116:117], v[254:255]
	v_pk_fma_f32 v[160:161], v[22:23], v[118:119], v[160:161]
	v_pk_fma_f32 v[246:247], v[24:25], v[120:121], v[246:247]
	v_pk_fma_f32 v[254:255], v[26:27], v[122:123], v[254:255]
	v_pk_fma_f32 v[160:161], v[28:29], v[124:125], v[160:161]
	v_pk_fma_f32 v[246:247], v[30:31], v[126:127], v[246:247]
	v_pk_add_f32 v[254:255], v[254:255], v[160:161]
	s_nop 0
	v_pk_add_f32 v[246:247], v[246:247], v[254:255]
	s_nop 0
	v_add_f32_e32 v162, v246, v247
	v_readlane_b32 s54, v92, 42
	v_readlane_b32 s55, v92, 43
	s_mul_i32 s0, s54, 0x300
	s_mul_i32 s1, s55, 0x300
	v_add_u32_e32 v167, s0, v195
	s_and_saveexec_b64 s[98:99], s[40:41]
	v_add_u32_e32 v167, s1, v195
	s_mov_b64 exec, s[98:99]
	s_waitcnt vmcnt(14)
	v_cvt_scalef32_pk32_f32_fp6 v[0:31], v[228:233], 1.0
	global_load_dwordx2 v[232:233], v167, s[62:63] offset:16
	global_load_dwordx4 v[228:231], v167, s[62:63]
	v_pk_mul_f32 v[246:247], v[0:1], v[96:97]
	v_pk_mul_f32 v[254:255], v[2:3], v[98:99]
	v_pk_mul_f32 v[160:161], v[4:5], v[100:101]
	v_pk_fma_f32 v[246:247], v[6:7], v[102:103], v[246:247]
	v_pk_fma_f32 v[254:255], v[8:9], v[104:105], v[254:255]
	v_pk_fma_f32 v[160:161], v[10:11], v[106:107], v[160:161]
	v_pk_fma_f32 v[246:247], v[12:13], v[108:109], v[246:247]
	v_pk_fma_f32 v[254:255], v[14:15], v[110:111], v[254:255]
	v_pk_fma_f32 v[160:161], v[16:17], v[112:113], v[160:161]
	v_pk_fma_f32 v[246:247], v[18:19], v[114:115], v[246:247]
	v_pk_fma_f32 v[254:255], v[20:21], v[116:117], v[254:255]
	v_pk_fma_f32 v[160:161], v[22:23], v[118:119], v[160:161]
	v_pk_fma_f32 v[246:247], v[24:25], v[120:121], v[246:247]
	v_pk_fma_f32 v[254:255], v[26:27], v[122:123], v[254:255]
	v_pk_fma_f32 v[160:161], v[28:29], v[124:125], v[160:161]
	v_pk_fma_f32 v[246:247], v[30:31], v[126:127], v[246:247]
	v_pk_add_f32 v[254:255], v[254:255], v[160:161]
	s_nop 0
	v_pk_add_f32 v[246:247], v[246:247], v[254:255]
	s_nop 0
	v_add_f32_e32 v163, v246, v247
	v_readlane_b32 s54, v92, 44
	v_readlane_b32 s55, v92, 45
	s_mul_i32 s0, s54, 0x300
	s_mul_i32 s1, s55, 0x300
	v_add_u32_e32 v167, s0, v195
	s_and_saveexec_b64 s[98:99], s[40:41]
	v_add_u32_e32 v167, s1, v195
	s_mov_b64 exec, s[98:99]
	s_waitcnt vmcnt(14)
	v_cvt_scalef32_pk32_f32_fp6 v[0:31], v[234:239], 1.0
	global_load_dwordx2 v[238:239], v167, s[62:63] offset:16
	global_load_dwordx4 v[234:237], v167, s[62:63]
	v_pk_mul_f32 v[246:247], v[0:1], v[96:97]
	v_pk_mul_f32 v[254:255], v[2:3], v[98:99]
	v_pk_mul_f32 v[160:161], v[4:5], v[100:101]
	v_pk_fma_f32 v[246:247], v[6:7], v[102:103], v[246:247]
	v_pk_fma_f32 v[254:255], v[8:9], v[104:105], v[254:255]
	v_pk_fma_f32 v[160:161], v[10:11], v[106:107], v[160:161]
	v_pk_fma_f32 v[246:247], v[12:13], v[108:109], v[246:247]
	v_pk_fma_f32 v[254:255], v[14:15], v[110:111], v[254:255]
	v_pk_fma_f32 v[160:161], v[16:17], v[112:113], v[160:161]
	v_pk_fma_f32 v[246:247], v[18:19], v[114:115], v[246:247]
	v_pk_fma_f32 v[254:255], v[20:21], v[116:117], v[254:255]
	v_pk_fma_f32 v[160:161], v[22:23], v[118:119], v[160:161]
	v_pk_fma_f32 v[246:247], v[24:25], v[120:121], v[246:247]
	v_pk_fma_f32 v[254:255], v[26:27], v[122:123], v[254:255]
	v_pk_fma_f32 v[160:161], v[28:29], v[124:125], v[160:161]
	v_pk_fma_f32 v[246:247], v[30:31], v[126:127], v[246:247]
	v_pk_add_f32 v[254:255], v[254:255], v[160:161]
	s_nop 0
	v_pk_add_f32 v[246:247], v[246:247], v[254:255]
	s_nop 0
	v_add_f32_e32 v164, v246, v247
	v_readlane_b32 s54, v92, 46
	v_readlane_b32 s55, v92, 47
	s_mul_i32 s0, s54, 0x300
	s_mul_i32 s1, s55, 0x300
	v_add_u32_e32 v167, s0, v195
	s_and_saveexec_b64 s[98:99], s[40:41]
	v_add_u32_e32 v167, s1, v195
	s_mov_b64 exec, s[98:99]
	s_waitcnt vmcnt(14)
; __device__ void peer_gather_phase(const Params& P, int l, bool do_store) {
;     ...
;       for (int pr = 0; pr < 4; ++pr) {
;         v6u_t qv; qv[0] = u6[3 * pr].x; qv[1] = u6[3 * pr].y; qv[2] = u6[3 * pr + 1].x; qv[3] = u6[3 * pr + 1].y; qv[4] = u6[3 * pr + 2].x; qv[5] = u6[3 * pr + 2].y;
;         const v32f_t wv = __builtin_amdgcn_cvt_scalef32_pk32_f32_fp6(qv, 1.0f);
;         f32x2 a2 = f32x2{0.f, 0.f};
; #pragma unroll
;         for (int i = 0; i < 16; ++i) a2 += f32x2{wv[2 * i], wv[2 * i + 1]} * xu[i];
;         float hs = a2.x + a2.y;
;         hs += dpp_row_shr(hs, 1); hs += dpp_row_shr(hs, 2); hs += dpp_row_shr(hs, 4); hs += dpp_row_shr(hs, 8);
;         hs += __builtin_bit_cast(float, __builtin_amdgcn_update_dpp(0, __builtin_bit_cast(int, hs), 0x142, 0xa, 0xf, false));
;         const float da = __builtin_bit_cast(float, __builtin_amdgcn_readlane(__builtin_bit_cast(int, hs), 31));
;         const float db = __builtin_bit_cast(float, __builtin_amdgcn_readlane(__builtin_bit_cast(int, hs), 63));
;         dvec = (lane == kb + 2 * pr) ? da : dvec;
;         dvec = (lane == kb + 2 * pr + 1) ? db : dvec;
	v_cvt_scalef32_pk32_f32_fp6 v[0:31], v[240:245], 1.0
	global_load_dwordx2 v[244:245], v167, s[62:63] offset:16
	global_load_dwordx4 v[240:243], v167, s[62:63]
	v_pk_mul_f32 v[246:247], v[0:1], v[96:97]
	v_pk_mul_f32 v[254:255], v[2:3], v[98:99]
	v_pk_mul_f32 v[160:161], v[4:5], v[100:101]
	v_pk_fma_f32 v[246:247], v[6:7], v[102:103], v[246:247]
	v_pk_fma_f32 v[254:255], v[8:9], v[104:105], v[254:255]
	v_pk_fma_f32 v[160:161], v[10:11], v[106:107], v[160:161]
	v_pk_fma_f32 v[246:247], v[12:13], v[108:109], v[246:247]
	v_pk_fma_f32 v[254:255], v[14:15], v[110:111], v[254:255]
	v_pk_fma_f32 v[160:161], v[16:17], v[112:113], v[160:161]
	v_pk_fma_f32 v[246:247], v[18:19], v[114:115], v[246:247]
	v_pk_fma_f32 v[254:255], v[20:21], v[116:117], v[254:255]
	v_pk_fma_f32 v[160:161], v[22:23], v[118:119], v[160:161]
	v_pk_fma_f32 v[246:247], v[24:25], v[120:121], v[246:247]
	v_pk_fma_f32 v[254:255], v[26:27], v[122:123], v[254:255]
	v_pk_fma_f32 v[160:161], v[28:29], v[124:125], v[160:161]
	v_pk_fma_f32 v[246:247], v[30:31], v[126:127], v[246:247]
	v_pk_add_f32 v[254:255], v[254:255], v[160:161]
	s_nop 0
	v_pk_add_f32 v[246:247], v[246:247], v[254:255]
	s_nop 0
	v_add_f32_e32 v165, v246, v247
	v_add_f32_dpp v162, v162, v162 row_shr:1 row_mask:0xf bank_mask:0xf bound_ctrl:1
	v_add_f32_dpp v163, v163, v163 row_shr:1 row_mask:0xf bank_mask:0xf bound_ctrl:1
	v_add_f32_dpp v164, v164, v164 row_shr:1 row_mask:0xf bank_mask:0xf bound_ctrl:1
	v_add_f32_dpp v165, v165, v165 row_shr:1 row_mask:0xf bank_mask:0xf bound_ctrl:1
	v_add_f32_dpp v162, v162, v162 row_shr:2 row_mask:0xf bank_mask:0xf bound_ctrl:1
	v_add_f32_dpp v163, v163, v163 row_shr:2 row_mask:0xf bank_mask:0xf bound_ctrl:1
	v_add_f32_dpp v164, v164, v164 row_shr:2 row_mask:0xf bank_mask:0xf bound_ctrl:1
	v_add_f32_dpp v165, v165, v165 row_shr:2 row_mask:0xf bank_mask:0xf bound_ctrl:1
	v_add_f32_dpp v162, v162, v162 row_shr:4 row_mask:0xf bank_mask:0xf bound_ctrl:1
	v_add_f32_dpp v163, v163, v163 row_shr:4 row_mask:0xf bank_mask:0xf bound_ctrl:1
	v_add_f32_dpp v164, v164, v164 row_shr:4 row_mask:0xf bank_mask:0xf bound_ctrl:1
	v_add_f32_dpp v165, v165, v165 row_shr:4 row_mask:0xf bank_mask:0xf bound_ctrl:1
	v_add_f32_dpp v162, v162, v162 row_shr:8 row_mask:0xf bank_mask:0xf bound_ctrl:1
	v_add_f32_dpp v163, v163, v163 row_shr:8 row_mask:0xf bank_mask:0xf bound_ctrl:1
	v_add_f32_dpp v164, v164, v164 row_shr:8 row_mask:0xf bank_mask:0xf bound_ctrl:1
	v_add_f32_dpp v165, v165, v165 row_shr:8 row_mask:0xf bank_mask:0xf bound_ctrl:1
	v_add_f32_dpp v162, v162, v162 row_bcast:15 row_mask:0xa bank_mask:0xf
	v_add_f32_dpp v163, v163, v163 row_bcast:15 row_mask:0xa bank_mask:0xf
	v_add_f32_dpp v164, v164, v164 row_bcast:15 row_mask:0xa bank_mask:0xf
	v_add_f32_dpp v165, v165, v165 row_bcast:15 row_mask:0xa bank_mask:0xf
	s_mov_b64 s[98:99], exec
	s_mov_b32 exec_lo, 0x80000000
	s_mov_b32 exec_hi, 0x80000000
	ds_write_b32 v74, v162 offset:96
	ds_write_b32 v74, v163 offset:104
	ds_write_b32 v74, v164 offset:112
	ds_write_b32 v74, v165 offset:120
	s_mov_b64 exec, s[98:99]
	v_readlane_b32 s54, v92, 48
	v_readlane_b32 s55, v92, 49
	s_mul_i32 s0, s54, 0x300
	s_mul_i32 s1, s55, 0x300
	v_add_u32_e32 v167, s0, v195
	s_and_saveexec_b64 s[98:99], s[40:41]
	v_add_u32_e32 v167, s1, v195
	s_mov_b64 exec, s[98:99]
	s_waitcnt vmcnt(14)
	v_cvt_scalef32_pk32_f32_fp6 v[0:31], v[50:55], 1.0
	global_load_dwordx2 v[54:55], v167, s[62:63] offset:16
	global_load_dwordx4 v[50:53], v167, s[62:63]
	v_pk_mul_f32 v[246:247], v[0:1], v[96:97]
	v_pk_mul_f32 v[254:255], v[2:3], v[98:99]
	v_pk_mul_f32 v[160:161], v[4:5], v[100:101]
	v_pk_fma_f32 v[246:247], v[6:7], v[102:103], v[246:247]
	v_pk_fma_f32 v[254:255], v[8:9], v[104:105], v[254:255]
	v_pk_fma_f32 v[160:161], v[10:11], v[106:107], v[160:161]
	v_pk_fma_f32 v[246:247], v[12:13], v[108:109], v[246:247]
	v_pk_fma_f32 v[254:255], v[14:15], v[110:111], v[254:255]
	v_pk_fma_f32 v[160:161], v[16:17], v[112:113], v[160:161]
	v_pk_fma_f32 v[246:247], v[18:19], v[114:115], v[246:247]
	v_pk_fma_f32 v[254:255], v[20:21], v[116:117], v[254:255]
	v_pk_fma_f32 v[160:161], v[22:23], v[118:119], v[160:161]
	v_pk_fma_f32 v[246:247], v[24:25], v[120:121], v[246:247]
	v_pk_fma_f32 v[254:255], v[26:27], v[122:123], v[254:255]
	v_pk_fma_f32 v[160:161], v[28:29], v[124:125], v[160:161]
	v_pk_fma_f32 v[246:247], v[30:31], v[126:127], v[246:247]
	v_pk_add_f32 v[254:255], v[254:255], v[160:161]
	s_nop 0
	v_pk_add_f32 v[246:247], v[246:247], v[254:255]
	s_nop 0
	v_add_f32_e32 v162, v246, v247
	v_readlane_b32 s54, v92, 50
	v_readlane_b32 s55, v92, 51
	s_mul_i32 s0, s54, 0x300
	s_mul_i32 s1, s55, 0x300
	v_add_u32_e32 v167, s0, v195
	s_and_saveexec_b64 s[98:99], s[40:41]
	v_add_u32_e32 v167, s1, v195
	s_mov_b64 exec, s[98:99]
	s_waitcnt vmcnt(14)
	v_cvt_scalef32_pk32_f32_fp6 v[0:31], v[44:49], 1.0
	global_load_dwordx2 v[48:49], v167, s[62:63] offset:16
	global_load_dwordx4 v[44:47], v167, s[62:63]
	v_pk_mul_f32 v[246:247], v[0:1], v[96:97]
	v_pk_mul_f32 v[254:255], v[2:3], v[98:99]
	v_pk_mul_f32 v[160:161], v[4:5], v[100:101]
	v_pk_fma_f32 v[246:247], v[6:7], v[102:103], v[246:247]
	v_pk_fma_f32 v[254:255], v[8:9], v[104:105], v[254:255]
	v_pk_fma_f32 v[160:161], v[10:11], v[106:107], v[160:161]
	v_pk_fma_f32 v[246:247], v[12:13], v[108:109], v[246:247]
	v_pk_fma_f32 v[254:255], v[14:15], v[110:111], v[254:255]
	v_pk_fma_f32 v[160:161], v[16:17], v[112:113], v[160:161]
	v_pk_fma_f32 v[246:247], v[18:19], v[114:115], v[246:247]
	v_pk_fma_f32 v[254:255], v[20:21], v[116:117], v[254:255]
	v_pk_fma_f32 v[160:161], v[22:23], v[118:119], v[160:161]
	v_pk_fma_f32 v[246:247], v[24:25], v[120:121], v[246:247]
	v_pk_fma_f32 v[254:255], v[26:27], v[122:123], v[254:255]
	v_pk_fma_f32 v[160:161], v[28:29], v[124:125], v[160:161]
	v_pk_fma_f32 v[246:247], v[30:31], v[126:127], v[246:247]
	v_pk_add_f32 v[254:255], v[254:255], v[160:161]
	s_nop 0
	v_pk_add_f32 v[246:247], v[246:247], v[254:255]
	s_nop 0
	v_add_f32_e32 v163, v246, v247
	v_readlane_b32 s54, v92, 52
	v_readlane_b32 s55, v92, 53
	s_mul_i32 s0, s54, 0x300
	s_mul_i32 s1, s55, 0x300
	v_add_u32_e32 v167, s0, v195
	s_and_saveexec_b64 s[98:99], s[40:41]
	v_add_u32_e32 v167, s1, v195
	s_mov_b64 exec, s[98:99]
	s_waitcnt vmcnt(14)
; __device__ void peer_gather_phase(const Params& P, int l, bool do_store) {
;     ...
;       for (int pr = 0; pr < 4; ++pr) {
;         v6u_t qv; qv[0] = u6[3 * pr].x; qv[1] = u6[3 * pr].y; qv[2] = u6[3 * pr + 1].x; qv[3] = u6[3 * pr + 1].y; qv[4] = u6[3 * pr + 2].x; qv[5] = u6[3 * pr + 2].y;
;         const v32f_t wv = __builtin_amdgcn_cvt_scalef32_pk32_f32_fp6(qv, 1.0f);
;         f32x2 a2 = f32x2{0.f, 0.f};
; #pragma unroll
;         for (int i = 0; i < 16; ++i) a2 += f32x2{wv[2 * i], wv[2 * i + 1]} * xu[i];
;         float hs = a2.x + a2.y;
;         hs += dpp_row_shr(hs, 1); hs += dpp_row_shr(hs, 2); hs += dpp_row_shr(hs, 4); hs += dpp_row_shr(hs, 8);
;         hs += __builtin_bit_cast(float, __builtin_amdgcn_update_dpp(0, __builtin_bit_cast(int, hs), 0x142, 0xa, 0xf, false));
;         const float da = __builtin_bit_cast(float, __builtin_amdgcn_readlane(__builtin_bit_cast(int, hs), 31));
;         const float db = __builtin_bit_cast(float, __builtin_amdgcn_readlane(__builtin_bit_cast(int, hs), 63));
;         dvec = (lane == kb + 2 * pr) ? da : dvec;
;         dvec = (lane == kb + 2 * pr + 1) ? db : dvec;
	v_cvt_scalef32_pk32_f32_fp6 v[0:31], v[38:43], 1.0
	global_load_dwordx2 v[42:43], v167, s[62:63] offset:16
	global_load_dwordx4 v[38:41], v167, s[62:63]
	v_pk_mul_f32 v[246:247], v[0:1], v[96:97]
	v_pk_mul_f32 v[254:255], v[2:3], v[98:99]
	v_pk_mul_f32 v[160:161], v[4:5], v[100:101]
	v_pk_fma_f32 v[246:247], v[6:7], v[102:103], v[246:247]
	v_pk_fma_f32 v[254:255], v[8:9], v[104:105], v[254:255]
	v_pk_fma_f32 v[160:161], v[10:11], v[106:107], v[160:161]
	v_pk_fma_f32 v[246:247], v[12:13], v[108:109], v[246:247]
	v_pk_fma_f32 v[254:255], v[14:15], v[110:111], v[254:255]
	v_pk_fma_f32 v[160:161], v[16:17], v[112:113], v[160:161]
	v_pk_fma_f32 v[246:247], v[18:19], v[114:115], v[246:247]
	v_pk_fma_f32 v[254:255], v[20:21], v[116:117], v[254:255]
	v_pk_fma_f32 v[160:161], v[22:23], v[118:119], v[160:161]
	v_pk_fma_f32 v[246:247], v[24:25], v[120:121], v[246:247]
	v_pk_fma_f32 v[254:255], v[26:27], v[122:123], v[254:255]
	v_pk_fma_f32 v[160:161], v[28:29], v[124:125], v[160:161]
	v_pk_fma_f32 v[246:247], v[30:31], v[126:127], v[246:247]
	v_pk_add_f32 v[254:255], v[254:255], v[160:161]
	s_nop 0
	v_pk_add_f32 v[246:247], v[246:247], v[254:255]
	s_nop 0
	v_add_f32_e32 v164, v246, v247
	v_readlane_b32 s54, v92, 54
	v_readlane_b32 s55, v92, 55
	s_mul_i32 s0, s54, 0x300
	s_mul_i32 s1, s55, 0x300
	v_add_u32_e32 v167, s0, v195
	s_and_saveexec_b64 s[98:99], s[40:41]
	v_add_u32_e32 v167, s1, v195
	s_mov_b64 exec, s[98:99]
	s_waitcnt vmcnt(14)
	v_cvt_scalef32_pk32_f32_fp6 v[0:31], v[32:37], 1.0
	global_load_dwordx2 v[36:37], v167, s[62:63] offset:16
	global_load_dwordx4 v[32:35], v167, s[62:63]
	v_pk_mul_f32 v[246:247], v[0:1], v[96:97]
	v_pk_mul_f32 v[254:255], v[2:3], v[98:99]
	v_pk_mul_f32 v[160:161], v[4:5], v[100:101]
	v_pk_fma_f32 v[246:247], v[6:7], v[102:103], v[246:247]
	v_pk_fma_f32 v[254:255], v[8:9], v[104:105], v[254:255]
	v_pk_fma_f32 v[160:161], v[10:11], v[106:107], v[160:161]
	v_pk_fma_f32 v[246:247], v[12:13], v[108:109], v[246:247]
	v_pk_fma_f32 v[254:255], v[14:15], v[110:111], v[254:255]
	v_pk_fma_f32 v[160:161], v[16:17], v[112:113], v[160:161]
	v_pk_fma_f32 v[246:247], v[18:19], v[114:115], v[246:247]
	v_pk_fma_f32 v[254:255], v[20:21], v[116:117], v[254:255]
	v_pk_fma_f32 v[160:161], v[22:23], v[118:119], v[160:161]
	v_pk_fma_f32 v[246:247], v[24:25], v[120:121], v[246:247]
	v_pk_fma_f32 v[254:255], v[26:27], v[122:123], v[254:255]
	v_pk_fma_f32 v[160:161], v[28:29], v[124:125], v[160:161]
	v_pk_fma_f32 v[246:247], v[30:31], v[126:127], v[246:247]
	v_pk_add_f32 v[254:255], v[254:255], v[160:161]
	s_nop 0
	v_pk_add_f32 v[246:247], v[246:247], v[254:255]
	s_nop 0
	v_add_f32_e32 v165, v246, v247
	v_add_f32_dpp v162, v162, v162 row_shr:1 row_mask:0xf bank_mask:0xf bound_ctrl:1
	v_add_f32_dpp v163, v163, v163 row_shr:1 row_mask:0xf bank_mask:0xf bound_ctrl:1
	v_add_f32_dpp v164, v164, v164 row_shr:1 row_mask:0xf bank_mask:0xf bound_ctrl:1
	v_add_f32_dpp v165, v165, v165 row_shr:1 row_mask:0xf bank_mask:0xf bound_ctrl:1
	v_add_f32_dpp v162, v162, v162 row_shr:2 row_mask:0xf bank_mask:0xf bound_ctrl:1
	v_add_f32_dpp v163, v163, v163 row_shr:2 row_mask:0xf bank_mask:0xf bound_ctrl:1
	v_add_f32_dpp v164, v164, v164 row_shr:2 row_mask:0xf bank_mask:0xf bound_ctrl:1
	v_add_f32_dpp v165, v165, v165 row_shr:2 row_mask:0xf bank_mask:0xf bound_ctrl:1
	v_add_f32_dpp v162, v162, v162 row_shr:4 row_mask:0xf bank_mask:0xf bound_ctrl:1
	v_add_f32_dpp v163, v163, v163 row_shr:4 row_mask:0xf bank_mask:0xf bound_ctrl:1
	v_add_f32_dpp v164, v164, v164 row_shr:4 row_mask:0xf bank_mask:0xf bound_ctrl:1
	v_add_f32_dpp v165, v165, v165 row_shr:4 row_mask:0xf bank_mask:0xf bound_ctrl:1
	v_add_f32_dpp v162, v162, v162 row_shr:8 row_mask:0xf bank_mask:0xf bound_ctrl:1
	v_add_f32_dpp v163, v163, v163 row_shr:8 row_mask:0xf bank_mask:0xf bound_ctrl:1
	v_add_f32_dpp v164, v164, v164 row_shr:8 row_mask:0xf bank_mask:0xf bound_ctrl:1
	v_add_f32_dpp v165, v165, v165 row_shr:8 row_mask:0xf bank_mask:0xf bound_ctrl:1
	v_add_f32_dpp v162, v162, v162 row_bcast:15 row_mask:0xa bank_mask:0xf
	v_add_f32_dpp v163, v163, v163 row_bcast:15 row_mask:0xa bank_mask:0xf
	v_add_f32_dpp v164, v164, v164 row_bcast:15 row_mask:0xa bank_mask:0xf
	v_add_f32_dpp v165, v165, v165 row_bcast:15 row_mask:0xa bank_mask:0xf
	s_mov_b64 s[98:99], exec
	s_mov_b32 exec_lo, 0x80000000
	s_mov_b32 exec_hi, 0x80000000
	ds_write_b32 v74, v162 offset:128
	ds_write_b32 v74, v163 offset:136
	ds_write_b32 v74, v164 offset:144
	ds_write_b32 v74, v165 offset:152
	s_mov_b64 exec, s[98:99]
	v_readlane_b32 s54, v92, 56
	v_readlane_b32 s55, v92, 57
	s_mul_i32 s0, s54, 0x300
	s_mul_i32 s1, s55, 0x300
	v_add_u32_e32 v167, s0, v195
	s_and_saveexec_b64 s[98:99], s[40:41]
	v_add_u32_e32 v167, s1, v195
	s_mov_b64 exec, s[98:99]
	s_waitcnt vmcnt(14)
	v_cvt_scalef32_pk32_f32_fp6 v[0:31], v[196:201], 1.0
	global_load_dwordx2 v[200:201], v167, s[62:63] offset:16
	global_load_dwordx4 v[196:199], v167, s[62:63]
	v_pk_mul_f32 v[246:247], v[0:1], v[96:97]
	v_pk_mul_f32 v[254:255], v[2:3], v[98:99]
	v_pk_mul_f32 v[160:161], v[4:5], v[100:101]
	v_pk_fma_f32 v[246:247], v[6:7], v[102:103], v[246:247]
	v_pk_fma_f32 v[254:255], v[8:9], v[104:105], v[254:255]
	v_pk_fma_f32 v[160:161], v[10:11], v[106:107], v[160:161]
	v_pk_fma_f32 v[246:247], v[12:13], v[108:109], v[246:247]
	v_pk_fma_f32 v[254:255], v[14:15], v[110:111], v[254:255]
	v_pk_fma_f32 v[160:161], v[16:17], v[112:113], v[160:161]
	v_pk_fma_f32 v[246:247], v[18:19], v[114:115], v[246:247]
	v_pk_fma_f32 v[254:255], v[20:21], v[116:117], v[254:255]
	v_pk_fma_f32 v[160:161], v[22:23], v[118:119], v[160:161]
	v_pk_fma_f32 v[246:247], v[24:25], v[120:121], v[246:247]
	v_pk_fma_f32 v[254:255], v[26:27], v[122:123], v[254:255]
	v_pk_fma_f32 v[160:161], v[28:29], v[124:125], v[160:161]
	v_pk_fma_f32 v[246:247], v[30:31], v[126:127], v[246:247]
	v_pk_add_f32 v[254:255], v[254:255], v[160:161]
	s_nop 0
	v_pk_add_f32 v[246:247], v[246:247], v[254:255]
	s_nop 0
	v_add_f32_e32 v162, v246, v247
	v_readlane_b32 s54, v92, 58
	v_readlane_b32 s55, v92, 59
	s_mul_i32 s0, s54, 0x300
	s_mul_i32 s1, s55, 0x300
	v_add_u32_e32 v167, s0, v195
	s_and_saveexec_b64 s[98:99], s[40:41]
	v_add_u32_e32 v167, s1, v195
	s_mov_b64 exec, s[98:99]
	s_waitcnt vmcnt(14)
; __device__ void peer_gather_phase(const Params& P, int l, bool do_store) {
;     ...
;       for (int pr = 0; pr < 4; ++pr) {
;         v6u_t qv; qv[0] = u6[3 * pr].x; qv[1] = u6[3 * pr].y; qv[2] = u6[3 * pr + 1].x; qv[3] = u6[3 * pr + 1].y; qv[4] = u6[3 * pr + 2].x; qv[5] = u6[3 * pr + 2].y;
;         const v32f_t wv = __builtin_amdgcn_cvt_scalef32_pk32_f32_fp6(qv, 1.0f);
;         f32x2 a2 = f32x2{0.f, 0.f};
; #pragma unroll
;         for (int i = 0; i < 16; ++i) a2 += f32x2{wv[2 * i], wv[2 * i + 1]} * xu[i];
;         float hs = a2.x + a2.y;
;         hs += dpp_row_shr(hs, 1); hs += dpp_row_shr(hs, 2); hs += dpp_row_shr(hs, 4); hs += dpp_row_shr(hs, 8);
;         hs += __builtin_bit_cast(float, __builtin_amdgcn_update_dpp(0, __builtin_bit_cast(int, hs), 0x142, 0xa, 0xf, false));
;         const float da = __builtin_bit_cast(float, __builtin_amdgcn_readlane(__builtin_bit_cast(int, hs), 31));
;         const float db = __builtin_bit_cast(float, __builtin_amdgcn_readlane(__builtin_bit_cast(int, hs), 63));
;         dvec = (lane == kb + 2 * pr) ? da : dvec;
;         dvec = (lane == kb + 2 * pr + 1) ? db : dvec;
	v_cvt_scalef32_pk32_f32_fp6 v[0:31], v[228:233], 1.0
	global_load_dwordx2 v[232:233], v167, s[62:63] offset:16
	global_load_dwordx4 v[228:231], v167, s[62:63]
	v_pk_mul_f32 v[246:247], v[0:1], v[96:97]
	v_pk_mul_f32 v[254:255], v[2:3], v[98:99]
	v_pk_mul_f32 v[160:161], v[4:5], v[100:101]
	v_pk_fma_f32 v[246:247], v[6:7], v[102:103], v[246:247]
	v_pk_fma_f32 v[254:255], v[8:9], v[104:105], v[254:255]
	v_pk_fma_f32 v[160:161], v[10:11], v[106:107], v[160:161]
	v_pk_fma_f32 v[246:247], v[12:13], v[108:109], v[246:247]
	v_pk_fma_f32 v[254:255], v[14:15], v[110:111], v[254:255]
	v_pk_fma_f32 v[160:161], v[16:17], v[112:113], v[160:161]
	v_pk_fma_f32 v[246:247], v[18:19], v[114:115], v[246:247]
	v_pk_fma_f32 v[254:255], v[20:21], v[116:117], v[254:255]
	v_pk_fma_f32 v[160:161], v[22:23], v[118:119], v[160:161]
	v_pk_fma_f32 v[246:247], v[24:25], v[120:121], v[246:247]
	v_pk_fma_f32 v[254:255], v[26:27], v[122:123], v[254:255]
	v_pk_fma_f32 v[160:161], v[28:29], v[124:125], v[160:161]
	v_pk_fma_f32 v[246:247], v[30:31], v[126:127], v[246:247]
	v_pk_add_f32 v[254:255], v[254:255], v[160:161]
	s_nop 0
	v_pk_add_f32 v[246:247], v[246:247], v[254:255]
	s_nop 0
	v_add_f32_e32 v163, v246, v247
	v_readlane_b32 s54, v92, 60
	v_readlane_b32 s55, v92, 61
	s_mul_i32 s0, s54, 0x300
	s_mul_i32 s1, s55, 0x300
	v_add_u32_e32 v167, s0, v195
	s_and_saveexec_b64 s[98:99], s[40:41]
	v_add_u32_e32 v167, s1, v195
	s_mov_b64 exec, s[98:99]
	s_waitcnt vmcnt(14)
	v_cvt_scalef32_pk32_f32_fp6 v[0:31], v[234:239], 1.0
	global_load_dwordx2 v[238:239], v167, s[62:63] offset:16
	global_load_dwordx4 v[234:237], v167, s[62:63]
	v_pk_mul_f32 v[246:247], v[0:1], v[96:97]
	v_pk_mul_f32 v[254:255], v[2:3], v[98:99]
	v_pk_mul_f32 v[160:161], v[4:5], v[100:101]
	v_pk_fma_f32 v[246:247], v[6:7], v[102:103], v[246:247]
	v_pk_fma_f32 v[254:255], v[8:9], v[104:105], v[254:255]
	v_pk_fma_f32 v[160:161], v[10:11], v[106:107], v[160:161]
	v_pk_fma_f32 v[246:247], v[12:13], v[108:109], v[246:247]
	v_pk_fma_f32 v[254:255], v[14:15], v[110:111], v[254:255]
	v_pk_fma_f32 v[160:161], v[16:17], v[112:113], v[160:161]
	v_pk_fma_f32 v[246:247], v[18:19], v[114:115], v[246:247]
	v_pk_fma_f32 v[254:255], v[20:21], v[116:117], v[254:255]
	v_pk_fma_f32 v[160:161], v[22:23], v[118:119], v[160:161]
	v_pk_fma_f32 v[246:247], v[24:25], v[120:121], v[246:247]
	v_pk_fma_f32 v[254:255], v[26:27], v[122:123], v[254:255]
	v_pk_fma_f32 v[160:161], v[28:29], v[124:125], v[160:161]
	v_pk_fma_f32 v[246:247], v[30:31], v[126:127], v[246:247]
	v_pk_add_f32 v[254:255], v[254:255], v[160:161]
	s_nop 0
	v_pk_add_f32 v[246:247], v[246:247], v[254:255]
	s_nop 0
	v_add_f32_e32 v164, v246, v247
	v_readlane_b32 s54, v92, 62
	v_readlane_b32 s55, v92, 63
	s_mul_i32 s0, s54, 0x300
	s_mul_i32 s1, s55, 0x300
	v_add_u32_e32 v167, s0, v195
	s_and_saveexec_b64 s[98:99], s[40:41]
	v_add_u32_e32 v167, s1, v195
	s_mov_b64 exec, s[98:99]
	s_waitcnt vmcnt(14)
	v_cvt_scalef32_pk32_f32_fp6 v[0:31], v[240:245], 1.0
	global_load_dwordx2 v[244:245], v167, s[62:63] offset:16
	global_load_dwordx4 v[240:243], v167, s[62:63]
	v_pk_mul_f32 v[246:247], v[0:1], v[96:97]
	v_pk_mul_f32 v[254:255], v[2:3], v[98:99]
	v_pk_mul_f32 v[160:161], v[4:5], v[100:101]
	v_pk_fma_f32 v[246:247], v[6:7], v[102:103], v[246:247]
	v_pk_fma_f32 v[254:255], v[8:9], v[104:105], v[254:255]
	v_pk_fma_f32 v[160:161], v[10:11], v[106:107], v[160:161]
	v_pk_fma_f32 v[246:247], v[12:13], v[108:109], v[246:247]
	v_pk_fma_f32 v[254:255], v[14:15], v[110:111], v[254:255]
	v_pk_fma_f32 v[160:161], v[16:17], v[112:113], v[160:161]
	v_pk_fma_f32 v[246:247], v[18:19], v[114:115], v[246:247]
	v_pk_fma_f32 v[254:255], v[20:21], v[116:117], v[254:255]
	v_pk_fma_f32 v[160:161], v[22:23], v[118:119], v[160:161]
	v_pk_fma_f32 v[246:247], v[24:25], v[120:121], v[246:247]
	v_pk_fma_f32 v[254:255], v[26:27], v[122:123], v[254:255]
	v_pk_fma_f32 v[160:161], v[28:29], v[124:125], v[160:161]
	v_pk_fma_f32 v[246:247], v[30:31], v[126:127], v[246:247]
	v_pk_add_f32 v[254:255], v[254:255], v[160:161]
	s_nop 0
	v_pk_add_f32 v[246:247], v[246:247], v[254:255]
	s_nop 0
	v_add_f32_e32 v165, v246, v247
	v_add_f32_dpp v162, v162, v162 row_shr:1 row_mask:0xf bank_mask:0xf bound_ctrl:1
	v_add_f32_dpp v163, v163, v163 row_shr:1 row_mask:0xf bank_mask:0xf bound_ctrl:1
	v_add_f32_dpp v164, v164, v164 row_shr:1 row_mask:0xf bank_mask:0xf bound_ctrl:1
	v_add_f32_dpp v165, v165, v165 row_shr:1 row_mask:0xf bank_mask:0xf bound_ctrl:1
	v_add_f32_dpp v162, v162, v162 row_shr:2 row_mask:0xf bank_mask:0xf bound_ctrl:1
	v_add_f32_dpp v163, v163, v163 row_shr:2 row_mask:0xf bank_mask:0xf bound_ctrl:1
	v_add_f32_dpp v164, v164, v164 row_shr:2 row_mask:0xf bank_mask:0xf bound_ctrl:1
	v_add_f32_dpp v165, v165, v165 row_shr:2 row_mask:0xf bank_mask:0xf bound_ctrl:1
	v_add_f32_dpp v162, v162, v162 row_shr:4 row_mask:0xf bank_mask:0xf bound_ctrl:1
	v_add_f32_dpp v163, v163, v163 row_shr:4 row_mask:0xf bank_mask:0xf bound_ctrl:1
	v_add_f32_dpp v164, v164, v164 row_shr:4 row_mask:0xf bank_mask:0xf bound_ctrl:1
	v_add_f32_dpp v165, v165, v165 row_shr:4 row_mask:0xf bank_mask:0xf bound_ctrl:1
	v_add_f32_dpp v162, v162, v162 row_shr:8 row_mask:0xf bank_mask:0xf bound_ctrl:1
	v_add_f32_dpp v163, v163, v163 row_shr:8 row_mask:0xf bank_mask:0xf bound_ctrl:1
	v_add_f32_dpp v164, v164, v164 row_shr:8 row_mask:0xf bank_mask:0xf bound_ctrl:1
	v_add_f32_dpp v165, v165, v165 row_shr:8 row_mask:0xf bank_mask:0xf bound_ctrl:1
	v_add_f32_dpp v162, v162, v162 row_bcast:15 row_mask:0xa bank_mask:0xf
	v_add_f32_dpp v163, v163, v163 row_bcast:15 row_mask:0xa bank_mask:0xf
	v_add_f32_dpp v164, v164, v164 row_bcast:15 row_mask:0xa bank_mask:0xf
	v_add_f32_dpp v165, v165, v165 row_bcast:15 row_mask:0xa bank_mask:0xf
	s_mov_b64 s[98:99], exec
	s_mov_b32 exec_lo, 0x80000000
	s_mov_b32 exec_hi, 0x80000000
	ds_write_b32 v74, v162 offset:160
	ds_write_b32 v74, v163 offset:168
	ds_write_b32 v74, v164 offset:176
	ds_write_b32 v74, v165 offset:184
	s_mov_b64 exec, s[98:99]
	v_readlane_b32 s54, v90, 0
	v_readlane_b32 s55, v90, 1
	s_mul_i32 s0, s54, 0x300
	s_mul_i32 s1, s55, 0x300
	v_add_u32_e32 v167, s0, v195
	s_and_saveexec_b64 s[98:99], s[40:41]
	v_add_u32_e32 v167, s1, v195
	s_mov_b64 exec, s[98:99]
	s_waitcnt vmcnt(14)
; __device__ void peer_gather_phase(const Params& P, int l, bool do_store) {
;     ...
;         const int ea = __builtin_amdgcn_readlane(evs, kb + 2 * pr), eb = __builtin_amdgcn_readlane(evs, kb + 2 * pr + 1);
;         const uint2* up = (const uint2*)(U + (size_t)(uphi ? eb : ea) * 768);
;         u6[3 * pr] = up[0]; u6[3 * pr + 1] = up[1]; u6[3 * pr + 2] = up[2];
;         v8[2 * pr] = *(const uint2*)(V + (size_t)ea * 512);
;         v8[2 * pr + 1] = *(const uint2*)(V + (size_t)eb * 512);
;       }
;     };
;     auto compute_batch = [&](const uint2 (&u6)[12], const uint2 (&v8)[8], int bt) {
;       const int kb = (bt & 7) * 8;
;       float dvec = 0.f;
; #pragma unroll
;       for (int pr = 0; pr < 4; ++pr) {
;         v6u_t qv; qv[0] = u6[3 * pr].x; qv[1] = u6[3 * pr].y; qv[2] = u6[3 * pr + 1].x; qv[3] = u6[3 * pr + 1].y; qv[4] = u6[3 * pr + 2].x; qv[5] = u6[3 * pr + 2].y;
;         const v32f_t wv = __builtin_amdgcn_cvt_scalef32_pk32_f32_fp6(qv, 1.0f);
;         f32x2 a2 = f32x2{0.f, 0.f};
; #pragma unroll
;         for (int i = 0; i < 16; ++i) a2 += f32x2{wv[2 * i], wv[2 * i + 1]} * xu[i];
;         float hs = a2.x + a2.y;
	v_cvt_scalef32_pk32_f32_fp6 v[0:31], v[50:55], 1.0
	global_load_dwordx2 v[54:55], v167, s[62:63] offset:16
	global_load_dwordx4 v[50:53], v167, s[62:63]
	v_pk_mul_f32 v[246:247], v[0:1], v[96:97]
	v_pk_mul_f32 v[254:255], v[2:3], v[98:99]
	v_pk_mul_f32 v[160:161], v[4:5], v[100:101]
	v_pk_fma_f32 v[246:247], v[6:7], v[102:103], v[246:247]
	v_pk_fma_f32 v[254:255], v[8:9], v[104:105], v[254:255]
	v_pk_fma_f32 v[160:161], v[10:11], v[106:107], v[160:161]
	v_pk_fma_f32 v[246:247], v[12:13], v[108:109], v[246:247]
	v_pk_fma_f32 v[254:255], v[14:15], v[110:111], v[254:255]
	v_pk_fma_f32 v[160:161], v[16:17], v[112:113], v[160:161]
	v_pk_fma_f32 v[246:247], v[18:19], v[114:115], v[246:247]
	v_pk_fma_f32 v[254:255], v[20:21], v[116:117], v[254:255]
	v_pk_fma_f32 v[160:161], v[22:23], v[118:119], v[160:161]
	v_pk_fma_f32 v[246:247], v[24:25], v[120:121], v[246:247]
	v_pk_fma_f32 v[254:255], v[26:27], v[122:123], v[254:255]
	v_pk_fma_f32 v[160:161], v[28:29], v[124:125], v[160:161]
	v_pk_fma_f32 v[246:247], v[30:31], v[126:127], v[246:247]
	v_pk_add_f32 v[254:255], v[254:255], v[160:161]
	s_nop 0
	v_pk_add_f32 v[246:247], v[246:247], v[254:255]
	s_nop 0
	v_add_f32_e32 v162, v246, v247
	v_readlane_b32 s54, v90, 2
	v_readlane_b32 s55, v90, 3
	s_mul_i32 s0, s54, 0x300
	s_mul_i32 s1, s55, 0x300
	v_add_u32_e32 v167, s0, v195
	s_and_saveexec_b64 s[98:99], s[40:41]
	v_add_u32_e32 v167, s1, v195
	s_mov_b64 exec, s[98:99]
	s_waitcnt vmcnt(14)
	v_cvt_scalef32_pk32_f32_fp6 v[0:31], v[44:49], 1.0
	global_load_dwordx2 v[48:49], v167, s[62:63] offset:16
	global_load_dwordx4 v[44:47], v167, s[62:63]
	v_pk_mul_f32 v[246:247], v[0:1], v[96:97]
	v_pk_mul_f32 v[254:255], v[2:3], v[98:99]
	v_pk_mul_f32 v[160:161], v[4:5], v[100:101]
	v_pk_fma_f32 v[246:247], v[6:7], v[102:103], v[246:247]
	v_pk_fma_f32 v[254:255], v[8:9], v[104:105], v[254:255]
	v_pk_fma_f32 v[160:161], v[10:11], v[106:107], v[160:161]
	v_pk_fma_f32 v[246:247], v[12:13], v[108:109], v[246:247]
	v_pk_fma_f32 v[254:255], v[14:15], v[110:111], v[254:255]
	v_pk_fma_f32 v[160:161], v[16:17], v[112:113], v[160:161]
	v_pk_fma_f32 v[246:247], v[18:19], v[114:115], v[246:247]
	v_pk_fma_f32 v[254:255], v[20:21], v[116:117], v[254:255]
	v_pk_fma_f32 v[160:161], v[22:23], v[118:119], v[160:161]
	v_pk_fma_f32 v[246:247], v[24:25], v[120:121], v[246:247]
	v_pk_fma_f32 v[254:255], v[26:27], v[122:123], v[254:255]
	v_pk_fma_f32 v[160:161], v[28:29], v[124:125], v[160:161]
	v_pk_fma_f32 v[246:247], v[30:31], v[126:127], v[246:247]
	v_pk_add_f32 v[254:255], v[254:255], v[160:161]
	s_nop 0
	v_pk_add_f32 v[246:247], v[246:247], v[254:255]
	s_nop 0
	v_add_f32_e32 v163, v246, v247
	v_readlane_b32 s54, v90, 4
	v_readlane_b32 s55, v90, 5
	s_mul_i32 s0, s54, 0x300
	s_mul_i32 s1, s55, 0x300
	v_add_u32_e32 v167, s0, v195
	s_and_saveexec_b64 s[98:99], s[40:41]
	v_add_u32_e32 v167, s1, v195
	s_mov_b64 exec, s[98:99]
	s_waitcnt vmcnt(14)
	v_cvt_scalef32_pk32_f32_fp6 v[0:31], v[38:43], 1.0
	global_load_dwordx2 v[42:43], v167, s[62:63] offset:16
	global_load_dwordx4 v[38:41], v167, s[62:63]
	v_pk_mul_f32 v[246:247], v[0:1], v[96:97]
	v_pk_mul_f32 v[254:255], v[2:3], v[98:99]
	v_pk_mul_f32 v[160:161], v[4:5], v[100:101]
	v_pk_fma_f32 v[246:247], v[6:7], v[102:103], v[246:247]
	v_pk_fma_f32 v[254:255], v[8:9], v[104:105], v[254:255]
	v_pk_fma_f32 v[160:161], v[10:11], v[106:107], v[160:161]
	v_pk_fma_f32 v[246:247], v[12:13], v[108:109], v[246:247]
	v_pk_fma_f32 v[254:255], v[14:15], v[110:111], v[254:255]
	v_pk_fma_f32 v[160:161], v[16:17], v[112:113], v[160:161]
	v_pk_fma_f32 v[246:247], v[18:19], v[114:115], v[246:247]
	v_pk_fma_f32 v[254:255], v[20:21], v[116:117], v[254:255]
	v_pk_fma_f32 v[160:161], v[22:23], v[118:119], v[160:161]
	v_pk_fma_f32 v[246:247], v[24:25], v[120:121], v[246:247]
	v_pk_fma_f32 v[254:255], v[26:27], v[122:123], v[254:255]
	v_pk_fma_f32 v[160:161], v[28:29], v[124:125], v[160:161]
	v_pk_fma_f32 v[246:247], v[30:31], v[126:127], v[246:247]
	v_pk_add_f32 v[254:255], v[254:255], v[160:161]
	s_nop 0
	v_pk_add_f32 v[246:247], v[246:247], v[254:255]
	s_nop 0
	v_add_f32_e32 v164, v246, v247
	v_readlane_b32 s54, v90, 6
	v_readlane_b32 s55, v90, 7
	s_mul_i32 s0, s54, 0x300
	s_mul_i32 s1, s55, 0x300
	v_add_u32_e32 v167, s0, v195
	s_and_saveexec_b64 s[98:99], s[40:41]
	v_add_u32_e32 v167, s1, v195
	s_mov_b64 exec, s[98:99]
	s_waitcnt vmcnt(14)
; __device__ void peer_gather_phase(const Params& P, int l, bool do_store) {
;     ...
;       for (int pr = 0; pr < 4; ++pr) {
;         v6u_t qv; qv[0] = u6[3 * pr].x; qv[1] = u6[3 * pr].y; qv[2] = u6[3 * pr + 1].x; qv[3] = u6[3 * pr + 1].y; qv[4] = u6[3 * pr + 2].x; qv[5] = u6[3 * pr + 2].y;
;         const v32f_t wv = __builtin_amdgcn_cvt_scalef32_pk32_f32_fp6(qv, 1.0f);
;         f32x2 a2 = f32x2{0.f, 0.f};
; #pragma unroll
;         for (int i = 0; i < 16; ++i) a2 += f32x2{wv[2 * i], wv[2 * i + 1]} * xu[i];
;         float hs = a2.x + a2.y;
;         hs += dpp_row_shr(hs, 1); hs += dpp_row_shr(hs, 2); hs += dpp_row_shr(hs, 4); hs += dpp_row_shr(hs, 8);
;         hs += __builtin_bit_cast(float, __builtin_amdgcn_update_dpp(0, __builtin_bit_cast(int, hs), 0x142, 0xa, 0xf, false));
;         const float da = __builtin_bit_cast(float, __builtin_amdgcn_readlane(__builtin_bit_cast(int, hs), 31));
;         const float db = __builtin_bit_cast(float, __builtin_amdgcn_readlane(__builtin_bit_cast(int, hs), 63));
;         dvec = (lane == kb + 2 * pr) ? da : dvec;
;         dvec = (lane == kb + 2 * pr + 1) ? db : dvec;
	v_cvt_scalef32_pk32_f32_fp6 v[0:31], v[32:37], 1.0
	global_load_dwordx2 v[36:37], v167, s[62:63] offset:16
	global_load_dwordx4 v[32:35], v167, s[62:63]
	v_pk_mul_f32 v[246:247], v[0:1], v[96:97]
	v_pk_mul_f32 v[254:255], v[2:3], v[98:99]
	v_pk_mul_f32 v[160:161], v[4:5], v[100:101]
	v_pk_fma_f32 v[246:247], v[6:7], v[102:103], v[246:247]
	v_pk_fma_f32 v[254:255], v[8:9], v[104:105], v[254:255]
	v_pk_fma_f32 v[160:161], v[10:11], v[106:107], v[160:161]
	v_pk_fma_f32 v[246:247], v[12:13], v[108:109], v[246:247]
	v_pk_fma_f32 v[254:255], v[14:15], v[110:111], v[254:255]
	v_pk_fma_f32 v[160:161], v[16:17], v[112:113], v[160:161]
	v_pk_fma_f32 v[246:247], v[18:19], v[114:115], v[246:247]
	v_pk_fma_f32 v[254:255], v[20:21], v[116:117], v[254:255]
	v_pk_fma_f32 v[160:161], v[22:23], v[118:119], v[160:161]
	v_pk_fma_f32 v[246:247], v[24:25], v[120:121], v[246:247]
	v_pk_fma_f32 v[254:255], v[26:27], v[122:123], v[254:255]
	v_pk_fma_f32 v[160:161], v[28:29], v[124:125], v[160:161]
	v_pk_fma_f32 v[246:247], v[30:31], v[126:127], v[246:247]
	v_pk_add_f32 v[254:255], v[254:255], v[160:161]
	s_nop 0
	v_pk_add_f32 v[246:247], v[246:247], v[254:255]
	s_nop 0
	v_add_f32_e32 v165, v246, v247
	v_add_f32_dpp v162, v162, v162 row_shr:1 row_mask:0xf bank_mask:0xf bound_ctrl:1
	v_add_f32_dpp v163, v163, v163 row_shr:1 row_mask:0xf bank_mask:0xf bound_ctrl:1
	v_add_f32_dpp v164, v164, v164 row_shr:1 row_mask:0xf bank_mask:0xf bound_ctrl:1
	v_add_f32_dpp v165, v165, v165 row_shr:1 row_mask:0xf bank_mask:0xf bound_ctrl:1
	v_add_f32_dpp v162, v162, v162 row_shr:2 row_mask:0xf bank_mask:0xf bound_ctrl:1
	v_add_f32_dpp v163, v163, v163 row_shr:2 row_mask:0xf bank_mask:0xf bound_ctrl:1
	v_add_f32_dpp v164, v164, v164 row_shr:2 row_mask:0xf bank_mask:0xf bound_ctrl:1
	v_add_f32_dpp v165, v165, v165 row_shr:2 row_mask:0xf bank_mask:0xf bound_ctrl:1
	v_add_f32_dpp v162, v162, v162 row_shr:4 row_mask:0xf bank_mask:0xf bound_ctrl:1
	v_add_f32_dpp v163, v163, v163 row_shr:4 row_mask:0xf bank_mask:0xf bound_ctrl:1
	v_add_f32_dpp v164, v164, v164 row_shr:4 row_mask:0xf bank_mask:0xf bound_ctrl:1
	v_add_f32_dpp v165, v165, v165 row_shr:4 row_mask:0xf bank_mask:0xf bound_ctrl:1
	v_add_f32_dpp v162, v162, v162 row_shr:8 row_mask:0xf bank_mask:0xf bound_ctrl:1
	v_add_f32_dpp v163, v163, v163 row_shr:8 row_mask:0xf bank_mask:0xf bound_ctrl:1
	v_add_f32_dpp v164, v164, v164 row_shr:8 row_mask:0xf bank_mask:0xf bound_ctrl:1
	v_add_f32_dpp v165, v165, v165 row_shr:8 row_mask:0xf bank_mask:0xf bound_ctrl:1
	v_add_f32_dpp v162, v162, v162 row_bcast:15 row_mask:0xa bank_mask:0xf
	v_add_f32_dpp v163, v163, v163 row_bcast:15 row_mask:0xa bank_mask:0xf
	v_add_f32_dpp v164, v164, v164 row_bcast:15 row_mask:0xa bank_mask:0xf
	v_add_f32_dpp v165, v165, v165 row_bcast:15 row_mask:0xa bank_mask:0xf
	s_mov_b64 s[98:99], exec
	s_mov_b32 exec_lo, 0x80000000
	s_mov_b32 exec_hi, 0x80000000
	ds_write_b32 v74, v162 offset:192
	ds_write_b32 v74, v163 offset:200
	ds_write_b32 v74, v164 offset:208
	ds_write_b32 v74, v165 offset:216
	s_mov_b64 exec, s[98:99]
	v_readlane_b32 s54, v90, 8
	v_readlane_b32 s55, v90, 9
	s_mul_i32 s0, s54, 0x300
	s_mul_i32 s1, s55, 0x300
	v_add_u32_e32 v167, s0, v195
	s_and_saveexec_b64 s[98:99], s[40:41]
	v_add_u32_e32 v167, s1, v195
	s_mov_b64 exec, s[98:99]
	s_waitcnt vmcnt(14)
	v_cvt_scalef32_pk32_f32_fp6 v[0:31], v[196:201], 1.0
	global_load_dwordx2 v[200:201], v167, s[62:63] offset:16
	global_load_dwordx4 v[196:199], v167, s[62:63]
	v_pk_mul_f32 v[246:247], v[0:1], v[96:97]
	v_pk_mul_f32 v[254:255], v[2:3], v[98:99]
	v_pk_mul_f32 v[160:161], v[4:5], v[100:101]
	v_pk_fma_f32 v[246:247], v[6:7], v[102:103], v[246:247]
	v_pk_fma_f32 v[254:255], v[8:9], v[104:105], v[254:255]
	v_pk_fma_f32 v[160:161], v[10:11], v[106:107], v[160:161]
	v_pk_fma_f32 v[246:247], v[12:13], v[108:109], v[246:247]
	v_pk_fma_f32 v[254:255], v[14:15], v[110:111], v[254:255]
	v_pk_fma_f32 v[160:161], v[16:17], v[112:113], v[160:161]
	v_pk_fma_f32 v[246:247], v[18:19], v[114:115], v[246:247]
	v_pk_fma_f32 v[254:255], v[20:21], v[116:117], v[254:255]
	v_pk_fma_f32 v[160:161], v[22:23], v[118:119], v[160:161]
	v_pk_fma_f32 v[246:247], v[24:25], v[120:121], v[246:247]
	v_pk_fma_f32 v[254:255], v[26:27], v[122:123], v[254:255]
	v_pk_fma_f32 v[160:161], v[28:29], v[124:125], v[160:161]
	v_pk_fma_f32 v[246:247], v[30:31], v[126:127], v[246:247]
	v_pk_add_f32 v[254:255], v[254:255], v[160:161]
	s_nop 0
	v_pk_add_f32 v[246:247], v[246:247], v[254:255]
	s_nop 0
	v_add_f32_e32 v162, v246, v247
	v_readlane_b32 s54, v90, 10
	v_readlane_b32 s55, v90, 11
	s_mul_i32 s0, s54, 0x300
	s_mul_i32 s1, s55, 0x300
	v_add_u32_e32 v167, s0, v195
	s_and_saveexec_b64 s[98:99], s[40:41]
	v_add_u32_e32 v167, s1, v195
	s_mov_b64 exec, s[98:99]
	s_waitcnt vmcnt(14)
	v_cvt_scalef32_pk32_f32_fp6 v[0:31], v[228:233], 1.0
	global_load_dwordx2 v[232:233], v167, s[62:63] offset:16
	global_load_dwordx4 v[228:231], v167, s[62:63]
	v_pk_mul_f32 v[246:247], v[0:1], v[96:97]
	v_pk_mul_f32 v[254:255], v[2:3], v[98:99]
	v_pk_mul_f32 v[160:161], v[4:5], v[100:101]
	v_pk_fma_f32 v[246:247], v[6:7], v[102:103], v[246:247]
	v_pk_fma_f32 v[254:255], v[8:9], v[104:105], v[254:255]
	v_pk_fma_f32 v[160:161], v[10:11], v[106:107], v[160:161]
	v_pk_fma_f32 v[246:247], v[12:13], v[108:109], v[246:247]
	v_pk_fma_f32 v[254:255], v[14:15], v[110:111], v[254:255]
	v_pk_fma_f32 v[160:161], v[16:17], v[112:113], v[160:161]
	v_pk_fma_f32 v[246:247], v[18:19], v[114:115], v[246:247]
	v_pk_fma_f32 v[254:255], v[20:21], v[116:117], v[254:255]
	v_pk_fma_f32 v[160:161], v[22:23], v[118:119], v[160:161]
	v_pk_fma_f32 v[246:247], v[24:25], v[120:121], v[246:247]
	v_pk_fma_f32 v[254:255], v[26:27], v[122:123], v[254:255]
	v_pk_fma_f32 v[160:161], v[28:29], v[124:125], v[160:161]
	v_pk_fma_f32 v[246:247], v[30:31], v[126:127], v[246:247]
	v_pk_add_f32 v[254:255], v[254:255], v[160:161]
	s_nop 0
	v_pk_add_f32 v[246:247], v[246:247], v[254:255]
	s_nop 0
	v_add_f32_e32 v163, v246, v247
	v_readlane_b32 s54, v90, 12
	v_readlane_b32 s55, v90, 13
	s_mul_i32 s0, s54, 0x300
	s_mul_i32 s1, s55, 0x300
	v_add_u32_e32 v167, s0, v195
	s_and_saveexec_b64 s[98:99], s[40:41]
	v_add_u32_e32 v167, s1, v195
	s_mov_b64 exec, s[98:99]
	s_waitcnt vmcnt(14)
; __device__ void peer_gather_phase(const Params& P, int l, bool do_store) {
;     ...
;       for (int pr = 0; pr < 4; ++pr) {
;         v6u_t qv; qv[0] = u6[3 * pr].x; qv[1] = u6[3 * pr].y; qv[2] = u6[3 * pr + 1].x; qv[3] = u6[3 * pr + 1].y; qv[4] = u6[3 * pr + 2].x; qv[5] = u6[3 * pr + 2].y;
;         const v32f_t wv = __builtin_amdgcn_cvt_scalef32_pk32_f32_fp6(qv, 1.0f);
;         f32x2 a2 = f32x2{0.f, 0.f};
; #pragma unroll
;         for (int i = 0; i < 16; ++i) a2 += f32x2{wv[2 * i], wv[2 * i + 1]} * xu[i];
;         float hs = a2.x + a2.y;
;         hs += dpp_row_shr(hs, 1); hs += dpp_row_shr(hs, 2); hs += dpp_row_shr(hs, 4); hs += dpp_row_shr(hs, 8);
;         hs += __builtin_bit_cast(float, __builtin_amdgcn_update_dpp(0, __builtin_bit_cast(int, hs), 0x142, 0xa, 0xf, false));
;         const float da = __builtin_bit_cast(float, __builtin_amdgcn_readlane(__builtin_bit_cast(int, hs), 31));
;         const float db = __builtin_bit_cast(float, __builtin_amdgcn_readlane(__builtin_bit_cast(int, hs), 63));
;         dvec = (lane == kb + 2 * pr) ? da : dvec;
;         dvec = (lane == kb + 2 * pr + 1) ? db : dvec;
;       }
;       const float sux = (bt < 8) ? sux0 : sux1;
;       const float gsx = (bt < 8) ? gsx0 : gsx1;
;       const float avec = gelu_t(dvec * sux) * gsx;
	v_cvt_scalef32_pk32_f32_fp6 v[0:31], v[234:239], 1.0
	global_load_dwordx2 v[238:239], v167, s[62:63] offset:16
	global_load_dwordx4 v[234:237], v167, s[62:63]
	v_pk_mul_f32 v[246:247], v[0:1], v[96:97]
	v_pk_mul_f32 v[254:255], v[2:3], v[98:99]
	v_pk_mul_f32 v[160:161], v[4:5], v[100:101]
	v_pk_fma_f32 v[246:247], v[6:7], v[102:103], v[246:247]
	v_pk_fma_f32 v[254:255], v[8:9], v[104:105], v[254:255]
	v_pk_fma_f32 v[160:161], v[10:11], v[106:107], v[160:161]
	v_pk_fma_f32 v[246:247], v[12:13], v[108:109], v[246:247]
	v_pk_fma_f32 v[254:255], v[14:15], v[110:111], v[254:255]
	v_pk_fma_f32 v[160:161], v[16:17], v[112:113], v[160:161]
	v_pk_fma_f32 v[246:247], v[18:19], v[114:115], v[246:247]
	v_pk_fma_f32 v[254:255], v[20:21], v[116:117], v[254:255]
	v_pk_fma_f32 v[160:161], v[22:23], v[118:119], v[160:161]
	v_pk_fma_f32 v[246:247], v[24:25], v[120:121], v[246:247]
	v_pk_fma_f32 v[254:255], v[26:27], v[122:123], v[254:255]
	v_pk_fma_f32 v[160:161], v[28:29], v[124:125], v[160:161]
	v_pk_fma_f32 v[246:247], v[30:31], v[126:127], v[246:247]
	v_pk_add_f32 v[254:255], v[254:255], v[160:161]
	s_nop 0
	v_pk_add_f32 v[246:247], v[246:247], v[254:255]
	s_nop 0
	v_add_f32_e32 v164, v246, v247
	v_readlane_b32 s54, v90, 14
	v_readlane_b32 s55, v90, 15
	s_mul_i32 s0, s54, 0x300
	s_mul_i32 s1, s55, 0x300
	v_add_u32_e32 v167, s0, v195
	s_and_saveexec_b64 s[98:99], s[40:41]
	v_add_u32_e32 v167, s1, v195
	s_mov_b64 exec, s[98:99]
	s_waitcnt vmcnt(14)
	v_cvt_scalef32_pk32_f32_fp6 v[0:31], v[240:245], 1.0
	global_load_dwordx2 v[244:245], v167, s[62:63] offset:16
	global_load_dwordx4 v[240:243], v167, s[62:63]
	v_pk_mul_f32 v[246:247], v[0:1], v[96:97]
	v_pk_mul_f32 v[254:255], v[2:3], v[98:99]
	v_pk_mul_f32 v[160:161], v[4:5], v[100:101]
	v_pk_fma_f32 v[246:247], v[6:7], v[102:103], v[246:247]
	v_pk_fma_f32 v[254:255], v[8:9], v[104:105], v[254:255]
	v_pk_fma_f32 v[160:161], v[10:11], v[106:107], v[160:161]
	v_pk_fma_f32 v[246:247], v[12:13], v[108:109], v[246:247]
	v_pk_fma_f32 v[254:255], v[14:15], v[110:111], v[254:255]
	v_pk_fma_f32 v[160:161], v[16:17], v[112:113], v[160:161]
	v_pk_fma_f32 v[246:247], v[18:19], v[114:115], v[246:247]
	v_pk_fma_f32 v[254:255], v[20:21], v[116:117], v[254:255]
	v_pk_fma_f32 v[160:161], v[22:23], v[118:119], v[160:161]
	v_pk_fma_f32 v[246:247], v[24:25], v[120:121], v[246:247]
	v_pk_fma_f32 v[254:255], v[26:27], v[122:123], v[254:255]
	v_pk_fma_f32 v[160:161], v[28:29], v[124:125], v[160:161]
	v_pk_fma_f32 v[246:247], v[30:31], v[126:127], v[246:247]
	v_pk_add_f32 v[254:255], v[254:255], v[160:161]
	s_nop 0
	v_pk_add_f32 v[246:247], v[246:247], v[254:255]
	s_nop 0
	v_add_f32_e32 v165, v246, v247
	v_add_f32_dpp v162, v162, v162 row_shr:1 row_mask:0xf bank_mask:0xf bound_ctrl:1
	v_add_f32_dpp v163, v163, v163 row_shr:1 row_mask:0xf bank_mask:0xf bound_ctrl:1
	v_add_f32_dpp v164, v164, v164 row_shr:1 row_mask:0xf bank_mask:0xf bound_ctrl:1
	v_add_f32_dpp v165, v165, v165 row_shr:1 row_mask:0xf bank_mask:0xf bound_ctrl:1
	v_add_f32_dpp v162, v162, v162 row_shr:2 row_mask:0xf bank_mask:0xf bound_ctrl:1
	v_add_f32_dpp v163, v163, v163 row_shr:2 row_mask:0xf bank_mask:0xf bound_ctrl:1
	v_add_f32_dpp v164, v164, v164 row_shr:2 row_mask:0xf bank_mask:0xf bound_ctrl:1
	v_add_f32_dpp v165, v165, v165 row_shr:2 row_mask:0xf bank_mask:0xf bound_ctrl:1
	v_add_f32_dpp v162, v162, v162 row_shr:4 row_mask:0xf bank_mask:0xf bound_ctrl:1
	v_add_f32_dpp v163, v163, v163 row_shr:4 row_mask:0xf bank_mask:0xf bound_ctrl:1
	v_add_f32_dpp v164, v164, v164 row_shr:4 row_mask:0xf bank_mask:0xf bound_ctrl:1
	v_add_f32_dpp v165, v165, v165 row_shr:4 row_mask:0xf bank_mask:0xf bound_ctrl:1
	v_add_f32_dpp v162, v162, v162 row_shr:8 row_mask:0xf bank_mask:0xf bound_ctrl:1
	v_add_f32_dpp v163, v163, v163 row_shr:8 row_mask:0xf bank_mask:0xf bound_ctrl:1
	v_add_f32_dpp v164, v164, v164 row_shr:8 row_mask:0xf bank_mask:0xf bound_ctrl:1
	v_add_f32_dpp v165, v165, v165 row_shr:8 row_mask:0xf bank_mask:0xf bound_ctrl:1
	v_add_f32_dpp v162, v162, v162 row_bcast:15 row_mask:0xa bank_mask:0xf
	v_add_f32_dpp v163, v163, v163 row_bcast:15 row_mask:0xa bank_mask:0xf
	v_add_f32_dpp v164, v164, v164 row_bcast:15 row_mask:0xa bank_mask:0xf
	v_add_f32_dpp v165, v165, v165 row_bcast:15 row_mask:0xa bank_mask:0xf
	s_mov_b64 s[98:99], exec
	s_mov_b32 exec_lo, 0x80000000
	s_mov_b32 exec_hi, 0x80000000
	ds_write_b32 v74, v162 offset:224
	ds_write_b32 v74, v163 offset:232
	ds_write_b32 v74, v164 offset:240
	ds_write_b32 v74, v165 offset:248
	s_mov_b64 exec, s[98:99]
	ds_read_b32 v166, v75
	s_waitcnt lgkmcnt(0)
	v_mul_f32_e32 v0, v189, v166
	v_mul_f32_e32 v1, 0x3d372713, v0
	v_mul_f32_e32 v1, v0, v1
	v_fma_f32 v1, v0, v1, v0
	v_mul_f32_e32 v1, 0x3f4c422a, v1
	v_add_f32_e32 v1, v1, v1
	v_mul_f32_e32 v1, 0x3fb8aa3b, v1
	v_exp_f32_e32 v1, v1
	v_mul_f32_e32 v0, 0.5, v0
	v_add_f32_e32 v1, 1.0, v1
	v_div_scale_f32 v2, s[0:1], v1, v1, 2.0
	v_rcp_f32_e32 v3, v2
	s_nop 0
	v_fma_f32 v4, -v2, v3, 1.0
	v_fmac_f32_e32 v3, v4, v3
	v_div_scale_f32 v4, vcc, 2.0, v1, 2.0
	v_mul_f32_e32 v5, v4, v3
	v_fma_f32 v6, -v2, v5, v4
	v_fmac_f32_e32 v5, v6, v3
	v_fma_f32 v2, -v2, v5, v4
	v_div_fmas_f32 v2, v2, v3, v5
	v_div_fixup_f32 v1, v2, v1, 2.0
	v_sub_f32_e32 v1, 1.0, v1
	v_add_f32_e32 v1, 1.0, v1
	v_mul_f32_e32 v0, v0, v1
	v_mul_f32_e32 v167, v191, v0
	s_nop 1
	v_readlane_b32 s0, v167, 0
	s_waitcnt vmcnt(48)
; __device__ void peer_gather_phase(const Params& P, int l, bool do_store) {
;     ...
;         v8[2 * pr] = *(const uint2*)(V + (size_t)ea * 512);
;         v8[2 * pr + 1] = *(const uint2*)(V + (size_t)eb * 512);
;     ...
; #pragma unroll
;       for (int j = 0; j < 8; ++j) {
;         const float a = __builtin_bit_cast(float, __builtin_amdgcn_readlane(__builtin_bit_cast(int, avec), kb + j));
;         const f32x2 aa = f32x2{a, a};
;         y[0] += aa * __builtin_amdgcn_cvt_scalef32_pk_f32_fp4(v8[j].x, 1.0f, 0); y[1] += aa * __builtin_amdgcn_cvt_scalef32_pk_f32_fp4(v8[j].x, 1.0f, 1);
;         y[2] += aa * __builtin_amdgcn_cvt_scalef32_pk_f32_fp4(v8[j].x, 1.0f, 2); y[3] += aa * __builtin_amdgcn_cvt_scalef32_pk_f32_fp4(v8[j].x, 1.0f, 3);
;         y[4] += aa * __builtin_amdgcn_cvt_scalef32_pk_f32_fp4(v8[j].y, 1.0f, 0); y[5] += aa * __builtin_amdgcn_cvt_scalef32_pk_f32_fp4(v8[j].y, 1.0f, 1);
;         y[6] += aa * __builtin_amdgcn_cvt_scalef32_pk_f32_fp4(v8[j].y, 1.0f, 2); y[7] += aa * __builtin_amdgcn_cvt_scalef32_pk_f32_fp4(v8[j].y, 1.0f, 3);
;       }
	v_cvt_scalef32_pk_f32_fp4 v[0:1], v144, 1.0
	v_cvt_scalef32_pk_f32_fp4 v[2:3], v144, 1.0 op_sel:[1,0,0]
	v_cvt_scalef32_pk_f32_fp4 v[4:5], v144, 1.0 op_sel:[0,1,0]
	v_cvt_scalef32_pk_f32_fp4 v[6:7], v144, 1.0 op_sel:[1,1,0]
	v_cvt_scalef32_pk_f32_fp4 v[8:9], v145, 1.0
	v_cvt_scalef32_pk_f32_fp4 v[10:11], v145, 1.0 op_sel:[1,0,0]
	v_cvt_scalef32_pk_f32_fp4 v[12:13], v145, 1.0 op_sel:[0,1,0]
	v_cvt_scalef32_pk_f32_fp4 v[14:15], v145, 1.0 op_sel:[1,1,0]
	v_readlane_b32 s54, v92, 16
	s_lshl_b32 s56, s54, 9
	s_add_u32 s56, s64, s56
	s_addc_u32 s57, s65, 0
	global_load_dwordx2 v[144:145], v227, s[56:57]
	v_pk_fma_f32 v[130:131], v[0:1], s[0:1], v[130:131] op_sel_hi:[1,0,1]
	v_pk_fma_f32 v[138:139], v[2:3], s[0:1], v[138:139] op_sel_hi:[1,0,1]
	v_pk_fma_f32 v[140:141], v[4:5], s[0:1], v[140:141] op_sel_hi:[1,0,1]
	v_pk_fma_f32 v[142:143], v[6:7], s[0:1], v[142:143] op_sel_hi:[1,0,1]
	v_pk_fma_f32 v[128:129], v[8:9], s[0:1], v[128:129] op_sel_hi:[1,0,1]
	v_pk_fma_f32 v[132:133], v[10:11], s[0:1], v[132:133] op_sel_hi:[1,0,1]
	v_pk_fma_f32 v[134:135], v[12:13], s[0:1], v[134:135] op_sel_hi:[1,0,1]
	v_pk_fma_f32 v[136:137], v[14:15], s[0:1], v[136:137] op_sel_hi:[1,0,1]
	v_readlane_b32 s0, v167, 1
	s_waitcnt vmcnt(48)
	v_cvt_scalef32_pk_f32_fp4 v[0:1], v146, 1.0
	v_cvt_scalef32_pk_f32_fp4 v[2:3], v146, 1.0 op_sel:[1,0,0]
	v_cvt_scalef32_pk_f32_fp4 v[4:5], v146, 1.0 op_sel:[0,1,0]
	v_cvt_scalef32_pk_f32_fp4 v[6:7], v146, 1.0 op_sel:[1,1,0]
	v_cvt_scalef32_pk_f32_fp4 v[8:9], v147, 1.0
	v_cvt_scalef32_pk_f32_fp4 v[10:11], v147, 1.0 op_sel:[1,0,0]
	v_cvt_scalef32_pk_f32_fp4 v[12:13], v147, 1.0 op_sel:[0,1,0]
	v_cvt_scalef32_pk_f32_fp4 v[14:15], v147, 1.0 op_sel:[1,1,0]
	v_readlane_b32 s54, v92, 17
	s_lshl_b32 s56, s54, 9
	s_add_u32 s56, s64, s56
	s_addc_u32 s57, s65, 0
	global_load_dwordx2 v[146:147], v227, s[56:57]
	v_pk_fma_f32 v[130:131], v[0:1], s[0:1], v[130:131] op_sel_hi:[1,0,1]
	v_pk_fma_f32 v[138:139], v[2:3], s[0:1], v[138:139] op_sel_hi:[1,0,1]
	v_pk_fma_f32 v[140:141], v[4:5], s[0:1], v[140:141] op_sel_hi:[1,0,1]
	v_pk_fma_f32 v[142:143], v[6:7], s[0:1], v[142:143] op_sel_hi:[1,0,1]
	v_pk_fma_f32 v[128:129], v[8:9], s[0:1], v[128:129] op_sel_hi:[1,0,1]
	v_pk_fma_f32 v[132:133], v[10:11], s[0:1], v[132:133] op_sel_hi:[1,0,1]
	v_pk_fma_f32 v[134:135], v[12:13], s[0:1], v[134:135] op_sel_hi:[1,0,1]
	v_pk_fma_f32 v[136:137], v[14:15], s[0:1], v[136:137] op_sel_hi:[1,0,1]
	v_readlane_b32 s0, v167, 2
	s_waitcnt vmcnt(48)
	v_cvt_scalef32_pk_f32_fp4 v[0:1], v148, 1.0
	v_cvt_scalef32_pk_f32_fp4 v[2:3], v148, 1.0 op_sel:[1,0,0]
	v_cvt_scalef32_pk_f32_fp4 v[4:5], v148, 1.0 op_sel:[0,1,0]
	v_cvt_scalef32_pk_f32_fp4 v[6:7], v148, 1.0 op_sel:[1,1,0]
	v_cvt_scalef32_pk_f32_fp4 v[8:9], v149, 1.0
	v_cvt_scalef32_pk_f32_fp4 v[10:11], v149, 1.0 op_sel:[1,0,0]
	v_cvt_scalef32_pk_f32_fp4 v[12:13], v149, 1.0 op_sel:[0,1,0]
	v_cvt_scalef32_pk_f32_fp4 v[14:15], v149, 1.0 op_sel:[1,1,0]
	v_readlane_b32 s54, v92, 18
	s_lshl_b32 s56, s54, 9
	s_add_u32 s56, s64, s56
	s_addc_u32 s57, s65, 0
	global_load_dwordx2 v[148:149], v227, s[56:57]
	v_pk_fma_f32 v[130:131], v[0:1], s[0:1], v[130:131] op_sel_hi:[1,0,1]
	v_pk_fma_f32 v[138:139], v[2:3], s[0:1], v[138:139] op_sel_hi:[1,0,1]
	v_pk_fma_f32 v[140:141], v[4:5], s[0:1], v[140:141] op_sel_hi:[1,0,1]
	v_pk_fma_f32 v[142:143], v[6:7], s[0:1], v[142:143] op_sel_hi:[1,0,1]
	v_pk_fma_f32 v[128:129], v[8:9], s[0:1], v[128:129] op_sel_hi:[1,0,1]
	v_pk_fma_f32 v[132:133], v[10:11], s[0:1], v[132:133] op_sel_hi:[1,0,1]
	v_pk_fma_f32 v[134:135], v[12:13], s[0:1], v[134:135] op_sel_hi:[1,0,1]
	v_pk_fma_f32 v[136:137], v[14:15], s[0:1], v[136:137] op_sel_hi:[1,0,1]
	v_readlane_b32 s0, v167, 3
	s_waitcnt vmcnt(48)
	v_cvt_scalef32_pk_f32_fp4 v[0:1], v150, 1.0
	v_cvt_scalef32_pk_f32_fp4 v[2:3], v150, 1.0 op_sel:[1,0,0]
	v_cvt_scalef32_pk_f32_fp4 v[4:5], v150, 1.0 op_sel:[0,1,0]
	v_cvt_scalef32_pk_f32_fp4 v[6:7], v150, 1.0 op_sel:[1,1,0]
	v_cvt_scalef32_pk_f32_fp4 v[8:9], v151, 1.0
	v_cvt_scalef32_pk_f32_fp4 v[10:11], v151, 1.0 op_sel:[1,0,0]
	v_cvt_scalef32_pk_f32_fp4 v[12:13], v151, 1.0 op_sel:[0,1,0]
	v_cvt_scalef32_pk_f32_fp4 v[14:15], v151, 1.0 op_sel:[1,1,0]
	v_readlane_b32 s54, v92, 19
	s_lshl_b32 s56, s54, 9
	s_add_u32 s56, s64, s56
	s_addc_u32 s57, s65, 0
	global_load_dwordx2 v[150:151], v227, s[56:57]
	v_pk_fma_f32 v[130:131], v[0:1], s[0:1], v[130:131] op_sel_hi:[1,0,1]
	v_pk_fma_f32 v[138:139], v[2:3], s[0:1], v[138:139] op_sel_hi:[1,0,1]
	v_pk_fma_f32 v[140:141], v[4:5], s[0:1], v[140:141] op_sel_hi:[1,0,1]
	v_pk_fma_f32 v[142:143], v[6:7], s[0:1], v[142:143] op_sel_hi:[1,0,1]
	v_pk_fma_f32 v[128:129], v[8:9], s[0:1], v[128:129] op_sel_hi:[1,0,1]
	v_pk_fma_f32 v[132:133], v[10:11], s[0:1], v[132:133] op_sel_hi:[1,0,1]
	v_pk_fma_f32 v[134:135], v[12:13], s[0:1], v[134:135] op_sel_hi:[1,0,1]
	v_pk_fma_f32 v[136:137], v[14:15], s[0:1], v[136:137] op_sel_hi:[1,0,1]
	v_readlane_b32 s0, v167, 4
	s_waitcnt vmcnt(48)
	v_cvt_scalef32_pk_f32_fp4 v[0:1], v152, 1.0
	v_cvt_scalef32_pk_f32_fp4 v[2:3], v152, 1.0 op_sel:[1,0,0]
	v_cvt_scalef32_pk_f32_fp4 v[4:5], v152, 1.0 op_sel:[0,1,0]
	v_cvt_scalef32_pk_f32_fp4 v[6:7], v152, 1.0 op_sel:[1,1,0]
	v_cvt_scalef32_pk_f32_fp4 v[8:9], v153, 1.0
	v_cvt_scalef32_pk_f32_fp4 v[10:11], v153, 1.0 op_sel:[1,0,0]
	v_cvt_scalef32_pk_f32_fp4 v[12:13], v153, 1.0 op_sel:[0,1,0]
	v_cvt_scalef32_pk_f32_fp4 v[14:15], v153, 1.0 op_sel:[1,1,0]
	v_readlane_b32 s54, v92, 20
	s_lshl_b32 s56, s54, 9
	s_add_u32 s56, s64, s56
	s_addc_u32 s57, s65, 0
	global_load_dwordx2 v[152:153], v227, s[56:57]
	v_pk_fma_f32 v[130:131], v[0:1], s[0:1], v[130:131] op_sel_hi:[1,0,1]
	v_pk_fma_f32 v[138:139], v[2:3], s[0:1], v[138:139] op_sel_hi:[1,0,1]
	v_pk_fma_f32 v[140:141], v[4:5], s[0:1], v[140:141] op_sel_hi:[1,0,1]
	v_pk_fma_f32 v[142:143], v[6:7], s[0:1], v[142:143] op_sel_hi:[1,0,1]
	v_pk_fma_f32 v[128:129], v[8:9], s[0:1], v[128:129] op_sel_hi:[1,0,1]
	v_pk_fma_f32 v[132:133], v[10:11], s[0:1], v[132:133] op_sel_hi:[1,0,1]
	v_pk_fma_f32 v[134:135], v[12:13], s[0:1], v[134:135] op_sel_hi:[1,0,1]
	v_pk_fma_f32 v[136:137], v[14:15], s[0:1], v[136:137] op_sel_hi:[1,0,1]
	v_readlane_b32 s0, v167, 5
	s_waitcnt vmcnt(48)
; __device__ void peer_gather_phase(const Params& P, int l, bool do_store) {
;     ...
;         v8[2 * pr] = *(const uint2*)(V + (size_t)ea * 512);
;         v8[2 * pr + 1] = *(const uint2*)(V + (size_t)eb * 512);
;     ...
; #pragma unroll
;       for (int j = 0; j < 8; ++j) {
;         const float a = __builtin_bit_cast(float, __builtin_amdgcn_readlane(__builtin_bit_cast(int, avec), kb + j));
;         const f32x2 aa = f32x2{a, a};
;         y[0] += aa * __builtin_amdgcn_cvt_scalef32_pk_f32_fp4(v8[j].x, 1.0f, 0); y[1] += aa * __builtin_amdgcn_cvt_scalef32_pk_f32_fp4(v8[j].x, 1.0f, 1);
;         y[2] += aa * __builtin_amdgcn_cvt_scalef32_pk_f32_fp4(v8[j].x, 1.0f, 2); y[3] += aa * __builtin_amdgcn_cvt_scalef32_pk_f32_fp4(v8[j].x, 1.0f, 3);
;         y[4] += aa * __builtin_amdgcn_cvt_scalef32_pk_f32_fp4(v8[j].y, 1.0f, 0); y[5] += aa * __builtin_amdgcn_cvt_scalef32_pk_f32_fp4(v8[j].y, 1.0f, 1);
;         y[6] += aa * __builtin_amdgcn_cvt_scalef32_pk_f32_fp4(v8[j].y, 1.0f, 2); y[7] += aa * __builtin_amdgcn_cvt_scalef32_pk_f32_fp4(v8[j].y, 1.0f, 3);
;       }
	v_cvt_scalef32_pk_f32_fp4 v[0:1], v154, 1.0
	v_cvt_scalef32_pk_f32_fp4 v[2:3], v154, 1.0 op_sel:[1,0,0]
	v_cvt_scalef32_pk_f32_fp4 v[4:5], v154, 1.0 op_sel:[0,1,0]
	v_cvt_scalef32_pk_f32_fp4 v[6:7], v154, 1.0 op_sel:[1,1,0]
	v_cvt_scalef32_pk_f32_fp4 v[8:9], v155, 1.0
	v_cvt_scalef32_pk_f32_fp4 v[10:11], v155, 1.0 op_sel:[1,0,0]
	v_cvt_scalef32_pk_f32_fp4 v[12:13], v155, 1.0 op_sel:[0,1,0]
	v_cvt_scalef32_pk_f32_fp4 v[14:15], v155, 1.0 op_sel:[1,1,0]
	v_readlane_b32 s54, v92, 21
	s_lshl_b32 s56, s54, 9
	s_add_u32 s56, s64, s56
	s_addc_u32 s57, s65, 0
	global_load_dwordx2 v[154:155], v227, s[56:57]
	v_pk_fma_f32 v[130:131], v[0:1], s[0:1], v[130:131] op_sel_hi:[1,0,1]
	v_pk_fma_f32 v[138:139], v[2:3], s[0:1], v[138:139] op_sel_hi:[1,0,1]
	v_pk_fma_f32 v[140:141], v[4:5], s[0:1], v[140:141] op_sel_hi:[1,0,1]
	v_pk_fma_f32 v[142:143], v[6:7], s[0:1], v[142:143] op_sel_hi:[1,0,1]
	v_pk_fma_f32 v[128:129], v[8:9], s[0:1], v[128:129] op_sel_hi:[1,0,1]
	v_pk_fma_f32 v[132:133], v[10:11], s[0:1], v[132:133] op_sel_hi:[1,0,1]
	v_pk_fma_f32 v[134:135], v[12:13], s[0:1], v[134:135] op_sel_hi:[1,0,1]
	v_pk_fma_f32 v[136:137], v[14:15], s[0:1], v[136:137] op_sel_hi:[1,0,1]
	v_readlane_b32 s0, v167, 6
	s_waitcnt vmcnt(48)
	v_cvt_scalef32_pk_f32_fp4 v[0:1], v156, 1.0
	v_cvt_scalef32_pk_f32_fp4 v[2:3], v156, 1.0 op_sel:[1,0,0]
	v_cvt_scalef32_pk_f32_fp4 v[4:5], v156, 1.0 op_sel:[0,1,0]
	v_cvt_scalef32_pk_f32_fp4 v[6:7], v156, 1.0 op_sel:[1,1,0]
	v_cvt_scalef32_pk_f32_fp4 v[8:9], v157, 1.0
	v_cvt_scalef32_pk_f32_fp4 v[10:11], v157, 1.0 op_sel:[1,0,0]
	v_cvt_scalef32_pk_f32_fp4 v[12:13], v157, 1.0 op_sel:[0,1,0]
	v_cvt_scalef32_pk_f32_fp4 v[14:15], v157, 1.0 op_sel:[1,1,0]
	v_readlane_b32 s54, v92, 22
	s_lshl_b32 s56, s54, 9
	s_add_u32 s56, s64, s56
	s_addc_u32 s57, s65, 0
	global_load_dwordx2 v[156:157], v227, s[56:57]
	v_pk_fma_f32 v[130:131], v[0:1], s[0:1], v[130:131] op_sel_hi:[1,0,1]
	v_pk_fma_f32 v[138:139], v[2:3], s[0:1], v[138:139] op_sel_hi:[1,0,1]
	v_pk_fma_f32 v[140:141], v[4:5], s[0:1], v[140:141] op_sel_hi:[1,0,1]
	v_pk_fma_f32 v[142:143], v[6:7], s[0:1], v[142:143] op_sel_hi:[1,0,1]
	v_pk_fma_f32 v[128:129], v[8:9], s[0:1], v[128:129] op_sel_hi:[1,0,1]
	v_pk_fma_f32 v[132:133], v[10:11], s[0:1], v[132:133] op_sel_hi:[1,0,1]
	v_pk_fma_f32 v[134:135], v[12:13], s[0:1], v[134:135] op_sel_hi:[1,0,1]
	v_pk_fma_f32 v[136:137], v[14:15], s[0:1], v[136:137] op_sel_hi:[1,0,1]
	v_readlane_b32 s0, v167, 7
	s_waitcnt vmcnt(48)
	v_cvt_scalef32_pk_f32_fp4 v[0:1], v158, 1.0
	v_cvt_scalef32_pk_f32_fp4 v[2:3], v158, 1.0 op_sel:[1,0,0]
	v_cvt_scalef32_pk_f32_fp4 v[4:5], v158, 1.0 op_sel:[0,1,0]
	v_cvt_scalef32_pk_f32_fp4 v[6:7], v158, 1.0 op_sel:[1,1,0]
	v_cvt_scalef32_pk_f32_fp4 v[8:9], v159, 1.0
	v_cvt_scalef32_pk_f32_fp4 v[10:11], v159, 1.0 op_sel:[1,0,0]
	v_cvt_scalef32_pk_f32_fp4 v[12:13], v159, 1.0 op_sel:[0,1,0]
	v_cvt_scalef32_pk_f32_fp4 v[14:15], v159, 1.0 op_sel:[1,1,0]
	v_readlane_b32 s54, v92, 23
	s_lshl_b32 s56, s54, 9
	s_add_u32 s56, s64, s56
	s_addc_u32 s57, s65, 0
	global_load_dwordx2 v[158:159], v227, s[56:57]
	v_pk_fma_f32 v[130:131], v[0:1], s[0:1], v[130:131] op_sel_hi:[1,0,1]
	v_pk_fma_f32 v[138:139], v[2:3], s[0:1], v[138:139] op_sel_hi:[1,0,1]
	v_pk_fma_f32 v[140:141], v[4:5], s[0:1], v[140:141] op_sel_hi:[1,0,1]
	v_pk_fma_f32 v[142:143], v[6:7], s[0:1], v[142:143] op_sel_hi:[1,0,1]
	v_pk_fma_f32 v[128:129], v[8:9], s[0:1], v[128:129] op_sel_hi:[1,0,1]
	v_pk_fma_f32 v[132:133], v[10:11], s[0:1], v[132:133] op_sel_hi:[1,0,1]
	v_pk_fma_f32 v[134:135], v[12:13], s[0:1], v[134:135] op_sel_hi:[1,0,1]
	v_pk_fma_f32 v[136:137], v[14:15], s[0:1], v[136:137] op_sel_hi:[1,0,1]
	v_readlane_b32 s0, v167, 8
	s_waitcnt vmcnt(48)
	v_cvt_scalef32_pk_f32_fp4 v[0:1], v168, 1.0
	v_cvt_scalef32_pk_f32_fp4 v[2:3], v168, 1.0 op_sel:[1,0,0]
	v_cvt_scalef32_pk_f32_fp4 v[4:5], v168, 1.0 op_sel:[0,1,0]
	v_cvt_scalef32_pk_f32_fp4 v[6:7], v168, 1.0 op_sel:[1,1,0]
	v_cvt_scalef32_pk_f32_fp4 v[8:9], v169, 1.0
	v_cvt_scalef32_pk_f32_fp4 v[10:11], v169, 1.0 op_sel:[1,0,0]
	v_cvt_scalef32_pk_f32_fp4 v[12:13], v169, 1.0 op_sel:[0,1,0]
	v_cvt_scalef32_pk_f32_fp4 v[14:15], v169, 1.0 op_sel:[1,1,0]
	v_readlane_b32 s54, v92, 24
	s_lshl_b32 s56, s54, 9
	s_add_u32 s56, s64, s56
	s_addc_u32 s57, s65, 0
	global_load_dwordx2 v[168:169], v227, s[56:57]
	v_pk_fma_f32 v[130:131], v[0:1], s[0:1], v[130:131] op_sel_hi:[1,0,1]
	v_pk_fma_f32 v[138:139], v[2:3], s[0:1], v[138:139] op_sel_hi:[1,0,1]
	v_pk_fma_f32 v[140:141], v[4:5], s[0:1], v[140:141] op_sel_hi:[1,0,1]
	v_pk_fma_f32 v[142:143], v[6:7], s[0:1], v[142:143] op_sel_hi:[1,0,1]
	v_pk_fma_f32 v[128:129], v[8:9], s[0:1], v[128:129] op_sel_hi:[1,0,1]
	v_pk_fma_f32 v[132:133], v[10:11], s[0:1], v[132:133] op_sel_hi:[1,0,1]
	v_pk_fma_f32 v[134:135], v[12:13], s[0:1], v[134:135] op_sel_hi:[1,0,1]
	v_pk_fma_f32 v[136:137], v[14:15], s[0:1], v[136:137] op_sel_hi:[1,0,1]
	v_readlane_b32 s0, v167, 9
	s_waitcnt vmcnt(48)
	v_cvt_scalef32_pk_f32_fp4 v[0:1], v170, 1.0
	v_cvt_scalef32_pk_f32_fp4 v[2:3], v170, 1.0 op_sel:[1,0,0]
	v_cvt_scalef32_pk_f32_fp4 v[4:5], v170, 1.0 op_sel:[0,1,0]
	v_cvt_scalef32_pk_f32_fp4 v[6:7], v170, 1.0 op_sel:[1,1,0]
	v_cvt_scalef32_pk_f32_fp4 v[8:9], v171, 1.0
	v_cvt_scalef32_pk_f32_fp4 v[10:11], v171, 1.0 op_sel:[1,0,0]
	v_cvt_scalef32_pk_f32_fp4 v[12:13], v171, 1.0 op_sel:[0,1,0]
	v_cvt_scalef32_pk_f32_fp4 v[14:15], v171, 1.0 op_sel:[1,1,0]
	v_readlane_b32 s54, v92, 25
	s_lshl_b32 s56, s54, 9
	s_add_u32 s56, s64, s56
	s_addc_u32 s57, s65, 0
	global_load_dwordx2 v[170:171], v227, s[56:57]
	v_pk_fma_f32 v[130:131], v[0:1], s[0:1], v[130:131] op_sel_hi:[1,0,1]
	v_pk_fma_f32 v[138:139], v[2:3], s[0:1], v[138:139] op_sel_hi:[1,0,1]
	v_pk_fma_f32 v[140:141], v[4:5], s[0:1], v[140:141] op_sel_hi:[1,0,1]
	v_pk_fma_f32 v[142:143], v[6:7], s[0:1], v[142:143] op_sel_hi:[1,0,1]
	v_pk_fma_f32 v[128:129], v[8:9], s[0:1], v[128:129] op_sel_hi:[1,0,1]
	v_pk_fma_f32 v[132:133], v[10:11], s[0:1], v[132:133] op_sel_hi:[1,0,1]
	v_pk_fma_f32 v[134:135], v[12:13], s[0:1], v[134:135] op_sel_hi:[1,0,1]
	v_pk_fma_f32 v[136:137], v[14:15], s[0:1], v[136:137] op_sel_hi:[1,0,1]
	v_readlane_b32 s0, v167, 10
	s_waitcnt vmcnt(48)
; __device__ void peer_gather_phase(const Params& P, int l, bool do_store) {
;     ...
;         v8[2 * pr] = *(const uint2*)(V + (size_t)ea * 512);
;         v8[2 * pr + 1] = *(const uint2*)(V + (size_t)eb * 512);
;     ...
; #pragma unroll
;       for (int j = 0; j < 8; ++j) {
;         const float a = __builtin_bit_cast(float, __builtin_amdgcn_readlane(__builtin_bit_cast(int, avec), kb + j));
;         const f32x2 aa = f32x2{a, a};
;         y[0] += aa * __builtin_amdgcn_cvt_scalef32_pk_f32_fp4(v8[j].x, 1.0f, 0); y[1] += aa * __builtin_amdgcn_cvt_scalef32_pk_f32_fp4(v8[j].x, 1.0f, 1);
;         y[2] += aa * __builtin_amdgcn_cvt_scalef32_pk_f32_fp4(v8[j].x, 1.0f, 2); y[3] += aa * __builtin_amdgcn_cvt_scalef32_pk_f32_fp4(v8[j].x, 1.0f, 3);
;         y[4] += aa * __builtin_amdgcn_cvt_scalef32_pk_f32_fp4(v8[j].y, 1.0f, 0); y[5] += aa * __builtin_amdgcn_cvt_scalef32_pk_f32_fp4(v8[j].y, 1.0f, 1);
;         y[6] += aa * __builtin_amdgcn_cvt_scalef32_pk_f32_fp4(v8[j].y, 1.0f, 2); y[7] += aa * __builtin_amdgcn_cvt_scalef32_pk_f32_fp4(v8[j].y, 1.0f, 3);
;       }
	v_cvt_scalef32_pk_f32_fp4 v[0:1], v172, 1.0
	v_cvt_scalef32_pk_f32_fp4 v[2:3], v172, 1.0 op_sel:[1,0,0]
	v_cvt_scalef32_pk_f32_fp4 v[4:5], v172, 1.0 op_sel:[0,1,0]
	v_cvt_scalef32_pk_f32_fp4 v[6:7], v172, 1.0 op_sel:[1,1,0]
	v_cvt_scalef32_pk_f32_fp4 v[8:9], v173, 1.0
	v_cvt_scalef32_pk_f32_fp4 v[10:11], v173, 1.0 op_sel:[1,0,0]
	v_cvt_scalef32_pk_f32_fp4 v[12:13], v173, 1.0 op_sel:[0,1,0]
	v_cvt_scalef32_pk_f32_fp4 v[14:15], v173, 1.0 op_sel:[1,1,0]
	v_readlane_b32 s54, v92, 26
	s_lshl_b32 s56, s54, 9
	s_add_u32 s56, s64, s56
	s_addc_u32 s57, s65, 0
	global_load_dwordx2 v[172:173], v227, s[56:57]
	v_pk_fma_f32 v[130:131], v[0:1], s[0:1], v[130:131] op_sel_hi:[1,0,1]
	v_pk_fma_f32 v[138:139], v[2:3], s[0:1], v[138:139] op_sel_hi:[1,0,1]
	v_pk_fma_f32 v[140:141], v[4:5], s[0:1], v[140:141] op_sel_hi:[1,0,1]
	v_pk_fma_f32 v[142:143], v[6:7], s[0:1], v[142:143] op_sel_hi:[1,0,1]
	v_pk_fma_f32 v[128:129], v[8:9], s[0:1], v[128:129] op_sel_hi:[1,0,1]
	v_pk_fma_f32 v[132:133], v[10:11], s[0:1], v[132:133] op_sel_hi:[1,0,1]
	v_pk_fma_f32 v[134:135], v[12:13], s[0:1], v[134:135] op_sel_hi:[1,0,1]
	v_pk_fma_f32 v[136:137], v[14:15], s[0:1], v[136:137] op_sel_hi:[1,0,1]
	v_readlane_b32 s0, v167, 11
	s_waitcnt vmcnt(48)
	v_cvt_scalef32_pk_f32_fp4 v[0:1], v174, 1.0
	v_cvt_scalef32_pk_f32_fp4 v[2:3], v174, 1.0 op_sel:[1,0,0]
	v_cvt_scalef32_pk_f32_fp4 v[4:5], v174, 1.0 op_sel:[0,1,0]
	v_cvt_scalef32_pk_f32_fp4 v[6:7], v174, 1.0 op_sel:[1,1,0]
	v_cvt_scalef32_pk_f32_fp4 v[8:9], v175, 1.0
	v_cvt_scalef32_pk_f32_fp4 v[10:11], v175, 1.0 op_sel:[1,0,0]
	v_cvt_scalef32_pk_f32_fp4 v[12:13], v175, 1.0 op_sel:[0,1,0]
	v_cvt_scalef32_pk_f32_fp4 v[14:15], v175, 1.0 op_sel:[1,1,0]
	v_readlane_b32 s54, v92, 27
	s_lshl_b32 s56, s54, 9
	s_add_u32 s56, s64, s56
	s_addc_u32 s57, s65, 0
	global_load_dwordx2 v[174:175], v227, s[56:57]
	v_pk_fma_f32 v[130:131], v[0:1], s[0:1], v[130:131] op_sel_hi:[1,0,1]
	v_pk_fma_f32 v[138:139], v[2:3], s[0:1], v[138:139] op_sel_hi:[1,0,1]
	v_pk_fma_f32 v[140:141], v[4:5], s[0:1], v[140:141] op_sel_hi:[1,0,1]
	v_pk_fma_f32 v[142:143], v[6:7], s[0:1], v[142:143] op_sel_hi:[1,0,1]
	v_pk_fma_f32 v[128:129], v[8:9], s[0:1], v[128:129] op_sel_hi:[1,0,1]
	v_pk_fma_f32 v[132:133], v[10:11], s[0:1], v[132:133] op_sel_hi:[1,0,1]
	v_pk_fma_f32 v[134:135], v[12:13], s[0:1], v[134:135] op_sel_hi:[1,0,1]
	v_pk_fma_f32 v[136:137], v[14:15], s[0:1], v[136:137] op_sel_hi:[1,0,1]
	v_readlane_b32 s0, v167, 12
	s_waitcnt vmcnt(48)
	v_cvt_scalef32_pk_f32_fp4 v[0:1], v180, 1.0
	v_cvt_scalef32_pk_f32_fp4 v[2:3], v180, 1.0 op_sel:[1,0,0]
	v_cvt_scalef32_pk_f32_fp4 v[4:5], v180, 1.0 op_sel:[0,1,0]
	v_cvt_scalef32_pk_f32_fp4 v[6:7], v180, 1.0 op_sel:[1,1,0]
	v_cvt_scalef32_pk_f32_fp4 v[8:9], v181, 1.0
	v_cvt_scalef32_pk_f32_fp4 v[10:11], v181, 1.0 op_sel:[1,0,0]
	v_cvt_scalef32_pk_f32_fp4 v[12:13], v181, 1.0 op_sel:[0,1,0]
	v_cvt_scalef32_pk_f32_fp4 v[14:15], v181, 1.0 op_sel:[1,1,0]
	v_readlane_b32 s54, v92, 28
	s_lshl_b32 s56, s54, 9
	s_add_u32 s56, s64, s56
	s_addc_u32 s57, s65, 0
	global_load_dwordx2 v[180:181], v227, s[56:57]
	v_pk_fma_f32 v[130:131], v[0:1], s[0:1], v[130:131] op_sel_hi:[1,0,1]
	v_pk_fma_f32 v[138:139], v[2:3], s[0:1], v[138:139] op_sel_hi:[1,0,1]
	v_pk_fma_f32 v[140:141], v[4:5], s[0:1], v[140:141] op_sel_hi:[1,0,1]
	v_pk_fma_f32 v[142:143], v[6:7], s[0:1], v[142:143] op_sel_hi:[1,0,1]
	v_pk_fma_f32 v[128:129], v[8:9], s[0:1], v[128:129] op_sel_hi:[1,0,1]
	v_pk_fma_f32 v[132:133], v[10:11], s[0:1], v[132:133] op_sel_hi:[1,0,1]
	v_pk_fma_f32 v[134:135], v[12:13], s[0:1], v[134:135] op_sel_hi:[1,0,1]
	v_pk_fma_f32 v[136:137], v[14:15], s[0:1], v[136:137] op_sel_hi:[1,0,1]
	v_readlane_b32 s0, v167, 13
	s_waitcnt vmcnt(48)
	v_cvt_scalef32_pk_f32_fp4 v[0:1], v182, 1.0
	v_cvt_scalef32_pk_f32_fp4 v[2:3], v182, 1.0 op_sel:[1,0,0]
	v_cvt_scalef32_pk_f32_fp4 v[4:5], v182, 1.0 op_sel:[0,1,0]
	v_cvt_scalef32_pk_f32_fp4 v[6:7], v182, 1.0 op_sel:[1,1,0]
	v_cvt_scalef32_pk_f32_fp4 v[8:9], v183, 1.0
	v_cvt_scalef32_pk_f32_fp4 v[10:11], v183, 1.0 op_sel:[1,0,0]
	v_cvt_scalef32_pk_f32_fp4 v[12:13], v183, 1.0 op_sel:[0,1,0]
	v_cvt_scalef32_pk_f32_fp4 v[14:15], v183, 1.0 op_sel:[1,1,0]
	v_readlane_b32 s54, v92, 29
	s_lshl_b32 s56, s54, 9
	s_add_u32 s56, s64, s56
	s_addc_u32 s57, s65, 0
	global_load_dwordx2 v[182:183], v227, s[56:57]
	v_pk_fma_f32 v[130:131], v[0:1], s[0:1], v[130:131] op_sel_hi:[1,0,1]
	v_pk_fma_f32 v[138:139], v[2:3], s[0:1], v[138:139] op_sel_hi:[1,0,1]
	v_pk_fma_f32 v[140:141], v[4:5], s[0:1], v[140:141] op_sel_hi:[1,0,1]
	v_pk_fma_f32 v[142:143], v[6:7], s[0:1], v[142:143] op_sel_hi:[1,0,1]
	v_pk_fma_f32 v[128:129], v[8:9], s[0:1], v[128:129] op_sel_hi:[1,0,1]
	v_pk_fma_f32 v[132:133], v[10:11], s[0:1], v[132:133] op_sel_hi:[1,0,1]
	v_pk_fma_f32 v[134:135], v[12:13], s[0:1], v[134:135] op_sel_hi:[1,0,1]
	v_pk_fma_f32 v[136:137], v[14:15], s[0:1], v[136:137] op_sel_hi:[1,0,1]
	v_readlane_b32 s0, v167, 14
	s_waitcnt vmcnt(48)
	v_cvt_scalef32_pk_f32_fp4 v[0:1], v184, 1.0
	v_cvt_scalef32_pk_f32_fp4 v[2:3], v184, 1.0 op_sel:[1,0,0]
	v_cvt_scalef32_pk_f32_fp4 v[4:5], v184, 1.0 op_sel:[0,1,0]
	v_cvt_scalef32_pk_f32_fp4 v[6:7], v184, 1.0 op_sel:[1,1,0]
	v_cvt_scalef32_pk_f32_fp4 v[8:9], v185, 1.0
	v_cvt_scalef32_pk_f32_fp4 v[10:11], v185, 1.0 op_sel:[1,0,0]
	v_cvt_scalef32_pk_f32_fp4 v[12:13], v185, 1.0 op_sel:[0,1,0]
	v_cvt_scalef32_pk_f32_fp4 v[14:15], v185, 1.0 op_sel:[1,1,0]
	v_readlane_b32 s54, v92, 30
	s_lshl_b32 s56, s54, 9
	s_add_u32 s56, s64, s56
	s_addc_u32 s57, s65, 0
	global_load_dwordx2 v[184:185], v227, s[56:57]
	v_pk_fma_f32 v[130:131], v[0:1], s[0:1], v[130:131] op_sel_hi:[1,0,1]
	v_pk_fma_f32 v[138:139], v[2:3], s[0:1], v[138:139] op_sel_hi:[1,0,1]
	v_pk_fma_f32 v[140:141], v[4:5], s[0:1], v[140:141] op_sel_hi:[1,0,1]
	v_pk_fma_f32 v[142:143], v[6:7], s[0:1], v[142:143] op_sel_hi:[1,0,1]
	v_pk_fma_f32 v[128:129], v[8:9], s[0:1], v[128:129] op_sel_hi:[1,0,1]
	v_pk_fma_f32 v[132:133], v[10:11], s[0:1], v[132:133] op_sel_hi:[1,0,1]
	v_pk_fma_f32 v[134:135], v[12:13], s[0:1], v[134:135] op_sel_hi:[1,0,1]
	v_pk_fma_f32 v[136:137], v[14:15], s[0:1], v[136:137] op_sel_hi:[1,0,1]
	v_readlane_b32 s0, v167, 15
	s_waitcnt vmcnt(48)
; __device__ void peer_gather_phase(const Params& P, int l, bool do_store) {
;     ...
;         v8[2 * pr] = *(const uint2*)(V + (size_t)ea * 512);
;         v8[2 * pr + 1] = *(const uint2*)(V + (size_t)eb * 512);
;     ...
; #pragma unroll
;       for (int j = 0; j < 8; ++j) {
;         const float a = __builtin_bit_cast(float, __builtin_amdgcn_readlane(__builtin_bit_cast(int, avec), kb + j));
;         const f32x2 aa = f32x2{a, a};
;         y[0] += aa * __builtin_amdgcn_cvt_scalef32_pk_f32_fp4(v8[j].x, 1.0f, 0); y[1] += aa * __builtin_amdgcn_cvt_scalef32_pk_f32_fp4(v8[j].x, 1.0f, 1);
;         y[2] += aa * __builtin_amdgcn_cvt_scalef32_pk_f32_fp4(v8[j].x, 1.0f, 2); y[3] += aa * __builtin_amdgcn_cvt_scalef32_pk_f32_fp4(v8[j].x, 1.0f, 3);
;         y[4] += aa * __builtin_amdgcn_cvt_scalef32_pk_f32_fp4(v8[j].y, 1.0f, 0); y[5] += aa * __builtin_amdgcn_cvt_scalef32_pk_f32_fp4(v8[j].y, 1.0f, 1);
;         y[6] += aa * __builtin_amdgcn_cvt_scalef32_pk_f32_fp4(v8[j].y, 1.0f, 2); y[7] += aa * __builtin_amdgcn_cvt_scalef32_pk_f32_fp4(v8[j].y, 1.0f, 3);
;       }
	v_cvt_scalef32_pk_f32_fp4 v[0:1], v186, 1.0
	v_cvt_scalef32_pk_f32_fp4 v[2:3], v186, 1.0 op_sel:[1,0,0]
	v_cvt_scalef32_pk_f32_fp4 v[4:5], v186, 1.0 op_sel:[0,1,0]
	v_cvt_scalef32_pk_f32_fp4 v[6:7], v186, 1.0 op_sel:[1,1,0]
	v_cvt_scalef32_pk_f32_fp4 v[8:9], v187, 1.0
	v_cvt_scalef32_pk_f32_fp4 v[10:11], v187, 1.0 op_sel:[1,0,0]
	v_cvt_scalef32_pk_f32_fp4 v[12:13], v187, 1.0 op_sel:[0,1,0]
	v_cvt_scalef32_pk_f32_fp4 v[14:15], v187, 1.0 op_sel:[1,1,0]
	v_readlane_b32 s54, v92, 31
	s_lshl_b32 s56, s54, 9
	s_add_u32 s56, s64, s56
	s_addc_u32 s57, s65, 0
	global_load_dwordx2 v[186:187], v227, s[56:57]
	v_pk_fma_f32 v[130:131], v[0:1], s[0:1], v[130:131] op_sel_hi:[1,0,1]
	v_pk_fma_f32 v[138:139], v[2:3], s[0:1], v[138:139] op_sel_hi:[1,0,1]
	v_pk_fma_f32 v[140:141], v[4:5], s[0:1], v[140:141] op_sel_hi:[1,0,1]
	v_pk_fma_f32 v[142:143], v[6:7], s[0:1], v[142:143] op_sel_hi:[1,0,1]
	v_pk_fma_f32 v[128:129], v[8:9], s[0:1], v[128:129] op_sel_hi:[1,0,1]
	v_pk_fma_f32 v[132:133], v[10:11], s[0:1], v[132:133] op_sel_hi:[1,0,1]
	v_pk_fma_f32 v[134:135], v[12:13], s[0:1], v[134:135] op_sel_hi:[1,0,1]
	v_pk_fma_f32 v[136:137], v[14:15], s[0:1], v[136:137] op_sel_hi:[1,0,1]
	v_readlane_b32 s0, v167, 16
	s_waitcnt vmcnt(15)
	v_cvt_scalef32_pk_f32_fp4 v[0:1], v144, 1.0
	v_cvt_scalef32_pk_f32_fp4 v[2:3], v144, 1.0 op_sel:[1,0,0]
	v_cvt_scalef32_pk_f32_fp4 v[4:5], v144, 1.0 op_sel:[0,1,0]
	v_cvt_scalef32_pk_f32_fp4 v[6:7], v144, 1.0 op_sel:[1,1,0]
	v_cvt_scalef32_pk_f32_fp4 v[8:9], v145, 1.0
	v_cvt_scalef32_pk_f32_fp4 v[10:11], v145, 1.0 op_sel:[1,0,0]
	v_cvt_scalef32_pk_f32_fp4 v[12:13], v145, 1.0 op_sel:[0,1,0]
	v_cvt_scalef32_pk_f32_fp4 v[14:15], v145, 1.0 op_sel:[1,1,0]
	v_readlane_b32 s54, v92, 32
	s_lshl_b32 s56, s54, 9
	s_add_u32 s56, s64, s56
	s_addc_u32 s57, s65, 0
	global_load_dwordx2 v[144:145], v227, s[56:57]
	v_pk_fma_f32 v[130:131], v[0:1], s[0:1], v[130:131] op_sel_hi:[1,0,1]
	v_pk_fma_f32 v[138:139], v[2:3], s[0:1], v[138:139] op_sel_hi:[1,0,1]
	v_pk_fma_f32 v[140:141], v[4:5], s[0:1], v[140:141] op_sel_hi:[1,0,1]
	v_pk_fma_f32 v[142:143], v[6:7], s[0:1], v[142:143] op_sel_hi:[1,0,1]
	v_pk_fma_f32 v[128:129], v[8:9], s[0:1], v[128:129] op_sel_hi:[1,0,1]
	v_pk_fma_f32 v[132:133], v[10:11], s[0:1], v[132:133] op_sel_hi:[1,0,1]
	v_pk_fma_f32 v[134:135], v[12:13], s[0:1], v[134:135] op_sel_hi:[1,0,1]
	v_pk_fma_f32 v[136:137], v[14:15], s[0:1], v[136:137] op_sel_hi:[1,0,1]
	v_readlane_b32 s0, v167, 17
	s_waitcnt vmcnt(15)
	v_cvt_scalef32_pk_f32_fp4 v[0:1], v146, 1.0
	v_cvt_scalef32_pk_f32_fp4 v[2:3], v146, 1.0 op_sel:[1,0,0]
	v_cvt_scalef32_pk_f32_fp4 v[4:5], v146, 1.0 op_sel:[0,1,0]
	v_cvt_scalef32_pk_f32_fp4 v[6:7], v146, 1.0 op_sel:[1,1,0]
	v_cvt_scalef32_pk_f32_fp4 v[8:9], v147, 1.0
	v_cvt_scalef32_pk_f32_fp4 v[10:11], v147, 1.0 op_sel:[1,0,0]
	v_cvt_scalef32_pk_f32_fp4 v[12:13], v147, 1.0 op_sel:[0,1,0]
	v_cvt_scalef32_pk_f32_fp4 v[14:15], v147, 1.0 op_sel:[1,1,0]
	v_readlane_b32 s54, v92, 33
	s_lshl_b32 s56, s54, 9
	s_add_u32 s56, s64, s56
	s_addc_u32 s57, s65, 0
	global_load_dwordx2 v[146:147], v227, s[56:57]
	v_pk_fma_f32 v[130:131], v[0:1], s[0:1], v[130:131] op_sel_hi:[1,0,1]
	v_pk_fma_f32 v[138:139], v[2:3], s[0:1], v[138:139] op_sel_hi:[1,0,1]
	v_pk_fma_f32 v[140:141], v[4:5], s[0:1], v[140:141] op_sel_hi:[1,0,1]
	v_pk_fma_f32 v[142:143], v[6:7], s[0:1], v[142:143] op_sel_hi:[1,0,1]
	v_pk_fma_f32 v[128:129], v[8:9], s[0:1], v[128:129] op_sel_hi:[1,0,1]
	v_pk_fma_f32 v[132:133], v[10:11], s[0:1], v[132:133] op_sel_hi:[1,0,1]
	v_pk_fma_f32 v[134:135], v[12:13], s[0:1], v[134:135] op_sel_hi:[1,0,1]
	v_pk_fma_f32 v[136:137], v[14:15], s[0:1], v[136:137] op_sel_hi:[1,0,1]
	v_readlane_b32 s0, v167, 18
	s_waitcnt vmcnt(15)
	v_cvt_scalef32_pk_f32_fp4 v[0:1], v148, 1.0
	v_cvt_scalef32_pk_f32_fp4 v[2:3], v148, 1.0 op_sel:[1,0,0]
	v_cvt_scalef32_pk_f32_fp4 v[4:5], v148, 1.0 op_sel:[0,1,0]
	v_cvt_scalef32_pk_f32_fp4 v[6:7], v148, 1.0 op_sel:[1,1,0]
	v_cvt_scalef32_pk_f32_fp4 v[8:9], v149, 1.0
	v_cvt_scalef32_pk_f32_fp4 v[10:11], v149, 1.0 op_sel:[1,0,0]
	v_cvt_scalef32_pk_f32_fp4 v[12:13], v149, 1.0 op_sel:[0,1,0]
	v_cvt_scalef32_pk_f32_fp4 v[14:15], v149, 1.0 op_sel:[1,1,0]
	v_readlane_b32 s54, v92, 34
	s_lshl_b32 s56, s54, 9
	s_add_u32 s56, s64, s56
	s_addc_u32 s57, s65, 0
	global_load_dwordx2 v[148:149], v227, s[56:57]
	v_pk_fma_f32 v[130:131], v[0:1], s[0:1], v[130:131] op_sel_hi:[1,0,1]
	v_pk_fma_f32 v[138:139], v[2:3], s[0:1], v[138:139] op_sel_hi:[1,0,1]
	v_pk_fma_f32 v[140:141], v[4:5], s[0:1], v[140:141] op_sel_hi:[1,0,1]
	v_pk_fma_f32 v[142:143], v[6:7], s[0:1], v[142:143] op_sel_hi:[1,0,1]
	v_pk_fma_f32 v[128:129], v[8:9], s[0:1], v[128:129] op_sel_hi:[1,0,1]
	v_pk_fma_f32 v[132:133], v[10:11], s[0:1], v[132:133] op_sel_hi:[1,0,1]
	v_pk_fma_f32 v[134:135], v[12:13], s[0:1], v[134:135] op_sel_hi:[1,0,1]
	v_pk_fma_f32 v[136:137], v[14:15], s[0:1], v[136:137] op_sel_hi:[1,0,1]
	v_readlane_b32 s0, v167, 19
	s_waitcnt vmcnt(15)
	v_cvt_scalef32_pk_f32_fp4 v[0:1], v150, 1.0
	v_cvt_scalef32_pk_f32_fp4 v[2:3], v150, 1.0 op_sel:[1,0,0]
	v_cvt_scalef32_pk_f32_fp4 v[4:5], v150, 1.0 op_sel:[0,1,0]
	v_cvt_scalef32_pk_f32_fp4 v[6:7], v150, 1.0 op_sel:[1,1,0]
	v_cvt_scalef32_pk_f32_fp4 v[8:9], v151, 1.0
	v_cvt_scalef32_pk_f32_fp4 v[10:11], v151, 1.0 op_sel:[1,0,0]
	v_cvt_scalef32_pk_f32_fp4 v[12:13], v151, 1.0 op_sel:[0,1,0]
	v_cvt_scalef32_pk_f32_fp4 v[14:15], v151, 1.0 op_sel:[1,1,0]
	v_readlane_b32 s54, v92, 35
	s_lshl_b32 s56, s54, 9
	s_add_u32 s56, s64, s56
	s_addc_u32 s57, s65, 0
	global_load_dwordx2 v[150:151], v227, s[56:57]
	v_pk_fma_f32 v[130:131], v[0:1], s[0:1], v[130:131] op_sel_hi:[1,0,1]
	v_pk_fma_f32 v[138:139], v[2:3], s[0:1], v[138:139] op_sel_hi:[1,0,1]
	v_pk_fma_f32 v[140:141], v[4:5], s[0:1], v[140:141] op_sel_hi:[1,0,1]
	v_pk_fma_f32 v[142:143], v[6:7], s[0:1], v[142:143] op_sel_hi:[1,0,1]
	v_pk_fma_f32 v[128:129], v[8:9], s[0:1], v[128:129] op_sel_hi:[1,0,1]
	v_pk_fma_f32 v[132:133], v[10:11], s[0:1], v[132:133] op_sel_hi:[1,0,1]
	v_pk_fma_f32 v[134:135], v[12:13], s[0:1], v[134:135] op_sel_hi:[1,0,1]
	v_pk_fma_f32 v[136:137], v[14:15], s[0:1], v[136:137] op_sel_hi:[1,0,1]
	v_readlane_b32 s0, v167, 20
	s_waitcnt vmcnt(15)
; __device__ void peer_gather_phase(const Params& P, int l, bool do_store) {
;     ...
;         v8[2 * pr] = *(const uint2*)(V + (size_t)ea * 512);
;         v8[2 * pr + 1] = *(const uint2*)(V + (size_t)eb * 512);
;     ...
; #pragma unroll
;       for (int j = 0; j < 8; ++j) {
;         const float a = __builtin_bit_cast(float, __builtin_amdgcn_readlane(__builtin_bit_cast(int, avec), kb + j));
;         const f32x2 aa = f32x2{a, a};
;         y[0] += aa * __builtin_amdgcn_cvt_scalef32_pk_f32_fp4(v8[j].x, 1.0f, 0); y[1] += aa * __builtin_amdgcn_cvt_scalef32_pk_f32_fp4(v8[j].x, 1.0f, 1);
;         y[2] += aa * __builtin_amdgcn_cvt_scalef32_pk_f32_fp4(v8[j].x, 1.0f, 2); y[3] += aa * __builtin_amdgcn_cvt_scalef32_pk_f32_fp4(v8[j].x, 1.0f, 3);
;         y[4] += aa * __builtin_amdgcn_cvt_scalef32_pk_f32_fp4(v8[j].y, 1.0f, 0); y[5] += aa * __builtin_amdgcn_cvt_scalef32_pk_f32_fp4(v8[j].y, 1.0f, 1);
;         y[6] += aa * __builtin_amdgcn_cvt_scalef32_pk_f32_fp4(v8[j].y, 1.0f, 2); y[7] += aa * __builtin_amdgcn_cvt_scalef32_pk_f32_fp4(v8[j].y, 1.0f, 3);
;       }
	v_cvt_scalef32_pk_f32_fp4 v[0:1], v152, 1.0
	v_cvt_scalef32_pk_f32_fp4 v[2:3], v152, 1.0 op_sel:[1,0,0]
	v_cvt_scalef32_pk_f32_fp4 v[4:5], v152, 1.0 op_sel:[0,1,0]
	v_cvt_scalef32_pk_f32_fp4 v[6:7], v152, 1.0 op_sel:[1,1,0]
	v_cvt_scalef32_pk_f32_fp4 v[8:9], v153, 1.0
	v_cvt_scalef32_pk_f32_fp4 v[10:11], v153, 1.0 op_sel:[1,0,0]
	v_cvt_scalef32_pk_f32_fp4 v[12:13], v153, 1.0 op_sel:[0,1,0]
	v_cvt_scalef32_pk_f32_fp4 v[14:15], v153, 1.0 op_sel:[1,1,0]
	v_readlane_b32 s54, v92, 36
	s_lshl_b32 s56, s54, 9
	s_add_u32 s56, s64, s56
	s_addc_u32 s57, s65, 0
	global_load_dwordx2 v[152:153], v227, s[56:57]
	v_pk_fma_f32 v[130:131], v[0:1], s[0:1], v[130:131] op_sel_hi:[1,0,1]
	v_pk_fma_f32 v[138:139], v[2:3], s[0:1], v[138:139] op_sel_hi:[1,0,1]
	v_pk_fma_f32 v[140:141], v[4:5], s[0:1], v[140:141] op_sel_hi:[1,0,1]
	v_pk_fma_f32 v[142:143], v[6:7], s[0:1], v[142:143] op_sel_hi:[1,0,1]
	v_pk_fma_f32 v[128:129], v[8:9], s[0:1], v[128:129] op_sel_hi:[1,0,1]
	v_pk_fma_f32 v[132:133], v[10:11], s[0:1], v[132:133] op_sel_hi:[1,0,1]
	v_pk_fma_f32 v[134:135], v[12:13], s[0:1], v[134:135] op_sel_hi:[1,0,1]
	v_pk_fma_f32 v[136:137], v[14:15], s[0:1], v[136:137] op_sel_hi:[1,0,1]
	v_readlane_b32 s0, v167, 21
	s_waitcnt vmcnt(15)
	v_cvt_scalef32_pk_f32_fp4 v[0:1], v154, 1.0
	v_cvt_scalef32_pk_f32_fp4 v[2:3], v154, 1.0 op_sel:[1,0,0]
	v_cvt_scalef32_pk_f32_fp4 v[4:5], v154, 1.0 op_sel:[0,1,0]
	v_cvt_scalef32_pk_f32_fp4 v[6:7], v154, 1.0 op_sel:[1,1,0]
	v_cvt_scalef32_pk_f32_fp4 v[8:9], v155, 1.0
	v_cvt_scalef32_pk_f32_fp4 v[10:11], v155, 1.0 op_sel:[1,0,0]
	v_cvt_scalef32_pk_f32_fp4 v[12:13], v155, 1.0 op_sel:[0,1,0]
	v_cvt_scalef32_pk_f32_fp4 v[14:15], v155, 1.0 op_sel:[1,1,0]
	v_readlane_b32 s54, v92, 37
	s_lshl_b32 s56, s54, 9
	s_add_u32 s56, s64, s56
	s_addc_u32 s57, s65, 0
	global_load_dwordx2 v[154:155], v227, s[56:57]
	v_pk_fma_f32 v[130:131], v[0:1], s[0:1], v[130:131] op_sel_hi:[1,0,1]
	v_pk_fma_f32 v[138:139], v[2:3], s[0:1], v[138:139] op_sel_hi:[1,0,1]
	v_pk_fma_f32 v[140:141], v[4:5], s[0:1], v[140:141] op_sel_hi:[1,0,1]
	v_pk_fma_f32 v[142:143], v[6:7], s[0:1], v[142:143] op_sel_hi:[1,0,1]
	v_pk_fma_f32 v[128:129], v[8:9], s[0:1], v[128:129] op_sel_hi:[1,0,1]
	v_pk_fma_f32 v[132:133], v[10:11], s[0:1], v[132:133] op_sel_hi:[1,0,1]
	v_pk_fma_f32 v[134:135], v[12:13], s[0:1], v[134:135] op_sel_hi:[1,0,1]
	v_pk_fma_f32 v[136:137], v[14:15], s[0:1], v[136:137] op_sel_hi:[1,0,1]
	v_readlane_b32 s0, v167, 22
	s_waitcnt vmcnt(15)
	v_cvt_scalef32_pk_f32_fp4 v[0:1], v156, 1.0
	v_cvt_scalef32_pk_f32_fp4 v[2:3], v156, 1.0 op_sel:[1,0,0]
	v_cvt_scalef32_pk_f32_fp4 v[4:5], v156, 1.0 op_sel:[0,1,0]
	v_cvt_scalef32_pk_f32_fp4 v[6:7], v156, 1.0 op_sel:[1,1,0]
	v_cvt_scalef32_pk_f32_fp4 v[8:9], v157, 1.0
	v_cvt_scalef32_pk_f32_fp4 v[10:11], v157, 1.0 op_sel:[1,0,0]
	v_cvt_scalef32_pk_f32_fp4 v[12:13], v157, 1.0 op_sel:[0,1,0]
	v_cvt_scalef32_pk_f32_fp4 v[14:15], v157, 1.0 op_sel:[1,1,0]
	v_readlane_b32 s54, v92, 38
	s_lshl_b32 s56, s54, 9
	s_add_u32 s56, s64, s56
	s_addc_u32 s57, s65, 0
	global_load_dwordx2 v[156:157], v227, s[56:57]
	v_pk_fma_f32 v[130:131], v[0:1], s[0:1], v[130:131] op_sel_hi:[1,0,1]
	v_pk_fma_f32 v[138:139], v[2:3], s[0:1], v[138:139] op_sel_hi:[1,0,1]
	v_pk_fma_f32 v[140:141], v[4:5], s[0:1], v[140:141] op_sel_hi:[1,0,1]
	v_pk_fma_f32 v[142:143], v[6:7], s[0:1], v[142:143] op_sel_hi:[1,0,1]
	v_pk_fma_f32 v[128:129], v[8:9], s[0:1], v[128:129] op_sel_hi:[1,0,1]
	v_pk_fma_f32 v[132:133], v[10:11], s[0:1], v[132:133] op_sel_hi:[1,0,1]
	v_pk_fma_f32 v[134:135], v[12:13], s[0:1], v[134:135] op_sel_hi:[1,0,1]
	v_pk_fma_f32 v[136:137], v[14:15], s[0:1], v[136:137] op_sel_hi:[1,0,1]
	v_readlane_b32 s0, v167, 23
	s_waitcnt vmcnt(15)
	v_cvt_scalef32_pk_f32_fp4 v[0:1], v158, 1.0
	v_cvt_scalef32_pk_f32_fp4 v[2:3], v158, 1.0 op_sel:[1,0,0]
	v_cvt_scalef32_pk_f32_fp4 v[4:5], v158, 1.0 op_sel:[0,1,0]
	v_cvt_scalef32_pk_f32_fp4 v[6:7], v158, 1.0 op_sel:[1,1,0]
	v_cvt_scalef32_pk_f32_fp4 v[8:9], v159, 1.0
	v_cvt_scalef32_pk_f32_fp4 v[10:11], v159, 1.0 op_sel:[1,0,0]
	v_cvt_scalef32_pk_f32_fp4 v[12:13], v159, 1.0 op_sel:[0,1,0]
	v_cvt_scalef32_pk_f32_fp4 v[14:15], v159, 1.0 op_sel:[1,1,0]
	v_readlane_b32 s54, v92, 39
	s_lshl_b32 s56, s54, 9
	s_add_u32 s56, s64, s56
	s_addc_u32 s57, s65, 0
	global_load_dwordx2 v[158:159], v227, s[56:57]
	v_pk_fma_f32 v[130:131], v[0:1], s[0:1], v[130:131] op_sel_hi:[1,0,1]
	v_pk_fma_f32 v[138:139], v[2:3], s[0:1], v[138:139] op_sel_hi:[1,0,1]
	v_pk_fma_f32 v[140:141], v[4:5], s[0:1], v[140:141] op_sel_hi:[1,0,1]
	v_pk_fma_f32 v[142:143], v[6:7], s[0:1], v[142:143] op_sel_hi:[1,0,1]
	v_pk_fma_f32 v[128:129], v[8:9], s[0:1], v[128:129] op_sel_hi:[1,0,1]
	v_pk_fma_f32 v[132:133], v[10:11], s[0:1], v[132:133] op_sel_hi:[1,0,1]
	v_pk_fma_f32 v[134:135], v[12:13], s[0:1], v[134:135] op_sel_hi:[1,0,1]
	v_pk_fma_f32 v[136:137], v[14:15], s[0:1], v[136:137] op_sel_hi:[1,0,1]
	v_readlane_b32 s0, v167, 24
	s_waitcnt vmcnt(15)
	v_cvt_scalef32_pk_f32_fp4 v[0:1], v168, 1.0
	v_cvt_scalef32_pk_f32_fp4 v[2:3], v168, 1.0 op_sel:[1,0,0]
	v_cvt_scalef32_pk_f32_fp4 v[4:5], v168, 1.0 op_sel:[0,1,0]
	v_cvt_scalef32_pk_f32_fp4 v[6:7], v168, 1.0 op_sel:[1,1,0]
	v_cvt_scalef32_pk_f32_fp4 v[8:9], v169, 1.0
	v_cvt_scalef32_pk_f32_fp4 v[10:11], v169, 1.0 op_sel:[1,0,0]
	v_cvt_scalef32_pk_f32_fp4 v[12:13], v169, 1.0 op_sel:[0,1,0]
	v_cvt_scalef32_pk_f32_fp4 v[14:15], v169, 1.0 op_sel:[1,1,0]
	v_readlane_b32 s54, v92, 40
	s_lshl_b32 s56, s54, 9
	s_add_u32 s56, s64, s56
	s_addc_u32 s57, s65, 0
	global_load_dwordx2 v[168:169], v227, s[56:57]
	v_pk_fma_f32 v[130:131], v[0:1], s[0:1], v[130:131] op_sel_hi:[1,0,1]
	v_pk_fma_f32 v[138:139], v[2:3], s[0:1], v[138:139] op_sel_hi:[1,0,1]
	v_pk_fma_f32 v[140:141], v[4:5], s[0:1], v[140:141] op_sel_hi:[1,0,1]
	v_pk_fma_f32 v[142:143], v[6:7], s[0:1], v[142:143] op_sel_hi:[1,0,1]
	v_pk_fma_f32 v[128:129], v[8:9], s[0:1], v[128:129] op_sel_hi:[1,0,1]
	v_pk_fma_f32 v[132:133], v[10:11], s[0:1], v[132:133] op_sel_hi:[1,0,1]
	v_pk_fma_f32 v[134:135], v[12:13], s[0:1], v[134:135] op_sel_hi:[1,0,1]
	v_pk_fma_f32 v[136:137], v[14:15], s[0:1], v[136:137] op_sel_hi:[1,0,1]
	v_readlane_b32 s0, v167, 25
	s_waitcnt vmcnt(15)
; __device__ void peer_gather_phase(const Params& P, int l, bool do_store) {
;     ...
;         v8[2 * pr] = *(const uint2*)(V + (size_t)ea * 512);
;         v8[2 * pr + 1] = *(const uint2*)(V + (size_t)eb * 512);
;     ...
; #pragma unroll
;       for (int j = 0; j < 8; ++j) {
;         const float a = __builtin_bit_cast(float, __builtin_amdgcn_readlane(__builtin_bit_cast(int, avec), kb + j));
;         const f32x2 aa = f32x2{a, a};
;         y[0] += aa * __builtin_amdgcn_cvt_scalef32_pk_f32_fp4(v8[j].x, 1.0f, 0); y[1] += aa * __builtin_amdgcn_cvt_scalef32_pk_f32_fp4(v8[j].x, 1.0f, 1);
;         y[2] += aa * __builtin_amdgcn_cvt_scalef32_pk_f32_fp4(v8[j].x, 1.0f, 2); y[3] += aa * __builtin_amdgcn_cvt_scalef32_pk_f32_fp4(v8[j].x, 1.0f, 3);
;         y[4] += aa * __builtin_amdgcn_cvt_scalef32_pk_f32_fp4(v8[j].y, 1.0f, 0); y[5] += aa * __builtin_amdgcn_cvt_scalef32_pk_f32_fp4(v8[j].y, 1.0f, 1);
;         y[6] += aa * __builtin_amdgcn_cvt_scalef32_pk_f32_fp4(v8[j].y, 1.0f, 2); y[7] += aa * __builtin_amdgcn_cvt_scalef32_pk_f32_fp4(v8[j].y, 1.0f, 3);
;       }
	v_cvt_scalef32_pk_f32_fp4 v[0:1], v170, 1.0
	v_cvt_scalef32_pk_f32_fp4 v[2:3], v170, 1.0 op_sel:[1,0,0]
	v_cvt_scalef32_pk_f32_fp4 v[4:5], v170, 1.0 op_sel:[0,1,0]
	v_cvt_scalef32_pk_f32_fp4 v[6:7], v170, 1.0 op_sel:[1,1,0]
	v_cvt_scalef32_pk_f32_fp4 v[8:9], v171, 1.0
	v_cvt_scalef32_pk_f32_fp4 v[10:11], v171, 1.0 op_sel:[1,0,0]
	v_cvt_scalef32_pk_f32_fp4 v[12:13], v171, 1.0 op_sel:[0,1,0]
	v_cvt_scalef32_pk_f32_fp4 v[14:15], v171, 1.0 op_sel:[1,1,0]
	v_readlane_b32 s54, v92, 41
	s_lshl_b32 s56, s54, 9
	s_add_u32 s56, s64, s56
	s_addc_u32 s57, s65, 0
	global_load_dwordx2 v[170:171], v227, s[56:57]
	v_pk_fma_f32 v[130:131], v[0:1], s[0:1], v[130:131] op_sel_hi:[1,0,1]
	v_pk_fma_f32 v[138:139], v[2:3], s[0:1], v[138:139] op_sel_hi:[1,0,1]
	v_pk_fma_f32 v[140:141], v[4:5], s[0:1], v[140:141] op_sel_hi:[1,0,1]
	v_pk_fma_f32 v[142:143], v[6:7], s[0:1], v[142:143] op_sel_hi:[1,0,1]
	v_pk_fma_f32 v[128:129], v[8:9], s[0:1], v[128:129] op_sel_hi:[1,0,1]
	v_pk_fma_f32 v[132:133], v[10:11], s[0:1], v[132:133] op_sel_hi:[1,0,1]
	v_pk_fma_f32 v[134:135], v[12:13], s[0:1], v[134:135] op_sel_hi:[1,0,1]
	v_pk_fma_f32 v[136:137], v[14:15], s[0:1], v[136:137] op_sel_hi:[1,0,1]
	v_readlane_b32 s0, v167, 26
	s_waitcnt vmcnt(15)
	v_cvt_scalef32_pk_f32_fp4 v[0:1], v172, 1.0
	v_cvt_scalef32_pk_f32_fp4 v[2:3], v172, 1.0 op_sel:[1,0,0]
	v_cvt_scalef32_pk_f32_fp4 v[4:5], v172, 1.0 op_sel:[0,1,0]
	v_cvt_scalef32_pk_f32_fp4 v[6:7], v172, 1.0 op_sel:[1,1,0]
	v_cvt_scalef32_pk_f32_fp4 v[8:9], v173, 1.0
	v_cvt_scalef32_pk_f32_fp4 v[10:11], v173, 1.0 op_sel:[1,0,0]
	v_cvt_scalef32_pk_f32_fp4 v[12:13], v173, 1.0 op_sel:[0,1,0]
	v_cvt_scalef32_pk_f32_fp4 v[14:15], v173, 1.0 op_sel:[1,1,0]
	v_readlane_b32 s54, v92, 42
	s_lshl_b32 s56, s54, 9
	s_add_u32 s56, s64, s56
	s_addc_u32 s57, s65, 0
	global_load_dwordx2 v[172:173], v227, s[56:57]
	v_pk_fma_f32 v[130:131], v[0:1], s[0:1], v[130:131] op_sel_hi:[1,0,1]
	v_pk_fma_f32 v[138:139], v[2:3], s[0:1], v[138:139] op_sel_hi:[1,0,1]
	v_pk_fma_f32 v[140:141], v[4:5], s[0:1], v[140:141] op_sel_hi:[1,0,1]
	v_pk_fma_f32 v[142:143], v[6:7], s[0:1], v[142:143] op_sel_hi:[1,0,1]
	v_pk_fma_f32 v[128:129], v[8:9], s[0:1], v[128:129] op_sel_hi:[1,0,1]
	v_pk_fma_f32 v[132:133], v[10:11], s[0:1], v[132:133] op_sel_hi:[1,0,1]
	v_pk_fma_f32 v[134:135], v[12:13], s[0:1], v[134:135] op_sel_hi:[1,0,1]
	v_pk_fma_f32 v[136:137], v[14:15], s[0:1], v[136:137] op_sel_hi:[1,0,1]
	v_readlane_b32 s0, v167, 27
	s_waitcnt vmcnt(15)
	v_cvt_scalef32_pk_f32_fp4 v[0:1], v174, 1.0
	v_cvt_scalef32_pk_f32_fp4 v[2:3], v174, 1.0 op_sel:[1,0,0]
	v_cvt_scalef32_pk_f32_fp4 v[4:5], v174, 1.0 op_sel:[0,1,0]
	v_cvt_scalef32_pk_f32_fp4 v[6:7], v174, 1.0 op_sel:[1,1,0]
	v_cvt_scalef32_pk_f32_fp4 v[8:9], v175, 1.0
	v_cvt_scalef32_pk_f32_fp4 v[10:11], v175, 1.0 op_sel:[1,0,0]
	v_cvt_scalef32_pk_f32_fp4 v[12:13], v175, 1.0 op_sel:[0,1,0]
	v_cvt_scalef32_pk_f32_fp4 v[14:15], v175, 1.0 op_sel:[1,1,0]
	v_readlane_b32 s54, v92, 43
	s_lshl_b32 s56, s54, 9
	s_add_u32 s56, s64, s56
	s_addc_u32 s57, s65, 0
	global_load_dwordx2 v[174:175], v227, s[56:57]
	v_pk_fma_f32 v[130:131], v[0:1], s[0:1], v[130:131] op_sel_hi:[1,0,1]
	v_pk_fma_f32 v[138:139], v[2:3], s[0:1], v[138:139] op_sel_hi:[1,0,1]
	v_pk_fma_f32 v[140:141], v[4:5], s[0:1], v[140:141] op_sel_hi:[1,0,1]
	v_pk_fma_f32 v[142:143], v[6:7], s[0:1], v[142:143] op_sel_hi:[1,0,1]
	v_pk_fma_f32 v[128:129], v[8:9], s[0:1], v[128:129] op_sel_hi:[1,0,1]
	v_pk_fma_f32 v[132:133], v[10:11], s[0:1], v[132:133] op_sel_hi:[1,0,1]
	v_pk_fma_f32 v[134:135], v[12:13], s[0:1], v[134:135] op_sel_hi:[1,0,1]
	v_pk_fma_f32 v[136:137], v[14:15], s[0:1], v[136:137] op_sel_hi:[1,0,1]
	v_readlane_b32 s0, v167, 28
	s_waitcnt vmcnt(15)
	v_cvt_scalef32_pk_f32_fp4 v[0:1], v180, 1.0
	v_cvt_scalef32_pk_f32_fp4 v[2:3], v180, 1.0 op_sel:[1,0,0]
	v_cvt_scalef32_pk_f32_fp4 v[4:5], v180, 1.0 op_sel:[0,1,0]
	v_cvt_scalef32_pk_f32_fp4 v[6:7], v180, 1.0 op_sel:[1,1,0]
	v_cvt_scalef32_pk_f32_fp4 v[8:9], v181, 1.0
	v_cvt_scalef32_pk_f32_fp4 v[10:11], v181, 1.0 op_sel:[1,0,0]
	v_cvt_scalef32_pk_f32_fp4 v[12:13], v181, 1.0 op_sel:[0,1,0]
	v_cvt_scalef32_pk_f32_fp4 v[14:15], v181, 1.0 op_sel:[1,1,0]
	v_readlane_b32 s54, v92, 44
	s_lshl_b32 s56, s54, 9
	s_add_u32 s56, s64, s56
	s_addc_u32 s57, s65, 0
	global_load_dwordx2 v[180:181], v227, s[56:57]
	v_pk_fma_f32 v[130:131], v[0:1], s[0:1], v[130:131] op_sel_hi:[1,0,1]
	v_pk_fma_f32 v[138:139], v[2:3], s[0:1], v[138:139] op_sel_hi:[1,0,1]
	v_pk_fma_f32 v[140:141], v[4:5], s[0:1], v[140:141] op_sel_hi:[1,0,1]
	v_pk_fma_f32 v[142:143], v[6:7], s[0:1], v[142:143] op_sel_hi:[1,0,1]
	v_pk_fma_f32 v[128:129], v[8:9], s[0:1], v[128:129] op_sel_hi:[1,0,1]
	v_pk_fma_f32 v[132:133], v[10:11], s[0:1], v[132:133] op_sel_hi:[1,0,1]
	v_pk_fma_f32 v[134:135], v[12:13], s[0:1], v[134:135] op_sel_hi:[1,0,1]
	v_pk_fma_f32 v[136:137], v[14:15], s[0:1], v[136:137] op_sel_hi:[1,0,1]
	v_readlane_b32 s0, v167, 29
	s_waitcnt vmcnt(15)
	v_cvt_scalef32_pk_f32_fp4 v[0:1], v182, 1.0
	v_cvt_scalef32_pk_f32_fp4 v[2:3], v182, 1.0 op_sel:[1,0,0]
	v_cvt_scalef32_pk_f32_fp4 v[4:5], v182, 1.0 op_sel:[0,1,0]
	v_cvt_scalef32_pk_f32_fp4 v[6:7], v182, 1.0 op_sel:[1,1,0]
	v_cvt_scalef32_pk_f32_fp4 v[8:9], v183, 1.0
	v_cvt_scalef32_pk_f32_fp4 v[10:11], v183, 1.0 op_sel:[1,0,0]
	v_cvt_scalef32_pk_f32_fp4 v[12:13], v183, 1.0 op_sel:[0,1,0]
	v_cvt_scalef32_pk_f32_fp4 v[14:15], v183, 1.0 op_sel:[1,1,0]
	v_readlane_b32 s54, v92, 45
	s_lshl_b32 s56, s54, 9
	s_add_u32 s56, s64, s56
	s_addc_u32 s57, s65, 0
	global_load_dwordx2 v[182:183], v227, s[56:57]
	v_pk_fma_f32 v[130:131], v[0:1], s[0:1], v[130:131] op_sel_hi:[1,0,1]
	v_pk_fma_f32 v[138:139], v[2:3], s[0:1], v[138:139] op_sel_hi:[1,0,1]
	v_pk_fma_f32 v[140:141], v[4:5], s[0:1], v[140:141] op_sel_hi:[1,0,1]
	v_pk_fma_f32 v[142:143], v[6:7], s[0:1], v[142:143] op_sel_hi:[1,0,1]
	v_pk_fma_f32 v[128:129], v[8:9], s[0:1], v[128:129] op_sel_hi:[1,0,1]
	v_pk_fma_f32 v[132:133], v[10:11], s[0:1], v[132:133] op_sel_hi:[1,0,1]
	v_pk_fma_f32 v[134:135], v[12:13], s[0:1], v[134:135] op_sel_hi:[1,0,1]
	v_pk_fma_f32 v[136:137], v[14:15], s[0:1], v[136:137] op_sel_hi:[1,0,1]
	v_readlane_b32 s0, v167, 30
	s_waitcnt vmcnt(15)
; __device__ void peer_gather_phase(const Params& P, int l, bool do_store) {
;     ...
;         v8[2 * pr] = *(const uint2*)(V + (size_t)ea * 512);
;         v8[2 * pr + 1] = *(const uint2*)(V + (size_t)eb * 512);
;     ...
; #pragma unroll
;       for (int j = 0; j < 8; ++j) {
;         const float a = __builtin_bit_cast(float, __builtin_amdgcn_readlane(__builtin_bit_cast(int, avec), kb + j));
;         const f32x2 aa = f32x2{a, a};
;         y[0] += aa * __builtin_amdgcn_cvt_scalef32_pk_f32_fp4(v8[j].x, 1.0f, 0); y[1] += aa * __builtin_amdgcn_cvt_scalef32_pk_f32_fp4(v8[j].x, 1.0f, 1);
;         y[2] += aa * __builtin_amdgcn_cvt_scalef32_pk_f32_fp4(v8[j].x, 1.0f, 2); y[3] += aa * __builtin_amdgcn_cvt_scalef32_pk_f32_fp4(v8[j].x, 1.0f, 3);
;         y[4] += aa * __builtin_amdgcn_cvt_scalef32_pk_f32_fp4(v8[j].y, 1.0f, 0); y[5] += aa * __builtin_amdgcn_cvt_scalef32_pk_f32_fp4(v8[j].y, 1.0f, 1);
;         y[6] += aa * __builtin_amdgcn_cvt_scalef32_pk_f32_fp4(v8[j].y, 1.0f, 2); y[7] += aa * __builtin_amdgcn_cvt_scalef32_pk_f32_fp4(v8[j].y, 1.0f, 3);
;       }
	v_cvt_scalef32_pk_f32_fp4 v[0:1], v184, 1.0
	v_cvt_scalef32_pk_f32_fp4 v[2:3], v184, 1.0 op_sel:[1,0,0]
	v_cvt_scalef32_pk_f32_fp4 v[4:5], v184, 1.0 op_sel:[0,1,0]
	v_cvt_scalef32_pk_f32_fp4 v[6:7], v184, 1.0 op_sel:[1,1,0]
	v_cvt_scalef32_pk_f32_fp4 v[8:9], v185, 1.0
	v_cvt_scalef32_pk_f32_fp4 v[10:11], v185, 1.0 op_sel:[1,0,0]
	v_cvt_scalef32_pk_f32_fp4 v[12:13], v185, 1.0 op_sel:[0,1,0]
	v_cvt_scalef32_pk_f32_fp4 v[14:15], v185, 1.0 op_sel:[1,1,0]
	v_readlane_b32 s54, v92, 46
	s_lshl_b32 s56, s54, 9
	s_add_u32 s56, s64, s56
	s_addc_u32 s57, s65, 0
	global_load_dwordx2 v[184:185], v227, s[56:57]
	v_pk_fma_f32 v[130:131], v[0:1], s[0:1], v[130:131] op_sel_hi:[1,0,1]
	v_pk_fma_f32 v[138:139], v[2:3], s[0:1], v[138:139] op_sel_hi:[1,0,1]
	v_pk_fma_f32 v[140:141], v[4:5], s[0:1], v[140:141] op_sel_hi:[1,0,1]
	v_pk_fma_f32 v[142:143], v[6:7], s[0:1], v[142:143] op_sel_hi:[1,0,1]
	v_pk_fma_f32 v[128:129], v[8:9], s[0:1], v[128:129] op_sel_hi:[1,0,1]
	v_pk_fma_f32 v[132:133], v[10:11], s[0:1], v[132:133] op_sel_hi:[1,0,1]
	v_pk_fma_f32 v[134:135], v[12:13], s[0:1], v[134:135] op_sel_hi:[1,0,1]
	v_pk_fma_f32 v[136:137], v[14:15], s[0:1], v[136:137] op_sel_hi:[1,0,1]
	v_readlane_b32 s0, v167, 31
	s_waitcnt vmcnt(15)
	v_cvt_scalef32_pk_f32_fp4 v[0:1], v186, 1.0
	v_cvt_scalef32_pk_f32_fp4 v[2:3], v186, 1.0 op_sel:[1,0,0]
	v_cvt_scalef32_pk_f32_fp4 v[4:5], v186, 1.0 op_sel:[0,1,0]
	v_cvt_scalef32_pk_f32_fp4 v[6:7], v186, 1.0 op_sel:[1,1,0]
	v_cvt_scalef32_pk_f32_fp4 v[8:9], v187, 1.0
	v_cvt_scalef32_pk_f32_fp4 v[10:11], v187, 1.0 op_sel:[1,0,0]
	v_cvt_scalef32_pk_f32_fp4 v[12:13], v187, 1.0 op_sel:[0,1,0]
	v_cvt_scalef32_pk_f32_fp4 v[14:15], v187, 1.0 op_sel:[1,1,0]
	v_readlane_b32 s54, v92, 47
	s_lshl_b32 s56, s54, 9
	s_add_u32 s56, s64, s56
	s_addc_u32 s57, s65, 0
	global_load_dwordx2 v[186:187], v227, s[56:57]
	v_pk_fma_f32 v[130:131], v[0:1], s[0:1], v[130:131] op_sel_hi:[1,0,1]
	v_pk_fma_f32 v[138:139], v[2:3], s[0:1], v[138:139] op_sel_hi:[1,0,1]
	v_pk_fma_f32 v[140:141], v[4:5], s[0:1], v[140:141] op_sel_hi:[1,0,1]
	v_pk_fma_f32 v[142:143], v[6:7], s[0:1], v[142:143] op_sel_hi:[1,0,1]
	v_pk_fma_f32 v[128:129], v[8:9], s[0:1], v[128:129] op_sel_hi:[1,0,1]
	v_pk_fma_f32 v[132:133], v[10:11], s[0:1], v[132:133] op_sel_hi:[1,0,1]
	v_pk_fma_f32 v[134:135], v[12:13], s[0:1], v[134:135] op_sel_hi:[1,0,1]
	v_pk_fma_f32 v[136:137], v[14:15], s[0:1], v[136:137] op_sel_hi:[1,0,1]
	v_readlane_b32 s0, v167, 32
	s_waitcnt vmcnt(15)
	v_cvt_scalef32_pk_f32_fp4 v[0:1], v144, 1.0
	v_cvt_scalef32_pk_f32_fp4 v[2:3], v144, 1.0 op_sel:[1,0,0]
	v_cvt_scalef32_pk_f32_fp4 v[4:5], v144, 1.0 op_sel:[0,1,0]
	v_cvt_scalef32_pk_f32_fp4 v[6:7], v144, 1.0 op_sel:[1,1,0]
	v_cvt_scalef32_pk_f32_fp4 v[8:9], v145, 1.0
	v_cvt_scalef32_pk_f32_fp4 v[10:11], v145, 1.0 op_sel:[1,0,0]
	v_cvt_scalef32_pk_f32_fp4 v[12:13], v145, 1.0 op_sel:[0,1,0]
	v_cvt_scalef32_pk_f32_fp4 v[14:15], v145, 1.0 op_sel:[1,1,0]
	v_readlane_b32 s54, v92, 48
	s_lshl_b32 s56, s54, 9
	s_add_u32 s56, s64, s56
	s_addc_u32 s57, s65, 0
	global_load_dwordx2 v[144:145], v227, s[56:57]
	v_pk_fma_f32 v[130:131], v[0:1], s[0:1], v[130:131] op_sel_hi:[1,0,1]
	v_pk_fma_f32 v[138:139], v[2:3], s[0:1], v[138:139] op_sel_hi:[1,0,1]
	v_pk_fma_f32 v[140:141], v[4:5], s[0:1], v[140:141] op_sel_hi:[1,0,1]
	v_pk_fma_f32 v[142:143], v[6:7], s[0:1], v[142:143] op_sel_hi:[1,0,1]
	v_pk_fma_f32 v[128:129], v[8:9], s[0:1], v[128:129] op_sel_hi:[1,0,1]
	v_pk_fma_f32 v[132:133], v[10:11], s[0:1], v[132:133] op_sel_hi:[1,0,1]
	v_pk_fma_f32 v[134:135], v[12:13], s[0:1], v[134:135] op_sel_hi:[1,0,1]
	v_pk_fma_f32 v[136:137], v[14:15], s[0:1], v[136:137] op_sel_hi:[1,0,1]
	v_readlane_b32 s0, v167, 33
	s_waitcnt vmcnt(15)
	v_cvt_scalef32_pk_f32_fp4 v[0:1], v146, 1.0
	v_cvt_scalef32_pk_f32_fp4 v[2:3], v146, 1.0 op_sel:[1,0,0]
	v_cvt_scalef32_pk_f32_fp4 v[4:5], v146, 1.0 op_sel:[0,1,0]
	v_cvt_scalef32_pk_f32_fp4 v[6:7], v146, 1.0 op_sel:[1,1,0]
	v_cvt_scalef32_pk_f32_fp4 v[8:9], v147, 1.0
	v_cvt_scalef32_pk_f32_fp4 v[10:11], v147, 1.0 op_sel:[1,0,0]
	v_cvt_scalef32_pk_f32_fp4 v[12:13], v147, 1.0 op_sel:[0,1,0]
	v_cvt_scalef32_pk_f32_fp4 v[14:15], v147, 1.0 op_sel:[1,1,0]
	v_readlane_b32 s54, v92, 49
	s_lshl_b32 s56, s54, 9
	s_add_u32 s56, s64, s56
	s_addc_u32 s57, s65, 0
	global_load_dwordx2 v[146:147], v227, s[56:57]
	v_pk_fma_f32 v[130:131], v[0:1], s[0:1], v[130:131] op_sel_hi:[1,0,1]
	v_pk_fma_f32 v[138:139], v[2:3], s[0:1], v[138:139] op_sel_hi:[1,0,1]
	v_pk_fma_f32 v[140:141], v[4:5], s[0:1], v[140:141] op_sel_hi:[1,0,1]
	v_pk_fma_f32 v[142:143], v[6:7], s[0:1], v[142:143] op_sel_hi:[1,0,1]
	v_pk_fma_f32 v[128:129], v[8:9], s[0:1], v[128:129] op_sel_hi:[1,0,1]
	v_pk_fma_f32 v[132:133], v[10:11], s[0:1], v[132:133] op_sel_hi:[1,0,1]
	v_pk_fma_f32 v[134:135], v[12:13], s[0:1], v[134:135] op_sel_hi:[1,0,1]
	v_pk_fma_f32 v[136:137], v[14:15], s[0:1], v[136:137] op_sel_hi:[1,0,1]
	v_readlane_b32 s0, v167, 34
	s_waitcnt vmcnt(15)
	v_cvt_scalef32_pk_f32_fp4 v[0:1], v148, 1.0
	v_cvt_scalef32_pk_f32_fp4 v[2:3], v148, 1.0 op_sel:[1,0,0]
	v_cvt_scalef32_pk_f32_fp4 v[4:5], v148, 1.0 op_sel:[0,1,0]
	v_cvt_scalef32_pk_f32_fp4 v[6:7], v148, 1.0 op_sel:[1,1,0]
	v_cvt_scalef32_pk_f32_fp4 v[8:9], v149, 1.0
	v_cvt_scalef32_pk_f32_fp4 v[10:11], v149, 1.0 op_sel:[1,0,0]
	v_cvt_scalef32_pk_f32_fp4 v[12:13], v149, 1.0 op_sel:[0,1,0]
	v_cvt_scalef32_pk_f32_fp4 v[14:15], v149, 1.0 op_sel:[1,1,0]
	v_readlane_b32 s54, v92, 50
	s_lshl_b32 s56, s54, 9
	s_add_u32 s56, s64, s56
	s_addc_u32 s57, s65, 0
	global_load_dwordx2 v[148:149], v227, s[56:57]
	v_pk_fma_f32 v[130:131], v[0:1], s[0:1], v[130:131] op_sel_hi:[1,0,1]
	v_pk_fma_f32 v[138:139], v[2:3], s[0:1], v[138:139] op_sel_hi:[1,0,1]
	v_pk_fma_f32 v[140:141], v[4:5], s[0:1], v[140:141] op_sel_hi:[1,0,1]
	v_pk_fma_f32 v[142:143], v[6:7], s[0:1], v[142:143] op_sel_hi:[1,0,1]
	v_pk_fma_f32 v[128:129], v[8:9], s[0:1], v[128:129] op_sel_hi:[1,0,1]
	v_pk_fma_f32 v[132:133], v[10:11], s[0:1], v[132:133] op_sel_hi:[1,0,1]
	v_pk_fma_f32 v[134:135], v[12:13], s[0:1], v[134:135] op_sel_hi:[1,0,1]
	v_pk_fma_f32 v[136:137], v[14:15], s[0:1], v[136:137] op_sel_hi:[1,0,1]
	v_readlane_b32 s0, v167, 35
	s_waitcnt vmcnt(15)
; __device__ void peer_gather_phase(const Params& P, int l, bool do_store) {
;     ...
;         v8[2 * pr] = *(const uint2*)(V + (size_t)ea * 512);
;         v8[2 * pr + 1] = *(const uint2*)(V + (size_t)eb * 512);
;     ...
; #pragma unroll
;       for (int j = 0; j < 8; ++j) {
;         const float a = __builtin_bit_cast(float, __builtin_amdgcn_readlane(__builtin_bit_cast(int, avec), kb + j));
;         const f32x2 aa = f32x2{a, a};
;         y[0] += aa * __builtin_amdgcn_cvt_scalef32_pk_f32_fp4(v8[j].x, 1.0f, 0); y[1] += aa * __builtin_amdgcn_cvt_scalef32_pk_f32_fp4(v8[j].x, 1.0f, 1);
;         y[2] += aa * __builtin_amdgcn_cvt_scalef32_pk_f32_fp4(v8[j].x, 1.0f, 2); y[3] += aa * __builtin_amdgcn_cvt_scalef32_pk_f32_fp4(v8[j].x, 1.0f, 3);
;         y[4] += aa * __builtin_amdgcn_cvt_scalef32_pk_f32_fp4(v8[j].y, 1.0f, 0); y[5] += aa * __builtin_amdgcn_cvt_scalef32_pk_f32_fp4(v8[j].y, 1.0f, 1);
;         y[6] += aa * __builtin_amdgcn_cvt_scalef32_pk_f32_fp4(v8[j].y, 1.0f, 2); y[7] += aa * __builtin_amdgcn_cvt_scalef32_pk_f32_fp4(v8[j].y, 1.0f, 3);
;       }
	v_cvt_scalef32_pk_f32_fp4 v[0:1], v150, 1.0
	v_cvt_scalef32_pk_f32_fp4 v[2:3], v150, 1.0 op_sel:[1,0,0]
	v_cvt_scalef32_pk_f32_fp4 v[4:5], v150, 1.0 op_sel:[0,1,0]
	v_cvt_scalef32_pk_f32_fp4 v[6:7], v150, 1.0 op_sel:[1,1,0]
	v_cvt_scalef32_pk_f32_fp4 v[8:9], v151, 1.0
	v_cvt_scalef32_pk_f32_fp4 v[10:11], v151, 1.0 op_sel:[1,0,0]
	v_cvt_scalef32_pk_f32_fp4 v[12:13], v151, 1.0 op_sel:[0,1,0]
	v_cvt_scalef32_pk_f32_fp4 v[14:15], v151, 1.0 op_sel:[1,1,0]
	v_readlane_b32 s54, v92, 51
	s_lshl_b32 s56, s54, 9
	s_add_u32 s56, s64, s56
	s_addc_u32 s57, s65, 0
	global_load_dwordx2 v[150:151], v227, s[56:57]
	v_pk_fma_f32 v[130:131], v[0:1], s[0:1], v[130:131] op_sel_hi:[1,0,1]
	v_pk_fma_f32 v[138:139], v[2:3], s[0:1], v[138:139] op_sel_hi:[1,0,1]
	v_pk_fma_f32 v[140:141], v[4:5], s[0:1], v[140:141] op_sel_hi:[1,0,1]
	v_pk_fma_f32 v[142:143], v[6:7], s[0:1], v[142:143] op_sel_hi:[1,0,1]
	v_pk_fma_f32 v[128:129], v[8:9], s[0:1], v[128:129] op_sel_hi:[1,0,1]
	v_pk_fma_f32 v[132:133], v[10:11], s[0:1], v[132:133] op_sel_hi:[1,0,1]
	v_pk_fma_f32 v[134:135], v[12:13], s[0:1], v[134:135] op_sel_hi:[1,0,1]
	v_pk_fma_f32 v[136:137], v[14:15], s[0:1], v[136:137] op_sel_hi:[1,0,1]
	v_readlane_b32 s0, v167, 36
	s_waitcnt vmcnt(15)
	v_cvt_scalef32_pk_f32_fp4 v[0:1], v152, 1.0
	v_cvt_scalef32_pk_f32_fp4 v[2:3], v152, 1.0 op_sel:[1,0,0]
	v_cvt_scalef32_pk_f32_fp4 v[4:5], v152, 1.0 op_sel:[0,1,0]
	v_cvt_scalef32_pk_f32_fp4 v[6:7], v152, 1.0 op_sel:[1,1,0]
	v_cvt_scalef32_pk_f32_fp4 v[8:9], v153, 1.0
	v_cvt_scalef32_pk_f32_fp4 v[10:11], v153, 1.0 op_sel:[1,0,0]
	v_cvt_scalef32_pk_f32_fp4 v[12:13], v153, 1.0 op_sel:[0,1,0]
	v_cvt_scalef32_pk_f32_fp4 v[14:15], v153, 1.0 op_sel:[1,1,0]
	v_readlane_b32 s54, v92, 52
	s_lshl_b32 s56, s54, 9
	s_add_u32 s56, s64, s56
	s_addc_u32 s57, s65, 0
	global_load_dwordx2 v[152:153], v227, s[56:57]
	v_pk_fma_f32 v[130:131], v[0:1], s[0:1], v[130:131] op_sel_hi:[1,0,1]
	v_pk_fma_f32 v[138:139], v[2:3], s[0:1], v[138:139] op_sel_hi:[1,0,1]
	v_pk_fma_f32 v[140:141], v[4:5], s[0:1], v[140:141] op_sel_hi:[1,0,1]
	v_pk_fma_f32 v[142:143], v[6:7], s[0:1], v[142:143] op_sel_hi:[1,0,1]
	v_pk_fma_f32 v[128:129], v[8:9], s[0:1], v[128:129] op_sel_hi:[1,0,1]
	v_pk_fma_f32 v[132:133], v[10:11], s[0:1], v[132:133] op_sel_hi:[1,0,1]
	v_pk_fma_f32 v[134:135], v[12:13], s[0:1], v[134:135] op_sel_hi:[1,0,1]
	v_pk_fma_f32 v[136:137], v[14:15], s[0:1], v[136:137] op_sel_hi:[1,0,1]
	v_readlane_b32 s0, v167, 37
	s_waitcnt vmcnt(15)
	v_cvt_scalef32_pk_f32_fp4 v[0:1], v154, 1.0
	v_cvt_scalef32_pk_f32_fp4 v[2:3], v154, 1.0 op_sel:[1,0,0]
	v_cvt_scalef32_pk_f32_fp4 v[4:5], v154, 1.0 op_sel:[0,1,0]
	v_cvt_scalef32_pk_f32_fp4 v[6:7], v154, 1.0 op_sel:[1,1,0]
	v_cvt_scalef32_pk_f32_fp4 v[8:9], v155, 1.0
	v_cvt_scalef32_pk_f32_fp4 v[10:11], v155, 1.0 op_sel:[1,0,0]
	v_cvt_scalef32_pk_f32_fp4 v[12:13], v155, 1.0 op_sel:[0,1,0]
	v_cvt_scalef32_pk_f32_fp4 v[14:15], v155, 1.0 op_sel:[1,1,0]
	v_readlane_b32 s54, v92, 53
	s_lshl_b32 s56, s54, 9
	s_add_u32 s56, s64, s56
	s_addc_u32 s57, s65, 0
	global_load_dwordx2 v[154:155], v227, s[56:57]
	v_pk_fma_f32 v[130:131], v[0:1], s[0:1], v[130:131] op_sel_hi:[1,0,1]
	v_pk_fma_f32 v[138:139], v[2:3], s[0:1], v[138:139] op_sel_hi:[1,0,1]
	v_pk_fma_f32 v[140:141], v[4:5], s[0:1], v[140:141] op_sel_hi:[1,0,1]
	v_pk_fma_f32 v[142:143], v[6:7], s[0:1], v[142:143] op_sel_hi:[1,0,1]
	v_pk_fma_f32 v[128:129], v[8:9], s[0:1], v[128:129] op_sel_hi:[1,0,1]
	v_pk_fma_f32 v[132:133], v[10:11], s[0:1], v[132:133] op_sel_hi:[1,0,1]
	v_pk_fma_f32 v[134:135], v[12:13], s[0:1], v[134:135] op_sel_hi:[1,0,1]
	v_pk_fma_f32 v[136:137], v[14:15], s[0:1], v[136:137] op_sel_hi:[1,0,1]
	v_readlane_b32 s0, v167, 38
	s_waitcnt vmcnt(15)
	v_cvt_scalef32_pk_f32_fp4 v[0:1], v156, 1.0
	v_cvt_scalef32_pk_f32_fp4 v[2:3], v156, 1.0 op_sel:[1,0,0]
	v_cvt_scalef32_pk_f32_fp4 v[4:5], v156, 1.0 op_sel:[0,1,0]
	v_cvt_scalef32_pk_f32_fp4 v[6:7], v156, 1.0 op_sel:[1,1,0]
	v_cvt_scalef32_pk_f32_fp4 v[8:9], v157, 1.0
	v_cvt_scalef32_pk_f32_fp4 v[10:11], v157, 1.0 op_sel:[1,0,0]
	v_cvt_scalef32_pk_f32_fp4 v[12:13], v157, 1.0 op_sel:[0,1,0]
	v_cvt_scalef32_pk_f32_fp4 v[14:15], v157, 1.0 op_sel:[1,1,0]
	v_readlane_b32 s54, v92, 54
	s_lshl_b32 s56, s54, 9
	s_add_u32 s56, s64, s56
	s_addc_u32 s57, s65, 0
	global_load_dwordx2 v[156:157], v227, s[56:57]
	v_pk_fma_f32 v[130:131], v[0:1], s[0:1], v[130:131] op_sel_hi:[1,0,1]
	v_pk_fma_f32 v[138:139], v[2:3], s[0:1], v[138:139] op_sel_hi:[1,0,1]
	v_pk_fma_f32 v[140:141], v[4:5], s[0:1], v[140:141] op_sel_hi:[1,0,1]
	v_pk_fma_f32 v[142:143], v[6:7], s[0:1], v[142:143] op_sel_hi:[1,0,1]
	v_pk_fma_f32 v[128:129], v[8:9], s[0:1], v[128:129] op_sel_hi:[1,0,1]
	v_pk_fma_f32 v[132:133], v[10:11], s[0:1], v[132:133] op_sel_hi:[1,0,1]
	v_pk_fma_f32 v[134:135], v[12:13], s[0:1], v[134:135] op_sel_hi:[1,0,1]
	v_pk_fma_f32 v[136:137], v[14:15], s[0:1], v[136:137] op_sel_hi:[1,0,1]
	v_readlane_b32 s0, v167, 39
	s_waitcnt vmcnt(15)
	v_cvt_scalef32_pk_f32_fp4 v[0:1], v158, 1.0
	v_cvt_scalef32_pk_f32_fp4 v[2:3], v158, 1.0 op_sel:[1,0,0]
	v_cvt_scalef32_pk_f32_fp4 v[4:5], v158, 1.0 op_sel:[0,1,0]
	v_cvt_scalef32_pk_f32_fp4 v[6:7], v158, 1.0 op_sel:[1,1,0]
	v_cvt_scalef32_pk_f32_fp4 v[8:9], v159, 1.0
	v_cvt_scalef32_pk_f32_fp4 v[10:11], v159, 1.0 op_sel:[1,0,0]
	v_cvt_scalef32_pk_f32_fp4 v[12:13], v159, 1.0 op_sel:[0,1,0]
	v_cvt_scalef32_pk_f32_fp4 v[14:15], v159, 1.0 op_sel:[1,1,0]
	v_readlane_b32 s54, v92, 55
	s_lshl_b32 s56, s54, 9
	s_add_u32 s56, s64, s56
	s_addc_u32 s57, s65, 0
	global_load_dwordx2 v[158:159], v227, s[56:57]
	v_pk_fma_f32 v[130:131], v[0:1], s[0:1], v[130:131] op_sel_hi:[1,0,1]
	v_pk_fma_f32 v[138:139], v[2:3], s[0:1], v[138:139] op_sel_hi:[1,0,1]
	v_pk_fma_f32 v[140:141], v[4:5], s[0:1], v[140:141] op_sel_hi:[1,0,1]
	v_pk_fma_f32 v[142:143], v[6:7], s[0:1], v[142:143] op_sel_hi:[1,0,1]
	v_pk_fma_f32 v[128:129], v[8:9], s[0:1], v[128:129] op_sel_hi:[1,0,1]
	v_pk_fma_f32 v[132:133], v[10:11], s[0:1], v[132:133] op_sel_hi:[1,0,1]
	v_pk_fma_f32 v[134:135], v[12:13], s[0:1], v[134:135] op_sel_hi:[1,0,1]
	v_pk_fma_f32 v[136:137], v[14:15], s[0:1], v[136:137] op_sel_hi:[1,0,1]
	v_readlane_b32 s0, v167, 40
	s_waitcnt vmcnt(15)
; __device__ void peer_gather_phase(const Params& P, int l, bool do_store) {
;     ...
;         v8[2 * pr] = *(const uint2*)(V + (size_t)ea * 512);
;         v8[2 * pr + 1] = *(const uint2*)(V + (size_t)eb * 512);
;     ...
; #pragma unroll
;       for (int j = 0; j < 8; ++j) {
;         const float a = __builtin_bit_cast(float, __builtin_amdgcn_readlane(__builtin_bit_cast(int, avec), kb + j));
;         const f32x2 aa = f32x2{a, a};
;         y[0] += aa * __builtin_amdgcn_cvt_scalef32_pk_f32_fp4(v8[j].x, 1.0f, 0); y[1] += aa * __builtin_amdgcn_cvt_scalef32_pk_f32_fp4(v8[j].x, 1.0f, 1);
;         y[2] += aa * __builtin_amdgcn_cvt_scalef32_pk_f32_fp4(v8[j].x, 1.0f, 2); y[3] += aa * __builtin_amdgcn_cvt_scalef32_pk_f32_fp4(v8[j].x, 1.0f, 3);
;         y[4] += aa * __builtin_amdgcn_cvt_scalef32_pk_f32_fp4(v8[j].y, 1.0f, 0); y[5] += aa * __builtin_amdgcn_cvt_scalef32_pk_f32_fp4(v8[j].y, 1.0f, 1);
;         y[6] += aa * __builtin_amdgcn_cvt_scalef32_pk_f32_fp4(v8[j].y, 1.0f, 2); y[7] += aa * __builtin_amdgcn_cvt_scalef32_pk_f32_fp4(v8[j].y, 1.0f, 3);
;       }
	v_cvt_scalef32_pk_f32_fp4 v[0:1], v168, 1.0
	v_cvt_scalef32_pk_f32_fp4 v[2:3], v168, 1.0 op_sel:[1,0,0]
	v_cvt_scalef32_pk_f32_fp4 v[4:5], v168, 1.0 op_sel:[0,1,0]
	v_cvt_scalef32_pk_f32_fp4 v[6:7], v168, 1.0 op_sel:[1,1,0]
	v_cvt_scalef32_pk_f32_fp4 v[8:9], v169, 1.0
	v_cvt_scalef32_pk_f32_fp4 v[10:11], v169, 1.0 op_sel:[1,0,0]
	v_cvt_scalef32_pk_f32_fp4 v[12:13], v169, 1.0 op_sel:[0,1,0]
	v_cvt_scalef32_pk_f32_fp4 v[14:15], v169, 1.0 op_sel:[1,1,0]
	v_readlane_b32 s54, v92, 56
	s_lshl_b32 s56, s54, 9
	s_add_u32 s56, s64, s56
	s_addc_u32 s57, s65, 0
	global_load_dwordx2 v[168:169], v227, s[56:57]
	v_pk_fma_f32 v[130:131], v[0:1], s[0:1], v[130:131] op_sel_hi:[1,0,1]
	v_pk_fma_f32 v[138:139], v[2:3], s[0:1], v[138:139] op_sel_hi:[1,0,1]
	v_pk_fma_f32 v[140:141], v[4:5], s[0:1], v[140:141] op_sel_hi:[1,0,1]
	v_pk_fma_f32 v[142:143], v[6:7], s[0:1], v[142:143] op_sel_hi:[1,0,1]
	v_pk_fma_f32 v[128:129], v[8:9], s[0:1], v[128:129] op_sel_hi:[1,0,1]
	v_pk_fma_f32 v[132:133], v[10:11], s[0:1], v[132:133] op_sel_hi:[1,0,1]
	v_pk_fma_f32 v[134:135], v[12:13], s[0:1], v[134:135] op_sel_hi:[1,0,1]
	v_pk_fma_f32 v[136:137], v[14:15], s[0:1], v[136:137] op_sel_hi:[1,0,1]
	v_readlane_b32 s0, v167, 41
	s_waitcnt vmcnt(15)
	v_cvt_scalef32_pk_f32_fp4 v[0:1], v170, 1.0
	v_cvt_scalef32_pk_f32_fp4 v[2:3], v170, 1.0 op_sel:[1,0,0]
	v_cvt_scalef32_pk_f32_fp4 v[4:5], v170, 1.0 op_sel:[0,1,0]
	v_cvt_scalef32_pk_f32_fp4 v[6:7], v170, 1.0 op_sel:[1,1,0]
	v_cvt_scalef32_pk_f32_fp4 v[8:9], v171, 1.0
	v_cvt_scalef32_pk_f32_fp4 v[10:11], v171, 1.0 op_sel:[1,0,0]
	v_cvt_scalef32_pk_f32_fp4 v[12:13], v171, 1.0 op_sel:[0,1,0]
	v_cvt_scalef32_pk_f32_fp4 v[14:15], v171, 1.0 op_sel:[1,1,0]
	v_readlane_b32 s54, v92, 57
	s_lshl_b32 s56, s54, 9
	s_add_u32 s56, s64, s56
	s_addc_u32 s57, s65, 0
	global_load_dwordx2 v[170:171], v227, s[56:57]
	v_pk_fma_f32 v[130:131], v[0:1], s[0:1], v[130:131] op_sel_hi:[1,0,1]
	v_pk_fma_f32 v[138:139], v[2:3], s[0:1], v[138:139] op_sel_hi:[1,0,1]
	v_pk_fma_f32 v[140:141], v[4:5], s[0:1], v[140:141] op_sel_hi:[1,0,1]
	v_pk_fma_f32 v[142:143], v[6:7], s[0:1], v[142:143] op_sel_hi:[1,0,1]
	v_pk_fma_f32 v[128:129], v[8:9], s[0:1], v[128:129] op_sel_hi:[1,0,1]
	v_pk_fma_f32 v[132:133], v[10:11], s[0:1], v[132:133] op_sel_hi:[1,0,1]
	v_pk_fma_f32 v[134:135], v[12:13], s[0:1], v[134:135] op_sel_hi:[1,0,1]
	v_pk_fma_f32 v[136:137], v[14:15], s[0:1], v[136:137] op_sel_hi:[1,0,1]
	v_readlane_b32 s0, v167, 42
	s_waitcnt vmcnt(15)
	v_cvt_scalef32_pk_f32_fp4 v[0:1], v172, 1.0
	v_cvt_scalef32_pk_f32_fp4 v[2:3], v172, 1.0 op_sel:[1,0,0]
	v_cvt_scalef32_pk_f32_fp4 v[4:5], v172, 1.0 op_sel:[0,1,0]
	v_cvt_scalef32_pk_f32_fp4 v[6:7], v172, 1.0 op_sel:[1,1,0]
	v_cvt_scalef32_pk_f32_fp4 v[8:9], v173, 1.0
	v_cvt_scalef32_pk_f32_fp4 v[10:11], v173, 1.0 op_sel:[1,0,0]
	v_cvt_scalef32_pk_f32_fp4 v[12:13], v173, 1.0 op_sel:[0,1,0]
	v_cvt_scalef32_pk_f32_fp4 v[14:15], v173, 1.0 op_sel:[1,1,0]
	v_readlane_b32 s54, v92, 58
	s_lshl_b32 s56, s54, 9
	s_add_u32 s56, s64, s56
	s_addc_u32 s57, s65, 0
	global_load_dwordx2 v[172:173], v227, s[56:57]
	v_pk_fma_f32 v[130:131], v[0:1], s[0:1], v[130:131] op_sel_hi:[1,0,1]
	v_pk_fma_f32 v[138:139], v[2:3], s[0:1], v[138:139] op_sel_hi:[1,0,1]
	v_pk_fma_f32 v[140:141], v[4:5], s[0:1], v[140:141] op_sel_hi:[1,0,1]
	v_pk_fma_f32 v[142:143], v[6:7], s[0:1], v[142:143] op_sel_hi:[1,0,1]
	v_pk_fma_f32 v[128:129], v[8:9], s[0:1], v[128:129] op_sel_hi:[1,0,1]
	v_pk_fma_f32 v[132:133], v[10:11], s[0:1], v[132:133] op_sel_hi:[1,0,1]
	v_pk_fma_f32 v[134:135], v[12:13], s[0:1], v[134:135] op_sel_hi:[1,0,1]
	v_pk_fma_f32 v[136:137], v[14:15], s[0:1], v[136:137] op_sel_hi:[1,0,1]
	v_readlane_b32 s0, v167, 43
	s_waitcnt vmcnt(15)
	v_cvt_scalef32_pk_f32_fp4 v[0:1], v174, 1.0
	v_cvt_scalef32_pk_f32_fp4 v[2:3], v174, 1.0 op_sel:[1,0,0]
	v_cvt_scalef32_pk_f32_fp4 v[4:5], v174, 1.0 op_sel:[0,1,0]
	v_cvt_scalef32_pk_f32_fp4 v[6:7], v174, 1.0 op_sel:[1,1,0]
	v_cvt_scalef32_pk_f32_fp4 v[8:9], v175, 1.0
	v_cvt_scalef32_pk_f32_fp4 v[10:11], v175, 1.0 op_sel:[1,0,0]
	v_cvt_scalef32_pk_f32_fp4 v[12:13], v175, 1.0 op_sel:[0,1,0]
	v_cvt_scalef32_pk_f32_fp4 v[14:15], v175, 1.0 op_sel:[1,1,0]
	v_readlane_b32 s54, v92, 59
	s_lshl_b32 s56, s54, 9
	s_add_u32 s56, s64, s56
	s_addc_u32 s57, s65, 0
	global_load_dwordx2 v[174:175], v227, s[56:57]
	v_pk_fma_f32 v[130:131], v[0:1], s[0:1], v[130:131] op_sel_hi:[1,0,1]
	v_pk_fma_f32 v[138:139], v[2:3], s[0:1], v[138:139] op_sel_hi:[1,0,1]
	v_pk_fma_f32 v[140:141], v[4:5], s[0:1], v[140:141] op_sel_hi:[1,0,1]
	v_pk_fma_f32 v[142:143], v[6:7], s[0:1], v[142:143] op_sel_hi:[1,0,1]
	v_pk_fma_f32 v[128:129], v[8:9], s[0:1], v[128:129] op_sel_hi:[1,0,1]
	v_pk_fma_f32 v[132:133], v[10:11], s[0:1], v[132:133] op_sel_hi:[1,0,1]
	v_pk_fma_f32 v[134:135], v[12:13], s[0:1], v[134:135] op_sel_hi:[1,0,1]
	v_pk_fma_f32 v[136:137], v[14:15], s[0:1], v[136:137] op_sel_hi:[1,0,1]
	v_readlane_b32 s0, v167, 44
	s_waitcnt vmcnt(15)
	v_cvt_scalef32_pk_f32_fp4 v[0:1], v180, 1.0
	v_cvt_scalef32_pk_f32_fp4 v[2:3], v180, 1.0 op_sel:[1,0,0]
	v_cvt_scalef32_pk_f32_fp4 v[4:5], v180, 1.0 op_sel:[0,1,0]
	v_cvt_scalef32_pk_f32_fp4 v[6:7], v180, 1.0 op_sel:[1,1,0]
	v_cvt_scalef32_pk_f32_fp4 v[8:9], v181, 1.0
	v_cvt_scalef32_pk_f32_fp4 v[10:11], v181, 1.0 op_sel:[1,0,0]
	v_cvt_scalef32_pk_f32_fp4 v[12:13], v181, 1.0 op_sel:[0,1,0]
	v_cvt_scalef32_pk_f32_fp4 v[14:15], v181, 1.0 op_sel:[1,1,0]
	v_readlane_b32 s54, v92, 60
	s_lshl_b32 s56, s54, 9
	s_add_u32 s56, s64, s56
	s_addc_u32 s57, s65, 0
	global_load_dwordx2 v[180:181], v227, s[56:57]
	v_pk_fma_f32 v[130:131], v[0:1], s[0:1], v[130:131] op_sel_hi:[1,0,1]
	v_pk_fma_f32 v[138:139], v[2:3], s[0:1], v[138:139] op_sel_hi:[1,0,1]
	v_pk_fma_f32 v[140:141], v[4:5], s[0:1], v[140:141] op_sel_hi:[1,0,1]
	v_pk_fma_f32 v[142:143], v[6:7], s[0:1], v[142:143] op_sel_hi:[1,0,1]
	v_pk_fma_f32 v[128:129], v[8:9], s[0:1], v[128:129] op_sel_hi:[1,0,1]
	v_pk_fma_f32 v[132:133], v[10:11], s[0:1], v[132:133] op_sel_hi:[1,0,1]
	v_pk_fma_f32 v[134:135], v[12:13], s[0:1], v[134:135] op_sel_hi:[1,0,1]
	v_pk_fma_f32 v[136:137], v[14:15], s[0:1], v[136:137] op_sel_hi:[1,0,1]
	v_readlane_b32 s0, v167, 45
	s_waitcnt vmcnt(15)
; __device__ void peer_gather_phase(const Params& P, int l, bool do_store) {
;     ...
;         v8[2 * pr] = *(const uint2*)(V + (size_t)ea * 512);
;         v8[2 * pr + 1] = *(const uint2*)(V + (size_t)eb * 512);
;     ...
; #pragma unroll
;       for (int j = 0; j < 8; ++j) {
;         const float a = __builtin_bit_cast(float, __builtin_amdgcn_readlane(__builtin_bit_cast(int, avec), kb + j));
;         const f32x2 aa = f32x2{a, a};
;         y[0] += aa * __builtin_amdgcn_cvt_scalef32_pk_f32_fp4(v8[j].x, 1.0f, 0); y[1] += aa * __builtin_amdgcn_cvt_scalef32_pk_f32_fp4(v8[j].x, 1.0f, 1);
;         y[2] += aa * __builtin_amdgcn_cvt_scalef32_pk_f32_fp4(v8[j].x, 1.0f, 2); y[3] += aa * __builtin_amdgcn_cvt_scalef32_pk_f32_fp4(v8[j].x, 1.0f, 3);
;         y[4] += aa * __builtin_amdgcn_cvt_scalef32_pk_f32_fp4(v8[j].y, 1.0f, 0); y[5] += aa * __builtin_amdgcn_cvt_scalef32_pk_f32_fp4(v8[j].y, 1.0f, 1);
;         y[6] += aa * __builtin_amdgcn_cvt_scalef32_pk_f32_fp4(v8[j].y, 1.0f, 2); y[7] += aa * __builtin_amdgcn_cvt_scalef32_pk_f32_fp4(v8[j].y, 1.0f, 3);
;       }
	v_cvt_scalef32_pk_f32_fp4 v[0:1], v182, 1.0
	v_cvt_scalef32_pk_f32_fp4 v[2:3], v182, 1.0 op_sel:[1,0,0]
	v_cvt_scalef32_pk_f32_fp4 v[4:5], v182, 1.0 op_sel:[0,1,0]
	v_cvt_scalef32_pk_f32_fp4 v[6:7], v182, 1.0 op_sel:[1,1,0]
	v_cvt_scalef32_pk_f32_fp4 v[8:9], v183, 1.0
	v_cvt_scalef32_pk_f32_fp4 v[10:11], v183, 1.0 op_sel:[1,0,0]
	v_cvt_scalef32_pk_f32_fp4 v[12:13], v183, 1.0 op_sel:[0,1,0]
	v_cvt_scalef32_pk_f32_fp4 v[14:15], v183, 1.0 op_sel:[1,1,0]
	v_readlane_b32 s54, v92, 61
	s_lshl_b32 s56, s54, 9
	s_add_u32 s56, s64, s56
	s_addc_u32 s57, s65, 0
	global_load_dwordx2 v[182:183], v227, s[56:57]
	v_pk_fma_f32 v[130:131], v[0:1], s[0:1], v[130:131] op_sel_hi:[1,0,1]
	v_pk_fma_f32 v[138:139], v[2:3], s[0:1], v[138:139] op_sel_hi:[1,0,1]
	v_pk_fma_f32 v[140:141], v[4:5], s[0:1], v[140:141] op_sel_hi:[1,0,1]
	v_pk_fma_f32 v[142:143], v[6:7], s[0:1], v[142:143] op_sel_hi:[1,0,1]
	v_pk_fma_f32 v[128:129], v[8:9], s[0:1], v[128:129] op_sel_hi:[1,0,1]
	v_pk_fma_f32 v[132:133], v[10:11], s[0:1], v[132:133] op_sel_hi:[1,0,1]
	v_pk_fma_f32 v[134:135], v[12:13], s[0:1], v[134:135] op_sel_hi:[1,0,1]
	v_pk_fma_f32 v[136:137], v[14:15], s[0:1], v[136:137] op_sel_hi:[1,0,1]
	v_readlane_b32 s0, v167, 46
	s_waitcnt vmcnt(15)
	v_cvt_scalef32_pk_f32_fp4 v[0:1], v184, 1.0
	v_cvt_scalef32_pk_f32_fp4 v[2:3], v184, 1.0 op_sel:[1,0,0]
	v_cvt_scalef32_pk_f32_fp4 v[4:5], v184, 1.0 op_sel:[0,1,0]
	v_cvt_scalef32_pk_f32_fp4 v[6:7], v184, 1.0 op_sel:[1,1,0]
	v_cvt_scalef32_pk_f32_fp4 v[8:9], v185, 1.0
	v_cvt_scalef32_pk_f32_fp4 v[10:11], v185, 1.0 op_sel:[1,0,0]
	v_cvt_scalef32_pk_f32_fp4 v[12:13], v185, 1.0 op_sel:[0,1,0]
	v_cvt_scalef32_pk_f32_fp4 v[14:15], v185, 1.0 op_sel:[1,1,0]
	v_readlane_b32 s54, v92, 62
	s_lshl_b32 s56, s54, 9
	s_add_u32 s56, s64, s56
	s_addc_u32 s57, s65, 0
	global_load_dwordx2 v[184:185], v227, s[56:57]
	v_pk_fma_f32 v[130:131], v[0:1], s[0:1], v[130:131] op_sel_hi:[1,0,1]
	v_pk_fma_f32 v[138:139], v[2:3], s[0:1], v[138:139] op_sel_hi:[1,0,1]
	v_pk_fma_f32 v[140:141], v[4:5], s[0:1], v[140:141] op_sel_hi:[1,0,1]
	v_pk_fma_f32 v[142:143], v[6:7], s[0:1], v[142:143] op_sel_hi:[1,0,1]
	v_pk_fma_f32 v[128:129], v[8:9], s[0:1], v[128:129] op_sel_hi:[1,0,1]
	v_pk_fma_f32 v[132:133], v[10:11], s[0:1], v[132:133] op_sel_hi:[1,0,1]
	v_pk_fma_f32 v[134:135], v[12:13], s[0:1], v[134:135] op_sel_hi:[1,0,1]
	v_pk_fma_f32 v[136:137], v[14:15], s[0:1], v[136:137] op_sel_hi:[1,0,1]
	v_readlane_b32 s0, v167, 47
	s_waitcnt vmcnt(15)
	v_cvt_scalef32_pk_f32_fp4 v[0:1], v186, 1.0
	v_cvt_scalef32_pk_f32_fp4 v[2:3], v186, 1.0 op_sel:[1,0,0]
	v_cvt_scalef32_pk_f32_fp4 v[4:5], v186, 1.0 op_sel:[0,1,0]
	v_cvt_scalef32_pk_f32_fp4 v[6:7], v186, 1.0 op_sel:[1,1,0]
	v_cvt_scalef32_pk_f32_fp4 v[8:9], v187, 1.0
	v_cvt_scalef32_pk_f32_fp4 v[10:11], v187, 1.0 op_sel:[1,0,0]
	v_cvt_scalef32_pk_f32_fp4 v[12:13], v187, 1.0 op_sel:[0,1,0]
	v_cvt_scalef32_pk_f32_fp4 v[14:15], v187, 1.0 op_sel:[1,1,0]
	v_readlane_b32 s54, v92, 63
	s_lshl_b32 s56, s54, 9
	s_add_u32 s56, s64, s56
	s_addc_u32 s57, s65, 0
	global_load_dwordx2 v[186:187], v227, s[56:57]
	v_pk_fma_f32 v[130:131], v[0:1], s[0:1], v[130:131] op_sel_hi:[1,0,1]
	v_pk_fma_f32 v[138:139], v[2:3], s[0:1], v[138:139] op_sel_hi:[1,0,1]
	v_pk_fma_f32 v[140:141], v[4:5], s[0:1], v[140:141] op_sel_hi:[1,0,1]
	v_pk_fma_f32 v[142:143], v[6:7], s[0:1], v[142:143] op_sel_hi:[1,0,1]
	v_pk_fma_f32 v[128:129], v[8:9], s[0:1], v[128:129] op_sel_hi:[1,0,1]
	v_pk_fma_f32 v[132:133], v[10:11], s[0:1], v[132:133] op_sel_hi:[1,0,1]
	v_pk_fma_f32 v[134:135], v[12:13], s[0:1], v[134:135] op_sel_hi:[1,0,1]
	v_pk_fma_f32 v[136:137], v[14:15], s[0:1], v[136:137] op_sel_hi:[1,0,1]
	v_readlane_b32 s0, v167, 48
	s_waitcnt vmcnt(15)
	v_cvt_scalef32_pk_f32_fp4 v[0:1], v144, 1.0
	v_cvt_scalef32_pk_f32_fp4 v[2:3], v144, 1.0 op_sel:[1,0,0]
	v_cvt_scalef32_pk_f32_fp4 v[4:5], v144, 1.0 op_sel:[0,1,0]
	v_cvt_scalef32_pk_f32_fp4 v[6:7], v144, 1.0 op_sel:[1,1,0]
	v_cvt_scalef32_pk_f32_fp4 v[8:9], v145, 1.0
	v_cvt_scalef32_pk_f32_fp4 v[10:11], v145, 1.0 op_sel:[1,0,0]
	v_cvt_scalef32_pk_f32_fp4 v[12:13], v145, 1.0 op_sel:[0,1,0]
	v_cvt_scalef32_pk_f32_fp4 v[14:15], v145, 1.0 op_sel:[1,1,0]
	v_readlane_b32 s54, v90, 0
	s_lshl_b32 s56, s54, 9
	s_add_u32 s56, s64, s56
	s_addc_u32 s57, s65, 0
	global_load_dwordx2 v[144:145], v227, s[56:57]
	v_pk_fma_f32 v[130:131], v[0:1], s[0:1], v[130:131] op_sel_hi:[1,0,1]
	v_pk_fma_f32 v[138:139], v[2:3], s[0:1], v[138:139] op_sel_hi:[1,0,1]
	v_pk_fma_f32 v[140:141], v[4:5], s[0:1], v[140:141] op_sel_hi:[1,0,1]
	v_pk_fma_f32 v[142:143], v[6:7], s[0:1], v[142:143] op_sel_hi:[1,0,1]
	v_pk_fma_f32 v[128:129], v[8:9], s[0:1], v[128:129] op_sel_hi:[1,0,1]
	v_pk_fma_f32 v[132:133], v[10:11], s[0:1], v[132:133] op_sel_hi:[1,0,1]
	v_pk_fma_f32 v[134:135], v[12:13], s[0:1], v[134:135] op_sel_hi:[1,0,1]
	v_pk_fma_f32 v[136:137], v[14:15], s[0:1], v[136:137] op_sel_hi:[1,0,1]
	v_readlane_b32 s0, v167, 49
	s_waitcnt vmcnt(15)
	v_cvt_scalef32_pk_f32_fp4 v[0:1], v146, 1.0
	v_cvt_scalef32_pk_f32_fp4 v[2:3], v146, 1.0 op_sel:[1,0,0]
	v_cvt_scalef32_pk_f32_fp4 v[4:5], v146, 1.0 op_sel:[0,1,0]
	v_cvt_scalef32_pk_f32_fp4 v[6:7], v146, 1.0 op_sel:[1,1,0]
	v_cvt_scalef32_pk_f32_fp4 v[8:9], v147, 1.0
	v_cvt_scalef32_pk_f32_fp4 v[10:11], v147, 1.0 op_sel:[1,0,0]
	v_cvt_scalef32_pk_f32_fp4 v[12:13], v147, 1.0 op_sel:[0,1,0]
	v_cvt_scalef32_pk_f32_fp4 v[14:15], v147, 1.0 op_sel:[1,1,0]
	v_readlane_b32 s54, v90, 1
	s_lshl_b32 s56, s54, 9
	s_add_u32 s56, s64, s56
	s_addc_u32 s57, s65, 0
	global_load_dwordx2 v[146:147], v227, s[56:57]
	v_pk_fma_f32 v[130:131], v[0:1], s[0:1], v[130:131] op_sel_hi:[1,0,1]
	v_pk_fma_f32 v[138:139], v[2:3], s[0:1], v[138:139] op_sel_hi:[1,0,1]
	v_pk_fma_f32 v[140:141], v[4:5], s[0:1], v[140:141] op_sel_hi:[1,0,1]
	v_pk_fma_f32 v[142:143], v[6:7], s[0:1], v[142:143] op_sel_hi:[1,0,1]
	v_pk_fma_f32 v[128:129], v[8:9], s[0:1], v[128:129] op_sel_hi:[1,0,1]
	v_pk_fma_f32 v[132:133], v[10:11], s[0:1], v[132:133] op_sel_hi:[1,0,1]
	v_pk_fma_f32 v[134:135], v[12:13], s[0:1], v[134:135] op_sel_hi:[1,0,1]
	v_pk_fma_f32 v[136:137], v[14:15], s[0:1], v[136:137] op_sel_hi:[1,0,1]
	v_readlane_b32 s0, v167, 50
	s_waitcnt vmcnt(15)
; __device__ void peer_gather_phase(const Params& P, int l, bool do_store) {
;     ...
;         v8[2 * pr] = *(const uint2*)(V + (size_t)ea * 512);
;         v8[2 * pr + 1] = *(const uint2*)(V + (size_t)eb * 512);
;     ...
; #pragma unroll
;       for (int j = 0; j < 8; ++j) {
;         const float a = __builtin_bit_cast(float, __builtin_amdgcn_readlane(__builtin_bit_cast(int, avec), kb + j));
;         const f32x2 aa = f32x2{a, a};
;         y[0] += aa * __builtin_amdgcn_cvt_scalef32_pk_f32_fp4(v8[j].x, 1.0f, 0); y[1] += aa * __builtin_amdgcn_cvt_scalef32_pk_f32_fp4(v8[j].x, 1.0f, 1);
;         y[2] += aa * __builtin_amdgcn_cvt_scalef32_pk_f32_fp4(v8[j].x, 1.0f, 2); y[3] += aa * __builtin_amdgcn_cvt_scalef32_pk_f32_fp4(v8[j].x, 1.0f, 3);
;         y[4] += aa * __builtin_amdgcn_cvt_scalef32_pk_f32_fp4(v8[j].y, 1.0f, 0); y[5] += aa * __builtin_amdgcn_cvt_scalef32_pk_f32_fp4(v8[j].y, 1.0f, 1);
;         y[6] += aa * __builtin_amdgcn_cvt_scalef32_pk_f32_fp4(v8[j].y, 1.0f, 2); y[7] += aa * __builtin_amdgcn_cvt_scalef32_pk_f32_fp4(v8[j].y, 1.0f, 3);
;       }
	v_cvt_scalef32_pk_f32_fp4 v[0:1], v148, 1.0
	v_cvt_scalef32_pk_f32_fp4 v[2:3], v148, 1.0 op_sel:[1,0,0]
	v_cvt_scalef32_pk_f32_fp4 v[4:5], v148, 1.0 op_sel:[0,1,0]
	v_cvt_scalef32_pk_f32_fp4 v[6:7], v148, 1.0 op_sel:[1,1,0]
	v_cvt_scalef32_pk_f32_fp4 v[8:9], v149, 1.0
	v_cvt_scalef32_pk_f32_fp4 v[10:11], v149, 1.0 op_sel:[1,0,0]
	v_cvt_scalef32_pk_f32_fp4 v[12:13], v149, 1.0 op_sel:[0,1,0]
	v_cvt_scalef32_pk_f32_fp4 v[14:15], v149, 1.0 op_sel:[1,1,0]
	v_readlane_b32 s54, v90, 2
	s_lshl_b32 s56, s54, 9
	s_add_u32 s56, s64, s56
	s_addc_u32 s57, s65, 0
	global_load_dwordx2 v[148:149], v227, s[56:57]
	v_pk_fma_f32 v[130:131], v[0:1], s[0:1], v[130:131] op_sel_hi:[1,0,1]
	v_pk_fma_f32 v[138:139], v[2:3], s[0:1], v[138:139] op_sel_hi:[1,0,1]
	v_pk_fma_f32 v[140:141], v[4:5], s[0:1], v[140:141] op_sel_hi:[1,0,1]
	v_pk_fma_f32 v[142:143], v[6:7], s[0:1], v[142:143] op_sel_hi:[1,0,1]
	v_pk_fma_f32 v[128:129], v[8:9], s[0:1], v[128:129] op_sel_hi:[1,0,1]
	v_pk_fma_f32 v[132:133], v[10:11], s[0:1], v[132:133] op_sel_hi:[1,0,1]
	v_pk_fma_f32 v[134:135], v[12:13], s[0:1], v[134:135] op_sel_hi:[1,0,1]
	v_pk_fma_f32 v[136:137], v[14:15], s[0:1], v[136:137] op_sel_hi:[1,0,1]
	v_readlane_b32 s0, v167, 51
	s_waitcnt vmcnt(15)
	v_cvt_scalef32_pk_f32_fp4 v[0:1], v150, 1.0
	v_cvt_scalef32_pk_f32_fp4 v[2:3], v150, 1.0 op_sel:[1,0,0]
	v_cvt_scalef32_pk_f32_fp4 v[4:5], v150, 1.0 op_sel:[0,1,0]
	v_cvt_scalef32_pk_f32_fp4 v[6:7], v150, 1.0 op_sel:[1,1,0]
	v_cvt_scalef32_pk_f32_fp4 v[8:9], v151, 1.0
	v_cvt_scalef32_pk_f32_fp4 v[10:11], v151, 1.0 op_sel:[1,0,0]
	v_cvt_scalef32_pk_f32_fp4 v[12:13], v151, 1.0 op_sel:[0,1,0]
	v_cvt_scalef32_pk_f32_fp4 v[14:15], v151, 1.0 op_sel:[1,1,0]
	v_readlane_b32 s54, v90, 3
	s_lshl_b32 s56, s54, 9
	s_add_u32 s56, s64, s56
	s_addc_u32 s57, s65, 0
	global_load_dwordx2 v[150:151], v227, s[56:57]
	v_pk_fma_f32 v[130:131], v[0:1], s[0:1], v[130:131] op_sel_hi:[1,0,1]
	v_pk_fma_f32 v[138:139], v[2:3], s[0:1], v[138:139] op_sel_hi:[1,0,1]
	v_pk_fma_f32 v[140:141], v[4:5], s[0:1], v[140:141] op_sel_hi:[1,0,1]
	v_pk_fma_f32 v[142:143], v[6:7], s[0:1], v[142:143] op_sel_hi:[1,0,1]
	v_pk_fma_f32 v[128:129], v[8:9], s[0:1], v[128:129] op_sel_hi:[1,0,1]
	v_pk_fma_f32 v[132:133], v[10:11], s[0:1], v[132:133] op_sel_hi:[1,0,1]
	v_pk_fma_f32 v[134:135], v[12:13], s[0:1], v[134:135] op_sel_hi:[1,0,1]
	v_pk_fma_f32 v[136:137], v[14:15], s[0:1], v[136:137] op_sel_hi:[1,0,1]
	v_readlane_b32 s0, v167, 52
	s_waitcnt vmcnt(15)
	v_cvt_scalef32_pk_f32_fp4 v[0:1], v152, 1.0
	v_cvt_scalef32_pk_f32_fp4 v[2:3], v152, 1.0 op_sel:[1,0,0]
	v_cvt_scalef32_pk_f32_fp4 v[4:5], v152, 1.0 op_sel:[0,1,0]
	v_cvt_scalef32_pk_f32_fp4 v[6:7], v152, 1.0 op_sel:[1,1,0]
	v_cvt_scalef32_pk_f32_fp4 v[8:9], v153, 1.0
	v_cvt_scalef32_pk_f32_fp4 v[10:11], v153, 1.0 op_sel:[1,0,0]
	v_cvt_scalef32_pk_f32_fp4 v[12:13], v153, 1.0 op_sel:[0,1,0]
	v_cvt_scalef32_pk_f32_fp4 v[14:15], v153, 1.0 op_sel:[1,1,0]
	v_readlane_b32 s54, v90, 4
	s_lshl_b32 s56, s54, 9
	s_add_u32 s56, s64, s56
	s_addc_u32 s57, s65, 0
	global_load_dwordx2 v[152:153], v227, s[56:57]
	v_pk_fma_f32 v[130:131], v[0:1], s[0:1], v[130:131] op_sel_hi:[1,0,1]
	v_pk_fma_f32 v[138:139], v[2:3], s[0:1], v[138:139] op_sel_hi:[1,0,1]
	v_pk_fma_f32 v[140:141], v[4:5], s[0:1], v[140:141] op_sel_hi:[1,0,1]
	v_pk_fma_f32 v[142:143], v[6:7], s[0:1], v[142:143] op_sel_hi:[1,0,1]
	v_pk_fma_f32 v[128:129], v[8:9], s[0:1], v[128:129] op_sel_hi:[1,0,1]
	v_pk_fma_f32 v[132:133], v[10:11], s[0:1], v[132:133] op_sel_hi:[1,0,1]
	v_pk_fma_f32 v[134:135], v[12:13], s[0:1], v[134:135] op_sel_hi:[1,0,1]
	v_pk_fma_f32 v[136:137], v[14:15], s[0:1], v[136:137] op_sel_hi:[1,0,1]
	v_readlane_b32 s0, v167, 53
	s_waitcnt vmcnt(15)
	v_cvt_scalef32_pk_f32_fp4 v[0:1], v154, 1.0
	v_cvt_scalef32_pk_f32_fp4 v[2:3], v154, 1.0 op_sel:[1,0,0]
	v_cvt_scalef32_pk_f32_fp4 v[4:5], v154, 1.0 op_sel:[0,1,0]
	v_cvt_scalef32_pk_f32_fp4 v[6:7], v154, 1.0 op_sel:[1,1,0]
	v_cvt_scalef32_pk_f32_fp4 v[8:9], v155, 1.0
	v_cvt_scalef32_pk_f32_fp4 v[10:11], v155, 1.0 op_sel:[1,0,0]
	v_cvt_scalef32_pk_f32_fp4 v[12:13], v155, 1.0 op_sel:[0,1,0]
	v_cvt_scalef32_pk_f32_fp4 v[14:15], v155, 1.0 op_sel:[1,1,0]
	v_readlane_b32 s54, v90, 5
	s_lshl_b32 s56, s54, 9
	s_add_u32 s56, s64, s56
	s_addc_u32 s57, s65, 0
	global_load_dwordx2 v[154:155], v227, s[56:57]
	v_pk_fma_f32 v[130:131], v[0:1], s[0:1], v[130:131] op_sel_hi:[1,0,1]
	v_pk_fma_f32 v[138:139], v[2:3], s[0:1], v[138:139] op_sel_hi:[1,0,1]
	v_pk_fma_f32 v[140:141], v[4:5], s[0:1], v[140:141] op_sel_hi:[1,0,1]
	v_pk_fma_f32 v[142:143], v[6:7], s[0:1], v[142:143] op_sel_hi:[1,0,1]
	v_pk_fma_f32 v[128:129], v[8:9], s[0:1], v[128:129] op_sel_hi:[1,0,1]
	v_pk_fma_f32 v[132:133], v[10:11], s[0:1], v[132:133] op_sel_hi:[1,0,1]
	v_pk_fma_f32 v[134:135], v[12:13], s[0:1], v[134:135] op_sel_hi:[1,0,1]
	v_pk_fma_f32 v[136:137], v[14:15], s[0:1], v[136:137] op_sel_hi:[1,0,1]
	v_readlane_b32 s0, v167, 54
	s_waitcnt vmcnt(15)
	v_cvt_scalef32_pk_f32_fp4 v[0:1], v156, 1.0
	v_cvt_scalef32_pk_f32_fp4 v[2:3], v156, 1.0 op_sel:[1,0,0]
	v_cvt_scalef32_pk_f32_fp4 v[4:5], v156, 1.0 op_sel:[0,1,0]
	v_cvt_scalef32_pk_f32_fp4 v[6:7], v156, 1.0 op_sel:[1,1,0]
	v_cvt_scalef32_pk_f32_fp4 v[8:9], v157, 1.0
	v_cvt_scalef32_pk_f32_fp4 v[10:11], v157, 1.0 op_sel:[1,0,0]
	v_cvt_scalef32_pk_f32_fp4 v[12:13], v157, 1.0 op_sel:[0,1,0]
	v_cvt_scalef32_pk_f32_fp4 v[14:15], v157, 1.0 op_sel:[1,1,0]
	v_readlane_b32 s54, v90, 6
	s_lshl_b32 s56, s54, 9
	s_add_u32 s56, s64, s56
	s_addc_u32 s57, s65, 0
	global_load_dwordx2 v[156:157], v227, s[56:57]
	v_pk_fma_f32 v[130:131], v[0:1], s[0:1], v[130:131] op_sel_hi:[1,0,1]
	v_pk_fma_f32 v[138:139], v[2:3], s[0:1], v[138:139] op_sel_hi:[1,0,1]
	v_pk_fma_f32 v[140:141], v[4:5], s[0:1], v[140:141] op_sel_hi:[1,0,1]
	v_pk_fma_f32 v[142:143], v[6:7], s[0:1], v[142:143] op_sel_hi:[1,0,1]
	v_pk_fma_f32 v[128:129], v[8:9], s[0:1], v[128:129] op_sel_hi:[1,0,1]
	v_pk_fma_f32 v[132:133], v[10:11], s[0:1], v[132:133] op_sel_hi:[1,0,1]
	v_pk_fma_f32 v[134:135], v[12:13], s[0:1], v[134:135] op_sel_hi:[1,0,1]
	v_pk_fma_f32 v[136:137], v[14:15], s[0:1], v[136:137] op_sel_hi:[1,0,1]
	v_readlane_b32 s0, v167, 55
	s_waitcnt vmcnt(15)
; __device__ void peer_gather_phase(const Params& P, int l, bool do_store) {
;     ...
;         v8[2 * pr] = *(const uint2*)(V + (size_t)ea * 512);
;         v8[2 * pr + 1] = *(const uint2*)(V + (size_t)eb * 512);
;     ...
; #pragma unroll
;       for (int j = 0; j < 8; ++j) {
;         const float a = __builtin_bit_cast(float, __builtin_amdgcn_readlane(__builtin_bit_cast(int, avec), kb + j));
;         const f32x2 aa = f32x2{a, a};
;         y[0] += aa * __builtin_amdgcn_cvt_scalef32_pk_f32_fp4(v8[j].x, 1.0f, 0); y[1] += aa * __builtin_amdgcn_cvt_scalef32_pk_f32_fp4(v8[j].x, 1.0f, 1);
;         y[2] += aa * __builtin_amdgcn_cvt_scalef32_pk_f32_fp4(v8[j].x, 1.0f, 2); y[3] += aa * __builtin_amdgcn_cvt_scalef32_pk_f32_fp4(v8[j].x, 1.0f, 3);
;         y[4] += aa * __builtin_amdgcn_cvt_scalef32_pk_f32_fp4(v8[j].y, 1.0f, 0); y[5] += aa * __builtin_amdgcn_cvt_scalef32_pk_f32_fp4(v8[j].y, 1.0f, 1);
;         y[6] += aa * __builtin_amdgcn_cvt_scalef32_pk_f32_fp4(v8[j].y, 1.0f, 2); y[7] += aa * __builtin_amdgcn_cvt_scalef32_pk_f32_fp4(v8[j].y, 1.0f, 3);
;       }
	v_cvt_scalef32_pk_f32_fp4 v[0:1], v158, 1.0
	v_cvt_scalef32_pk_f32_fp4 v[2:3], v158, 1.0 op_sel:[1,0,0]
	v_cvt_scalef32_pk_f32_fp4 v[4:5], v158, 1.0 op_sel:[0,1,0]
	v_cvt_scalef32_pk_f32_fp4 v[6:7], v158, 1.0 op_sel:[1,1,0]
	v_cvt_scalef32_pk_f32_fp4 v[8:9], v159, 1.0
	v_cvt_scalef32_pk_f32_fp4 v[10:11], v159, 1.0 op_sel:[1,0,0]
	v_cvt_scalef32_pk_f32_fp4 v[12:13], v159, 1.0 op_sel:[0,1,0]
	v_cvt_scalef32_pk_f32_fp4 v[14:15], v159, 1.0 op_sel:[1,1,0]
	v_readlane_b32 s54, v90, 7
	s_lshl_b32 s56, s54, 9
	s_add_u32 s56, s64, s56
	s_addc_u32 s57, s65, 0
	global_load_dwordx2 v[158:159], v227, s[56:57]
	v_pk_fma_f32 v[130:131], v[0:1], s[0:1], v[130:131] op_sel_hi:[1,0,1]
	v_pk_fma_f32 v[138:139], v[2:3], s[0:1], v[138:139] op_sel_hi:[1,0,1]
	v_pk_fma_f32 v[140:141], v[4:5], s[0:1], v[140:141] op_sel_hi:[1,0,1]
	v_pk_fma_f32 v[142:143], v[6:7], s[0:1], v[142:143] op_sel_hi:[1,0,1]
	v_pk_fma_f32 v[128:129], v[8:9], s[0:1], v[128:129] op_sel_hi:[1,0,1]
	v_pk_fma_f32 v[132:133], v[10:11], s[0:1], v[132:133] op_sel_hi:[1,0,1]
	v_pk_fma_f32 v[134:135], v[12:13], s[0:1], v[134:135] op_sel_hi:[1,0,1]
	v_pk_fma_f32 v[136:137], v[14:15], s[0:1], v[136:137] op_sel_hi:[1,0,1]
	v_readlane_b32 s0, v167, 56
	s_waitcnt vmcnt(15)
	v_cvt_scalef32_pk_f32_fp4 v[0:1], v168, 1.0
	v_cvt_scalef32_pk_f32_fp4 v[2:3], v168, 1.0 op_sel:[1,0,0]
	v_cvt_scalef32_pk_f32_fp4 v[4:5], v168, 1.0 op_sel:[0,1,0]
	v_cvt_scalef32_pk_f32_fp4 v[6:7], v168, 1.0 op_sel:[1,1,0]
	v_cvt_scalef32_pk_f32_fp4 v[8:9], v169, 1.0
	v_cvt_scalef32_pk_f32_fp4 v[10:11], v169, 1.0 op_sel:[1,0,0]
	v_cvt_scalef32_pk_f32_fp4 v[12:13], v169, 1.0 op_sel:[0,1,0]
	v_cvt_scalef32_pk_f32_fp4 v[14:15], v169, 1.0 op_sel:[1,1,0]
	v_readlane_b32 s54, v90, 8
	s_lshl_b32 s56, s54, 9
	s_add_u32 s56, s64, s56
	s_addc_u32 s57, s65, 0
	global_load_dwordx2 v[168:169], v227, s[56:57]
	v_pk_fma_f32 v[130:131], v[0:1], s[0:1], v[130:131] op_sel_hi:[1,0,1]
	v_pk_fma_f32 v[138:139], v[2:3], s[0:1], v[138:139] op_sel_hi:[1,0,1]
	v_pk_fma_f32 v[140:141], v[4:5], s[0:1], v[140:141] op_sel_hi:[1,0,1]
	v_pk_fma_f32 v[142:143], v[6:7], s[0:1], v[142:143] op_sel_hi:[1,0,1]
	v_pk_fma_f32 v[128:129], v[8:9], s[0:1], v[128:129] op_sel_hi:[1,0,1]
	v_pk_fma_f32 v[132:133], v[10:11], s[0:1], v[132:133] op_sel_hi:[1,0,1]
	v_pk_fma_f32 v[134:135], v[12:13], s[0:1], v[134:135] op_sel_hi:[1,0,1]
	v_pk_fma_f32 v[136:137], v[14:15], s[0:1], v[136:137] op_sel_hi:[1,0,1]
	v_readlane_b32 s0, v167, 57
	s_waitcnt vmcnt(15)
	v_cvt_scalef32_pk_f32_fp4 v[0:1], v170, 1.0
	v_cvt_scalef32_pk_f32_fp4 v[2:3], v170, 1.0 op_sel:[1,0,0]
	v_cvt_scalef32_pk_f32_fp4 v[4:5], v170, 1.0 op_sel:[0,1,0]
	v_cvt_scalef32_pk_f32_fp4 v[6:7], v170, 1.0 op_sel:[1,1,0]
	v_cvt_scalef32_pk_f32_fp4 v[8:9], v171, 1.0
	v_cvt_scalef32_pk_f32_fp4 v[10:11], v171, 1.0 op_sel:[1,0,0]
	v_cvt_scalef32_pk_f32_fp4 v[12:13], v171, 1.0 op_sel:[0,1,0]
	v_cvt_scalef32_pk_f32_fp4 v[14:15], v171, 1.0 op_sel:[1,1,0]
	v_readlane_b32 s54, v90, 9
	s_lshl_b32 s56, s54, 9
	s_add_u32 s56, s64, s56
	s_addc_u32 s57, s65, 0
	global_load_dwordx2 v[170:171], v227, s[56:57]
	v_pk_fma_f32 v[130:131], v[0:1], s[0:1], v[130:131] op_sel_hi:[1,0,1]
	v_pk_fma_f32 v[138:139], v[2:3], s[0:1], v[138:139] op_sel_hi:[1,0,1]
	v_pk_fma_f32 v[140:141], v[4:5], s[0:1], v[140:141] op_sel_hi:[1,0,1]
	v_pk_fma_f32 v[142:143], v[6:7], s[0:1], v[142:143] op_sel_hi:[1,0,1]
	v_pk_fma_f32 v[128:129], v[8:9], s[0:1], v[128:129] op_sel_hi:[1,0,1]
	v_pk_fma_f32 v[132:133], v[10:11], s[0:1], v[132:133] op_sel_hi:[1,0,1]
	v_pk_fma_f32 v[134:135], v[12:13], s[0:1], v[134:135] op_sel_hi:[1,0,1]
	v_pk_fma_f32 v[136:137], v[14:15], s[0:1], v[136:137] op_sel_hi:[1,0,1]
	v_readlane_b32 s0, v167, 58
	s_waitcnt vmcnt(15)
	v_cvt_scalef32_pk_f32_fp4 v[0:1], v172, 1.0
	v_cvt_scalef32_pk_f32_fp4 v[2:3], v172, 1.0 op_sel:[1,0,0]
	v_cvt_scalef32_pk_f32_fp4 v[4:5], v172, 1.0 op_sel:[0,1,0]
	v_cvt_scalef32_pk_f32_fp4 v[6:7], v172, 1.0 op_sel:[1,1,0]
	v_cvt_scalef32_pk_f32_fp4 v[8:9], v173, 1.0
	v_cvt_scalef32_pk_f32_fp4 v[10:11], v173, 1.0 op_sel:[1,0,0]
	v_cvt_scalef32_pk_f32_fp4 v[12:13], v173, 1.0 op_sel:[0,1,0]
	v_cvt_scalef32_pk_f32_fp4 v[14:15], v173, 1.0 op_sel:[1,1,0]
	v_readlane_b32 s54, v90, 10
	s_lshl_b32 s56, s54, 9
	s_add_u32 s56, s64, s56
	s_addc_u32 s57, s65, 0
	global_load_dwordx2 v[172:173], v227, s[56:57]
	v_pk_fma_f32 v[130:131], v[0:1], s[0:1], v[130:131] op_sel_hi:[1,0,1]
	v_pk_fma_f32 v[138:139], v[2:3], s[0:1], v[138:139] op_sel_hi:[1,0,1]
	v_pk_fma_f32 v[140:141], v[4:5], s[0:1], v[140:141] op_sel_hi:[1,0,1]
	v_pk_fma_f32 v[142:143], v[6:7], s[0:1], v[142:143] op_sel_hi:[1,0,1]
	v_pk_fma_f32 v[128:129], v[8:9], s[0:1], v[128:129] op_sel_hi:[1,0,1]
	v_pk_fma_f32 v[132:133], v[10:11], s[0:1], v[132:133] op_sel_hi:[1,0,1]
	v_pk_fma_f32 v[134:135], v[12:13], s[0:1], v[134:135] op_sel_hi:[1,0,1]
	v_pk_fma_f32 v[136:137], v[14:15], s[0:1], v[136:137] op_sel_hi:[1,0,1]
	v_readlane_b32 s0, v167, 59
	s_waitcnt vmcnt(15)
	v_cvt_scalef32_pk_f32_fp4 v[0:1], v174, 1.0
	v_cvt_scalef32_pk_f32_fp4 v[2:3], v174, 1.0 op_sel:[1,0,0]
	v_cvt_scalef32_pk_f32_fp4 v[4:5], v174, 1.0 op_sel:[0,1,0]
	v_cvt_scalef32_pk_f32_fp4 v[6:7], v174, 1.0 op_sel:[1,1,0]
	v_cvt_scalef32_pk_f32_fp4 v[8:9], v175, 1.0
	v_cvt_scalef32_pk_f32_fp4 v[10:11], v175, 1.0 op_sel:[1,0,0]
	v_cvt_scalef32_pk_f32_fp4 v[12:13], v175, 1.0 op_sel:[0,1,0]
	v_cvt_scalef32_pk_f32_fp4 v[14:15], v175, 1.0 op_sel:[1,1,0]
	v_readlane_b32 s54, v90, 11
	s_lshl_b32 s56, s54, 9
	s_add_u32 s56, s64, s56
	s_addc_u32 s57, s65, 0
	global_load_dwordx2 v[174:175], v227, s[56:57]
	v_pk_fma_f32 v[130:131], v[0:1], s[0:1], v[130:131] op_sel_hi:[1,0,1]
	v_pk_fma_f32 v[138:139], v[2:3], s[0:1], v[138:139] op_sel_hi:[1,0,1]
	v_pk_fma_f32 v[140:141], v[4:5], s[0:1], v[140:141] op_sel_hi:[1,0,1]
	v_pk_fma_f32 v[142:143], v[6:7], s[0:1], v[142:143] op_sel_hi:[1,0,1]
	v_pk_fma_f32 v[128:129], v[8:9], s[0:1], v[128:129] op_sel_hi:[1,0,1]
	v_pk_fma_f32 v[132:133], v[10:11], s[0:1], v[132:133] op_sel_hi:[1,0,1]
	v_pk_fma_f32 v[134:135], v[12:13], s[0:1], v[134:135] op_sel_hi:[1,0,1]
	v_pk_fma_f32 v[136:137], v[14:15], s[0:1], v[136:137] op_sel_hi:[1,0,1]
	v_readlane_b32 s0, v167, 60
	s_waitcnt vmcnt(15)
; __device__ void peer_gather_phase(const Params& P, int l, bool do_store) {
;     ...
;         const int ea = __builtin_amdgcn_readlane(evs, kb + 2 * pr), eb = __builtin_amdgcn_readlane(evs, kb + 2 * pr + 1);
;         const uint2* up = (const uint2*)(U + (size_t)(uphi ? eb : ea) * 768);
;         u6[3 * pr] = up[0]; u6[3 * pr + 1] = up[1]; u6[3 * pr + 2] = up[2];
;     ...
; #pragma unroll
;       for (int j = 0; j < 8; ++j) {
;         const float a = __builtin_bit_cast(float, __builtin_amdgcn_readlane(__builtin_bit_cast(int, avec), kb + j));
;         const f32x2 aa = f32x2{a, a};
;         y[0] += aa * __builtin_amdgcn_cvt_scalef32_pk_f32_fp4(v8[j].x, 1.0f, 0); y[1] += aa * __builtin_amdgcn_cvt_scalef32_pk_f32_fp4(v8[j].x, 1.0f, 1);
;         y[2] += aa * __builtin_amdgcn_cvt_scalef32_pk_f32_fp4(v8[j].x, 1.0f, 2); y[3] += aa * __builtin_amdgcn_cvt_scalef32_pk_f32_fp4(v8[j].x, 1.0f, 3);
;         y[4] += aa * __builtin_amdgcn_cvt_scalef32_pk_f32_fp4(v8[j].y, 1.0f, 0); y[5] += aa * __builtin_amdgcn_cvt_scalef32_pk_f32_fp4(v8[j].y, 1.0f, 1);
;         y[6] += aa * __builtin_amdgcn_cvt_scalef32_pk_f32_fp4(v8[j].y, 1.0f, 2); y[7] += aa * __builtin_amdgcn_cvt_scalef32_pk_f32_fp4(v8[j].y, 1.0f, 3);
;       }
	v_cvt_scalef32_pk_f32_fp4 v[0:1], v180, 1.0
	v_cvt_scalef32_pk_f32_fp4 v[2:3], v180, 1.0 op_sel:[1,0,0]
	v_cvt_scalef32_pk_f32_fp4 v[4:5], v180, 1.0 op_sel:[0,1,0]
	v_cvt_scalef32_pk_f32_fp4 v[6:7], v180, 1.0 op_sel:[1,1,0]
	v_cvt_scalef32_pk_f32_fp4 v[8:9], v181, 1.0
	v_cvt_scalef32_pk_f32_fp4 v[10:11], v181, 1.0 op_sel:[1,0,0]
	v_cvt_scalef32_pk_f32_fp4 v[12:13], v181, 1.0 op_sel:[0,1,0]
	v_cvt_scalef32_pk_f32_fp4 v[14:15], v181, 1.0 op_sel:[1,1,0]
	v_readlane_b32 s54, v90, 12
	s_lshl_b32 s56, s54, 9
	s_add_u32 s56, s64, s56
	s_addc_u32 s57, s65, 0
	global_load_dwordx2 v[180:181], v227, s[56:57]
	v_pk_fma_f32 v[130:131], v[0:1], s[0:1], v[130:131] op_sel_hi:[1,0,1]
	v_pk_fma_f32 v[138:139], v[2:3], s[0:1], v[138:139] op_sel_hi:[1,0,1]
	v_pk_fma_f32 v[140:141], v[4:5], s[0:1], v[140:141] op_sel_hi:[1,0,1]
	v_pk_fma_f32 v[142:143], v[6:7], s[0:1], v[142:143] op_sel_hi:[1,0,1]
	v_pk_fma_f32 v[128:129], v[8:9], s[0:1], v[128:129] op_sel_hi:[1,0,1]
	v_pk_fma_f32 v[132:133], v[10:11], s[0:1], v[132:133] op_sel_hi:[1,0,1]
	v_pk_fma_f32 v[134:135], v[12:13], s[0:1], v[134:135] op_sel_hi:[1,0,1]
	v_pk_fma_f32 v[136:137], v[14:15], s[0:1], v[136:137] op_sel_hi:[1,0,1]
	v_readlane_b32 s0, v167, 61
	s_waitcnt vmcnt(15)
	v_cvt_scalef32_pk_f32_fp4 v[0:1], v182, 1.0
	v_cvt_scalef32_pk_f32_fp4 v[2:3], v182, 1.0 op_sel:[1,0,0]
	v_cvt_scalef32_pk_f32_fp4 v[4:5], v182, 1.0 op_sel:[0,1,0]
	v_cvt_scalef32_pk_f32_fp4 v[6:7], v182, 1.0 op_sel:[1,1,0]
	v_cvt_scalef32_pk_f32_fp4 v[8:9], v183, 1.0
	v_cvt_scalef32_pk_f32_fp4 v[10:11], v183, 1.0 op_sel:[1,0,0]
	v_cvt_scalef32_pk_f32_fp4 v[12:13], v183, 1.0 op_sel:[0,1,0]
	v_cvt_scalef32_pk_f32_fp4 v[14:15], v183, 1.0 op_sel:[1,1,0]
	v_readlane_b32 s54, v90, 13
	s_lshl_b32 s56, s54, 9
	s_add_u32 s56, s64, s56
	s_addc_u32 s57, s65, 0
	global_load_dwordx2 v[182:183], v227, s[56:57]
	v_pk_fma_f32 v[130:131], v[0:1], s[0:1], v[130:131] op_sel_hi:[1,0,1]
	v_pk_fma_f32 v[138:139], v[2:3], s[0:1], v[138:139] op_sel_hi:[1,0,1]
	v_pk_fma_f32 v[140:141], v[4:5], s[0:1], v[140:141] op_sel_hi:[1,0,1]
	v_pk_fma_f32 v[142:143], v[6:7], s[0:1], v[142:143] op_sel_hi:[1,0,1]
	v_pk_fma_f32 v[128:129], v[8:9], s[0:1], v[128:129] op_sel_hi:[1,0,1]
	v_pk_fma_f32 v[132:133], v[10:11], s[0:1], v[132:133] op_sel_hi:[1,0,1]
	v_pk_fma_f32 v[134:135], v[12:13], s[0:1], v[134:135] op_sel_hi:[1,0,1]
	v_pk_fma_f32 v[136:137], v[14:15], s[0:1], v[136:137] op_sel_hi:[1,0,1]
	v_readlane_b32 s0, v167, 62
	s_waitcnt vmcnt(15)
	v_cvt_scalef32_pk_f32_fp4 v[0:1], v184, 1.0
	v_cvt_scalef32_pk_f32_fp4 v[2:3], v184, 1.0 op_sel:[1,0,0]
	v_cvt_scalef32_pk_f32_fp4 v[4:5], v184, 1.0 op_sel:[0,1,0]
	v_cvt_scalef32_pk_f32_fp4 v[6:7], v184, 1.0 op_sel:[1,1,0]
	v_cvt_scalef32_pk_f32_fp4 v[8:9], v185, 1.0
	v_cvt_scalef32_pk_f32_fp4 v[10:11], v185, 1.0 op_sel:[1,0,0]
	v_cvt_scalef32_pk_f32_fp4 v[12:13], v185, 1.0 op_sel:[0,1,0]
	v_cvt_scalef32_pk_f32_fp4 v[14:15], v185, 1.0 op_sel:[1,1,0]
	v_readlane_b32 s54, v90, 14
	s_lshl_b32 s56, s54, 9
	s_add_u32 s56, s64, s56
	s_addc_u32 s57, s65, 0
	global_load_dwordx2 v[184:185], v227, s[56:57]
	v_pk_fma_f32 v[130:131], v[0:1], s[0:1], v[130:131] op_sel_hi:[1,0,1]
	v_pk_fma_f32 v[138:139], v[2:3], s[0:1], v[138:139] op_sel_hi:[1,0,1]
	v_pk_fma_f32 v[140:141], v[4:5], s[0:1], v[140:141] op_sel_hi:[1,0,1]
	v_pk_fma_f32 v[142:143], v[6:7], s[0:1], v[142:143] op_sel_hi:[1,0,1]
	v_pk_fma_f32 v[128:129], v[8:9], s[0:1], v[128:129] op_sel_hi:[1,0,1]
	v_pk_fma_f32 v[132:133], v[10:11], s[0:1], v[132:133] op_sel_hi:[1,0,1]
	v_pk_fma_f32 v[134:135], v[12:13], s[0:1], v[134:135] op_sel_hi:[1,0,1]
	v_pk_fma_f32 v[136:137], v[14:15], s[0:1], v[136:137] op_sel_hi:[1,0,1]
	v_readlane_b32 s0, v167, 63
	s_waitcnt vmcnt(15)
	v_cvt_scalef32_pk_f32_fp4 v[0:1], v186, 1.0
	v_cvt_scalef32_pk_f32_fp4 v[2:3], v186, 1.0 op_sel:[1,0,0]
	v_cvt_scalef32_pk_f32_fp4 v[4:5], v186, 1.0 op_sel:[0,1,0]
	v_cvt_scalef32_pk_f32_fp4 v[6:7], v186, 1.0 op_sel:[1,1,0]
	v_cvt_scalef32_pk_f32_fp4 v[8:9], v187, 1.0
	v_cvt_scalef32_pk_f32_fp4 v[10:11], v187, 1.0 op_sel:[1,0,0]
	v_cvt_scalef32_pk_f32_fp4 v[12:13], v187, 1.0 op_sel:[0,1,0]
	v_cvt_scalef32_pk_f32_fp4 v[14:15], v187, 1.0 op_sel:[1,1,0]
	v_readlane_b32 s54, v90, 15
	s_lshl_b32 s56, s54, 9
	s_add_u32 s56, s64, s56
	s_addc_u32 s57, s65, 0
	global_load_dwordx2 v[186:187], v227, s[56:57]
	v_pk_fma_f32 v[130:131], v[0:1], s[0:1], v[130:131] op_sel_hi:[1,0,1]
	v_pk_fma_f32 v[138:139], v[2:3], s[0:1], v[138:139] op_sel_hi:[1,0,1]
	v_pk_fma_f32 v[140:141], v[4:5], s[0:1], v[140:141] op_sel_hi:[1,0,1]
	v_pk_fma_f32 v[142:143], v[6:7], s[0:1], v[142:143] op_sel_hi:[1,0,1]
	v_pk_fma_f32 v[128:129], v[8:9], s[0:1], v[128:129] op_sel_hi:[1,0,1]
	v_pk_fma_f32 v[132:133], v[10:11], s[0:1], v[132:133] op_sel_hi:[1,0,1]
	v_pk_fma_f32 v[134:135], v[12:13], s[0:1], v[134:135] op_sel_hi:[1,0,1]
	v_pk_fma_f32 v[136:137], v[14:15], s[0:1], v[136:137] op_sel_hi:[1,0,1]
	v_readlane_b32 s54, v90, 16
	v_readlane_b32 s55, v90, 17
	s_mul_i32 s0, s54, 0x300
	s_mul_i32 s1, s55, 0x300
	v_add_u32_e32 v167, s0, v195
	s_and_saveexec_b64 s[98:99], s[40:41]
	v_add_u32_e32 v167, s1, v195
	s_mov_b64 exec, s[98:99]
	s_waitcnt vmcnt(48)
; __device__ void peer_gather_phase(const Params& P, int l, bool do_store) {
;     ...
;         const int ea = __builtin_amdgcn_readlane(evs, kb + 2 * pr), eb = __builtin_amdgcn_readlane(evs, kb + 2 * pr + 1);
;         const uint2* up = (const uint2*)(U + (size_t)(uphi ? eb : ea) * 768);
;         u6[3 * pr] = up[0]; u6[3 * pr + 1] = up[1]; u6[3 * pr + 2] = up[2];
;     ...
;         v6u_t qv; qv[0] = u6[3 * pr].x; qv[1] = u6[3 * pr].y; qv[2] = u6[3 * pr + 1].x; qv[3] = u6[3 * pr + 1].y; qv[4] = u6[3 * pr + 2].x; qv[5] = u6[3 * pr + 2].y;
;         const v32f_t wv = __builtin_amdgcn_cvt_scalef32_pk32_f32_fp6(qv, 1.0f);
;         f32x2 a2 = f32x2{0.f, 0.f};
; #pragma unroll
;         for (int i = 0; i < 16; ++i) a2 += f32x2{wv[2 * i], wv[2 * i + 1]} * xu[i];
;         float hs = a2.x + a2.y;
	v_cvt_scalef32_pk32_f32_fp6 v[0:31], v[50:55], 1.0
	global_load_dwordx2 v[54:55], v167, s[62:63] offset:16
	global_load_dwordx4 v[50:53], v167, s[62:63]
	v_pk_mul_f32 v[246:247], v[0:1], v[96:97]
	v_pk_mul_f32 v[254:255], v[2:3], v[98:99]
	v_pk_mul_f32 v[160:161], v[4:5], v[100:101]
	v_pk_fma_f32 v[246:247], v[6:7], v[102:103], v[246:247]
	v_pk_fma_f32 v[254:255], v[8:9], v[104:105], v[254:255]
	v_pk_fma_f32 v[160:161], v[10:11], v[106:107], v[160:161]
	v_pk_fma_f32 v[246:247], v[12:13], v[108:109], v[246:247]
	v_pk_fma_f32 v[254:255], v[14:15], v[110:111], v[254:255]
	v_pk_fma_f32 v[160:161], v[16:17], v[112:113], v[160:161]
	v_pk_fma_f32 v[246:247], v[18:19], v[114:115], v[246:247]
	v_pk_fma_f32 v[254:255], v[20:21], v[116:117], v[254:255]
	v_pk_fma_f32 v[160:161], v[22:23], v[118:119], v[160:161]
	v_pk_fma_f32 v[246:247], v[24:25], v[120:121], v[246:247]
	v_pk_fma_f32 v[254:255], v[26:27], v[122:123], v[254:255]
	v_pk_fma_f32 v[160:161], v[28:29], v[124:125], v[160:161]
	v_pk_fma_f32 v[246:247], v[30:31], v[126:127], v[246:247]
	v_pk_add_f32 v[254:255], v[254:255], v[160:161]
	s_nop 0
	v_pk_add_f32 v[246:247], v[246:247], v[254:255]
	s_nop 0
	v_add_f32_e32 v162, v246, v247
	v_readlane_b32 s54, v90, 18
	v_readlane_b32 s55, v90, 19
	s_mul_i32 s0, s54, 0x300
	s_mul_i32 s1, s55, 0x300
	v_add_u32_e32 v167, s0, v195
	s_and_saveexec_b64 s[98:99], s[40:41]
	v_add_u32_e32 v167, s1, v195
	s_mov_b64 exec, s[98:99]
	s_waitcnt vmcnt(48)
	v_cvt_scalef32_pk32_f32_fp6 v[0:31], v[44:49], 1.0
	global_load_dwordx2 v[48:49], v167, s[62:63] offset:16
	global_load_dwordx4 v[44:47], v167, s[62:63]
	v_pk_mul_f32 v[246:247], v[0:1], v[96:97]
	v_pk_mul_f32 v[254:255], v[2:3], v[98:99]
	v_pk_mul_f32 v[160:161], v[4:5], v[100:101]
	v_pk_fma_f32 v[246:247], v[6:7], v[102:103], v[246:247]
	v_pk_fma_f32 v[254:255], v[8:9], v[104:105], v[254:255]
	v_pk_fma_f32 v[160:161], v[10:11], v[106:107], v[160:161]
	v_pk_fma_f32 v[246:247], v[12:13], v[108:109], v[246:247]
	v_pk_fma_f32 v[254:255], v[14:15], v[110:111], v[254:255]
	v_pk_fma_f32 v[160:161], v[16:17], v[112:113], v[160:161]
	v_pk_fma_f32 v[246:247], v[18:19], v[114:115], v[246:247]
	v_pk_fma_f32 v[254:255], v[20:21], v[116:117], v[254:255]
	v_pk_fma_f32 v[160:161], v[22:23], v[118:119], v[160:161]
	v_pk_fma_f32 v[246:247], v[24:25], v[120:121], v[246:247]
	v_pk_fma_f32 v[254:255], v[26:27], v[122:123], v[254:255]
	v_pk_fma_f32 v[160:161], v[28:29], v[124:125], v[160:161]
	v_pk_fma_f32 v[246:247], v[30:31], v[126:127], v[246:247]
	v_pk_add_f32 v[254:255], v[254:255], v[160:161]
	s_nop 0
	v_pk_add_f32 v[246:247], v[246:247], v[254:255]
	s_nop 0
	v_add_f32_e32 v163, v246, v247
	v_readlane_b32 s54, v90, 20
	v_readlane_b32 s55, v90, 21
	s_mul_i32 s0, s54, 0x300
	s_mul_i32 s1, s55, 0x300
	v_add_u32_e32 v167, s0, v195
	s_and_saveexec_b64 s[98:99], s[40:41]
	v_add_u32_e32 v167, s1, v195
	s_mov_b64 exec, s[98:99]
	s_waitcnt vmcnt(48)
	v_cvt_scalef32_pk32_f32_fp6 v[0:31], v[38:43], 1.0
	global_load_dwordx2 v[42:43], v167, s[62:63] offset:16
	global_load_dwordx4 v[38:41], v167, s[62:63]
	v_pk_mul_f32 v[246:247], v[0:1], v[96:97]
	v_pk_mul_f32 v[254:255], v[2:3], v[98:99]
	v_pk_mul_f32 v[160:161], v[4:5], v[100:101]
	v_pk_fma_f32 v[246:247], v[6:7], v[102:103], v[246:247]
	v_pk_fma_f32 v[254:255], v[8:9], v[104:105], v[254:255]
	v_pk_fma_f32 v[160:161], v[10:11], v[106:107], v[160:161]
	v_pk_fma_f32 v[246:247], v[12:13], v[108:109], v[246:247]
	v_pk_fma_f32 v[254:255], v[14:15], v[110:111], v[254:255]
	v_pk_fma_f32 v[160:161], v[16:17], v[112:113], v[160:161]
	v_pk_fma_f32 v[246:247], v[18:19], v[114:115], v[246:247]
	v_pk_fma_f32 v[254:255], v[20:21], v[116:117], v[254:255]
	v_pk_fma_f32 v[160:161], v[22:23], v[118:119], v[160:161]
	v_pk_fma_f32 v[246:247], v[24:25], v[120:121], v[246:247]
	v_pk_fma_f32 v[254:255], v[26:27], v[122:123], v[254:255]
	v_pk_fma_f32 v[160:161], v[28:29], v[124:125], v[160:161]
	v_pk_fma_f32 v[246:247], v[30:31], v[126:127], v[246:247]
	v_pk_add_f32 v[254:255], v[254:255], v[160:161]
	s_nop 0
	v_pk_add_f32 v[246:247], v[246:247], v[254:255]
	s_nop 0
	v_add_f32_e32 v164, v246, v247
	v_readlane_b32 s54, v90, 22
	v_readlane_b32 s55, v90, 23
	s_mul_i32 s0, s54, 0x300
	s_mul_i32 s1, s55, 0x300
	v_add_u32_e32 v167, s0, v195
	s_and_saveexec_b64 s[98:99], s[40:41]
	v_add_u32_e32 v167, s1, v195
	s_mov_b64 exec, s[98:99]
	s_waitcnt vmcnt(48)
; __device__ void peer_gather_phase(const Params& P, int l, bool do_store) {
;     ...
;         v6u_t qv; qv[0] = u6[3 * pr].x; qv[1] = u6[3 * pr].y; qv[2] = u6[3 * pr + 1].x; qv[3] = u6[3 * pr + 1].y; qv[4] = u6[3 * pr + 2].x; qv[5] = u6[3 * pr + 2].y;
;         const v32f_t wv = __builtin_amdgcn_cvt_scalef32_pk32_f32_fp6(qv, 1.0f);
;         f32x2 a2 = f32x2{0.f, 0.f};
; #pragma unroll
;         for (int i = 0; i < 16; ++i) a2 += f32x2{wv[2 * i], wv[2 * i + 1]} * xu[i];
;         float hs = a2.x + a2.y;
;         hs += dpp_row_shr(hs, 1); hs += dpp_row_shr(hs, 2); hs += dpp_row_shr(hs, 4); hs += dpp_row_shr(hs, 8);
;         hs += __builtin_bit_cast(float, __builtin_amdgcn_update_dpp(0, __builtin_bit_cast(int, hs), 0x142, 0xa, 0xf, false));
;         const float da = __builtin_bit_cast(float, __builtin_amdgcn_readlane(__builtin_bit_cast(int, hs), 31));
;         const float db = __builtin_bit_cast(float, __builtin_amdgcn_readlane(__builtin_bit_cast(int, hs), 63));
;         dvec = (lane == kb + 2 * pr) ? da : dvec;
;         dvec = (lane == kb + 2 * pr + 1) ? db : dvec;
	v_cvt_scalef32_pk32_f32_fp6 v[0:31], v[32:37], 1.0
	global_load_dwordx2 v[36:37], v167, s[62:63] offset:16
	global_load_dwordx4 v[32:35], v167, s[62:63]
	v_pk_mul_f32 v[246:247], v[0:1], v[96:97]
	v_pk_mul_f32 v[254:255], v[2:3], v[98:99]
	v_pk_mul_f32 v[160:161], v[4:5], v[100:101]
	v_pk_fma_f32 v[246:247], v[6:7], v[102:103], v[246:247]
	v_pk_fma_f32 v[254:255], v[8:9], v[104:105], v[254:255]
	v_pk_fma_f32 v[160:161], v[10:11], v[106:107], v[160:161]
	v_pk_fma_f32 v[246:247], v[12:13], v[108:109], v[246:247]
	v_pk_fma_f32 v[254:255], v[14:15], v[110:111], v[254:255]
	v_pk_fma_f32 v[160:161], v[16:17], v[112:113], v[160:161]
	v_pk_fma_f32 v[246:247], v[18:19], v[114:115], v[246:247]
	v_pk_fma_f32 v[254:255], v[20:21], v[116:117], v[254:255]
	v_pk_fma_f32 v[160:161], v[22:23], v[118:119], v[160:161]
	v_pk_fma_f32 v[246:247], v[24:25], v[120:121], v[246:247]
	v_pk_fma_f32 v[254:255], v[26:27], v[122:123], v[254:255]
	v_pk_fma_f32 v[160:161], v[28:29], v[124:125], v[160:161]
	v_pk_fma_f32 v[246:247], v[30:31], v[126:127], v[246:247]
	v_pk_add_f32 v[254:255], v[254:255], v[160:161]
	s_nop 0
	v_pk_add_f32 v[246:247], v[246:247], v[254:255]
	s_nop 0
	v_add_f32_e32 v165, v246, v247
	v_add_f32_dpp v162, v162, v162 row_shr:1 row_mask:0xf bank_mask:0xf bound_ctrl:1
	v_add_f32_dpp v163, v163, v163 row_shr:1 row_mask:0xf bank_mask:0xf bound_ctrl:1
	v_add_f32_dpp v164, v164, v164 row_shr:1 row_mask:0xf bank_mask:0xf bound_ctrl:1
	v_add_f32_dpp v165, v165, v165 row_shr:1 row_mask:0xf bank_mask:0xf bound_ctrl:1
	v_add_f32_dpp v162, v162, v162 row_shr:2 row_mask:0xf bank_mask:0xf bound_ctrl:1
	v_add_f32_dpp v163, v163, v163 row_shr:2 row_mask:0xf bank_mask:0xf bound_ctrl:1
	v_add_f32_dpp v164, v164, v164 row_shr:2 row_mask:0xf bank_mask:0xf bound_ctrl:1
	v_add_f32_dpp v165, v165, v165 row_shr:2 row_mask:0xf bank_mask:0xf bound_ctrl:1
	v_add_f32_dpp v162, v162, v162 row_shr:4 row_mask:0xf bank_mask:0xf bound_ctrl:1
	v_add_f32_dpp v163, v163, v163 row_shr:4 row_mask:0xf bank_mask:0xf bound_ctrl:1
	v_add_f32_dpp v164, v164, v164 row_shr:4 row_mask:0xf bank_mask:0xf bound_ctrl:1
	v_add_f32_dpp v165, v165, v165 row_shr:4 row_mask:0xf bank_mask:0xf bound_ctrl:1
	v_add_f32_dpp v162, v162, v162 row_shr:8 row_mask:0xf bank_mask:0xf bound_ctrl:1
	v_add_f32_dpp v163, v163, v163 row_shr:8 row_mask:0xf bank_mask:0xf bound_ctrl:1
	v_add_f32_dpp v164, v164, v164 row_shr:8 row_mask:0xf bank_mask:0xf bound_ctrl:1
	v_add_f32_dpp v165, v165, v165 row_shr:8 row_mask:0xf bank_mask:0xf bound_ctrl:1
	v_add_f32_dpp v162, v162, v162 row_bcast:15 row_mask:0xa bank_mask:0xf
	v_add_f32_dpp v163, v163, v163 row_bcast:15 row_mask:0xa bank_mask:0xf
	v_add_f32_dpp v164, v164, v164 row_bcast:15 row_mask:0xa bank_mask:0xf
	v_add_f32_dpp v165, v165, v165 row_bcast:15 row_mask:0xa bank_mask:0xf
	s_mov_b64 s[98:99], exec
	s_mov_b32 exec_lo, 0x80000000
	s_mov_b32 exec_hi, 0x80000000
	ds_write_b32 v74, v162
	ds_write_b32 v74, v163 offset:8
	ds_write_b32 v74, v164 offset:16
	ds_write_b32 v74, v165 offset:24
	s_mov_b64 exec, s[98:99]
	v_readlane_b32 s54, v90, 24
	v_readlane_b32 s55, v90, 25
	s_mul_i32 s0, s54, 0x300
	s_mul_i32 s1, s55, 0x300
	v_add_u32_e32 v167, s0, v195
	s_and_saveexec_b64 s[98:99], s[40:41]
	v_add_u32_e32 v167, s1, v195
	s_mov_b64 exec, s[98:99]
	s_waitcnt vmcnt(48)
	v_cvt_scalef32_pk32_f32_fp6 v[0:31], v[196:201], 1.0
	global_load_dwordx2 v[200:201], v167, s[62:63] offset:16
	global_load_dwordx4 v[196:199], v167, s[62:63]
	v_pk_mul_f32 v[246:247], v[0:1], v[96:97]
	v_pk_mul_f32 v[254:255], v[2:3], v[98:99]
	v_pk_mul_f32 v[160:161], v[4:5], v[100:101]
	v_pk_fma_f32 v[246:247], v[6:7], v[102:103], v[246:247]
	v_pk_fma_f32 v[254:255], v[8:9], v[104:105], v[254:255]
	v_pk_fma_f32 v[160:161], v[10:11], v[106:107], v[160:161]
	v_pk_fma_f32 v[246:247], v[12:13], v[108:109], v[246:247]
	v_pk_fma_f32 v[254:255], v[14:15], v[110:111], v[254:255]
	v_pk_fma_f32 v[160:161], v[16:17], v[112:113], v[160:161]
	v_pk_fma_f32 v[246:247], v[18:19], v[114:115], v[246:247]
	v_pk_fma_f32 v[254:255], v[20:21], v[116:117], v[254:255]
	v_pk_fma_f32 v[160:161], v[22:23], v[118:119], v[160:161]
	v_pk_fma_f32 v[246:247], v[24:25], v[120:121], v[246:247]
	v_pk_fma_f32 v[254:255], v[26:27], v[122:123], v[254:255]
	v_pk_fma_f32 v[160:161], v[28:29], v[124:125], v[160:161]
	v_pk_fma_f32 v[246:247], v[30:31], v[126:127], v[246:247]
	v_pk_add_f32 v[254:255], v[254:255], v[160:161]
	s_nop 0
	v_pk_add_f32 v[246:247], v[246:247], v[254:255]
	s_nop 0
	v_add_f32_e32 v162, v246, v247
	v_readlane_b32 s54, v90, 26
	v_readlane_b32 s55, v90, 27
	s_mul_i32 s0, s54, 0x300
	s_mul_i32 s1, s55, 0x300
	v_add_u32_e32 v167, s0, v195
	s_and_saveexec_b64 s[98:99], s[40:41]
	v_add_u32_e32 v167, s1, v195
	s_mov_b64 exec, s[98:99]
	s_waitcnt vmcnt(48)
	v_cvt_scalef32_pk32_f32_fp6 v[0:31], v[228:233], 1.0
	global_load_dwordx2 v[232:233], v167, s[62:63] offset:16
	global_load_dwordx4 v[228:231], v167, s[62:63]
	v_pk_mul_f32 v[246:247], v[0:1], v[96:97]
	v_pk_mul_f32 v[254:255], v[2:3], v[98:99]
	v_pk_mul_f32 v[160:161], v[4:5], v[100:101]
	v_pk_fma_f32 v[246:247], v[6:7], v[102:103], v[246:247]
	v_pk_fma_f32 v[254:255], v[8:9], v[104:105], v[254:255]
	v_pk_fma_f32 v[160:161], v[10:11], v[106:107], v[160:161]
	v_pk_fma_f32 v[246:247], v[12:13], v[108:109], v[246:247]
	v_pk_fma_f32 v[254:255], v[14:15], v[110:111], v[254:255]
	v_pk_fma_f32 v[160:161], v[16:17], v[112:113], v[160:161]
	v_pk_fma_f32 v[246:247], v[18:19], v[114:115], v[246:247]
	v_pk_fma_f32 v[254:255], v[20:21], v[116:117], v[254:255]
	v_pk_fma_f32 v[160:161], v[22:23], v[118:119], v[160:161]
	v_pk_fma_f32 v[246:247], v[24:25], v[120:121], v[246:247]
	v_pk_fma_f32 v[254:255], v[26:27], v[122:123], v[254:255]
	v_pk_fma_f32 v[160:161], v[28:29], v[124:125], v[160:161]
	v_pk_fma_f32 v[246:247], v[30:31], v[126:127], v[246:247]
	v_pk_add_f32 v[254:255], v[254:255], v[160:161]
	s_nop 0
	v_pk_add_f32 v[246:247], v[246:247], v[254:255]
	s_nop 0
	v_add_f32_e32 v163, v246, v247
	v_readlane_b32 s54, v90, 28
	v_readlane_b32 s55, v90, 29
	s_mul_i32 s0, s54, 0x300
	s_mul_i32 s1, s55, 0x300
	v_add_u32_e32 v167, s0, v195
	s_and_saveexec_b64 s[98:99], s[40:41]
	v_add_u32_e32 v167, s1, v195
	s_mov_b64 exec, s[98:99]
	s_waitcnt vmcnt(48)
; __device__ void peer_gather_phase(const Params& P, int l, bool do_store) {
;     ...
;         v6u_t qv; qv[0] = u6[3 * pr].x; qv[1] = u6[3 * pr].y; qv[2] = u6[3 * pr + 1].x; qv[3] = u6[3 * pr + 1].y; qv[4] = u6[3 * pr + 2].x; qv[5] = u6[3 * pr + 2].y;
;         const v32f_t wv = __builtin_amdgcn_cvt_scalef32_pk32_f32_fp6(qv, 1.0f);
;         f32x2 a2 = f32x2{0.f, 0.f};
; #pragma unroll
;         for (int i = 0; i < 16; ++i) a2 += f32x2{wv[2 * i], wv[2 * i + 1]} * xu[i];
;         float hs = a2.x + a2.y;
;         hs += dpp_row_shr(hs, 1); hs += dpp_row_shr(hs, 2); hs += dpp_row_shr(hs, 4); hs += dpp_row_shr(hs, 8);
;         hs += __builtin_bit_cast(float, __builtin_amdgcn_update_dpp(0, __builtin_bit_cast(int, hs), 0x142, 0xa, 0xf, false));
;         const float da = __builtin_bit_cast(float, __builtin_amdgcn_readlane(__builtin_bit_cast(int, hs), 31));
;         const float db = __builtin_bit_cast(float, __builtin_amdgcn_readlane(__builtin_bit_cast(int, hs), 63));
;         dvec = (lane == kb + 2 * pr) ? da : dvec;
;         dvec = (lane == kb + 2 * pr + 1) ? db : dvec;
	v_cvt_scalef32_pk32_f32_fp6 v[0:31], v[234:239], 1.0
	global_load_dwordx2 v[238:239], v167, s[62:63] offset:16
	global_load_dwordx4 v[234:237], v167, s[62:63]
	v_pk_mul_f32 v[246:247], v[0:1], v[96:97]
	v_pk_mul_f32 v[254:255], v[2:3], v[98:99]
	v_pk_mul_f32 v[160:161], v[4:5], v[100:101]
	v_pk_fma_f32 v[246:247], v[6:7], v[102:103], v[246:247]
	v_pk_fma_f32 v[254:255], v[8:9], v[104:105], v[254:255]
	v_pk_fma_f32 v[160:161], v[10:11], v[106:107], v[160:161]
	v_pk_fma_f32 v[246:247], v[12:13], v[108:109], v[246:247]
	v_pk_fma_f32 v[254:255], v[14:15], v[110:111], v[254:255]
	v_pk_fma_f32 v[160:161], v[16:17], v[112:113], v[160:161]
	v_pk_fma_f32 v[246:247], v[18:19], v[114:115], v[246:247]
	v_pk_fma_f32 v[254:255], v[20:21], v[116:117], v[254:255]
	v_pk_fma_f32 v[160:161], v[22:23], v[118:119], v[160:161]
	v_pk_fma_f32 v[246:247], v[24:25], v[120:121], v[246:247]
	v_pk_fma_f32 v[254:255], v[26:27], v[122:123], v[254:255]
	v_pk_fma_f32 v[160:161], v[28:29], v[124:125], v[160:161]
	v_pk_fma_f32 v[246:247], v[30:31], v[126:127], v[246:247]
	v_pk_add_f32 v[254:255], v[254:255], v[160:161]
	s_nop 0
	v_pk_add_f32 v[246:247], v[246:247], v[254:255]
	s_nop 0
	v_add_f32_e32 v164, v246, v247
	v_readlane_b32 s54, v90, 30
	v_readlane_b32 s55, v90, 31
	s_mul_i32 s0, s54, 0x300
	s_mul_i32 s1, s55, 0x300
	v_add_u32_e32 v167, s0, v195
	s_and_saveexec_b64 s[98:99], s[40:41]
	v_add_u32_e32 v167, s1, v195
	s_mov_b64 exec, s[98:99]
	s_waitcnt vmcnt(48)
	v_cvt_scalef32_pk32_f32_fp6 v[0:31], v[240:245], 1.0
	global_load_dwordx2 v[244:245], v167, s[62:63] offset:16
	global_load_dwordx4 v[240:243], v167, s[62:63]
	v_pk_mul_f32 v[246:247], v[0:1], v[96:97]
	v_pk_mul_f32 v[254:255], v[2:3], v[98:99]
	v_pk_mul_f32 v[160:161], v[4:5], v[100:101]
	v_pk_fma_f32 v[246:247], v[6:7], v[102:103], v[246:247]
	v_pk_fma_f32 v[254:255], v[8:9], v[104:105], v[254:255]
	v_pk_fma_f32 v[160:161], v[10:11], v[106:107], v[160:161]
	v_pk_fma_f32 v[246:247], v[12:13], v[108:109], v[246:247]
	v_pk_fma_f32 v[254:255], v[14:15], v[110:111], v[254:255]
	v_pk_fma_f32 v[160:161], v[16:17], v[112:113], v[160:161]
	v_pk_fma_f32 v[246:247], v[18:19], v[114:115], v[246:247]
	v_pk_fma_f32 v[254:255], v[20:21], v[116:117], v[254:255]
	v_pk_fma_f32 v[160:161], v[22:23], v[118:119], v[160:161]
	v_pk_fma_f32 v[246:247], v[24:25], v[120:121], v[246:247]
	v_pk_fma_f32 v[254:255], v[26:27], v[122:123], v[254:255]
	v_pk_fma_f32 v[160:161], v[28:29], v[124:125], v[160:161]
	v_pk_fma_f32 v[246:247], v[30:31], v[126:127], v[246:247]
	v_pk_add_f32 v[254:255], v[254:255], v[160:161]
	s_nop 0
	v_pk_add_f32 v[246:247], v[246:247], v[254:255]
	s_nop 0
	v_add_f32_e32 v165, v246, v247
	v_add_f32_dpp v162, v162, v162 row_shr:1 row_mask:0xf bank_mask:0xf bound_ctrl:1
	v_add_f32_dpp v163, v163, v163 row_shr:1 row_mask:0xf bank_mask:0xf bound_ctrl:1
	v_add_f32_dpp v164, v164, v164 row_shr:1 row_mask:0xf bank_mask:0xf bound_ctrl:1
	v_add_f32_dpp v165, v165, v165 row_shr:1 row_mask:0xf bank_mask:0xf bound_ctrl:1
	v_add_f32_dpp v162, v162, v162 row_shr:2 row_mask:0xf bank_mask:0xf bound_ctrl:1
	v_add_f32_dpp v163, v163, v163 row_shr:2 row_mask:0xf bank_mask:0xf bound_ctrl:1
	v_add_f32_dpp v164, v164, v164 row_shr:2 row_mask:0xf bank_mask:0xf bound_ctrl:1
	v_add_f32_dpp v165, v165, v165 row_shr:2 row_mask:0xf bank_mask:0xf bound_ctrl:1
	v_add_f32_dpp v162, v162, v162 row_shr:4 row_mask:0xf bank_mask:0xf bound_ctrl:1
	v_add_f32_dpp v163, v163, v163 row_shr:4 row_mask:0xf bank_mask:0xf bound_ctrl:1
	v_add_f32_dpp v164, v164, v164 row_shr:4 row_mask:0xf bank_mask:0xf bound_ctrl:1
	v_add_f32_dpp v165, v165, v165 row_shr:4 row_mask:0xf bank_mask:0xf bound_ctrl:1
	v_add_f32_dpp v162, v162, v162 row_shr:8 row_mask:0xf bank_mask:0xf bound_ctrl:1
	v_add_f32_dpp v163, v163, v163 row_shr:8 row_mask:0xf bank_mask:0xf bound_ctrl:1
	v_add_f32_dpp v164, v164, v164 row_shr:8 row_mask:0xf bank_mask:0xf bound_ctrl:1
	v_add_f32_dpp v165, v165, v165 row_shr:8 row_mask:0xf bank_mask:0xf bound_ctrl:1
	v_add_f32_dpp v162, v162, v162 row_bcast:15 row_mask:0xa bank_mask:0xf
	v_add_f32_dpp v163, v163, v163 row_bcast:15 row_mask:0xa bank_mask:0xf
	v_add_f32_dpp v164, v164, v164 row_bcast:15 row_mask:0xa bank_mask:0xf
	v_add_f32_dpp v165, v165, v165 row_bcast:15 row_mask:0xa bank_mask:0xf
	s_mov_b64 s[98:99], exec
	s_mov_b32 exec_lo, 0x80000000
	s_mov_b32 exec_hi, 0x80000000
	ds_write_b32 v74, v162 offset:32
	ds_write_b32 v74, v163 offset:40
	ds_write_b32 v74, v164 offset:48
	ds_write_b32 v74, v165 offset:56
	s_mov_b64 exec, s[98:99]
	v_readlane_b32 s54, v90, 32
	v_readlane_b32 s55, v90, 33
	s_mul_i32 s0, s54, 0x300
	s_mul_i32 s1, s55, 0x300
	v_add_u32_e32 v167, s0, v195
	s_and_saveexec_b64 s[98:99], s[40:41]
	v_add_u32_e32 v167, s1, v195
	s_mov_b64 exec, s[98:99]
	s_waitcnt vmcnt(14)
	v_cvt_scalef32_pk32_f32_fp6 v[0:31], v[50:55], 1.0
	global_load_dwordx2 v[54:55], v167, s[62:63] offset:16
	global_load_dwordx4 v[50:53], v167, s[62:63]
	v_pk_mul_f32 v[246:247], v[0:1], v[96:97]
	v_pk_mul_f32 v[254:255], v[2:3], v[98:99]
	v_pk_mul_f32 v[160:161], v[4:5], v[100:101]
	v_pk_fma_f32 v[246:247], v[6:7], v[102:103], v[246:247]
	v_pk_fma_f32 v[254:255], v[8:9], v[104:105], v[254:255]
	v_pk_fma_f32 v[160:161], v[10:11], v[106:107], v[160:161]
	v_pk_fma_f32 v[246:247], v[12:13], v[108:109], v[246:247]
	v_pk_fma_f32 v[254:255], v[14:15], v[110:111], v[254:255]
	v_pk_fma_f32 v[160:161], v[16:17], v[112:113], v[160:161]
	v_pk_fma_f32 v[246:247], v[18:19], v[114:115], v[246:247]
	v_pk_fma_f32 v[254:255], v[20:21], v[116:117], v[254:255]
	v_pk_fma_f32 v[160:161], v[22:23], v[118:119], v[160:161]
	v_pk_fma_f32 v[246:247], v[24:25], v[120:121], v[246:247]
	v_pk_fma_f32 v[254:255], v[26:27], v[122:123], v[254:255]
	v_pk_fma_f32 v[160:161], v[28:29], v[124:125], v[160:161]
	v_pk_fma_f32 v[246:247], v[30:31], v[126:127], v[246:247]
	v_pk_add_f32 v[254:255], v[254:255], v[160:161]
	s_nop 0
	v_pk_add_f32 v[246:247], v[246:247], v[254:255]
	s_nop 0
	v_add_f32_e32 v162, v246, v247
	v_readlane_b32 s54, v90, 34
	v_readlane_b32 s55, v90, 35
	s_mul_i32 s0, s54, 0x300
	s_mul_i32 s1, s55, 0x300
	v_add_u32_e32 v167, s0, v195
	s_and_saveexec_b64 s[98:99], s[40:41]
	v_add_u32_e32 v167, s1, v195
	s_mov_b64 exec, s[98:99]
	s_waitcnt vmcnt(14)
; __device__ void peer_gather_phase(const Params& P, int l, bool do_store) {
;     ...
;         v6u_t qv; qv[0] = u6[3 * pr].x; qv[1] = u6[3 * pr].y; qv[2] = u6[3 * pr + 1].x; qv[3] = u6[3 * pr + 1].y; qv[4] = u6[3 * pr + 2].x; qv[5] = u6[3 * pr + 2].y;
;         const v32f_t wv = __builtin_amdgcn_cvt_scalef32_pk32_f32_fp6(qv, 1.0f);
;         f32x2 a2 = f32x2{0.f, 0.f};
; #pragma unroll
;         for (int i = 0; i < 16; ++i) a2 += f32x2{wv[2 * i], wv[2 * i + 1]} * xu[i];
;         float hs = a2.x + a2.y;
;         hs += dpp_row_shr(hs, 1); hs += dpp_row_shr(hs, 2); hs += dpp_row_shr(hs, 4); hs += dpp_row_shr(hs, 8);
;         hs += __builtin_bit_cast(float, __builtin_amdgcn_update_dpp(0, __builtin_bit_cast(int, hs), 0x142, 0xa, 0xf, false));
;         const float da = __builtin_bit_cast(float, __builtin_amdgcn_readlane(__builtin_bit_cast(int, hs), 31));
;         const float db = __builtin_bit_cast(float, __builtin_amdgcn_readlane(__builtin_bit_cast(int, hs), 63));
;         dvec = (lane == kb + 2 * pr) ? da : dvec;
;         dvec = (lane == kb + 2 * pr + 1) ? db : dvec;
	v_cvt_scalef32_pk32_f32_fp6 v[0:31], v[44:49], 1.0
	global_load_dwordx2 v[48:49], v167, s[62:63] offset:16
	global_load_dwordx4 v[44:47], v167, s[62:63]
	v_pk_mul_f32 v[246:247], v[0:1], v[96:97]
	v_pk_mul_f32 v[254:255], v[2:3], v[98:99]
	v_pk_mul_f32 v[160:161], v[4:5], v[100:101]
	v_pk_fma_f32 v[246:247], v[6:7], v[102:103], v[246:247]
	v_pk_fma_f32 v[254:255], v[8:9], v[104:105], v[254:255]
	v_pk_fma_f32 v[160:161], v[10:11], v[106:107], v[160:161]
	v_pk_fma_f32 v[246:247], v[12:13], v[108:109], v[246:247]
	v_pk_fma_f32 v[254:255], v[14:15], v[110:111], v[254:255]
	v_pk_fma_f32 v[160:161], v[16:17], v[112:113], v[160:161]
	v_pk_fma_f32 v[246:247], v[18:19], v[114:115], v[246:247]
	v_pk_fma_f32 v[254:255], v[20:21], v[116:117], v[254:255]
	v_pk_fma_f32 v[160:161], v[22:23], v[118:119], v[160:161]
	v_pk_fma_f32 v[246:247], v[24:25], v[120:121], v[246:247]
	v_pk_fma_f32 v[254:255], v[26:27], v[122:123], v[254:255]
	v_pk_fma_f32 v[160:161], v[28:29], v[124:125], v[160:161]
	v_pk_fma_f32 v[246:247], v[30:31], v[126:127], v[246:247]
	v_pk_add_f32 v[254:255], v[254:255], v[160:161]
	s_nop 0
	v_pk_add_f32 v[246:247], v[246:247], v[254:255]
	s_nop 0
	v_add_f32_e32 v163, v246, v247
	v_readlane_b32 s54, v90, 36
	v_readlane_b32 s55, v90, 37
	s_mul_i32 s0, s54, 0x300
	s_mul_i32 s1, s55, 0x300
	v_add_u32_e32 v167, s0, v195
	s_and_saveexec_b64 s[98:99], s[40:41]
	v_add_u32_e32 v167, s1, v195
	s_mov_b64 exec, s[98:99]
	s_waitcnt vmcnt(14)
	v_cvt_scalef32_pk32_f32_fp6 v[0:31], v[38:43], 1.0
	global_load_dwordx2 v[42:43], v167, s[62:63] offset:16
	global_load_dwordx4 v[38:41], v167, s[62:63]
	v_pk_mul_f32 v[246:247], v[0:1], v[96:97]
	v_pk_mul_f32 v[254:255], v[2:3], v[98:99]
	v_pk_mul_f32 v[160:161], v[4:5], v[100:101]
	v_pk_fma_f32 v[246:247], v[6:7], v[102:103], v[246:247]
	v_pk_fma_f32 v[254:255], v[8:9], v[104:105], v[254:255]
	v_pk_fma_f32 v[160:161], v[10:11], v[106:107], v[160:161]
	v_pk_fma_f32 v[246:247], v[12:13], v[108:109], v[246:247]
	v_pk_fma_f32 v[254:255], v[14:15], v[110:111], v[254:255]
	v_pk_fma_f32 v[160:161], v[16:17], v[112:113], v[160:161]
	v_pk_fma_f32 v[246:247], v[18:19], v[114:115], v[246:247]
	v_pk_fma_f32 v[254:255], v[20:21], v[116:117], v[254:255]
	v_pk_fma_f32 v[160:161], v[22:23], v[118:119], v[160:161]
	v_pk_fma_f32 v[246:247], v[24:25], v[120:121], v[246:247]
	v_pk_fma_f32 v[254:255], v[26:27], v[122:123], v[254:255]
	v_pk_fma_f32 v[160:161], v[28:29], v[124:125], v[160:161]
	v_pk_fma_f32 v[246:247], v[30:31], v[126:127], v[246:247]
	v_pk_add_f32 v[254:255], v[254:255], v[160:161]
	s_nop 0
	v_pk_add_f32 v[246:247], v[246:247], v[254:255]
	s_nop 0
	v_add_f32_e32 v164, v246, v247
	v_readlane_b32 s54, v90, 38
	v_readlane_b32 s55, v90, 39
	s_mul_i32 s0, s54, 0x300
	s_mul_i32 s1, s55, 0x300
	v_add_u32_e32 v167, s0, v195
	s_and_saveexec_b64 s[98:99], s[40:41]
	v_add_u32_e32 v167, s1, v195
	s_mov_b64 exec, s[98:99]
	s_waitcnt vmcnt(14)
	v_cvt_scalef32_pk32_f32_fp6 v[0:31], v[32:37], 1.0
	global_load_dwordx2 v[36:37], v167, s[62:63] offset:16
	global_load_dwordx4 v[32:35], v167, s[62:63]
	v_pk_mul_f32 v[246:247], v[0:1], v[96:97]
	v_pk_mul_f32 v[254:255], v[2:3], v[98:99]
	v_pk_mul_f32 v[160:161], v[4:5], v[100:101]
	v_pk_fma_f32 v[246:247], v[6:7], v[102:103], v[246:247]
	v_pk_fma_f32 v[254:255], v[8:9], v[104:105], v[254:255]
	v_pk_fma_f32 v[160:161], v[10:11], v[106:107], v[160:161]
	v_pk_fma_f32 v[246:247], v[12:13], v[108:109], v[246:247]
	v_pk_fma_f32 v[254:255], v[14:15], v[110:111], v[254:255]
	v_pk_fma_f32 v[160:161], v[16:17], v[112:113], v[160:161]
	v_pk_fma_f32 v[246:247], v[18:19], v[114:115], v[246:247]
	v_pk_fma_f32 v[254:255], v[20:21], v[116:117], v[254:255]
	v_pk_fma_f32 v[160:161], v[22:23], v[118:119], v[160:161]
	v_pk_fma_f32 v[246:247], v[24:25], v[120:121], v[246:247]
	v_pk_fma_f32 v[254:255], v[26:27], v[122:123], v[254:255]
	v_pk_fma_f32 v[160:161], v[28:29], v[124:125], v[160:161]
	v_pk_fma_f32 v[246:247], v[30:31], v[126:127], v[246:247]
	v_pk_add_f32 v[254:255], v[254:255], v[160:161]
	s_nop 0
	v_pk_add_f32 v[246:247], v[246:247], v[254:255]
	s_nop 0
	v_add_f32_e32 v165, v246, v247
	v_add_f32_dpp v162, v162, v162 row_shr:1 row_mask:0xf bank_mask:0xf bound_ctrl:1
	v_add_f32_dpp v163, v163, v163 row_shr:1 row_mask:0xf bank_mask:0xf bound_ctrl:1
	v_add_f32_dpp v164, v164, v164 row_shr:1 row_mask:0xf bank_mask:0xf bound_ctrl:1
	v_add_f32_dpp v165, v165, v165 row_shr:1 row_mask:0xf bank_mask:0xf bound_ctrl:1
	v_add_f32_dpp v162, v162, v162 row_shr:2 row_mask:0xf bank_mask:0xf bound_ctrl:1
	v_add_f32_dpp v163, v163, v163 row_shr:2 row_mask:0xf bank_mask:0xf bound_ctrl:1
	v_add_f32_dpp v164, v164, v164 row_shr:2 row_mask:0xf bank_mask:0xf bound_ctrl:1
	v_add_f32_dpp v165, v165, v165 row_shr:2 row_mask:0xf bank_mask:0xf bound_ctrl:1
	v_add_f32_dpp v162, v162, v162 row_shr:4 row_mask:0xf bank_mask:0xf bound_ctrl:1
	v_add_f32_dpp v163, v163, v163 row_shr:4 row_mask:0xf bank_mask:0xf bound_ctrl:1
	v_add_f32_dpp v164, v164, v164 row_shr:4 row_mask:0xf bank_mask:0xf bound_ctrl:1
	v_add_f32_dpp v165, v165, v165 row_shr:4 row_mask:0xf bank_mask:0xf bound_ctrl:1
	v_add_f32_dpp v162, v162, v162 row_shr:8 row_mask:0xf bank_mask:0xf bound_ctrl:1
	v_add_f32_dpp v163, v163, v163 row_shr:8 row_mask:0xf bank_mask:0xf bound_ctrl:1
	v_add_f32_dpp v164, v164, v164 row_shr:8 row_mask:0xf bank_mask:0xf bound_ctrl:1
	v_add_f32_dpp v165, v165, v165 row_shr:8 row_mask:0xf bank_mask:0xf bound_ctrl:1
	v_add_f32_dpp v162, v162, v162 row_bcast:15 row_mask:0xa bank_mask:0xf
	v_add_f32_dpp v163, v163, v163 row_bcast:15 row_mask:0xa bank_mask:0xf
	v_add_f32_dpp v164, v164, v164 row_bcast:15 row_mask:0xa bank_mask:0xf
	v_add_f32_dpp v165, v165, v165 row_bcast:15 row_mask:0xa bank_mask:0xf
	s_mov_b64 s[98:99], exec
	s_mov_b32 exec_lo, 0x80000000
	s_mov_b32 exec_hi, 0x80000000
	ds_write_b32 v74, v162 offset:64
	ds_write_b32 v74, v163 offset:72
	ds_write_b32 v74, v164 offset:80
	ds_write_b32 v74, v165 offset:88
	s_mov_b64 exec, s[98:99]
	v_readlane_b32 s54, v90, 40
	v_readlane_b32 s55, v90, 41
	s_mul_i32 s0, s54, 0x300
	s_mul_i32 s1, s55, 0x300
	v_add_u32_e32 v167, s0, v195
	s_and_saveexec_b64 s[98:99], s[40:41]
	v_add_u32_e32 v167, s1, v195
	s_mov_b64 exec, s[98:99]
	s_waitcnt vmcnt(14)
; __device__ void peer_gather_phase(const Params& P, int l, bool do_store) {
;     ...
;         const int ea = __builtin_amdgcn_readlane(evs, kb + 2 * pr), eb = __builtin_amdgcn_readlane(evs, kb + 2 * pr + 1);
;         const uint2* up = (const uint2*)(U + (size_t)(uphi ? eb : ea) * 768);
;         u6[3 * pr] = up[0]; u6[3 * pr + 1] = up[1]; u6[3 * pr + 2] = up[2];
;     ...
;         v6u_t qv; qv[0] = u6[3 * pr].x; qv[1] = u6[3 * pr].y; qv[2] = u6[3 * pr + 1].x; qv[3] = u6[3 * pr + 1].y; qv[4] = u6[3 * pr + 2].x; qv[5] = u6[3 * pr + 2].y;
;         const v32f_t wv = __builtin_amdgcn_cvt_scalef32_pk32_f32_fp6(qv, 1.0f);
;         f32x2 a2 = f32x2{0.f, 0.f};
; #pragma unroll
;         for (int i = 0; i < 16; ++i) a2 += f32x2{wv[2 * i], wv[2 * i + 1]} * xu[i];
;         float hs = a2.x + a2.y;
	v_cvt_scalef32_pk32_f32_fp6 v[0:31], v[196:201], 1.0
	global_load_dwordx2 v[200:201], v167, s[62:63] offset:16
	global_load_dwordx4 v[196:199], v167, s[62:63]
	v_pk_mul_f32 v[246:247], v[0:1], v[96:97]
	v_pk_mul_f32 v[254:255], v[2:3], v[98:99]
	v_pk_mul_f32 v[160:161], v[4:5], v[100:101]
	v_pk_fma_f32 v[246:247], v[6:7], v[102:103], v[246:247]
	v_pk_fma_f32 v[254:255], v[8:9], v[104:105], v[254:255]
	v_pk_fma_f32 v[160:161], v[10:11], v[106:107], v[160:161]
	v_pk_fma_f32 v[246:247], v[12:13], v[108:109], v[246:247]
	v_pk_fma_f32 v[254:255], v[14:15], v[110:111], v[254:255]
	v_pk_fma_f32 v[160:161], v[16:17], v[112:113], v[160:161]
	v_pk_fma_f32 v[246:247], v[18:19], v[114:115], v[246:247]
	v_pk_fma_f32 v[254:255], v[20:21], v[116:117], v[254:255]
	v_pk_fma_f32 v[160:161], v[22:23], v[118:119], v[160:161]
	v_pk_fma_f32 v[246:247], v[24:25], v[120:121], v[246:247]
	v_pk_fma_f32 v[254:255], v[26:27], v[122:123], v[254:255]
	v_pk_fma_f32 v[160:161], v[28:29], v[124:125], v[160:161]
	v_pk_fma_f32 v[246:247], v[30:31], v[126:127], v[246:247]
	v_pk_add_f32 v[254:255], v[254:255], v[160:161]
	s_nop 0
	v_pk_add_f32 v[246:247], v[246:247], v[254:255]
	s_nop 0
	v_add_f32_e32 v162, v246, v247
	v_readlane_b32 s54, v90, 42
	v_readlane_b32 s55, v90, 43
	s_mul_i32 s0, s54, 0x300
	s_mul_i32 s1, s55, 0x300
	v_add_u32_e32 v167, s0, v195
	s_and_saveexec_b64 s[98:99], s[40:41]
	v_add_u32_e32 v167, s1, v195
	s_mov_b64 exec, s[98:99]
	s_waitcnt vmcnt(14)
	v_cvt_scalef32_pk32_f32_fp6 v[0:31], v[228:233], 1.0
	global_load_dwordx2 v[232:233], v167, s[62:63] offset:16
	global_load_dwordx4 v[228:231], v167, s[62:63]
	v_pk_mul_f32 v[246:247], v[0:1], v[96:97]
	v_pk_mul_f32 v[254:255], v[2:3], v[98:99]
	v_pk_mul_f32 v[160:161], v[4:5], v[100:101]
	v_pk_fma_f32 v[246:247], v[6:7], v[102:103], v[246:247]
	v_pk_fma_f32 v[254:255], v[8:9], v[104:105], v[254:255]
	v_pk_fma_f32 v[160:161], v[10:11], v[106:107], v[160:161]
	v_pk_fma_f32 v[246:247], v[12:13], v[108:109], v[246:247]
	v_pk_fma_f32 v[254:255], v[14:15], v[110:111], v[254:255]
	v_pk_fma_f32 v[160:161], v[16:17], v[112:113], v[160:161]
	v_pk_fma_f32 v[246:247], v[18:19], v[114:115], v[246:247]
	v_pk_fma_f32 v[254:255], v[20:21], v[116:117], v[254:255]
	v_pk_fma_f32 v[160:161], v[22:23], v[118:119], v[160:161]
	v_pk_fma_f32 v[246:247], v[24:25], v[120:121], v[246:247]
	v_pk_fma_f32 v[254:255], v[26:27], v[122:123], v[254:255]
	v_pk_fma_f32 v[160:161], v[28:29], v[124:125], v[160:161]
	v_pk_fma_f32 v[246:247], v[30:31], v[126:127], v[246:247]
	v_pk_add_f32 v[254:255], v[254:255], v[160:161]
	s_nop 0
	v_pk_add_f32 v[246:247], v[246:247], v[254:255]
	s_nop 0
	v_add_f32_e32 v163, v246, v247
	v_readlane_b32 s54, v90, 44
	v_readlane_b32 s55, v90, 45
	s_mul_i32 s0, s54, 0x300
	s_mul_i32 s1, s55, 0x300
	v_add_u32_e32 v167, s0, v195
	s_and_saveexec_b64 s[98:99], s[40:41]
	v_add_u32_e32 v167, s1, v195
	s_mov_b64 exec, s[98:99]
	s_waitcnt vmcnt(14)
	v_cvt_scalef32_pk32_f32_fp6 v[0:31], v[234:239], 1.0
	global_load_dwordx2 v[238:239], v167, s[62:63] offset:16
	global_load_dwordx4 v[234:237], v167, s[62:63]
	v_pk_mul_f32 v[246:247], v[0:1], v[96:97]
	v_pk_mul_f32 v[254:255], v[2:3], v[98:99]
	v_pk_mul_f32 v[160:161], v[4:5], v[100:101]
	v_pk_fma_f32 v[246:247], v[6:7], v[102:103], v[246:247]
	v_pk_fma_f32 v[254:255], v[8:9], v[104:105], v[254:255]
	v_pk_fma_f32 v[160:161], v[10:11], v[106:107], v[160:161]
	v_pk_fma_f32 v[246:247], v[12:13], v[108:109], v[246:247]
	v_pk_fma_f32 v[254:255], v[14:15], v[110:111], v[254:255]
	v_pk_fma_f32 v[160:161], v[16:17], v[112:113], v[160:161]
	v_pk_fma_f32 v[246:247], v[18:19], v[114:115], v[246:247]
	v_pk_fma_f32 v[254:255], v[20:21], v[116:117], v[254:255]
	v_pk_fma_f32 v[160:161], v[22:23], v[118:119], v[160:161]
	v_pk_fma_f32 v[246:247], v[24:25], v[120:121], v[246:247]
	v_pk_fma_f32 v[254:255], v[26:27], v[122:123], v[254:255]
	v_pk_fma_f32 v[160:161], v[28:29], v[124:125], v[160:161]
	v_pk_fma_f32 v[246:247], v[30:31], v[126:127], v[246:247]
	v_pk_add_f32 v[254:255], v[254:255], v[160:161]
	s_nop 0
	v_pk_add_f32 v[246:247], v[246:247], v[254:255]
	s_nop 0
	v_add_f32_e32 v164, v246, v247
	v_readlane_b32 s54, v90, 46
	v_readlane_b32 s55, v90, 47
	s_mul_i32 s0, s54, 0x300
	s_mul_i32 s1, s55, 0x300
	v_add_u32_e32 v167, s0, v195
	s_and_saveexec_b64 s[98:99], s[40:41]
	v_add_u32_e32 v167, s1, v195
	s_mov_b64 exec, s[98:99]
	s_waitcnt vmcnt(14)
; __device__ void peer_gather_phase(const Params& P, int l, bool do_store) {
;     ...
;         v6u_t qv; qv[0] = u6[3 * pr].x; qv[1] = u6[3 * pr].y; qv[2] = u6[3 * pr + 1].x; qv[3] = u6[3 * pr + 1].y; qv[4] = u6[3 * pr + 2].x; qv[5] = u6[3 * pr + 2].y;
;         const v32f_t wv = __builtin_amdgcn_cvt_scalef32_pk32_f32_fp6(qv, 1.0f);
;         f32x2 a2 = f32x2{0.f, 0.f};
; #pragma unroll
;         for (int i = 0; i < 16; ++i) a2 += f32x2{wv[2 * i], wv[2 * i + 1]} * xu[i];
;         float hs = a2.x + a2.y;
;         hs += dpp_row_shr(hs, 1); hs += dpp_row_shr(hs, 2); hs += dpp_row_shr(hs, 4); hs += dpp_row_shr(hs, 8);
;         hs += __builtin_bit_cast(float, __builtin_amdgcn_update_dpp(0, __builtin_bit_cast(int, hs), 0x142, 0xa, 0xf, false));
;         const float da = __builtin_bit_cast(float, __builtin_amdgcn_readlane(__builtin_bit_cast(int, hs), 31));
;         const float db = __builtin_bit_cast(float, __builtin_amdgcn_readlane(__builtin_bit_cast(int, hs), 63));
;         dvec = (lane == kb + 2 * pr) ? da : dvec;
;         dvec = (lane == kb + 2 * pr + 1) ? db : dvec;
	v_cvt_scalef32_pk32_f32_fp6 v[0:31], v[240:245], 1.0
	global_load_dwordx2 v[244:245], v167, s[62:63] offset:16
	global_load_dwordx4 v[240:243], v167, s[62:63]
	v_pk_mul_f32 v[246:247], v[0:1], v[96:97]
	v_pk_mul_f32 v[254:255], v[2:3], v[98:99]
	v_pk_mul_f32 v[160:161], v[4:5], v[100:101]
	v_pk_fma_f32 v[246:247], v[6:7], v[102:103], v[246:247]
	v_pk_fma_f32 v[254:255], v[8:9], v[104:105], v[254:255]
	v_pk_fma_f32 v[160:161], v[10:11], v[106:107], v[160:161]
	v_pk_fma_f32 v[246:247], v[12:13], v[108:109], v[246:247]
	v_pk_fma_f32 v[254:255], v[14:15], v[110:111], v[254:255]
	v_pk_fma_f32 v[160:161], v[16:17], v[112:113], v[160:161]
	v_pk_fma_f32 v[246:247], v[18:19], v[114:115], v[246:247]
	v_pk_fma_f32 v[254:255], v[20:21], v[116:117], v[254:255]
	v_pk_fma_f32 v[160:161], v[22:23], v[118:119], v[160:161]
	v_pk_fma_f32 v[246:247], v[24:25], v[120:121], v[246:247]
	v_pk_fma_f32 v[254:255], v[26:27], v[122:123], v[254:255]
	v_pk_fma_f32 v[160:161], v[28:29], v[124:125], v[160:161]
	v_pk_fma_f32 v[246:247], v[30:31], v[126:127], v[246:247]
	v_pk_add_f32 v[254:255], v[254:255], v[160:161]
	s_nop 0
	v_pk_add_f32 v[246:247], v[246:247], v[254:255]
	s_nop 0
	v_add_f32_e32 v165, v246, v247
	v_add_f32_dpp v162, v162, v162 row_shr:1 row_mask:0xf bank_mask:0xf bound_ctrl:1
	v_add_f32_dpp v163, v163, v163 row_shr:1 row_mask:0xf bank_mask:0xf bound_ctrl:1
	v_add_f32_dpp v164, v164, v164 row_shr:1 row_mask:0xf bank_mask:0xf bound_ctrl:1
	v_add_f32_dpp v165, v165, v165 row_shr:1 row_mask:0xf bank_mask:0xf bound_ctrl:1
	v_add_f32_dpp v162, v162, v162 row_shr:2 row_mask:0xf bank_mask:0xf bound_ctrl:1
	v_add_f32_dpp v163, v163, v163 row_shr:2 row_mask:0xf bank_mask:0xf bound_ctrl:1
	v_add_f32_dpp v164, v164, v164 row_shr:2 row_mask:0xf bank_mask:0xf bound_ctrl:1
	v_add_f32_dpp v165, v165, v165 row_shr:2 row_mask:0xf bank_mask:0xf bound_ctrl:1
	v_add_f32_dpp v162, v162, v162 row_shr:4 row_mask:0xf bank_mask:0xf bound_ctrl:1
	v_add_f32_dpp v163, v163, v163 row_shr:4 row_mask:0xf bank_mask:0xf bound_ctrl:1
	v_add_f32_dpp v164, v164, v164 row_shr:4 row_mask:0xf bank_mask:0xf bound_ctrl:1
	v_add_f32_dpp v165, v165, v165 row_shr:4 row_mask:0xf bank_mask:0xf bound_ctrl:1
	v_add_f32_dpp v162, v162, v162 row_shr:8 row_mask:0xf bank_mask:0xf bound_ctrl:1
	v_add_f32_dpp v163, v163, v163 row_shr:8 row_mask:0xf bank_mask:0xf bound_ctrl:1
	v_add_f32_dpp v164, v164, v164 row_shr:8 row_mask:0xf bank_mask:0xf bound_ctrl:1
	v_add_f32_dpp v165, v165, v165 row_shr:8 row_mask:0xf bank_mask:0xf bound_ctrl:1
	v_add_f32_dpp v162, v162, v162 row_bcast:15 row_mask:0xa bank_mask:0xf
	v_add_f32_dpp v163, v163, v163 row_bcast:15 row_mask:0xa bank_mask:0xf
	v_add_f32_dpp v164, v164, v164 row_bcast:15 row_mask:0xa bank_mask:0xf
	v_add_f32_dpp v165, v165, v165 row_bcast:15 row_mask:0xa bank_mask:0xf
	s_mov_b64 s[98:99], exec
	s_mov_b32 exec_lo, 0x80000000
	s_mov_b32 exec_hi, 0x80000000
	ds_write_b32 v74, v162 offset:96
	ds_write_b32 v74, v163 offset:104
	ds_write_b32 v74, v164 offset:112
	ds_write_b32 v74, v165 offset:120
	s_mov_b64 exec, s[98:99]
	v_readlane_b32 s54, v90, 48
	v_readlane_b32 s55, v90, 49
	s_mul_i32 s0, s54, 0x300
	s_mul_i32 s1, s55, 0x300
	v_add_u32_e32 v167, s0, v195
	s_and_saveexec_b64 s[98:99], s[40:41]
	v_add_u32_e32 v167, s1, v195
	s_mov_b64 exec, s[98:99]
	s_waitcnt vmcnt(14)
	v_cvt_scalef32_pk32_f32_fp6 v[0:31], v[50:55], 1.0
	global_load_dwordx2 v[54:55], v167, s[62:63] offset:16
	global_load_dwordx4 v[50:53], v167, s[62:63]
	v_pk_mul_f32 v[246:247], v[0:1], v[96:97]
	v_pk_mul_f32 v[254:255], v[2:3], v[98:99]
	v_pk_mul_f32 v[160:161], v[4:5], v[100:101]
	v_pk_fma_f32 v[246:247], v[6:7], v[102:103], v[246:247]
	v_pk_fma_f32 v[254:255], v[8:9], v[104:105], v[254:255]
	v_pk_fma_f32 v[160:161], v[10:11], v[106:107], v[160:161]
	v_pk_fma_f32 v[246:247], v[12:13], v[108:109], v[246:247]
	v_pk_fma_f32 v[254:255], v[14:15], v[110:111], v[254:255]
	v_pk_fma_f32 v[160:161], v[16:17], v[112:113], v[160:161]
	v_pk_fma_f32 v[246:247], v[18:19], v[114:115], v[246:247]
	v_pk_fma_f32 v[254:255], v[20:21], v[116:117], v[254:255]
	v_pk_fma_f32 v[160:161], v[22:23], v[118:119], v[160:161]
	v_pk_fma_f32 v[246:247], v[24:25], v[120:121], v[246:247]
	v_pk_fma_f32 v[254:255], v[26:27], v[122:123], v[254:255]
	v_pk_fma_f32 v[160:161], v[28:29], v[124:125], v[160:161]
	v_pk_fma_f32 v[246:247], v[30:31], v[126:127], v[246:247]
	v_pk_add_f32 v[254:255], v[254:255], v[160:161]
	s_nop 0
	v_pk_add_f32 v[246:247], v[246:247], v[254:255]
	s_nop 0
	v_add_f32_e32 v162, v246, v247
	v_readlane_b32 s54, v90, 50
	v_readlane_b32 s55, v90, 51
	s_mul_i32 s0, s54, 0x300
	s_mul_i32 s1, s55, 0x300
	v_add_u32_e32 v167, s0, v195
	s_and_saveexec_b64 s[98:99], s[40:41]
	v_add_u32_e32 v167, s1, v195
	s_mov_b64 exec, s[98:99]
	s_waitcnt vmcnt(14)
	v_cvt_scalef32_pk32_f32_fp6 v[0:31], v[44:49], 1.0
	global_load_dwordx2 v[48:49], v167, s[62:63] offset:16
	global_load_dwordx4 v[44:47], v167, s[62:63]
	v_pk_mul_f32 v[246:247], v[0:1], v[96:97]
	v_pk_mul_f32 v[254:255], v[2:3], v[98:99]
	v_pk_mul_f32 v[160:161], v[4:5], v[100:101]
	v_pk_fma_f32 v[246:247], v[6:7], v[102:103], v[246:247]
	v_pk_fma_f32 v[254:255], v[8:9], v[104:105], v[254:255]
	v_pk_fma_f32 v[160:161], v[10:11], v[106:107], v[160:161]
	v_pk_fma_f32 v[246:247], v[12:13], v[108:109], v[246:247]
	v_pk_fma_f32 v[254:255], v[14:15], v[110:111], v[254:255]
	v_pk_fma_f32 v[160:161], v[16:17], v[112:113], v[160:161]
	v_pk_fma_f32 v[246:247], v[18:19], v[114:115], v[246:247]
	v_pk_fma_f32 v[254:255], v[20:21], v[116:117], v[254:255]
	v_pk_fma_f32 v[160:161], v[22:23], v[118:119], v[160:161]
	v_pk_fma_f32 v[246:247], v[24:25], v[120:121], v[246:247]
	v_pk_fma_f32 v[254:255], v[26:27], v[122:123], v[254:255]
	v_pk_fma_f32 v[160:161], v[28:29], v[124:125], v[160:161]
	v_pk_fma_f32 v[246:247], v[30:31], v[126:127], v[246:247]
	v_pk_add_f32 v[254:255], v[254:255], v[160:161]
	s_nop 0
	v_pk_add_f32 v[246:247], v[246:247], v[254:255]
	s_nop 0
	v_add_f32_e32 v163, v246, v247
	v_readlane_b32 s54, v90, 52
	v_readlane_b32 s55, v90, 53
	s_mul_i32 s0, s54, 0x300
	s_mul_i32 s1, s55, 0x300
	v_add_u32_e32 v167, s0, v195
	s_and_saveexec_b64 s[98:99], s[40:41]
	v_add_u32_e32 v167, s1, v195
	s_mov_b64 exec, s[98:99]
	s_waitcnt vmcnt(14)
; __device__ void peer_gather_phase(const Params& P, int l, bool do_store) {
;     ...
;         v6u_t qv; qv[0] = u6[3 * pr].x; qv[1] = u6[3 * pr].y; qv[2] = u6[3 * pr + 1].x; qv[3] = u6[3 * pr + 1].y; qv[4] = u6[3 * pr + 2].x; qv[5] = u6[3 * pr + 2].y;
;         const v32f_t wv = __builtin_amdgcn_cvt_scalef32_pk32_f32_fp6(qv, 1.0f);
;         f32x2 a2 = f32x2{0.f, 0.f};
; #pragma unroll
;         for (int i = 0; i < 16; ++i) a2 += f32x2{wv[2 * i], wv[2 * i + 1]} * xu[i];
;         float hs = a2.x + a2.y;
;         hs += dpp_row_shr(hs, 1); hs += dpp_row_shr(hs, 2); hs += dpp_row_shr(hs, 4); hs += dpp_row_shr(hs, 8);
;         hs += __builtin_bit_cast(float, __builtin_amdgcn_update_dpp(0, __builtin_bit_cast(int, hs), 0x142, 0xa, 0xf, false));
;         const float da = __builtin_bit_cast(float, __builtin_amdgcn_readlane(__builtin_bit_cast(int, hs), 31));
;         const float db = __builtin_bit_cast(float, __builtin_amdgcn_readlane(__builtin_bit_cast(int, hs), 63));
;         dvec = (lane == kb + 2 * pr) ? da : dvec;
;         dvec = (lane == kb + 2 * pr + 1) ? db : dvec;
	v_cvt_scalef32_pk32_f32_fp6 v[0:31], v[38:43], 1.0
	global_load_dwordx2 v[42:43], v167, s[62:63] offset:16
	global_load_dwordx4 v[38:41], v167, s[62:63]
	v_pk_mul_f32 v[246:247], v[0:1], v[96:97]
	v_pk_mul_f32 v[254:255], v[2:3], v[98:99]
	v_pk_mul_f32 v[160:161], v[4:5], v[100:101]
	v_pk_fma_f32 v[246:247], v[6:7], v[102:103], v[246:247]
	v_pk_fma_f32 v[254:255], v[8:9], v[104:105], v[254:255]
	v_pk_fma_f32 v[160:161], v[10:11], v[106:107], v[160:161]
	v_pk_fma_f32 v[246:247], v[12:13], v[108:109], v[246:247]
	v_pk_fma_f32 v[254:255], v[14:15], v[110:111], v[254:255]
	v_pk_fma_f32 v[160:161], v[16:17], v[112:113], v[160:161]
	v_pk_fma_f32 v[246:247], v[18:19], v[114:115], v[246:247]
	v_pk_fma_f32 v[254:255], v[20:21], v[116:117], v[254:255]
	v_pk_fma_f32 v[160:161], v[22:23], v[118:119], v[160:161]
	v_pk_fma_f32 v[246:247], v[24:25], v[120:121], v[246:247]
	v_pk_fma_f32 v[254:255], v[26:27], v[122:123], v[254:255]
	v_pk_fma_f32 v[160:161], v[28:29], v[124:125], v[160:161]
	v_pk_fma_f32 v[246:247], v[30:31], v[126:127], v[246:247]
	v_pk_add_f32 v[254:255], v[254:255], v[160:161]
	s_nop 0
	v_pk_add_f32 v[246:247], v[246:247], v[254:255]
	s_nop 0
	v_add_f32_e32 v164, v246, v247
	v_readlane_b32 s54, v90, 54
	v_readlane_b32 s55, v90, 55
	s_mul_i32 s0, s54, 0x300
	s_mul_i32 s1, s55, 0x300
	v_add_u32_e32 v167, s0, v195
	s_and_saveexec_b64 s[98:99], s[40:41]
	v_add_u32_e32 v167, s1, v195
	s_mov_b64 exec, s[98:99]
	s_waitcnt vmcnt(14)
	v_cvt_scalef32_pk32_f32_fp6 v[0:31], v[32:37], 1.0
	global_load_dwordx2 v[36:37], v167, s[62:63] offset:16
	global_load_dwordx4 v[32:35], v167, s[62:63]
	v_pk_mul_f32 v[246:247], v[0:1], v[96:97]
	v_pk_mul_f32 v[254:255], v[2:3], v[98:99]
	v_pk_mul_f32 v[160:161], v[4:5], v[100:101]
	v_pk_fma_f32 v[246:247], v[6:7], v[102:103], v[246:247]
	v_pk_fma_f32 v[254:255], v[8:9], v[104:105], v[254:255]
	v_pk_fma_f32 v[160:161], v[10:11], v[106:107], v[160:161]
	v_pk_fma_f32 v[246:247], v[12:13], v[108:109], v[246:247]
	v_pk_fma_f32 v[254:255], v[14:15], v[110:111], v[254:255]
	v_pk_fma_f32 v[160:161], v[16:17], v[112:113], v[160:161]
	v_pk_fma_f32 v[246:247], v[18:19], v[114:115], v[246:247]
	v_pk_fma_f32 v[254:255], v[20:21], v[116:117], v[254:255]
	v_pk_fma_f32 v[160:161], v[22:23], v[118:119], v[160:161]
	v_pk_fma_f32 v[246:247], v[24:25], v[120:121], v[246:247]
	v_pk_fma_f32 v[254:255], v[26:27], v[122:123], v[254:255]
	v_pk_fma_f32 v[160:161], v[28:29], v[124:125], v[160:161]
	v_pk_fma_f32 v[246:247], v[30:31], v[126:127], v[246:247]
	v_pk_add_f32 v[254:255], v[254:255], v[160:161]
	s_nop 0
	v_pk_add_f32 v[246:247], v[246:247], v[254:255]
	s_nop 0
	v_add_f32_e32 v165, v246, v247
	v_add_f32_dpp v162, v162, v162 row_shr:1 row_mask:0xf bank_mask:0xf bound_ctrl:1
	v_add_f32_dpp v163, v163, v163 row_shr:1 row_mask:0xf bank_mask:0xf bound_ctrl:1
	v_add_f32_dpp v164, v164, v164 row_shr:1 row_mask:0xf bank_mask:0xf bound_ctrl:1
	v_add_f32_dpp v165, v165, v165 row_shr:1 row_mask:0xf bank_mask:0xf bound_ctrl:1
	v_add_f32_dpp v162, v162, v162 row_shr:2 row_mask:0xf bank_mask:0xf bound_ctrl:1
	v_add_f32_dpp v163, v163, v163 row_shr:2 row_mask:0xf bank_mask:0xf bound_ctrl:1
	v_add_f32_dpp v164, v164, v164 row_shr:2 row_mask:0xf bank_mask:0xf bound_ctrl:1
	v_add_f32_dpp v165, v165, v165 row_shr:2 row_mask:0xf bank_mask:0xf bound_ctrl:1
	v_add_f32_dpp v162, v162, v162 row_shr:4 row_mask:0xf bank_mask:0xf bound_ctrl:1
	v_add_f32_dpp v163, v163, v163 row_shr:4 row_mask:0xf bank_mask:0xf bound_ctrl:1
	v_add_f32_dpp v164, v164, v164 row_shr:4 row_mask:0xf bank_mask:0xf bound_ctrl:1
	v_add_f32_dpp v165, v165, v165 row_shr:4 row_mask:0xf bank_mask:0xf bound_ctrl:1
	v_add_f32_dpp v162, v162, v162 row_shr:8 row_mask:0xf bank_mask:0xf bound_ctrl:1
	v_add_f32_dpp v163, v163, v163 row_shr:8 row_mask:0xf bank_mask:0xf bound_ctrl:1
	v_add_f32_dpp v164, v164, v164 row_shr:8 row_mask:0xf bank_mask:0xf bound_ctrl:1
	v_add_f32_dpp v165, v165, v165 row_shr:8 row_mask:0xf bank_mask:0xf bound_ctrl:1
	v_add_f32_dpp v162, v162, v162 row_bcast:15 row_mask:0xa bank_mask:0xf
	v_add_f32_dpp v163, v163, v163 row_bcast:15 row_mask:0xa bank_mask:0xf
	v_add_f32_dpp v164, v164, v164 row_bcast:15 row_mask:0xa bank_mask:0xf
	v_add_f32_dpp v165, v165, v165 row_bcast:15 row_mask:0xa bank_mask:0xf
	s_mov_b64 s[98:99], exec
	s_mov_b32 exec_lo, 0x80000000
	s_mov_b32 exec_hi, 0x80000000
	ds_write_b32 v74, v162 offset:128
	ds_write_b32 v74, v163 offset:136
	ds_write_b32 v74, v164 offset:144
	ds_write_b32 v74, v165 offset:152
	s_mov_b64 exec, s[98:99]
	v_readlane_b32 s54, v90, 56
	v_readlane_b32 s55, v90, 57
	s_mul_i32 s0, s54, 0x300
	s_mul_i32 s1, s55, 0x300
	v_add_u32_e32 v167, s0, v195
	s_and_saveexec_b64 s[98:99], s[40:41]
	v_add_u32_e32 v167, s1, v195
	s_mov_b64 exec, s[98:99]
	s_waitcnt vmcnt(14)
	v_cvt_scalef32_pk32_f32_fp6 v[0:31], v[196:201], 1.0
	global_load_dwordx2 v[200:201], v167, s[62:63] offset:16
	global_load_dwordx4 v[196:199], v167, s[62:63]
	v_pk_mul_f32 v[246:247], v[0:1], v[96:97]
	v_pk_mul_f32 v[254:255], v[2:3], v[98:99]
	v_pk_mul_f32 v[160:161], v[4:5], v[100:101]
	v_pk_fma_f32 v[246:247], v[6:7], v[102:103], v[246:247]
	v_pk_fma_f32 v[254:255], v[8:9], v[104:105], v[254:255]
	v_pk_fma_f32 v[160:161], v[10:11], v[106:107], v[160:161]
	v_pk_fma_f32 v[246:247], v[12:13], v[108:109], v[246:247]
	v_pk_fma_f32 v[254:255], v[14:15], v[110:111], v[254:255]
	v_pk_fma_f32 v[160:161], v[16:17], v[112:113], v[160:161]
	v_pk_fma_f32 v[246:247], v[18:19], v[114:115], v[246:247]
	v_pk_fma_f32 v[254:255], v[20:21], v[116:117], v[254:255]
	v_pk_fma_f32 v[160:161], v[22:23], v[118:119], v[160:161]
	v_pk_fma_f32 v[246:247], v[24:25], v[120:121], v[246:247]
	v_pk_fma_f32 v[254:255], v[26:27], v[122:123], v[254:255]
	v_pk_fma_f32 v[160:161], v[28:29], v[124:125], v[160:161]
	v_pk_fma_f32 v[246:247], v[30:31], v[126:127], v[246:247]
	v_pk_add_f32 v[254:255], v[254:255], v[160:161]
	s_nop 0
	v_pk_add_f32 v[246:247], v[246:247], v[254:255]
	s_nop 0
	v_add_f32_e32 v162, v246, v247
	v_readlane_b32 s54, v90, 58
	v_readlane_b32 s55, v90, 59
	s_mul_i32 s0, s54, 0x300
	s_mul_i32 s1, s55, 0x300
	v_add_u32_e32 v167, s0, v195
	s_and_saveexec_b64 s[98:99], s[40:41]
	v_add_u32_e32 v167, s1, v195
	s_mov_b64 exec, s[98:99]
	s_waitcnt vmcnt(14)
; __device__ void peer_gather_phase(const Params& P, int l, bool do_store) {
;     ...
;         v6u_t qv; qv[0] = u6[3 * pr].x; qv[1] = u6[3 * pr].y; qv[2] = u6[3 * pr + 1].x; qv[3] = u6[3 * pr + 1].y; qv[4] = u6[3 * pr + 2].x; qv[5] = u6[3 * pr + 2].y;
;         const v32f_t wv = __builtin_amdgcn_cvt_scalef32_pk32_f32_fp6(qv, 1.0f);
;         f32x2 a2 = f32x2{0.f, 0.f};
; #pragma unroll
;         for (int i = 0; i < 16; ++i) a2 += f32x2{wv[2 * i], wv[2 * i + 1]} * xu[i];
;         float hs = a2.x + a2.y;
;         hs += dpp_row_shr(hs, 1); hs += dpp_row_shr(hs, 2); hs += dpp_row_shr(hs, 4); hs += dpp_row_shr(hs, 8);
;         hs += __builtin_bit_cast(float, __builtin_amdgcn_update_dpp(0, __builtin_bit_cast(int, hs), 0x142, 0xa, 0xf, false));
;         const float da = __builtin_bit_cast(float, __builtin_amdgcn_readlane(__builtin_bit_cast(int, hs), 31));
;         const float db = __builtin_bit_cast(float, __builtin_amdgcn_readlane(__builtin_bit_cast(int, hs), 63));
;         dvec = (lane == kb + 2 * pr) ? da : dvec;
;         dvec = (lane == kb + 2 * pr + 1) ? db : dvec;
	v_cvt_scalef32_pk32_f32_fp6 v[0:31], v[228:233], 1.0
	global_load_dwordx2 v[232:233], v167, s[62:63] offset:16
	global_load_dwordx4 v[228:231], v167, s[62:63]
	v_pk_mul_f32 v[246:247], v[0:1], v[96:97]
	v_pk_mul_f32 v[254:255], v[2:3], v[98:99]
	v_pk_mul_f32 v[160:161], v[4:5], v[100:101]
	v_pk_fma_f32 v[246:247], v[6:7], v[102:103], v[246:247]
	v_pk_fma_f32 v[254:255], v[8:9], v[104:105], v[254:255]
	v_pk_fma_f32 v[160:161], v[10:11], v[106:107], v[160:161]
	v_pk_fma_f32 v[246:247], v[12:13], v[108:109], v[246:247]
	v_pk_fma_f32 v[254:255], v[14:15], v[110:111], v[254:255]
	v_pk_fma_f32 v[160:161], v[16:17], v[112:113], v[160:161]
	v_pk_fma_f32 v[246:247], v[18:19], v[114:115], v[246:247]
	v_pk_fma_f32 v[254:255], v[20:21], v[116:117], v[254:255]
	v_pk_fma_f32 v[160:161], v[22:23], v[118:119], v[160:161]
	v_pk_fma_f32 v[246:247], v[24:25], v[120:121], v[246:247]
	v_pk_fma_f32 v[254:255], v[26:27], v[122:123], v[254:255]
	v_pk_fma_f32 v[160:161], v[28:29], v[124:125], v[160:161]
	v_pk_fma_f32 v[246:247], v[30:31], v[126:127], v[246:247]
	v_pk_add_f32 v[254:255], v[254:255], v[160:161]
	s_nop 0
	v_pk_add_f32 v[246:247], v[246:247], v[254:255]
	s_nop 0
	v_add_f32_e32 v163, v246, v247
	v_readlane_b32 s54, v90, 60
	v_readlane_b32 s55, v90, 61
	s_mul_i32 s0, s54, 0x300
	s_mul_i32 s1, s55, 0x300
	v_add_u32_e32 v167, s0, v195
	s_and_saveexec_b64 s[98:99], s[40:41]
	v_add_u32_e32 v167, s1, v195
	s_mov_b64 exec, s[98:99]
	s_waitcnt vmcnt(14)
	v_cvt_scalef32_pk32_f32_fp6 v[0:31], v[234:239], 1.0
	global_load_dwordx2 v[238:239], v167, s[62:63] offset:16
	global_load_dwordx4 v[234:237], v167, s[62:63]
	v_pk_mul_f32 v[246:247], v[0:1], v[96:97]
	v_pk_mul_f32 v[254:255], v[2:3], v[98:99]
	v_pk_mul_f32 v[160:161], v[4:5], v[100:101]
	v_pk_fma_f32 v[246:247], v[6:7], v[102:103], v[246:247]
	v_pk_fma_f32 v[254:255], v[8:9], v[104:105], v[254:255]
	v_pk_fma_f32 v[160:161], v[10:11], v[106:107], v[160:161]
	v_pk_fma_f32 v[246:247], v[12:13], v[108:109], v[246:247]
	v_pk_fma_f32 v[254:255], v[14:15], v[110:111], v[254:255]
	v_pk_fma_f32 v[160:161], v[16:17], v[112:113], v[160:161]
	v_pk_fma_f32 v[246:247], v[18:19], v[114:115], v[246:247]
	v_pk_fma_f32 v[254:255], v[20:21], v[116:117], v[254:255]
	v_pk_fma_f32 v[160:161], v[22:23], v[118:119], v[160:161]
	v_pk_fma_f32 v[246:247], v[24:25], v[120:121], v[246:247]
	v_pk_fma_f32 v[254:255], v[26:27], v[122:123], v[254:255]
	v_pk_fma_f32 v[160:161], v[28:29], v[124:125], v[160:161]
	v_pk_fma_f32 v[246:247], v[30:31], v[126:127], v[246:247]
	v_pk_add_f32 v[254:255], v[254:255], v[160:161]
	s_nop 0
	v_pk_add_f32 v[246:247], v[246:247], v[254:255]
	s_nop 0
	v_add_f32_e32 v164, v246, v247
	v_readlane_b32 s54, v90, 62
	v_readlane_b32 s55, v90, 63
	s_mul_i32 s0, s54, 0x300
	s_mul_i32 s1, s55, 0x300
	v_add_u32_e32 v167, s0, v195
	s_and_saveexec_b64 s[98:99], s[40:41]
	v_add_u32_e32 v167, s1, v195
	s_mov_b64 exec, s[98:99]
	s_waitcnt vmcnt(14)
	v_cvt_scalef32_pk32_f32_fp6 v[0:31], v[240:245], 1.0
	global_load_dwordx2 v[244:245], v167, s[62:63] offset:16
	global_load_dwordx4 v[240:243], v167, s[62:63]
	v_pk_mul_f32 v[246:247], v[0:1], v[96:97]
	v_pk_mul_f32 v[254:255], v[2:3], v[98:99]
	v_pk_mul_f32 v[160:161], v[4:5], v[100:101]
	v_pk_fma_f32 v[246:247], v[6:7], v[102:103], v[246:247]
	v_pk_fma_f32 v[254:255], v[8:9], v[104:105], v[254:255]
	v_pk_fma_f32 v[160:161], v[10:11], v[106:107], v[160:161]
	v_pk_fma_f32 v[246:247], v[12:13], v[108:109], v[246:247]
	v_pk_fma_f32 v[254:255], v[14:15], v[110:111], v[254:255]
	v_pk_fma_f32 v[160:161], v[16:17], v[112:113], v[160:161]
	v_pk_fma_f32 v[246:247], v[18:19], v[114:115], v[246:247]
	v_pk_fma_f32 v[254:255], v[20:21], v[116:117], v[254:255]
	v_pk_fma_f32 v[160:161], v[22:23], v[118:119], v[160:161]
	v_pk_fma_f32 v[246:247], v[24:25], v[120:121], v[246:247]
	v_pk_fma_f32 v[254:255], v[26:27], v[122:123], v[254:255]
	v_pk_fma_f32 v[160:161], v[28:29], v[124:125], v[160:161]
	v_pk_fma_f32 v[246:247], v[30:31], v[126:127], v[246:247]
	v_pk_add_f32 v[254:255], v[254:255], v[160:161]
	s_nop 0
	v_pk_add_f32 v[246:247], v[246:247], v[254:255]
	s_nop 0
	v_add_f32_e32 v165, v246, v247
	v_add_f32_dpp v162, v162, v162 row_shr:1 row_mask:0xf bank_mask:0xf bound_ctrl:1
	v_add_f32_dpp v163, v163, v163 row_shr:1 row_mask:0xf bank_mask:0xf bound_ctrl:1
	v_add_f32_dpp v164, v164, v164 row_shr:1 row_mask:0xf bank_mask:0xf bound_ctrl:1
	v_add_f32_dpp v165, v165, v165 row_shr:1 row_mask:0xf bank_mask:0xf bound_ctrl:1
	v_add_f32_dpp v162, v162, v162 row_shr:2 row_mask:0xf bank_mask:0xf bound_ctrl:1
	v_add_f32_dpp v163, v163, v163 row_shr:2 row_mask:0xf bank_mask:0xf bound_ctrl:1
	v_add_f32_dpp v164, v164, v164 row_shr:2 row_mask:0xf bank_mask:0xf bound_ctrl:1
	v_add_f32_dpp v165, v165, v165 row_shr:2 row_mask:0xf bank_mask:0xf bound_ctrl:1
	v_add_f32_dpp v162, v162, v162 row_shr:4 row_mask:0xf bank_mask:0xf bound_ctrl:1
	v_add_f32_dpp v163, v163, v163 row_shr:4 row_mask:0xf bank_mask:0xf bound_ctrl:1
	v_add_f32_dpp v164, v164, v164 row_shr:4 row_mask:0xf bank_mask:0xf bound_ctrl:1
	v_add_f32_dpp v165, v165, v165 row_shr:4 row_mask:0xf bank_mask:0xf bound_ctrl:1
	v_add_f32_dpp v162, v162, v162 row_shr:8 row_mask:0xf bank_mask:0xf bound_ctrl:1
	v_add_f32_dpp v163, v163, v163 row_shr:8 row_mask:0xf bank_mask:0xf bound_ctrl:1
	v_add_f32_dpp v164, v164, v164 row_shr:8 row_mask:0xf bank_mask:0xf bound_ctrl:1
	v_add_f32_dpp v165, v165, v165 row_shr:8 row_mask:0xf bank_mask:0xf bound_ctrl:1
	v_add_f32_dpp v162, v162, v162 row_bcast:15 row_mask:0xa bank_mask:0xf
	v_add_f32_dpp v163, v163, v163 row_bcast:15 row_mask:0xa bank_mask:0xf
	v_add_f32_dpp v164, v164, v164 row_bcast:15 row_mask:0xa bank_mask:0xf
	v_add_f32_dpp v165, v165, v165 row_bcast:15 row_mask:0xa bank_mask:0xf
	s_mov_b64 s[98:99], exec
	s_mov_b32 exec_lo, 0x80000000
	s_mov_b32 exec_hi, 0x80000000
	ds_write_b32 v74, v162 offset:160
	ds_write_b32 v74, v163 offset:168
	ds_write_b32 v74, v164 offset:176
	ds_write_b32 v74, v165 offset:184
	s_mov_b64 exec, s[98:99]
	s_waitcnt vmcnt(14)
; __device__ void peer_gather_phase(const Params& P, int l, bool do_store) {
;     ...
;         v6u_t qv; qv[0] = u6[3 * pr].x; qv[1] = u6[3 * pr].y; qv[2] = u6[3 * pr + 1].x; qv[3] = u6[3 * pr + 1].y; qv[4] = u6[3 * pr + 2].x; qv[5] = u6[3 * pr + 2].y;
;         const v32f_t wv = __builtin_amdgcn_cvt_scalef32_pk32_f32_fp6(qv, 1.0f);
;         f32x2 a2 = f32x2{0.f, 0.f};
; #pragma unroll
;         for (int i = 0; i < 16; ++i) a2 += f32x2{wv[2 * i], wv[2 * i + 1]} * xu[i];
;         float hs = a2.x + a2.y;
;         hs += dpp_row_shr(hs, 1); hs += dpp_row_shr(hs, 2); hs += dpp_row_shr(hs, 4); hs += dpp_row_shr(hs, 8);
;         hs += __builtin_bit_cast(float, __builtin_amdgcn_update_dpp(0, __builtin_bit_cast(int, hs), 0x142, 0xa, 0xf, false));
;         const float da = __builtin_bit_cast(float, __builtin_amdgcn_readlane(__builtin_bit_cast(int, hs), 31));
;         const float db = __builtin_bit_cast(float, __builtin_amdgcn_readlane(__builtin_bit_cast(int, hs), 63));
;         dvec = (lane == kb + 2 * pr) ? da : dvec;
;         dvec = (lane == kb + 2 * pr + 1) ? db : dvec;
	v_cvt_scalef32_pk32_f32_fp6 v[0:31], v[50:55], 1.0
	v_pk_mul_f32 v[246:247], v[0:1], v[96:97]
	v_pk_mul_f32 v[254:255], v[2:3], v[98:99]
	v_pk_mul_f32 v[160:161], v[4:5], v[100:101]
	v_pk_fma_f32 v[246:247], v[6:7], v[102:103], v[246:247]
	v_pk_fma_f32 v[254:255], v[8:9], v[104:105], v[254:255]
	v_pk_fma_f32 v[160:161], v[10:11], v[106:107], v[160:161]
	v_pk_fma_f32 v[246:247], v[12:13], v[108:109], v[246:247]
	v_pk_fma_f32 v[254:255], v[14:15], v[110:111], v[254:255]
	v_pk_fma_f32 v[160:161], v[16:17], v[112:113], v[160:161]
	v_pk_fma_f32 v[246:247], v[18:19], v[114:115], v[246:247]
	v_pk_fma_f32 v[254:255], v[20:21], v[116:117], v[254:255]
	v_pk_fma_f32 v[160:161], v[22:23], v[118:119], v[160:161]
	v_pk_fma_f32 v[246:247], v[24:25], v[120:121], v[246:247]
	v_pk_fma_f32 v[254:255], v[26:27], v[122:123], v[254:255]
	v_pk_fma_f32 v[160:161], v[28:29], v[124:125], v[160:161]
	v_pk_fma_f32 v[246:247], v[30:31], v[126:127], v[246:247]
	v_pk_add_f32 v[254:255], v[254:255], v[160:161]
	s_nop 0
	v_pk_add_f32 v[246:247], v[246:247], v[254:255]
	s_nop 0
	v_add_f32_e32 v162, v246, v247
	s_waitcnt vmcnt(12)
	v_cvt_scalef32_pk32_f32_fp6 v[0:31], v[44:49], 1.0
	v_pk_mul_f32 v[246:247], v[0:1], v[96:97]
	v_pk_mul_f32 v[254:255], v[2:3], v[98:99]
	v_pk_mul_f32 v[160:161], v[4:5], v[100:101]
	v_pk_fma_f32 v[246:247], v[6:7], v[102:103], v[246:247]
	v_pk_fma_f32 v[254:255], v[8:9], v[104:105], v[254:255]
	v_pk_fma_f32 v[160:161], v[10:11], v[106:107], v[160:161]
	v_pk_fma_f32 v[246:247], v[12:13], v[108:109], v[246:247]
	v_pk_fma_f32 v[254:255], v[14:15], v[110:111], v[254:255]
	v_pk_fma_f32 v[160:161], v[16:17], v[112:113], v[160:161]
	v_pk_fma_f32 v[246:247], v[18:19], v[114:115], v[246:247]
	v_pk_fma_f32 v[254:255], v[20:21], v[116:117], v[254:255]
	v_pk_fma_f32 v[160:161], v[22:23], v[118:119], v[160:161]
	v_pk_fma_f32 v[246:247], v[24:25], v[120:121], v[246:247]
	v_pk_fma_f32 v[254:255], v[26:27], v[122:123], v[254:255]
	v_pk_fma_f32 v[160:161], v[28:29], v[124:125], v[160:161]
	v_pk_fma_f32 v[246:247], v[30:31], v[126:127], v[246:247]
	v_pk_add_f32 v[254:255], v[254:255], v[160:161]
	s_nop 0
	v_pk_add_f32 v[246:247], v[246:247], v[254:255]
	s_nop 0
	v_add_f32_e32 v163, v246, v247
	s_waitcnt vmcnt(10)
	v_cvt_scalef32_pk32_f32_fp6 v[0:31], v[38:43], 1.0
	v_pk_mul_f32 v[246:247], v[0:1], v[96:97]
	v_pk_mul_f32 v[254:255], v[2:3], v[98:99]
	v_pk_mul_f32 v[160:161], v[4:5], v[100:101]
	v_pk_fma_f32 v[246:247], v[6:7], v[102:103], v[246:247]
	v_pk_fma_f32 v[254:255], v[8:9], v[104:105], v[254:255]
	v_pk_fma_f32 v[160:161], v[10:11], v[106:107], v[160:161]
	v_pk_fma_f32 v[246:247], v[12:13], v[108:109], v[246:247]
	v_pk_fma_f32 v[254:255], v[14:15], v[110:111], v[254:255]
	v_pk_fma_f32 v[160:161], v[16:17], v[112:113], v[160:161]
	v_pk_fma_f32 v[246:247], v[18:19], v[114:115], v[246:247]
	v_pk_fma_f32 v[254:255], v[20:21], v[116:117], v[254:255]
	v_pk_fma_f32 v[160:161], v[22:23], v[118:119], v[160:161]
	v_pk_fma_f32 v[246:247], v[24:25], v[120:121], v[246:247]
	v_pk_fma_f32 v[254:255], v[26:27], v[122:123], v[254:255]
	v_pk_fma_f32 v[160:161], v[28:29], v[124:125], v[160:161]
	v_pk_fma_f32 v[246:247], v[30:31], v[126:127], v[246:247]
	v_pk_add_f32 v[254:255], v[254:255], v[160:161]
	s_nop 0
	v_pk_add_f32 v[246:247], v[246:247], v[254:255]
	s_nop 0
	v_add_f32_e32 v164, v246, v247
	s_waitcnt vmcnt(8)
	v_cvt_scalef32_pk32_f32_fp6 v[0:31], v[32:37], 1.0
	v_pk_mul_f32 v[246:247], v[0:1], v[96:97]
	v_pk_mul_f32 v[254:255], v[2:3], v[98:99]
	v_pk_mul_f32 v[160:161], v[4:5], v[100:101]
	v_pk_fma_f32 v[246:247], v[6:7], v[102:103], v[246:247]
	v_pk_fma_f32 v[254:255], v[8:9], v[104:105], v[254:255]
	v_pk_fma_f32 v[160:161], v[10:11], v[106:107], v[160:161]
	v_pk_fma_f32 v[246:247], v[12:13], v[108:109], v[246:247]
	v_pk_fma_f32 v[254:255], v[14:15], v[110:111], v[254:255]
	v_pk_fma_f32 v[160:161], v[16:17], v[112:113], v[160:161]
	v_pk_fma_f32 v[246:247], v[18:19], v[114:115], v[246:247]
	v_pk_fma_f32 v[254:255], v[20:21], v[116:117], v[254:255]
	v_pk_fma_f32 v[160:161], v[22:23], v[118:119], v[160:161]
	v_pk_fma_f32 v[246:247], v[24:25], v[120:121], v[246:247]
	v_pk_fma_f32 v[254:255], v[26:27], v[122:123], v[254:255]
	v_pk_fma_f32 v[160:161], v[28:29], v[124:125], v[160:161]
	v_pk_fma_f32 v[246:247], v[30:31], v[126:127], v[246:247]
	v_pk_add_f32 v[254:255], v[254:255], v[160:161]
	s_nop 0
	v_pk_add_f32 v[246:247], v[246:247], v[254:255]
	s_nop 0
	v_add_f32_e32 v165, v246, v247
	v_add_f32_dpp v162, v162, v162 row_shr:1 row_mask:0xf bank_mask:0xf bound_ctrl:1
	v_add_f32_dpp v163, v163, v163 row_shr:1 row_mask:0xf bank_mask:0xf bound_ctrl:1
	v_add_f32_dpp v164, v164, v164 row_shr:1 row_mask:0xf bank_mask:0xf bound_ctrl:1
	v_add_f32_dpp v165, v165, v165 row_shr:1 row_mask:0xf bank_mask:0xf bound_ctrl:1
	v_add_f32_dpp v162, v162, v162 row_shr:2 row_mask:0xf bank_mask:0xf bound_ctrl:1
	v_add_f32_dpp v163, v163, v163 row_shr:2 row_mask:0xf bank_mask:0xf bound_ctrl:1
	v_add_f32_dpp v164, v164, v164 row_shr:2 row_mask:0xf bank_mask:0xf bound_ctrl:1
	v_add_f32_dpp v165, v165, v165 row_shr:2 row_mask:0xf bank_mask:0xf bound_ctrl:1
	v_add_f32_dpp v162, v162, v162 row_shr:4 row_mask:0xf bank_mask:0xf bound_ctrl:1
	v_add_f32_dpp v163, v163, v163 row_shr:4 row_mask:0xf bank_mask:0xf bound_ctrl:1
	v_add_f32_dpp v164, v164, v164 row_shr:4 row_mask:0xf bank_mask:0xf bound_ctrl:1
	v_add_f32_dpp v165, v165, v165 row_shr:4 row_mask:0xf bank_mask:0xf bound_ctrl:1
	v_add_f32_dpp v162, v162, v162 row_shr:8 row_mask:0xf bank_mask:0xf bound_ctrl:1
	v_add_f32_dpp v163, v163, v163 row_shr:8 row_mask:0xf bank_mask:0xf bound_ctrl:1
	v_add_f32_dpp v164, v164, v164 row_shr:8 row_mask:0xf bank_mask:0xf bound_ctrl:1
	v_add_f32_dpp v165, v165, v165 row_shr:8 row_mask:0xf bank_mask:0xf bound_ctrl:1
	v_add_f32_dpp v162, v162, v162 row_bcast:15 row_mask:0xa bank_mask:0xf
	v_add_f32_dpp v163, v163, v163 row_bcast:15 row_mask:0xa bank_mask:0xf
	v_add_f32_dpp v164, v164, v164 row_bcast:15 row_mask:0xa bank_mask:0xf
	v_add_f32_dpp v165, v165, v165 row_bcast:15 row_mask:0xa bank_mask:0xf
	s_mov_b64 s[98:99], exec
	s_mov_b32 exec_lo, 0x80000000
	s_mov_b32 exec_hi, 0x80000000
	ds_write_b32 v74, v162 offset:192
	ds_write_b32 v74, v163 offset:200
	ds_write_b32 v74, v164 offset:208
	ds_write_b32 v74, v165 offset:216
	s_mov_b64 exec, s[98:99]
	s_waitcnt vmcnt(6)
; __device__ void peer_gather_phase(const Params& P, int l, bool do_store) {
;     ...
;         v6u_t qv; qv[0] = u6[3 * pr].x; qv[1] = u6[3 * pr].y; qv[2] = u6[3 * pr + 1].x; qv[3] = u6[3 * pr + 1].y; qv[4] = u6[3 * pr + 2].x; qv[5] = u6[3 * pr + 2].y;
;         const v32f_t wv = __builtin_amdgcn_cvt_scalef32_pk32_f32_fp6(qv, 1.0f);
;         f32x2 a2 = f32x2{0.f, 0.f};
; #pragma unroll
;         for (int i = 0; i < 16; ++i) a2 += f32x2{wv[2 * i], wv[2 * i + 1]} * xu[i];
;         float hs = a2.x + a2.y;
;         hs += dpp_row_shr(hs, 1); hs += dpp_row_shr(hs, 2); hs += dpp_row_shr(hs, 4); hs += dpp_row_shr(hs, 8);
;         hs += __builtin_bit_cast(float, __builtin_amdgcn_update_dpp(0, __builtin_bit_cast(int, hs), 0x142, 0xa, 0xf, false));
;         const float da = __builtin_bit_cast(float, __builtin_amdgcn_readlane(__builtin_bit_cast(int, hs), 31));
;         const float db = __builtin_bit_cast(float, __builtin_amdgcn_readlane(__builtin_bit_cast(int, hs), 63));
;         dvec = (lane == kb + 2 * pr) ? da : dvec;
;         dvec = (lane == kb + 2 * pr + 1) ? db : dvec;
	v_cvt_scalef32_pk32_f32_fp6 v[0:31], v[196:201], 1.0
	v_pk_mul_f32 v[246:247], v[0:1], v[96:97]
	v_pk_mul_f32 v[254:255], v[2:3], v[98:99]
	v_pk_mul_f32 v[160:161], v[4:5], v[100:101]
	v_pk_fma_f32 v[246:247], v[6:7], v[102:103], v[246:247]
	v_pk_fma_f32 v[254:255], v[8:9], v[104:105], v[254:255]
	v_pk_fma_f32 v[160:161], v[10:11], v[106:107], v[160:161]
	v_pk_fma_f32 v[246:247], v[12:13], v[108:109], v[246:247]
	v_pk_fma_f32 v[254:255], v[14:15], v[110:111], v[254:255]
	v_pk_fma_f32 v[160:161], v[16:17], v[112:113], v[160:161]
	v_pk_fma_f32 v[246:247], v[18:19], v[114:115], v[246:247]
	v_pk_fma_f32 v[254:255], v[20:21], v[116:117], v[254:255]
	v_pk_fma_f32 v[160:161], v[22:23], v[118:119], v[160:161]
	v_pk_fma_f32 v[246:247], v[24:25], v[120:121], v[246:247]
	v_pk_fma_f32 v[254:255], v[26:27], v[122:123], v[254:255]
	v_pk_fma_f32 v[160:161], v[28:29], v[124:125], v[160:161]
	v_pk_fma_f32 v[246:247], v[30:31], v[126:127], v[246:247]
	v_pk_add_f32 v[254:255], v[254:255], v[160:161]
	s_nop 0
	v_pk_add_f32 v[246:247], v[246:247], v[254:255]
	s_nop 0
	v_add_f32_e32 v162, v246, v247
	s_waitcnt vmcnt(4)
	v_cvt_scalef32_pk32_f32_fp6 v[0:31], v[228:233], 1.0
	v_pk_mul_f32 v[246:247], v[0:1], v[96:97]
	v_pk_mul_f32 v[254:255], v[2:3], v[98:99]
	v_pk_mul_f32 v[160:161], v[4:5], v[100:101]
	v_pk_fma_f32 v[246:247], v[6:7], v[102:103], v[246:247]
	v_pk_fma_f32 v[254:255], v[8:9], v[104:105], v[254:255]
	v_pk_fma_f32 v[160:161], v[10:11], v[106:107], v[160:161]
	v_pk_fma_f32 v[246:247], v[12:13], v[108:109], v[246:247]
	v_pk_fma_f32 v[254:255], v[14:15], v[110:111], v[254:255]
	v_pk_fma_f32 v[160:161], v[16:17], v[112:113], v[160:161]
	v_pk_fma_f32 v[246:247], v[18:19], v[114:115], v[246:247]
	v_pk_fma_f32 v[254:255], v[20:21], v[116:117], v[254:255]
	v_pk_fma_f32 v[160:161], v[22:23], v[118:119], v[160:161]
	v_pk_fma_f32 v[246:247], v[24:25], v[120:121], v[246:247]
	v_pk_fma_f32 v[254:255], v[26:27], v[122:123], v[254:255]
	v_pk_fma_f32 v[160:161], v[28:29], v[124:125], v[160:161]
	v_pk_fma_f32 v[246:247], v[30:31], v[126:127], v[246:247]
	v_pk_add_f32 v[254:255], v[254:255], v[160:161]
	s_nop 0
	v_pk_add_f32 v[246:247], v[246:247], v[254:255]
	s_nop 0
	v_add_f32_e32 v163, v246, v247
	s_waitcnt vmcnt(2)
	v_cvt_scalef32_pk32_f32_fp6 v[0:31], v[234:239], 1.0
	v_pk_mul_f32 v[246:247], v[0:1], v[96:97]
	v_pk_mul_f32 v[254:255], v[2:3], v[98:99]
	v_pk_mul_f32 v[160:161], v[4:5], v[100:101]
	v_pk_fma_f32 v[246:247], v[6:7], v[102:103], v[246:247]
	v_pk_fma_f32 v[254:255], v[8:9], v[104:105], v[254:255]
	v_pk_fma_f32 v[160:161], v[10:11], v[106:107], v[160:161]
	v_pk_fma_f32 v[246:247], v[12:13], v[108:109], v[246:247]
	v_pk_fma_f32 v[254:255], v[14:15], v[110:111], v[254:255]
	v_pk_fma_f32 v[160:161], v[16:17], v[112:113], v[160:161]
	v_pk_fma_f32 v[246:247], v[18:19], v[114:115], v[246:247]
	v_pk_fma_f32 v[254:255], v[20:21], v[116:117], v[254:255]
	v_pk_fma_f32 v[160:161], v[22:23], v[118:119], v[160:161]
	v_pk_fma_f32 v[246:247], v[24:25], v[120:121], v[246:247]
	v_pk_fma_f32 v[254:255], v[26:27], v[122:123], v[254:255]
	v_pk_fma_f32 v[160:161], v[28:29], v[124:125], v[160:161]
	v_pk_fma_f32 v[246:247], v[30:31], v[126:127], v[246:247]
	v_pk_add_f32 v[254:255], v[254:255], v[160:161]
	s_nop 0
	v_pk_add_f32 v[246:247], v[246:247], v[254:255]
	s_nop 0
	v_add_f32_e32 v164, v246, v247
	s_waitcnt vmcnt(0)
	v_cvt_scalef32_pk32_f32_fp6 v[0:31], v[240:245], 1.0
	v_pk_mul_f32 v[246:247], v[0:1], v[96:97]
	v_pk_mul_f32 v[254:255], v[2:3], v[98:99]
	v_pk_mul_f32 v[160:161], v[4:5], v[100:101]
	v_pk_fma_f32 v[246:247], v[6:7], v[102:103], v[246:247]
	v_pk_fma_f32 v[254:255], v[8:9], v[104:105], v[254:255]
	v_pk_fma_f32 v[160:161], v[10:11], v[106:107], v[160:161]
	v_pk_fma_f32 v[246:247], v[12:13], v[108:109], v[246:247]
	v_pk_fma_f32 v[254:255], v[14:15], v[110:111], v[254:255]
	v_pk_fma_f32 v[160:161], v[16:17], v[112:113], v[160:161]
	v_pk_fma_f32 v[246:247], v[18:19], v[114:115], v[246:247]
	v_pk_fma_f32 v[254:255], v[20:21], v[116:117], v[254:255]
	v_pk_fma_f32 v[160:161], v[22:23], v[118:119], v[160:161]
	v_pk_fma_f32 v[246:247], v[24:25], v[120:121], v[246:247]
	v_pk_fma_f32 v[254:255], v[26:27], v[122:123], v[254:255]
	v_pk_fma_f32 v[160:161], v[28:29], v[124:125], v[160:161]
	v_pk_fma_f32 v[246:247], v[30:31], v[126:127], v[246:247]
	v_pk_add_f32 v[254:255], v[254:255], v[160:161]
	s_nop 0
	v_pk_add_f32 v[246:247], v[246:247], v[254:255]
	s_nop 0
	v_add_f32_e32 v165, v246, v247
	v_add_f32_dpp v162, v162, v162 row_shr:1 row_mask:0xf bank_mask:0xf bound_ctrl:1
	v_add_f32_dpp v163, v163, v163 row_shr:1 row_mask:0xf bank_mask:0xf bound_ctrl:1
	v_add_f32_dpp v164, v164, v164 row_shr:1 row_mask:0xf bank_mask:0xf bound_ctrl:1
	v_add_f32_dpp v165, v165, v165 row_shr:1 row_mask:0xf bank_mask:0xf bound_ctrl:1
	v_add_f32_dpp v162, v162, v162 row_shr:2 row_mask:0xf bank_mask:0xf bound_ctrl:1
	v_add_f32_dpp v163, v163, v163 row_shr:2 row_mask:0xf bank_mask:0xf bound_ctrl:1
	v_add_f32_dpp v164, v164, v164 row_shr:2 row_mask:0xf bank_mask:0xf bound_ctrl:1
	v_add_f32_dpp v165, v165, v165 row_shr:2 row_mask:0xf bank_mask:0xf bound_ctrl:1
	v_add_f32_dpp v162, v162, v162 row_shr:4 row_mask:0xf bank_mask:0xf bound_ctrl:1
	v_add_f32_dpp v163, v163, v163 row_shr:4 row_mask:0xf bank_mask:0xf bound_ctrl:1
	v_add_f32_dpp v164, v164, v164 row_shr:4 row_mask:0xf bank_mask:0xf bound_ctrl:1
	v_add_f32_dpp v165, v165, v165 row_shr:4 row_mask:0xf bank_mask:0xf bound_ctrl:1
	v_add_f32_dpp v162, v162, v162 row_shr:8 row_mask:0xf bank_mask:0xf bound_ctrl:1
	v_add_f32_dpp v163, v163, v163 row_shr:8 row_mask:0xf bank_mask:0xf bound_ctrl:1
	v_add_f32_dpp v164, v164, v164 row_shr:8 row_mask:0xf bank_mask:0xf bound_ctrl:1
	v_add_f32_dpp v165, v165, v165 row_shr:8 row_mask:0xf bank_mask:0xf bound_ctrl:1
	v_add_f32_dpp v162, v162, v162 row_bcast:15 row_mask:0xa bank_mask:0xf
	v_add_f32_dpp v163, v163, v163 row_bcast:15 row_mask:0xa bank_mask:0xf
	v_add_f32_dpp v164, v164, v164 row_bcast:15 row_mask:0xa bank_mask:0xf
	v_add_f32_dpp v165, v165, v165 row_bcast:15 row_mask:0xa bank_mask:0xf
	s_mov_b64 s[98:99], exec
	s_mov_b32 exec_lo, 0x80000000
	s_mov_b32 exec_hi, 0x80000000
	ds_write_b32 v74, v162 offset:224
	ds_write_b32 v74, v163 offset:232
	ds_write_b32 v74, v164 offset:240
	ds_write_b32 v74, v165 offset:248
	s_mov_b64 exec, s[98:99]
	ds_read_b32 v166, v75
	s_waitcnt lgkmcnt(0)
; __device__ void peer_gather_phase(const Params& P, int l, bool do_store) {
;     ...
;         v8[2 * pr] = *(const uint2*)(V + (size_t)ea * 512);
;         v8[2 * pr + 1] = *(const uint2*)(V + (size_t)eb * 512);
;     ...
;       const float sux = (bt < 8) ? sux0 : sux1;
;       const float gsx = (bt < 8) ? gsx0 : gsx1;
;       const float avec = gelu_t(dvec * sux) * gsx;
; #pragma unroll
;       for (int j = 0; j < 8; ++j) {
;         const float a = __builtin_bit_cast(float, __builtin_amdgcn_readlane(__builtin_bit_cast(int, avec), kb + j));
;         const f32x2 aa = f32x2{a, a};
;         y[0] += aa * __builtin_amdgcn_cvt_scalef32_pk_f32_fp4(v8[j].x, 1.0f, 0); y[1] += aa * __builtin_amdgcn_cvt_scalef32_pk_f32_fp4(v8[j].x, 1.0f, 1);
;         y[2] += aa * __builtin_amdgcn_cvt_scalef32_pk_f32_fp4(v8[j].x, 1.0f, 2); y[3] += aa * __builtin_amdgcn_cvt_scalef32_pk_f32_fp4(v8[j].x, 1.0f, 3);
;         y[4] += aa * __builtin_amdgcn_cvt_scalef32_pk_f32_fp4(v8[j].y, 1.0f, 0); y[5] += aa * __builtin_amdgcn_cvt_scalef32_pk_f32_fp4(v8[j].y, 1.0f, 1);
;         y[6] += aa * __builtin_amdgcn_cvt_scalef32_pk_f32_fp4(v8[j].y, 1.0f, 2); y[7] += aa * __builtin_amdgcn_cvt_scalef32_pk_f32_fp4(v8[j].y, 1.0f, 3);
;       }
	v_mul_f32_e32 v0, v190, v166
	v_mul_f32_e32 v1, 0x3d372713, v0
	v_mul_f32_e32 v1, v0, v1
	v_fma_f32 v1, v0, v1, v0
	v_mul_f32_e32 v1, 0x3f4c422a, v1
	v_add_f32_e32 v1, v1, v1
	v_mul_f32_e32 v1, 0x3fb8aa3b, v1
	v_exp_f32_e32 v1, v1
	v_mul_f32_e32 v0, 0.5, v0
	v_add_f32_e32 v1, 1.0, v1
	v_div_scale_f32 v2, s[0:1], v1, v1, 2.0
	v_rcp_f32_e32 v3, v2
	s_nop 0
	v_fma_f32 v4, -v2, v3, 1.0
	v_fmac_f32_e32 v3, v4, v3
	v_div_scale_f32 v4, vcc, 2.0, v1, 2.0
	v_mul_f32_e32 v5, v4, v3
	v_fma_f32 v6, -v2, v5, v4
	v_fmac_f32_e32 v5, v6, v3
	v_fma_f32 v2, -v2, v5, v4
	v_div_fmas_f32 v2, v2, v3, v5
	v_div_fixup_f32 v1, v2, v1, 2.0
	v_sub_f32_e32 v1, 1.0, v1
	v_add_f32_e32 v1, 1.0, v1
	v_mul_f32_e32 v0, v0, v1
	v_mul_f32_e32 v167, v192, v0
	s_nop 1
	v_readlane_b32 s0, v167, 0
	s_waitcnt vmcnt(48)
	v_cvt_scalef32_pk_f32_fp4 v[0:1], v144, 1.0
	v_cvt_scalef32_pk_f32_fp4 v[2:3], v144, 1.0 op_sel:[1,0,0]
	v_cvt_scalef32_pk_f32_fp4 v[4:5], v144, 1.0 op_sel:[0,1,0]
	v_cvt_scalef32_pk_f32_fp4 v[6:7], v144, 1.0 op_sel:[1,1,0]
	v_cvt_scalef32_pk_f32_fp4 v[8:9], v145, 1.0
	v_cvt_scalef32_pk_f32_fp4 v[10:11], v145, 1.0 op_sel:[1,0,0]
	v_cvt_scalef32_pk_f32_fp4 v[12:13], v145, 1.0 op_sel:[0,1,0]
	v_cvt_scalef32_pk_f32_fp4 v[14:15], v145, 1.0 op_sel:[1,1,0]
	v_readlane_b32 s54, v90, 16
	s_lshl_b32 s56, s54, 9
	s_add_u32 s56, s64, s56
	s_addc_u32 s57, s65, 0
	global_load_dwordx2 v[144:145], v227, s[56:57]
	v_pk_fma_f32 v[130:131], v[0:1], s[0:1], v[130:131] op_sel_hi:[1,0,1]
	v_pk_fma_f32 v[138:139], v[2:3], s[0:1], v[138:139] op_sel_hi:[1,0,1]
	v_pk_fma_f32 v[140:141], v[4:5], s[0:1], v[140:141] op_sel_hi:[1,0,1]
	v_pk_fma_f32 v[142:143], v[6:7], s[0:1], v[142:143] op_sel_hi:[1,0,1]
	v_pk_fma_f32 v[128:129], v[8:9], s[0:1], v[128:129] op_sel_hi:[1,0,1]
	v_pk_fma_f32 v[132:133], v[10:11], s[0:1], v[132:133] op_sel_hi:[1,0,1]
	v_pk_fma_f32 v[134:135], v[12:13], s[0:1], v[134:135] op_sel_hi:[1,0,1]
	v_pk_fma_f32 v[136:137], v[14:15], s[0:1], v[136:137] op_sel_hi:[1,0,1]
	v_readlane_b32 s0, v167, 1
	s_waitcnt vmcnt(48)
	v_cvt_scalef32_pk_f32_fp4 v[0:1], v146, 1.0
	v_cvt_scalef32_pk_f32_fp4 v[2:3], v146, 1.0 op_sel:[1,0,0]
	v_cvt_scalef32_pk_f32_fp4 v[4:5], v146, 1.0 op_sel:[0,1,0]
	v_cvt_scalef32_pk_f32_fp4 v[6:7], v146, 1.0 op_sel:[1,1,0]
	v_cvt_scalef32_pk_f32_fp4 v[8:9], v147, 1.0
	v_cvt_scalef32_pk_f32_fp4 v[10:11], v147, 1.0 op_sel:[1,0,0]
	v_cvt_scalef32_pk_f32_fp4 v[12:13], v147, 1.0 op_sel:[0,1,0]
	v_cvt_scalef32_pk_f32_fp4 v[14:15], v147, 1.0 op_sel:[1,1,0]
	v_readlane_b32 s54, v90, 17
	s_lshl_b32 s56, s54, 9
	s_add_u32 s56, s64, s56
	s_addc_u32 s57, s65, 0
	global_load_dwordx2 v[146:147], v227, s[56:57]
	v_pk_fma_f32 v[130:131], v[0:1], s[0:1], v[130:131] op_sel_hi:[1,0,1]
	v_pk_fma_f32 v[138:139], v[2:3], s[0:1], v[138:139] op_sel_hi:[1,0,1]
	v_pk_fma_f32 v[140:141], v[4:5], s[0:1], v[140:141] op_sel_hi:[1,0,1]
	v_pk_fma_f32 v[142:143], v[6:7], s[0:1], v[142:143] op_sel_hi:[1,0,1]
	v_pk_fma_f32 v[128:129], v[8:9], s[0:1], v[128:129] op_sel_hi:[1,0,1]
	v_pk_fma_f32 v[132:133], v[10:11], s[0:1], v[132:133] op_sel_hi:[1,0,1]
	v_pk_fma_f32 v[134:135], v[12:13], s[0:1], v[134:135] op_sel_hi:[1,0,1]
	v_pk_fma_f32 v[136:137], v[14:15], s[0:1], v[136:137] op_sel_hi:[1,0,1]
	v_readlane_b32 s0, v167, 2
	s_waitcnt vmcnt(48)
	v_cvt_scalef32_pk_f32_fp4 v[0:1], v148, 1.0
	v_cvt_scalef32_pk_f32_fp4 v[2:3], v148, 1.0 op_sel:[1,0,0]
	v_cvt_scalef32_pk_f32_fp4 v[4:5], v148, 1.0 op_sel:[0,1,0]
	v_cvt_scalef32_pk_f32_fp4 v[6:7], v148, 1.0 op_sel:[1,1,0]
	v_cvt_scalef32_pk_f32_fp4 v[8:9], v149, 1.0
	v_cvt_scalef32_pk_f32_fp4 v[10:11], v149, 1.0 op_sel:[1,0,0]
	v_cvt_scalef32_pk_f32_fp4 v[12:13], v149, 1.0 op_sel:[0,1,0]
	v_cvt_scalef32_pk_f32_fp4 v[14:15], v149, 1.0 op_sel:[1,1,0]
	v_readlane_b32 s54, v90, 18
	s_lshl_b32 s56, s54, 9
	s_add_u32 s56, s64, s56
	s_addc_u32 s57, s65, 0
	global_load_dwordx2 v[148:149], v227, s[56:57]
	v_pk_fma_f32 v[130:131], v[0:1], s[0:1], v[130:131] op_sel_hi:[1,0,1]
	v_pk_fma_f32 v[138:139], v[2:3], s[0:1], v[138:139] op_sel_hi:[1,0,1]
	v_pk_fma_f32 v[140:141], v[4:5], s[0:1], v[140:141] op_sel_hi:[1,0,1]
	v_pk_fma_f32 v[142:143], v[6:7], s[0:1], v[142:143] op_sel_hi:[1,0,1]
	v_pk_fma_f32 v[128:129], v[8:9], s[0:1], v[128:129] op_sel_hi:[1,0,1]
	v_pk_fma_f32 v[132:133], v[10:11], s[0:1], v[132:133] op_sel_hi:[1,0,1]
	v_pk_fma_f32 v[134:135], v[12:13], s[0:1], v[134:135] op_sel_hi:[1,0,1]
	v_pk_fma_f32 v[136:137], v[14:15], s[0:1], v[136:137] op_sel_hi:[1,0,1]
	v_readlane_b32 s0, v167, 3
	s_waitcnt vmcnt(48)
	v_cvt_scalef32_pk_f32_fp4 v[0:1], v150, 1.0
	v_cvt_scalef32_pk_f32_fp4 v[2:3], v150, 1.0 op_sel:[1,0,0]
	v_cvt_scalef32_pk_f32_fp4 v[4:5], v150, 1.0 op_sel:[0,1,0]
	v_cvt_scalef32_pk_f32_fp4 v[6:7], v150, 1.0 op_sel:[1,1,0]
	v_cvt_scalef32_pk_f32_fp4 v[8:9], v151, 1.0
	v_cvt_scalef32_pk_f32_fp4 v[10:11], v151, 1.0 op_sel:[1,0,0]
	v_cvt_scalef32_pk_f32_fp4 v[12:13], v151, 1.0 op_sel:[0,1,0]
	v_cvt_scalef32_pk_f32_fp4 v[14:15], v151, 1.0 op_sel:[1,1,0]
	v_readlane_b32 s54, v90, 19
	s_lshl_b32 s56, s54, 9
	s_add_u32 s56, s64, s56
	s_addc_u32 s57, s65, 0
	global_load_dwordx2 v[150:151], v227, s[56:57]
	v_pk_fma_f32 v[130:131], v[0:1], s[0:1], v[130:131] op_sel_hi:[1,0,1]
	v_pk_fma_f32 v[138:139], v[2:3], s[0:1], v[138:139] op_sel_hi:[1,0,1]
	v_pk_fma_f32 v[140:141], v[4:5], s[0:1], v[140:141] op_sel_hi:[1,0,1]
	v_pk_fma_f32 v[142:143], v[6:7], s[0:1], v[142:143] op_sel_hi:[1,0,1]
	v_pk_fma_f32 v[128:129], v[8:9], s[0:1], v[128:129] op_sel_hi:[1,0,1]
	v_pk_fma_f32 v[132:133], v[10:11], s[0:1], v[132:133] op_sel_hi:[1,0,1]
	v_pk_fma_f32 v[134:135], v[12:13], s[0:1], v[134:135] op_sel_hi:[1,0,1]
	v_pk_fma_f32 v[136:137], v[14:15], s[0:1], v[136:137] op_sel_hi:[1,0,1]
	v_readlane_b32 s0, v167, 4
	s_waitcnt vmcnt(48)
; __device__ void peer_gather_phase(const Params& P, int l, bool do_store) {
;     ...
;         v8[2 * pr] = *(const uint2*)(V + (size_t)ea * 512);
;         v8[2 * pr + 1] = *(const uint2*)(V + (size_t)eb * 512);
;     ...
;       for (int j = 0; j < 8; ++j) {
;         const float a = __builtin_bit_cast(float, __builtin_amdgcn_readlane(__builtin_bit_cast(int, avec), kb + j));
;         const f32x2 aa = f32x2{a, a};
;         y[0] += aa * __builtin_amdgcn_cvt_scalef32_pk_f32_fp4(v8[j].x, 1.0f, 0); y[1] += aa * __builtin_amdgcn_cvt_scalef32_pk_f32_fp4(v8[j].x, 1.0f, 1);
;         y[2] += aa * __builtin_amdgcn_cvt_scalef32_pk_f32_fp4(v8[j].x, 1.0f, 2); y[3] += aa * __builtin_amdgcn_cvt_scalef32_pk_f32_fp4(v8[j].x, 1.0f, 3);
;         y[4] += aa * __builtin_amdgcn_cvt_scalef32_pk_f32_fp4(v8[j].y, 1.0f, 0); y[5] += aa * __builtin_amdgcn_cvt_scalef32_pk_f32_fp4(v8[j].y, 1.0f, 1);
;         y[6] += aa * __builtin_amdgcn_cvt_scalef32_pk_f32_fp4(v8[j].y, 1.0f, 2); y[7] += aa * __builtin_amdgcn_cvt_scalef32_pk_f32_fp4(v8[j].y, 1.0f, 3);
;       }
	v_cvt_scalef32_pk_f32_fp4 v[0:1], v152, 1.0
	v_cvt_scalef32_pk_f32_fp4 v[2:3], v152, 1.0 op_sel:[1,0,0]
	v_cvt_scalef32_pk_f32_fp4 v[4:5], v152, 1.0 op_sel:[0,1,0]
	v_cvt_scalef32_pk_f32_fp4 v[6:7], v152, 1.0 op_sel:[1,1,0]
	v_cvt_scalef32_pk_f32_fp4 v[8:9], v153, 1.0
	v_cvt_scalef32_pk_f32_fp4 v[10:11], v153, 1.0 op_sel:[1,0,0]
	v_cvt_scalef32_pk_f32_fp4 v[12:13], v153, 1.0 op_sel:[0,1,0]
	v_cvt_scalef32_pk_f32_fp4 v[14:15], v153, 1.0 op_sel:[1,1,0]
	v_readlane_b32 s54, v90, 20
	s_lshl_b32 s56, s54, 9
	s_add_u32 s56, s64, s56
	s_addc_u32 s57, s65, 0
	global_load_dwordx2 v[152:153], v227, s[56:57]
	v_pk_fma_f32 v[130:131], v[0:1], s[0:1], v[130:131] op_sel_hi:[1,0,1]
	v_pk_fma_f32 v[138:139], v[2:3], s[0:1], v[138:139] op_sel_hi:[1,0,1]
	v_pk_fma_f32 v[140:141], v[4:5], s[0:1], v[140:141] op_sel_hi:[1,0,1]
	v_pk_fma_f32 v[142:143], v[6:7], s[0:1], v[142:143] op_sel_hi:[1,0,1]
	v_pk_fma_f32 v[128:129], v[8:9], s[0:1], v[128:129] op_sel_hi:[1,0,1]
	v_pk_fma_f32 v[132:133], v[10:11], s[0:1], v[132:133] op_sel_hi:[1,0,1]
	v_pk_fma_f32 v[134:135], v[12:13], s[0:1], v[134:135] op_sel_hi:[1,0,1]
	v_pk_fma_f32 v[136:137], v[14:15], s[0:1], v[136:137] op_sel_hi:[1,0,1]
	v_readlane_b32 s0, v167, 5
	s_waitcnt vmcnt(48)
	v_cvt_scalef32_pk_f32_fp4 v[0:1], v154, 1.0
	v_cvt_scalef32_pk_f32_fp4 v[2:3], v154, 1.0 op_sel:[1,0,0]
	v_cvt_scalef32_pk_f32_fp4 v[4:5], v154, 1.0 op_sel:[0,1,0]
	v_cvt_scalef32_pk_f32_fp4 v[6:7], v154, 1.0 op_sel:[1,1,0]
	v_cvt_scalef32_pk_f32_fp4 v[8:9], v155, 1.0
	v_cvt_scalef32_pk_f32_fp4 v[10:11], v155, 1.0 op_sel:[1,0,0]
	v_cvt_scalef32_pk_f32_fp4 v[12:13], v155, 1.0 op_sel:[0,1,0]
	v_cvt_scalef32_pk_f32_fp4 v[14:15], v155, 1.0 op_sel:[1,1,0]
	v_readlane_b32 s54, v90, 21
	s_lshl_b32 s56, s54, 9
	s_add_u32 s56, s64, s56
	s_addc_u32 s57, s65, 0
	global_load_dwordx2 v[154:155], v227, s[56:57]
	v_pk_fma_f32 v[130:131], v[0:1], s[0:1], v[130:131] op_sel_hi:[1,0,1]
	v_pk_fma_f32 v[138:139], v[2:3], s[0:1], v[138:139] op_sel_hi:[1,0,1]
	v_pk_fma_f32 v[140:141], v[4:5], s[0:1], v[140:141] op_sel_hi:[1,0,1]
	v_pk_fma_f32 v[142:143], v[6:7], s[0:1], v[142:143] op_sel_hi:[1,0,1]
	v_pk_fma_f32 v[128:129], v[8:9], s[0:1], v[128:129] op_sel_hi:[1,0,1]
	v_pk_fma_f32 v[132:133], v[10:11], s[0:1], v[132:133] op_sel_hi:[1,0,1]
	v_pk_fma_f32 v[134:135], v[12:13], s[0:1], v[134:135] op_sel_hi:[1,0,1]
	v_pk_fma_f32 v[136:137], v[14:15], s[0:1], v[136:137] op_sel_hi:[1,0,1]
	v_readlane_b32 s0, v167, 6
	s_waitcnt vmcnt(48)
	v_cvt_scalef32_pk_f32_fp4 v[0:1], v156, 1.0
	v_cvt_scalef32_pk_f32_fp4 v[2:3], v156, 1.0 op_sel:[1,0,0]
	v_cvt_scalef32_pk_f32_fp4 v[4:5], v156, 1.0 op_sel:[0,1,0]
	v_cvt_scalef32_pk_f32_fp4 v[6:7], v156, 1.0 op_sel:[1,1,0]
	v_cvt_scalef32_pk_f32_fp4 v[8:9], v157, 1.0
	v_cvt_scalef32_pk_f32_fp4 v[10:11], v157, 1.0 op_sel:[1,0,0]
	v_cvt_scalef32_pk_f32_fp4 v[12:13], v157, 1.0 op_sel:[0,1,0]
	v_cvt_scalef32_pk_f32_fp4 v[14:15], v157, 1.0 op_sel:[1,1,0]
	v_readlane_b32 s54, v90, 22
	s_lshl_b32 s56, s54, 9
	s_add_u32 s56, s64, s56
	s_addc_u32 s57, s65, 0
	global_load_dwordx2 v[156:157], v227, s[56:57]
	v_pk_fma_f32 v[130:131], v[0:1], s[0:1], v[130:131] op_sel_hi:[1,0,1]
	v_pk_fma_f32 v[138:139], v[2:3], s[0:1], v[138:139] op_sel_hi:[1,0,1]
	v_pk_fma_f32 v[140:141], v[4:5], s[0:1], v[140:141] op_sel_hi:[1,0,1]
	v_pk_fma_f32 v[142:143], v[6:7], s[0:1], v[142:143] op_sel_hi:[1,0,1]
	v_pk_fma_f32 v[128:129], v[8:9], s[0:1], v[128:129] op_sel_hi:[1,0,1]
	v_pk_fma_f32 v[132:133], v[10:11], s[0:1], v[132:133] op_sel_hi:[1,0,1]
	v_pk_fma_f32 v[134:135], v[12:13], s[0:1], v[134:135] op_sel_hi:[1,0,1]
	v_pk_fma_f32 v[136:137], v[14:15], s[0:1], v[136:137] op_sel_hi:[1,0,1]
	v_readlane_b32 s0, v167, 7
	s_waitcnt vmcnt(48)
	v_cvt_scalef32_pk_f32_fp4 v[0:1], v158, 1.0
	v_cvt_scalef32_pk_f32_fp4 v[2:3], v158, 1.0 op_sel:[1,0,0]
	v_cvt_scalef32_pk_f32_fp4 v[4:5], v158, 1.0 op_sel:[0,1,0]
	v_cvt_scalef32_pk_f32_fp4 v[6:7], v158, 1.0 op_sel:[1,1,0]
	v_cvt_scalef32_pk_f32_fp4 v[8:9], v159, 1.0
	v_cvt_scalef32_pk_f32_fp4 v[10:11], v159, 1.0 op_sel:[1,0,0]
	v_cvt_scalef32_pk_f32_fp4 v[12:13], v159, 1.0 op_sel:[0,1,0]
	v_cvt_scalef32_pk_f32_fp4 v[14:15], v159, 1.0 op_sel:[1,1,0]
	v_readlane_b32 s54, v90, 23
	s_lshl_b32 s56, s54, 9
	s_add_u32 s56, s64, s56
	s_addc_u32 s57, s65, 0
	global_load_dwordx2 v[158:159], v227, s[56:57]
	v_pk_fma_f32 v[130:131], v[0:1], s[0:1], v[130:131] op_sel_hi:[1,0,1]
	v_pk_fma_f32 v[138:139], v[2:3], s[0:1], v[138:139] op_sel_hi:[1,0,1]
	v_pk_fma_f32 v[140:141], v[4:5], s[0:1], v[140:141] op_sel_hi:[1,0,1]
	v_pk_fma_f32 v[142:143], v[6:7], s[0:1], v[142:143] op_sel_hi:[1,0,1]
	v_pk_fma_f32 v[128:129], v[8:9], s[0:1], v[128:129] op_sel_hi:[1,0,1]
	v_pk_fma_f32 v[132:133], v[10:11], s[0:1], v[132:133] op_sel_hi:[1,0,1]
	v_pk_fma_f32 v[134:135], v[12:13], s[0:1], v[134:135] op_sel_hi:[1,0,1]
	v_pk_fma_f32 v[136:137], v[14:15], s[0:1], v[136:137] op_sel_hi:[1,0,1]
	v_readlane_b32 s0, v167, 8
	s_waitcnt vmcnt(48)
	v_cvt_scalef32_pk_f32_fp4 v[0:1], v168, 1.0
	v_cvt_scalef32_pk_f32_fp4 v[2:3], v168, 1.0 op_sel:[1,0,0]
	v_cvt_scalef32_pk_f32_fp4 v[4:5], v168, 1.0 op_sel:[0,1,0]
	v_cvt_scalef32_pk_f32_fp4 v[6:7], v168, 1.0 op_sel:[1,1,0]
	v_cvt_scalef32_pk_f32_fp4 v[8:9], v169, 1.0
	v_cvt_scalef32_pk_f32_fp4 v[10:11], v169, 1.0 op_sel:[1,0,0]
	v_cvt_scalef32_pk_f32_fp4 v[12:13], v169, 1.0 op_sel:[0,1,0]
	v_cvt_scalef32_pk_f32_fp4 v[14:15], v169, 1.0 op_sel:[1,1,0]
	v_readlane_b32 s54, v90, 24
	s_lshl_b32 s56, s54, 9
	s_add_u32 s56, s64, s56
	s_addc_u32 s57, s65, 0
	global_load_dwordx2 v[168:169], v227, s[56:57]
	v_pk_fma_f32 v[130:131], v[0:1], s[0:1], v[130:131] op_sel_hi:[1,0,1]
	v_pk_fma_f32 v[138:139], v[2:3], s[0:1], v[138:139] op_sel_hi:[1,0,1]
	v_pk_fma_f32 v[140:141], v[4:5], s[0:1], v[140:141] op_sel_hi:[1,0,1]
	v_pk_fma_f32 v[142:143], v[6:7], s[0:1], v[142:143] op_sel_hi:[1,0,1]
	v_pk_fma_f32 v[128:129], v[8:9], s[0:1], v[128:129] op_sel_hi:[1,0,1]
	v_pk_fma_f32 v[132:133], v[10:11], s[0:1], v[132:133] op_sel_hi:[1,0,1]
	v_pk_fma_f32 v[134:135], v[12:13], s[0:1], v[134:135] op_sel_hi:[1,0,1]
	v_pk_fma_f32 v[136:137], v[14:15], s[0:1], v[136:137] op_sel_hi:[1,0,1]
	v_readlane_b32 s0, v167, 9
	s_waitcnt vmcnt(48)
; __device__ void peer_gather_phase(const Params& P, int l, bool do_store) {
;     ...
;         v8[2 * pr] = *(const uint2*)(V + (size_t)ea * 512);
;         v8[2 * pr + 1] = *(const uint2*)(V + (size_t)eb * 512);
;     ...
;       for (int j = 0; j < 8; ++j) {
;         const float a = __builtin_bit_cast(float, __builtin_amdgcn_readlane(__builtin_bit_cast(int, avec), kb + j));
;         const f32x2 aa = f32x2{a, a};
;         y[0] += aa * __builtin_amdgcn_cvt_scalef32_pk_f32_fp4(v8[j].x, 1.0f, 0); y[1] += aa * __builtin_amdgcn_cvt_scalef32_pk_f32_fp4(v8[j].x, 1.0f, 1);
;         y[2] += aa * __builtin_amdgcn_cvt_scalef32_pk_f32_fp4(v8[j].x, 1.0f, 2); y[3] += aa * __builtin_amdgcn_cvt_scalef32_pk_f32_fp4(v8[j].x, 1.0f, 3);
;         y[4] += aa * __builtin_amdgcn_cvt_scalef32_pk_f32_fp4(v8[j].y, 1.0f, 0); y[5] += aa * __builtin_amdgcn_cvt_scalef32_pk_f32_fp4(v8[j].y, 1.0f, 1);
;         y[6] += aa * __builtin_amdgcn_cvt_scalef32_pk_f32_fp4(v8[j].y, 1.0f, 2); y[7] += aa * __builtin_amdgcn_cvt_scalef32_pk_f32_fp4(v8[j].y, 1.0f, 3);
;       }
	v_cvt_scalef32_pk_f32_fp4 v[0:1], v170, 1.0
	v_cvt_scalef32_pk_f32_fp4 v[2:3], v170, 1.0 op_sel:[1,0,0]
	v_cvt_scalef32_pk_f32_fp4 v[4:5], v170, 1.0 op_sel:[0,1,0]
	v_cvt_scalef32_pk_f32_fp4 v[6:7], v170, 1.0 op_sel:[1,1,0]
	v_cvt_scalef32_pk_f32_fp4 v[8:9], v171, 1.0
	v_cvt_scalef32_pk_f32_fp4 v[10:11], v171, 1.0 op_sel:[1,0,0]
	v_cvt_scalef32_pk_f32_fp4 v[12:13], v171, 1.0 op_sel:[0,1,0]
	v_cvt_scalef32_pk_f32_fp4 v[14:15], v171, 1.0 op_sel:[1,1,0]
	v_readlane_b32 s54, v90, 25
	s_lshl_b32 s56, s54, 9
	s_add_u32 s56, s64, s56
	s_addc_u32 s57, s65, 0
	global_load_dwordx2 v[170:171], v227, s[56:57]
	v_pk_fma_f32 v[130:131], v[0:1], s[0:1], v[130:131] op_sel_hi:[1,0,1]
	v_pk_fma_f32 v[138:139], v[2:3], s[0:1], v[138:139] op_sel_hi:[1,0,1]
	v_pk_fma_f32 v[140:141], v[4:5], s[0:1], v[140:141] op_sel_hi:[1,0,1]
	v_pk_fma_f32 v[142:143], v[6:7], s[0:1], v[142:143] op_sel_hi:[1,0,1]
	v_pk_fma_f32 v[128:129], v[8:9], s[0:1], v[128:129] op_sel_hi:[1,0,1]
	v_pk_fma_f32 v[132:133], v[10:11], s[0:1], v[132:133] op_sel_hi:[1,0,1]
	v_pk_fma_f32 v[134:135], v[12:13], s[0:1], v[134:135] op_sel_hi:[1,0,1]
	v_pk_fma_f32 v[136:137], v[14:15], s[0:1], v[136:137] op_sel_hi:[1,0,1]
	v_readlane_b32 s0, v167, 10
	s_waitcnt vmcnt(48)
	v_cvt_scalef32_pk_f32_fp4 v[0:1], v172, 1.0
	v_cvt_scalef32_pk_f32_fp4 v[2:3], v172, 1.0 op_sel:[1,0,0]
	v_cvt_scalef32_pk_f32_fp4 v[4:5], v172, 1.0 op_sel:[0,1,0]
	v_cvt_scalef32_pk_f32_fp4 v[6:7], v172, 1.0 op_sel:[1,1,0]
	v_cvt_scalef32_pk_f32_fp4 v[8:9], v173, 1.0
	v_cvt_scalef32_pk_f32_fp4 v[10:11], v173, 1.0 op_sel:[1,0,0]
	v_cvt_scalef32_pk_f32_fp4 v[12:13], v173, 1.0 op_sel:[0,1,0]
	v_cvt_scalef32_pk_f32_fp4 v[14:15], v173, 1.0 op_sel:[1,1,0]
	v_readlane_b32 s54, v90, 26
	s_lshl_b32 s56, s54, 9
	s_add_u32 s56, s64, s56
	s_addc_u32 s57, s65, 0
	global_load_dwordx2 v[172:173], v227, s[56:57]
	v_pk_fma_f32 v[130:131], v[0:1], s[0:1], v[130:131] op_sel_hi:[1,0,1]
	v_pk_fma_f32 v[138:139], v[2:3], s[0:1], v[138:139] op_sel_hi:[1,0,1]
	v_pk_fma_f32 v[140:141], v[4:5], s[0:1], v[140:141] op_sel_hi:[1,0,1]
	v_pk_fma_f32 v[142:143], v[6:7], s[0:1], v[142:143] op_sel_hi:[1,0,1]
	v_pk_fma_f32 v[128:129], v[8:9], s[0:1], v[128:129] op_sel_hi:[1,0,1]
	v_pk_fma_f32 v[132:133], v[10:11], s[0:1], v[132:133] op_sel_hi:[1,0,1]
	v_pk_fma_f32 v[134:135], v[12:13], s[0:1], v[134:135] op_sel_hi:[1,0,1]
	v_pk_fma_f32 v[136:137], v[14:15], s[0:1], v[136:137] op_sel_hi:[1,0,1]
	v_readlane_b32 s0, v167, 11
	s_waitcnt vmcnt(48)
	v_cvt_scalef32_pk_f32_fp4 v[0:1], v174, 1.0
	v_cvt_scalef32_pk_f32_fp4 v[2:3], v174, 1.0 op_sel:[1,0,0]
	v_cvt_scalef32_pk_f32_fp4 v[4:5], v174, 1.0 op_sel:[0,1,0]
	v_cvt_scalef32_pk_f32_fp4 v[6:7], v174, 1.0 op_sel:[1,1,0]
	v_cvt_scalef32_pk_f32_fp4 v[8:9], v175, 1.0
	v_cvt_scalef32_pk_f32_fp4 v[10:11], v175, 1.0 op_sel:[1,0,0]
	v_cvt_scalef32_pk_f32_fp4 v[12:13], v175, 1.0 op_sel:[0,1,0]
	v_cvt_scalef32_pk_f32_fp4 v[14:15], v175, 1.0 op_sel:[1,1,0]
	v_readlane_b32 s54, v90, 27
	s_lshl_b32 s56, s54, 9
	s_add_u32 s56, s64, s56
	s_addc_u32 s57, s65, 0
	global_load_dwordx2 v[174:175], v227, s[56:57]
	v_pk_fma_f32 v[130:131], v[0:1], s[0:1], v[130:131] op_sel_hi:[1,0,1]
	v_pk_fma_f32 v[138:139], v[2:3], s[0:1], v[138:139] op_sel_hi:[1,0,1]
	v_pk_fma_f32 v[140:141], v[4:5], s[0:1], v[140:141] op_sel_hi:[1,0,1]
	v_pk_fma_f32 v[142:143], v[6:7], s[0:1], v[142:143] op_sel_hi:[1,0,1]
	v_pk_fma_f32 v[128:129], v[8:9], s[0:1], v[128:129] op_sel_hi:[1,0,1]
	v_pk_fma_f32 v[132:133], v[10:11], s[0:1], v[132:133] op_sel_hi:[1,0,1]
	v_pk_fma_f32 v[134:135], v[12:13], s[0:1], v[134:135] op_sel_hi:[1,0,1]
	v_pk_fma_f32 v[136:137], v[14:15], s[0:1], v[136:137] op_sel_hi:[1,0,1]
	v_readlane_b32 s0, v167, 12
	s_waitcnt vmcnt(48)
	v_cvt_scalef32_pk_f32_fp4 v[0:1], v180, 1.0
	v_cvt_scalef32_pk_f32_fp4 v[2:3], v180, 1.0 op_sel:[1,0,0]
	v_cvt_scalef32_pk_f32_fp4 v[4:5], v180, 1.0 op_sel:[0,1,0]
	v_cvt_scalef32_pk_f32_fp4 v[6:7], v180, 1.0 op_sel:[1,1,0]
	v_cvt_scalef32_pk_f32_fp4 v[8:9], v181, 1.0
	v_cvt_scalef32_pk_f32_fp4 v[10:11], v181, 1.0 op_sel:[1,0,0]
	v_cvt_scalef32_pk_f32_fp4 v[12:13], v181, 1.0 op_sel:[0,1,0]
	v_cvt_scalef32_pk_f32_fp4 v[14:15], v181, 1.0 op_sel:[1,1,0]
	v_readlane_b32 s54, v90, 28
	s_lshl_b32 s56, s54, 9
	s_add_u32 s56, s64, s56
	s_addc_u32 s57, s65, 0
	global_load_dwordx2 v[180:181], v227, s[56:57]
	v_pk_fma_f32 v[130:131], v[0:1], s[0:1], v[130:131] op_sel_hi:[1,0,1]
	v_pk_fma_f32 v[138:139], v[2:3], s[0:1], v[138:139] op_sel_hi:[1,0,1]
	v_pk_fma_f32 v[140:141], v[4:5], s[0:1], v[140:141] op_sel_hi:[1,0,1]
	v_pk_fma_f32 v[142:143], v[6:7], s[0:1], v[142:143] op_sel_hi:[1,0,1]
	v_pk_fma_f32 v[128:129], v[8:9], s[0:1], v[128:129] op_sel_hi:[1,0,1]
	v_pk_fma_f32 v[132:133], v[10:11], s[0:1], v[132:133] op_sel_hi:[1,0,1]
	v_pk_fma_f32 v[134:135], v[12:13], s[0:1], v[134:135] op_sel_hi:[1,0,1]
	v_pk_fma_f32 v[136:137], v[14:15], s[0:1], v[136:137] op_sel_hi:[1,0,1]
	v_readlane_b32 s0, v167, 13
	s_waitcnt vmcnt(48)
	v_cvt_scalef32_pk_f32_fp4 v[0:1], v182, 1.0
	v_cvt_scalef32_pk_f32_fp4 v[2:3], v182, 1.0 op_sel:[1,0,0]
	v_cvt_scalef32_pk_f32_fp4 v[4:5], v182, 1.0 op_sel:[0,1,0]
	v_cvt_scalef32_pk_f32_fp4 v[6:7], v182, 1.0 op_sel:[1,1,0]
	v_cvt_scalef32_pk_f32_fp4 v[8:9], v183, 1.0
	v_cvt_scalef32_pk_f32_fp4 v[10:11], v183, 1.0 op_sel:[1,0,0]
	v_cvt_scalef32_pk_f32_fp4 v[12:13], v183, 1.0 op_sel:[0,1,0]
	v_cvt_scalef32_pk_f32_fp4 v[14:15], v183, 1.0 op_sel:[1,1,0]
	v_readlane_b32 s54, v90, 29
	s_lshl_b32 s56, s54, 9
	s_add_u32 s56, s64, s56
	s_addc_u32 s57, s65, 0
	global_load_dwordx2 v[182:183], v227, s[56:57]
	v_pk_fma_f32 v[130:131], v[0:1], s[0:1], v[130:131] op_sel_hi:[1,0,1]
	v_pk_fma_f32 v[138:139], v[2:3], s[0:1], v[138:139] op_sel_hi:[1,0,1]
	v_pk_fma_f32 v[140:141], v[4:5], s[0:1], v[140:141] op_sel_hi:[1,0,1]
	v_pk_fma_f32 v[142:143], v[6:7], s[0:1], v[142:143] op_sel_hi:[1,0,1]
	v_pk_fma_f32 v[128:129], v[8:9], s[0:1], v[128:129] op_sel_hi:[1,0,1]
	v_pk_fma_f32 v[132:133], v[10:11], s[0:1], v[132:133] op_sel_hi:[1,0,1]
	v_pk_fma_f32 v[134:135], v[12:13], s[0:1], v[134:135] op_sel_hi:[1,0,1]
	v_pk_fma_f32 v[136:137], v[14:15], s[0:1], v[136:137] op_sel_hi:[1,0,1]
	v_readlane_b32 s0, v167, 14
	s_waitcnt vmcnt(48)
; __device__ void peer_gather_phase(const Params& P, int l, bool do_store) {
;     ...
;         v8[2 * pr] = *(const uint2*)(V + (size_t)ea * 512);
;         v8[2 * pr + 1] = *(const uint2*)(V + (size_t)eb * 512);
;     ...
;       for (int j = 0; j < 8; ++j) {
;         const float a = __builtin_bit_cast(float, __builtin_amdgcn_readlane(__builtin_bit_cast(int, avec), kb + j));
;         const f32x2 aa = f32x2{a, a};
;         y[0] += aa * __builtin_amdgcn_cvt_scalef32_pk_f32_fp4(v8[j].x, 1.0f, 0); y[1] += aa * __builtin_amdgcn_cvt_scalef32_pk_f32_fp4(v8[j].x, 1.0f, 1);
;         y[2] += aa * __builtin_amdgcn_cvt_scalef32_pk_f32_fp4(v8[j].x, 1.0f, 2); y[3] += aa * __builtin_amdgcn_cvt_scalef32_pk_f32_fp4(v8[j].x, 1.0f, 3);
;         y[4] += aa * __builtin_amdgcn_cvt_scalef32_pk_f32_fp4(v8[j].y, 1.0f, 0); y[5] += aa * __builtin_amdgcn_cvt_scalef32_pk_f32_fp4(v8[j].y, 1.0f, 1);
;         y[6] += aa * __builtin_amdgcn_cvt_scalef32_pk_f32_fp4(v8[j].y, 1.0f, 2); y[7] += aa * __builtin_amdgcn_cvt_scalef32_pk_f32_fp4(v8[j].y, 1.0f, 3);
;       }
	v_cvt_scalef32_pk_f32_fp4 v[0:1], v184, 1.0
	v_cvt_scalef32_pk_f32_fp4 v[2:3], v184, 1.0 op_sel:[1,0,0]
	v_cvt_scalef32_pk_f32_fp4 v[4:5], v184, 1.0 op_sel:[0,1,0]
	v_cvt_scalef32_pk_f32_fp4 v[6:7], v184, 1.0 op_sel:[1,1,0]
	v_cvt_scalef32_pk_f32_fp4 v[8:9], v185, 1.0
	v_cvt_scalef32_pk_f32_fp4 v[10:11], v185, 1.0 op_sel:[1,0,0]
	v_cvt_scalef32_pk_f32_fp4 v[12:13], v185, 1.0 op_sel:[0,1,0]
	v_cvt_scalef32_pk_f32_fp4 v[14:15], v185, 1.0 op_sel:[1,1,0]
	v_readlane_b32 s54, v90, 30
	s_lshl_b32 s56, s54, 9
	s_add_u32 s56, s64, s56
	s_addc_u32 s57, s65, 0
	global_load_dwordx2 v[184:185], v227, s[56:57]
	v_pk_fma_f32 v[130:131], v[0:1], s[0:1], v[130:131] op_sel_hi:[1,0,1]
	v_pk_fma_f32 v[138:139], v[2:3], s[0:1], v[138:139] op_sel_hi:[1,0,1]
	v_pk_fma_f32 v[140:141], v[4:5], s[0:1], v[140:141] op_sel_hi:[1,0,1]
	v_pk_fma_f32 v[142:143], v[6:7], s[0:1], v[142:143] op_sel_hi:[1,0,1]
	v_pk_fma_f32 v[128:129], v[8:9], s[0:1], v[128:129] op_sel_hi:[1,0,1]
	v_pk_fma_f32 v[132:133], v[10:11], s[0:1], v[132:133] op_sel_hi:[1,0,1]
	v_pk_fma_f32 v[134:135], v[12:13], s[0:1], v[134:135] op_sel_hi:[1,0,1]
	v_pk_fma_f32 v[136:137], v[14:15], s[0:1], v[136:137] op_sel_hi:[1,0,1]
	v_readlane_b32 s0, v167, 15
	s_waitcnt vmcnt(48)
	v_cvt_scalef32_pk_f32_fp4 v[0:1], v186, 1.0
	v_cvt_scalef32_pk_f32_fp4 v[2:3], v186, 1.0 op_sel:[1,0,0]
	v_cvt_scalef32_pk_f32_fp4 v[4:5], v186, 1.0 op_sel:[0,1,0]
	v_cvt_scalef32_pk_f32_fp4 v[6:7], v186, 1.0 op_sel:[1,1,0]
	v_cvt_scalef32_pk_f32_fp4 v[8:9], v187, 1.0
	v_cvt_scalef32_pk_f32_fp4 v[10:11], v187, 1.0 op_sel:[1,0,0]
	v_cvt_scalef32_pk_f32_fp4 v[12:13], v187, 1.0 op_sel:[0,1,0]
	v_cvt_scalef32_pk_f32_fp4 v[14:15], v187, 1.0 op_sel:[1,1,0]
	v_readlane_b32 s54, v90, 31
	s_lshl_b32 s56, s54, 9
	s_add_u32 s56, s64, s56
	s_addc_u32 s57, s65, 0
	global_load_dwordx2 v[186:187], v227, s[56:57]
	v_pk_fma_f32 v[130:131], v[0:1], s[0:1], v[130:131] op_sel_hi:[1,0,1]
	v_pk_fma_f32 v[138:139], v[2:3], s[0:1], v[138:139] op_sel_hi:[1,0,1]
	v_pk_fma_f32 v[140:141], v[4:5], s[0:1], v[140:141] op_sel_hi:[1,0,1]
	v_pk_fma_f32 v[142:143], v[6:7], s[0:1], v[142:143] op_sel_hi:[1,0,1]
	v_pk_fma_f32 v[128:129], v[8:9], s[0:1], v[128:129] op_sel_hi:[1,0,1]
	v_pk_fma_f32 v[132:133], v[10:11], s[0:1], v[132:133] op_sel_hi:[1,0,1]
	v_pk_fma_f32 v[134:135], v[12:13], s[0:1], v[134:135] op_sel_hi:[1,0,1]
	v_pk_fma_f32 v[136:137], v[14:15], s[0:1], v[136:137] op_sel_hi:[1,0,1]
	v_readlane_b32 s0, v167, 16
	s_waitcnt vmcnt(15)
	v_cvt_scalef32_pk_f32_fp4 v[0:1], v144, 1.0
	v_cvt_scalef32_pk_f32_fp4 v[2:3], v144, 1.0 op_sel:[1,0,0]
	v_cvt_scalef32_pk_f32_fp4 v[4:5], v144, 1.0 op_sel:[0,1,0]
	v_cvt_scalef32_pk_f32_fp4 v[6:7], v144, 1.0 op_sel:[1,1,0]
	v_cvt_scalef32_pk_f32_fp4 v[8:9], v145, 1.0
	v_cvt_scalef32_pk_f32_fp4 v[10:11], v145, 1.0 op_sel:[1,0,0]
	v_cvt_scalef32_pk_f32_fp4 v[12:13], v145, 1.0 op_sel:[0,1,0]
	v_cvt_scalef32_pk_f32_fp4 v[14:15], v145, 1.0 op_sel:[1,1,0]
	v_readlane_b32 s54, v90, 32
	s_lshl_b32 s56, s54, 9
	s_add_u32 s56, s64, s56
	s_addc_u32 s57, s65, 0
	global_load_dwordx2 v[144:145], v227, s[56:57]
	v_pk_fma_f32 v[130:131], v[0:1], s[0:1], v[130:131] op_sel_hi:[1,0,1]
	v_pk_fma_f32 v[138:139], v[2:3], s[0:1], v[138:139] op_sel_hi:[1,0,1]
	v_pk_fma_f32 v[140:141], v[4:5], s[0:1], v[140:141] op_sel_hi:[1,0,1]
	v_pk_fma_f32 v[142:143], v[6:7], s[0:1], v[142:143] op_sel_hi:[1,0,1]
	v_pk_fma_f32 v[128:129], v[8:9], s[0:1], v[128:129] op_sel_hi:[1,0,1]
	v_pk_fma_f32 v[132:133], v[10:11], s[0:1], v[132:133] op_sel_hi:[1,0,1]
	v_pk_fma_f32 v[134:135], v[12:13], s[0:1], v[134:135] op_sel_hi:[1,0,1]
	v_pk_fma_f32 v[136:137], v[14:15], s[0:1], v[136:137] op_sel_hi:[1,0,1]
	v_readlane_b32 s0, v167, 17
	s_waitcnt vmcnt(15)
	v_cvt_scalef32_pk_f32_fp4 v[0:1], v146, 1.0
	v_cvt_scalef32_pk_f32_fp4 v[2:3], v146, 1.0 op_sel:[1,0,0]
	v_cvt_scalef32_pk_f32_fp4 v[4:5], v146, 1.0 op_sel:[0,1,0]
	v_cvt_scalef32_pk_f32_fp4 v[6:7], v146, 1.0 op_sel:[1,1,0]
	v_cvt_scalef32_pk_f32_fp4 v[8:9], v147, 1.0
	v_cvt_scalef32_pk_f32_fp4 v[10:11], v147, 1.0 op_sel:[1,0,0]
	v_cvt_scalef32_pk_f32_fp4 v[12:13], v147, 1.0 op_sel:[0,1,0]
	v_cvt_scalef32_pk_f32_fp4 v[14:15], v147, 1.0 op_sel:[1,1,0]
	v_readlane_b32 s54, v90, 33
	s_lshl_b32 s56, s54, 9
	s_add_u32 s56, s64, s56
	s_addc_u32 s57, s65, 0
	global_load_dwordx2 v[146:147], v227, s[56:57]
	v_pk_fma_f32 v[130:131], v[0:1], s[0:1], v[130:131] op_sel_hi:[1,0,1]
	v_pk_fma_f32 v[138:139], v[2:3], s[0:1], v[138:139] op_sel_hi:[1,0,1]
	v_pk_fma_f32 v[140:141], v[4:5], s[0:1], v[140:141] op_sel_hi:[1,0,1]
	v_pk_fma_f32 v[142:143], v[6:7], s[0:1], v[142:143] op_sel_hi:[1,0,1]
	v_pk_fma_f32 v[128:129], v[8:9], s[0:1], v[128:129] op_sel_hi:[1,0,1]
	v_pk_fma_f32 v[132:133], v[10:11], s[0:1], v[132:133] op_sel_hi:[1,0,1]
	v_pk_fma_f32 v[134:135], v[12:13], s[0:1], v[134:135] op_sel_hi:[1,0,1]
	v_pk_fma_f32 v[136:137], v[14:15], s[0:1], v[136:137] op_sel_hi:[1,0,1]
	v_readlane_b32 s0, v167, 18
	s_waitcnt vmcnt(15)
	v_cvt_scalef32_pk_f32_fp4 v[0:1], v148, 1.0
	v_cvt_scalef32_pk_f32_fp4 v[2:3], v148, 1.0 op_sel:[1,0,0]
	v_cvt_scalef32_pk_f32_fp4 v[4:5], v148, 1.0 op_sel:[0,1,0]
	v_cvt_scalef32_pk_f32_fp4 v[6:7], v148, 1.0 op_sel:[1,1,0]
	v_cvt_scalef32_pk_f32_fp4 v[8:9], v149, 1.0
	v_cvt_scalef32_pk_f32_fp4 v[10:11], v149, 1.0 op_sel:[1,0,0]
	v_cvt_scalef32_pk_f32_fp4 v[12:13], v149, 1.0 op_sel:[0,1,0]
	v_cvt_scalef32_pk_f32_fp4 v[14:15], v149, 1.0 op_sel:[1,1,0]
	v_readlane_b32 s54, v90, 34
	s_lshl_b32 s56, s54, 9
	s_add_u32 s56, s64, s56
	s_addc_u32 s57, s65, 0
	global_load_dwordx2 v[148:149], v227, s[56:57]
	v_pk_fma_f32 v[130:131], v[0:1], s[0:1], v[130:131] op_sel_hi:[1,0,1]
	v_pk_fma_f32 v[138:139], v[2:3], s[0:1], v[138:139] op_sel_hi:[1,0,1]
	v_pk_fma_f32 v[140:141], v[4:5], s[0:1], v[140:141] op_sel_hi:[1,0,1]
	v_pk_fma_f32 v[142:143], v[6:7], s[0:1], v[142:143] op_sel_hi:[1,0,1]
	v_pk_fma_f32 v[128:129], v[8:9], s[0:1], v[128:129] op_sel_hi:[1,0,1]
	v_pk_fma_f32 v[132:133], v[10:11], s[0:1], v[132:133] op_sel_hi:[1,0,1]
	v_pk_fma_f32 v[134:135], v[12:13], s[0:1], v[134:135] op_sel_hi:[1,0,1]
	v_pk_fma_f32 v[136:137], v[14:15], s[0:1], v[136:137] op_sel_hi:[1,0,1]
	v_readlane_b32 s0, v167, 19
	s_waitcnt vmcnt(15)
; __device__ void peer_gather_phase(const Params& P, int l, bool do_store) {
;     ...
;         v8[2 * pr] = *(const uint2*)(V + (size_t)ea * 512);
;         v8[2 * pr + 1] = *(const uint2*)(V + (size_t)eb * 512);
;     ...
;       for (int j = 0; j < 8; ++j) {
;         const float a = __builtin_bit_cast(float, __builtin_amdgcn_readlane(__builtin_bit_cast(int, avec), kb + j));
;         const f32x2 aa = f32x2{a, a};
;         y[0] += aa * __builtin_amdgcn_cvt_scalef32_pk_f32_fp4(v8[j].x, 1.0f, 0); y[1] += aa * __builtin_amdgcn_cvt_scalef32_pk_f32_fp4(v8[j].x, 1.0f, 1);
;         y[2] += aa * __builtin_amdgcn_cvt_scalef32_pk_f32_fp4(v8[j].x, 1.0f, 2); y[3] += aa * __builtin_amdgcn_cvt_scalef32_pk_f32_fp4(v8[j].x, 1.0f, 3);
;         y[4] += aa * __builtin_amdgcn_cvt_scalef32_pk_f32_fp4(v8[j].y, 1.0f, 0); y[5] += aa * __builtin_amdgcn_cvt_scalef32_pk_f32_fp4(v8[j].y, 1.0f, 1);
;         y[6] += aa * __builtin_amdgcn_cvt_scalef32_pk_f32_fp4(v8[j].y, 1.0f, 2); y[7] += aa * __builtin_amdgcn_cvt_scalef32_pk_f32_fp4(v8[j].y, 1.0f, 3);
;       }
	v_cvt_scalef32_pk_f32_fp4 v[0:1], v150, 1.0
	v_cvt_scalef32_pk_f32_fp4 v[2:3], v150, 1.0 op_sel:[1,0,0]
	v_cvt_scalef32_pk_f32_fp4 v[4:5], v150, 1.0 op_sel:[0,1,0]
	v_cvt_scalef32_pk_f32_fp4 v[6:7], v150, 1.0 op_sel:[1,1,0]
	v_cvt_scalef32_pk_f32_fp4 v[8:9], v151, 1.0
	v_cvt_scalef32_pk_f32_fp4 v[10:11], v151, 1.0 op_sel:[1,0,0]
	v_cvt_scalef32_pk_f32_fp4 v[12:13], v151, 1.0 op_sel:[0,1,0]
	v_cvt_scalef32_pk_f32_fp4 v[14:15], v151, 1.0 op_sel:[1,1,0]
	v_readlane_b32 s54, v90, 35
	s_lshl_b32 s56, s54, 9
	s_add_u32 s56, s64, s56
	s_addc_u32 s57, s65, 0
	global_load_dwordx2 v[150:151], v227, s[56:57]
	v_pk_fma_f32 v[130:131], v[0:1], s[0:1], v[130:131] op_sel_hi:[1,0,1]
	v_pk_fma_f32 v[138:139], v[2:3], s[0:1], v[138:139] op_sel_hi:[1,0,1]
	v_pk_fma_f32 v[140:141], v[4:5], s[0:1], v[140:141] op_sel_hi:[1,0,1]
	v_pk_fma_f32 v[142:143], v[6:7], s[0:1], v[142:143] op_sel_hi:[1,0,1]
	v_pk_fma_f32 v[128:129], v[8:9], s[0:1], v[128:129] op_sel_hi:[1,0,1]
	v_pk_fma_f32 v[132:133], v[10:11], s[0:1], v[132:133] op_sel_hi:[1,0,1]
	v_pk_fma_f32 v[134:135], v[12:13], s[0:1], v[134:135] op_sel_hi:[1,0,1]
	v_pk_fma_f32 v[136:137], v[14:15], s[0:1], v[136:137] op_sel_hi:[1,0,1]
	v_readlane_b32 s0, v167, 20
	s_waitcnt vmcnt(15)
	v_cvt_scalef32_pk_f32_fp4 v[0:1], v152, 1.0
	v_cvt_scalef32_pk_f32_fp4 v[2:3], v152, 1.0 op_sel:[1,0,0]
	v_cvt_scalef32_pk_f32_fp4 v[4:5], v152, 1.0 op_sel:[0,1,0]
	v_cvt_scalef32_pk_f32_fp4 v[6:7], v152, 1.0 op_sel:[1,1,0]
	v_cvt_scalef32_pk_f32_fp4 v[8:9], v153, 1.0
	v_cvt_scalef32_pk_f32_fp4 v[10:11], v153, 1.0 op_sel:[1,0,0]
	v_cvt_scalef32_pk_f32_fp4 v[12:13], v153, 1.0 op_sel:[0,1,0]
	v_cvt_scalef32_pk_f32_fp4 v[14:15], v153, 1.0 op_sel:[1,1,0]
	v_readlane_b32 s54, v90, 36
	s_lshl_b32 s56, s54, 9
	s_add_u32 s56, s64, s56
	s_addc_u32 s57, s65, 0
	global_load_dwordx2 v[152:153], v227, s[56:57]
	v_pk_fma_f32 v[130:131], v[0:1], s[0:1], v[130:131] op_sel_hi:[1,0,1]
	v_pk_fma_f32 v[138:139], v[2:3], s[0:1], v[138:139] op_sel_hi:[1,0,1]
	v_pk_fma_f32 v[140:141], v[4:5], s[0:1], v[140:141] op_sel_hi:[1,0,1]
	v_pk_fma_f32 v[142:143], v[6:7], s[0:1], v[142:143] op_sel_hi:[1,0,1]
	v_pk_fma_f32 v[128:129], v[8:9], s[0:1], v[128:129] op_sel_hi:[1,0,1]
	v_pk_fma_f32 v[132:133], v[10:11], s[0:1], v[132:133] op_sel_hi:[1,0,1]
	v_pk_fma_f32 v[134:135], v[12:13], s[0:1], v[134:135] op_sel_hi:[1,0,1]
	v_pk_fma_f32 v[136:137], v[14:15], s[0:1], v[136:137] op_sel_hi:[1,0,1]
	v_readlane_b32 s0, v167, 21
	s_waitcnt vmcnt(15)
	v_cvt_scalef32_pk_f32_fp4 v[0:1], v154, 1.0
	v_cvt_scalef32_pk_f32_fp4 v[2:3], v154, 1.0 op_sel:[1,0,0]
	v_cvt_scalef32_pk_f32_fp4 v[4:5], v154, 1.0 op_sel:[0,1,0]
	v_cvt_scalef32_pk_f32_fp4 v[6:7], v154, 1.0 op_sel:[1,1,0]
	v_cvt_scalef32_pk_f32_fp4 v[8:9], v155, 1.0
	v_cvt_scalef32_pk_f32_fp4 v[10:11], v155, 1.0 op_sel:[1,0,0]
	v_cvt_scalef32_pk_f32_fp4 v[12:13], v155, 1.0 op_sel:[0,1,0]
	v_cvt_scalef32_pk_f32_fp4 v[14:15], v155, 1.0 op_sel:[1,1,0]
	v_readlane_b32 s54, v90, 37
	s_lshl_b32 s56, s54, 9
	s_add_u32 s56, s64, s56
	s_addc_u32 s57, s65, 0
	global_load_dwordx2 v[154:155], v227, s[56:57]
	v_pk_fma_f32 v[130:131], v[0:1], s[0:1], v[130:131] op_sel_hi:[1,0,1]
	v_pk_fma_f32 v[138:139], v[2:3], s[0:1], v[138:139] op_sel_hi:[1,0,1]
	v_pk_fma_f32 v[140:141], v[4:5], s[0:1], v[140:141] op_sel_hi:[1,0,1]
	v_pk_fma_f32 v[142:143], v[6:7], s[0:1], v[142:143] op_sel_hi:[1,0,1]
	v_pk_fma_f32 v[128:129], v[8:9], s[0:1], v[128:129] op_sel_hi:[1,0,1]
	v_pk_fma_f32 v[132:133], v[10:11], s[0:1], v[132:133] op_sel_hi:[1,0,1]
	v_pk_fma_f32 v[134:135], v[12:13], s[0:1], v[134:135] op_sel_hi:[1,0,1]
	v_pk_fma_f32 v[136:137], v[14:15], s[0:1], v[136:137] op_sel_hi:[1,0,1]
	v_readlane_b32 s0, v167, 22
	s_waitcnt vmcnt(15)
	v_cvt_scalef32_pk_f32_fp4 v[0:1], v156, 1.0
	v_cvt_scalef32_pk_f32_fp4 v[2:3], v156, 1.0 op_sel:[1,0,0]
	v_cvt_scalef32_pk_f32_fp4 v[4:5], v156, 1.0 op_sel:[0,1,0]
	v_cvt_scalef32_pk_f32_fp4 v[6:7], v156, 1.0 op_sel:[1,1,0]
	v_cvt_scalef32_pk_f32_fp4 v[8:9], v157, 1.0
	v_cvt_scalef32_pk_f32_fp4 v[10:11], v157, 1.0 op_sel:[1,0,0]
	v_cvt_scalef32_pk_f32_fp4 v[12:13], v157, 1.0 op_sel:[0,1,0]
	v_cvt_scalef32_pk_f32_fp4 v[14:15], v157, 1.0 op_sel:[1,1,0]
	v_readlane_b32 s54, v90, 38
	s_lshl_b32 s56, s54, 9
	s_add_u32 s56, s64, s56
	s_addc_u32 s57, s65, 0
	global_load_dwordx2 v[156:157], v227, s[56:57]
	v_pk_fma_f32 v[130:131], v[0:1], s[0:1], v[130:131] op_sel_hi:[1,0,1]
	v_pk_fma_f32 v[138:139], v[2:3], s[0:1], v[138:139] op_sel_hi:[1,0,1]
	v_pk_fma_f32 v[140:141], v[4:5], s[0:1], v[140:141] op_sel_hi:[1,0,1]
	v_pk_fma_f32 v[142:143], v[6:7], s[0:1], v[142:143] op_sel_hi:[1,0,1]
	v_pk_fma_f32 v[128:129], v[8:9], s[0:1], v[128:129] op_sel_hi:[1,0,1]
	v_pk_fma_f32 v[132:133], v[10:11], s[0:1], v[132:133] op_sel_hi:[1,0,1]
	v_pk_fma_f32 v[134:135], v[12:13], s[0:1], v[134:135] op_sel_hi:[1,0,1]
	v_pk_fma_f32 v[136:137], v[14:15], s[0:1], v[136:137] op_sel_hi:[1,0,1]
	v_readlane_b32 s0, v167, 23
	s_waitcnt vmcnt(15)
	v_cvt_scalef32_pk_f32_fp4 v[0:1], v158, 1.0
	v_cvt_scalef32_pk_f32_fp4 v[2:3], v158, 1.0 op_sel:[1,0,0]
	v_cvt_scalef32_pk_f32_fp4 v[4:5], v158, 1.0 op_sel:[0,1,0]
	v_cvt_scalef32_pk_f32_fp4 v[6:7], v158, 1.0 op_sel:[1,1,0]
	v_cvt_scalef32_pk_f32_fp4 v[8:9], v159, 1.0
	v_cvt_scalef32_pk_f32_fp4 v[10:11], v159, 1.0 op_sel:[1,0,0]
	v_cvt_scalef32_pk_f32_fp4 v[12:13], v159, 1.0 op_sel:[0,1,0]
	v_cvt_scalef32_pk_f32_fp4 v[14:15], v159, 1.0 op_sel:[1,1,0]
	v_readlane_b32 s54, v90, 39
	s_lshl_b32 s56, s54, 9
	s_add_u32 s56, s64, s56
	s_addc_u32 s57, s65, 0
	global_load_dwordx2 v[158:159], v227, s[56:57]
	v_pk_fma_f32 v[130:131], v[0:1], s[0:1], v[130:131] op_sel_hi:[1,0,1]
	v_pk_fma_f32 v[138:139], v[2:3], s[0:1], v[138:139] op_sel_hi:[1,0,1]
	v_pk_fma_f32 v[140:141], v[4:5], s[0:1], v[140:141] op_sel_hi:[1,0,1]
	v_pk_fma_f32 v[142:143], v[6:7], s[0:1], v[142:143] op_sel_hi:[1,0,1]
	v_pk_fma_f32 v[128:129], v[8:9], s[0:1], v[128:129] op_sel_hi:[1,0,1]
	v_pk_fma_f32 v[132:133], v[10:11], s[0:1], v[132:133] op_sel_hi:[1,0,1]
	v_pk_fma_f32 v[134:135], v[12:13], s[0:1], v[134:135] op_sel_hi:[1,0,1]
	v_pk_fma_f32 v[136:137], v[14:15], s[0:1], v[136:137] op_sel_hi:[1,0,1]
	v_readlane_b32 s0, v167, 24
	s_waitcnt vmcnt(15)
; __device__ void peer_gather_phase(const Params& P, int l, bool do_store) {
;     ...
;         v8[2 * pr] = *(const uint2*)(V + (size_t)ea * 512);
;         v8[2 * pr + 1] = *(const uint2*)(V + (size_t)eb * 512);
;     ...
;       for (int j = 0; j < 8; ++j) {
;         const float a = __builtin_bit_cast(float, __builtin_amdgcn_readlane(__builtin_bit_cast(int, avec), kb + j));
;         const f32x2 aa = f32x2{a, a};
;         y[0] += aa * __builtin_amdgcn_cvt_scalef32_pk_f32_fp4(v8[j].x, 1.0f, 0); y[1] += aa * __builtin_amdgcn_cvt_scalef32_pk_f32_fp4(v8[j].x, 1.0f, 1);
;         y[2] += aa * __builtin_amdgcn_cvt_scalef32_pk_f32_fp4(v8[j].x, 1.0f, 2); y[3] += aa * __builtin_amdgcn_cvt_scalef32_pk_f32_fp4(v8[j].x, 1.0f, 3);
;         y[4] += aa * __builtin_amdgcn_cvt_scalef32_pk_f32_fp4(v8[j].y, 1.0f, 0); y[5] += aa * __builtin_amdgcn_cvt_scalef32_pk_f32_fp4(v8[j].y, 1.0f, 1);
;         y[6] += aa * __builtin_amdgcn_cvt_scalef32_pk_f32_fp4(v8[j].y, 1.0f, 2); y[7] += aa * __builtin_amdgcn_cvt_scalef32_pk_f32_fp4(v8[j].y, 1.0f, 3);
;       }
	v_cvt_scalef32_pk_f32_fp4 v[0:1], v168, 1.0
	v_cvt_scalef32_pk_f32_fp4 v[2:3], v168, 1.0 op_sel:[1,0,0]
	v_cvt_scalef32_pk_f32_fp4 v[4:5], v168, 1.0 op_sel:[0,1,0]
	v_cvt_scalef32_pk_f32_fp4 v[6:7], v168, 1.0 op_sel:[1,1,0]
	v_cvt_scalef32_pk_f32_fp4 v[8:9], v169, 1.0
	v_cvt_scalef32_pk_f32_fp4 v[10:11], v169, 1.0 op_sel:[1,0,0]
	v_cvt_scalef32_pk_f32_fp4 v[12:13], v169, 1.0 op_sel:[0,1,0]
	v_cvt_scalef32_pk_f32_fp4 v[14:15], v169, 1.0 op_sel:[1,1,0]
	v_readlane_b32 s54, v90, 40
	s_lshl_b32 s56, s54, 9
	s_add_u32 s56, s64, s56
	s_addc_u32 s57, s65, 0
	global_load_dwordx2 v[168:169], v227, s[56:57]
	v_pk_fma_f32 v[130:131], v[0:1], s[0:1], v[130:131] op_sel_hi:[1,0,1]
	v_pk_fma_f32 v[138:139], v[2:3], s[0:1], v[138:139] op_sel_hi:[1,0,1]
	v_pk_fma_f32 v[140:141], v[4:5], s[0:1], v[140:141] op_sel_hi:[1,0,1]
	v_pk_fma_f32 v[142:143], v[6:7], s[0:1], v[142:143] op_sel_hi:[1,0,1]
	v_pk_fma_f32 v[128:129], v[8:9], s[0:1], v[128:129] op_sel_hi:[1,0,1]
	v_pk_fma_f32 v[132:133], v[10:11], s[0:1], v[132:133] op_sel_hi:[1,0,1]
	v_pk_fma_f32 v[134:135], v[12:13], s[0:1], v[134:135] op_sel_hi:[1,0,1]
	v_pk_fma_f32 v[136:137], v[14:15], s[0:1], v[136:137] op_sel_hi:[1,0,1]
	v_readlane_b32 s0, v167, 25
	s_waitcnt vmcnt(15)
	v_cvt_scalef32_pk_f32_fp4 v[0:1], v170, 1.0
	v_cvt_scalef32_pk_f32_fp4 v[2:3], v170, 1.0 op_sel:[1,0,0]
	v_cvt_scalef32_pk_f32_fp4 v[4:5], v170, 1.0 op_sel:[0,1,0]
	v_cvt_scalef32_pk_f32_fp4 v[6:7], v170, 1.0 op_sel:[1,1,0]
	v_cvt_scalef32_pk_f32_fp4 v[8:9], v171, 1.0
	v_cvt_scalef32_pk_f32_fp4 v[10:11], v171, 1.0 op_sel:[1,0,0]
	v_cvt_scalef32_pk_f32_fp4 v[12:13], v171, 1.0 op_sel:[0,1,0]
	v_cvt_scalef32_pk_f32_fp4 v[14:15], v171, 1.0 op_sel:[1,1,0]
	v_readlane_b32 s54, v90, 41
	s_lshl_b32 s56, s54, 9
	s_add_u32 s56, s64, s56
	s_addc_u32 s57, s65, 0
	global_load_dwordx2 v[170:171], v227, s[56:57]
	v_pk_fma_f32 v[130:131], v[0:1], s[0:1], v[130:131] op_sel_hi:[1,0,1]
	v_pk_fma_f32 v[138:139], v[2:3], s[0:1], v[138:139] op_sel_hi:[1,0,1]
	v_pk_fma_f32 v[140:141], v[4:5], s[0:1], v[140:141] op_sel_hi:[1,0,1]
	v_pk_fma_f32 v[142:143], v[6:7], s[0:1], v[142:143] op_sel_hi:[1,0,1]
	v_pk_fma_f32 v[128:129], v[8:9], s[0:1], v[128:129] op_sel_hi:[1,0,1]
	v_pk_fma_f32 v[132:133], v[10:11], s[0:1], v[132:133] op_sel_hi:[1,0,1]
	v_pk_fma_f32 v[134:135], v[12:13], s[0:1], v[134:135] op_sel_hi:[1,0,1]
	v_pk_fma_f32 v[136:137], v[14:15], s[0:1], v[136:137] op_sel_hi:[1,0,1]
	v_readlane_b32 s0, v167, 26
	s_waitcnt vmcnt(15)
	v_cvt_scalef32_pk_f32_fp4 v[0:1], v172, 1.0
	v_cvt_scalef32_pk_f32_fp4 v[2:3], v172, 1.0 op_sel:[1,0,0]
	v_cvt_scalef32_pk_f32_fp4 v[4:5], v172, 1.0 op_sel:[0,1,0]
	v_cvt_scalef32_pk_f32_fp4 v[6:7], v172, 1.0 op_sel:[1,1,0]
	v_cvt_scalef32_pk_f32_fp4 v[8:9], v173, 1.0
	v_cvt_scalef32_pk_f32_fp4 v[10:11], v173, 1.0 op_sel:[1,0,0]
	v_cvt_scalef32_pk_f32_fp4 v[12:13], v173, 1.0 op_sel:[0,1,0]
	v_cvt_scalef32_pk_f32_fp4 v[14:15], v173, 1.0 op_sel:[1,1,0]
	v_readlane_b32 s54, v90, 42
	s_lshl_b32 s56, s54, 9
	s_add_u32 s56, s64, s56
	s_addc_u32 s57, s65, 0
	global_load_dwordx2 v[172:173], v227, s[56:57]
	v_pk_fma_f32 v[130:131], v[0:1], s[0:1], v[130:131] op_sel_hi:[1,0,1]
	v_pk_fma_f32 v[138:139], v[2:3], s[0:1], v[138:139] op_sel_hi:[1,0,1]
	v_pk_fma_f32 v[140:141], v[4:5], s[0:1], v[140:141] op_sel_hi:[1,0,1]
	v_pk_fma_f32 v[142:143], v[6:7], s[0:1], v[142:143] op_sel_hi:[1,0,1]
	v_pk_fma_f32 v[128:129], v[8:9], s[0:1], v[128:129] op_sel_hi:[1,0,1]
	v_pk_fma_f32 v[132:133], v[10:11], s[0:1], v[132:133] op_sel_hi:[1,0,1]
	v_pk_fma_f32 v[134:135], v[12:13], s[0:1], v[134:135] op_sel_hi:[1,0,1]
	v_pk_fma_f32 v[136:137], v[14:15], s[0:1], v[136:137] op_sel_hi:[1,0,1]
	v_readlane_b32 s0, v167, 27
	s_waitcnt vmcnt(15)
	v_cvt_scalef32_pk_f32_fp4 v[0:1], v174, 1.0
	v_cvt_scalef32_pk_f32_fp4 v[2:3], v174, 1.0 op_sel:[1,0,0]
	v_cvt_scalef32_pk_f32_fp4 v[4:5], v174, 1.0 op_sel:[0,1,0]
	v_cvt_scalef32_pk_f32_fp4 v[6:7], v174, 1.0 op_sel:[1,1,0]
	v_cvt_scalef32_pk_f32_fp4 v[8:9], v175, 1.0
	v_cvt_scalef32_pk_f32_fp4 v[10:11], v175, 1.0 op_sel:[1,0,0]
	v_cvt_scalef32_pk_f32_fp4 v[12:13], v175, 1.0 op_sel:[0,1,0]
	v_cvt_scalef32_pk_f32_fp4 v[14:15], v175, 1.0 op_sel:[1,1,0]
	v_readlane_b32 s54, v90, 43
	s_lshl_b32 s56, s54, 9
	s_add_u32 s56, s64, s56
	s_addc_u32 s57, s65, 0
	global_load_dwordx2 v[174:175], v227, s[56:57]
	v_pk_fma_f32 v[130:131], v[0:1], s[0:1], v[130:131] op_sel_hi:[1,0,1]
	v_pk_fma_f32 v[138:139], v[2:3], s[0:1], v[138:139] op_sel_hi:[1,0,1]
	v_pk_fma_f32 v[140:141], v[4:5], s[0:1], v[140:141] op_sel_hi:[1,0,1]
	v_pk_fma_f32 v[142:143], v[6:7], s[0:1], v[142:143] op_sel_hi:[1,0,1]
	v_pk_fma_f32 v[128:129], v[8:9], s[0:1], v[128:129] op_sel_hi:[1,0,1]
	v_pk_fma_f32 v[132:133], v[10:11], s[0:1], v[132:133] op_sel_hi:[1,0,1]
	v_pk_fma_f32 v[134:135], v[12:13], s[0:1], v[134:135] op_sel_hi:[1,0,1]
	v_pk_fma_f32 v[136:137], v[14:15], s[0:1], v[136:137] op_sel_hi:[1,0,1]
	v_readlane_b32 s0, v167, 28
	s_waitcnt vmcnt(15)
	v_cvt_scalef32_pk_f32_fp4 v[0:1], v180, 1.0
	v_cvt_scalef32_pk_f32_fp4 v[2:3], v180, 1.0 op_sel:[1,0,0]
	v_cvt_scalef32_pk_f32_fp4 v[4:5], v180, 1.0 op_sel:[0,1,0]
	v_cvt_scalef32_pk_f32_fp4 v[6:7], v180, 1.0 op_sel:[1,1,0]
	v_cvt_scalef32_pk_f32_fp4 v[8:9], v181, 1.0
	v_cvt_scalef32_pk_f32_fp4 v[10:11], v181, 1.0 op_sel:[1,0,0]
	v_cvt_scalef32_pk_f32_fp4 v[12:13], v181, 1.0 op_sel:[0,1,0]
	v_cvt_scalef32_pk_f32_fp4 v[14:15], v181, 1.0 op_sel:[1,1,0]
	v_readlane_b32 s54, v90, 44
	s_lshl_b32 s56, s54, 9
	s_add_u32 s56, s64, s56
	s_addc_u32 s57, s65, 0
	global_load_dwordx2 v[180:181], v227, s[56:57]
	v_pk_fma_f32 v[130:131], v[0:1], s[0:1], v[130:131] op_sel_hi:[1,0,1]
	v_pk_fma_f32 v[138:139], v[2:3], s[0:1], v[138:139] op_sel_hi:[1,0,1]
	v_pk_fma_f32 v[140:141], v[4:5], s[0:1], v[140:141] op_sel_hi:[1,0,1]
	v_pk_fma_f32 v[142:143], v[6:7], s[0:1], v[142:143] op_sel_hi:[1,0,1]
	v_pk_fma_f32 v[128:129], v[8:9], s[0:1], v[128:129] op_sel_hi:[1,0,1]
	v_pk_fma_f32 v[132:133], v[10:11], s[0:1], v[132:133] op_sel_hi:[1,0,1]
	v_pk_fma_f32 v[134:135], v[12:13], s[0:1], v[134:135] op_sel_hi:[1,0,1]
	v_pk_fma_f32 v[136:137], v[14:15], s[0:1], v[136:137] op_sel_hi:[1,0,1]
	v_readlane_b32 s0, v167, 29
	s_waitcnt vmcnt(15)
; __device__ void peer_gather_phase(const Params& P, int l, bool do_store) {
;     ...
;         v8[2 * pr] = *(const uint2*)(V + (size_t)ea * 512);
;         v8[2 * pr + 1] = *(const uint2*)(V + (size_t)eb * 512);
;     ...
;       for (int j = 0; j < 8; ++j) {
;         const float a = __builtin_bit_cast(float, __builtin_amdgcn_readlane(__builtin_bit_cast(int, avec), kb + j));
;         const f32x2 aa = f32x2{a, a};
;         y[0] += aa * __builtin_amdgcn_cvt_scalef32_pk_f32_fp4(v8[j].x, 1.0f, 0); y[1] += aa * __builtin_amdgcn_cvt_scalef32_pk_f32_fp4(v8[j].x, 1.0f, 1);
;         y[2] += aa * __builtin_amdgcn_cvt_scalef32_pk_f32_fp4(v8[j].x, 1.0f, 2); y[3] += aa * __builtin_amdgcn_cvt_scalef32_pk_f32_fp4(v8[j].x, 1.0f, 3);
;         y[4] += aa * __builtin_amdgcn_cvt_scalef32_pk_f32_fp4(v8[j].y, 1.0f, 0); y[5] += aa * __builtin_amdgcn_cvt_scalef32_pk_f32_fp4(v8[j].y, 1.0f, 1);
;         y[6] += aa * __builtin_amdgcn_cvt_scalef32_pk_f32_fp4(v8[j].y, 1.0f, 2); y[7] += aa * __builtin_amdgcn_cvt_scalef32_pk_f32_fp4(v8[j].y, 1.0f, 3);
;       }
	v_cvt_scalef32_pk_f32_fp4 v[0:1], v182, 1.0
	v_cvt_scalef32_pk_f32_fp4 v[2:3], v182, 1.0 op_sel:[1,0,0]
	v_cvt_scalef32_pk_f32_fp4 v[4:5], v182, 1.0 op_sel:[0,1,0]
	v_cvt_scalef32_pk_f32_fp4 v[6:7], v182, 1.0 op_sel:[1,1,0]
	v_cvt_scalef32_pk_f32_fp4 v[8:9], v183, 1.0
	v_cvt_scalef32_pk_f32_fp4 v[10:11], v183, 1.0 op_sel:[1,0,0]
	v_cvt_scalef32_pk_f32_fp4 v[12:13], v183, 1.0 op_sel:[0,1,0]
	v_cvt_scalef32_pk_f32_fp4 v[14:15], v183, 1.0 op_sel:[1,1,0]
	v_readlane_b32 s54, v90, 45
	s_lshl_b32 s56, s54, 9
	s_add_u32 s56, s64, s56
	s_addc_u32 s57, s65, 0
	global_load_dwordx2 v[182:183], v227, s[56:57]
	v_pk_fma_f32 v[130:131], v[0:1], s[0:1], v[130:131] op_sel_hi:[1,0,1]
	v_pk_fma_f32 v[138:139], v[2:3], s[0:1], v[138:139] op_sel_hi:[1,0,1]
	v_pk_fma_f32 v[140:141], v[4:5], s[0:1], v[140:141] op_sel_hi:[1,0,1]
	v_pk_fma_f32 v[142:143], v[6:7], s[0:1], v[142:143] op_sel_hi:[1,0,1]
	v_pk_fma_f32 v[128:129], v[8:9], s[0:1], v[128:129] op_sel_hi:[1,0,1]
	v_pk_fma_f32 v[132:133], v[10:11], s[0:1], v[132:133] op_sel_hi:[1,0,1]
	v_pk_fma_f32 v[134:135], v[12:13], s[0:1], v[134:135] op_sel_hi:[1,0,1]
	v_pk_fma_f32 v[136:137], v[14:15], s[0:1], v[136:137] op_sel_hi:[1,0,1]
	v_readlane_b32 s0, v167, 30
	s_waitcnt vmcnt(15)
	v_cvt_scalef32_pk_f32_fp4 v[0:1], v184, 1.0
	v_cvt_scalef32_pk_f32_fp4 v[2:3], v184, 1.0 op_sel:[1,0,0]
	v_cvt_scalef32_pk_f32_fp4 v[4:5], v184, 1.0 op_sel:[0,1,0]
	v_cvt_scalef32_pk_f32_fp4 v[6:7], v184, 1.0 op_sel:[1,1,0]
	v_cvt_scalef32_pk_f32_fp4 v[8:9], v185, 1.0
	v_cvt_scalef32_pk_f32_fp4 v[10:11], v185, 1.0 op_sel:[1,0,0]
	v_cvt_scalef32_pk_f32_fp4 v[12:13], v185, 1.0 op_sel:[0,1,0]
	v_cvt_scalef32_pk_f32_fp4 v[14:15], v185, 1.0 op_sel:[1,1,0]
	v_readlane_b32 s54, v90, 46
	s_lshl_b32 s56, s54, 9
	s_add_u32 s56, s64, s56
	s_addc_u32 s57, s65, 0
	global_load_dwordx2 v[184:185], v227, s[56:57]
	v_pk_fma_f32 v[130:131], v[0:1], s[0:1], v[130:131] op_sel_hi:[1,0,1]
	v_pk_fma_f32 v[138:139], v[2:3], s[0:1], v[138:139] op_sel_hi:[1,0,1]
	v_pk_fma_f32 v[140:141], v[4:5], s[0:1], v[140:141] op_sel_hi:[1,0,1]
	v_pk_fma_f32 v[142:143], v[6:7], s[0:1], v[142:143] op_sel_hi:[1,0,1]
	v_pk_fma_f32 v[128:129], v[8:9], s[0:1], v[128:129] op_sel_hi:[1,0,1]
	v_pk_fma_f32 v[132:133], v[10:11], s[0:1], v[132:133] op_sel_hi:[1,0,1]
	v_pk_fma_f32 v[134:135], v[12:13], s[0:1], v[134:135] op_sel_hi:[1,0,1]
	v_pk_fma_f32 v[136:137], v[14:15], s[0:1], v[136:137] op_sel_hi:[1,0,1]
	v_readlane_b32 s0, v167, 31
	s_waitcnt vmcnt(15)
	v_cvt_scalef32_pk_f32_fp4 v[0:1], v186, 1.0
	v_cvt_scalef32_pk_f32_fp4 v[2:3], v186, 1.0 op_sel:[1,0,0]
	v_cvt_scalef32_pk_f32_fp4 v[4:5], v186, 1.0 op_sel:[0,1,0]
	v_cvt_scalef32_pk_f32_fp4 v[6:7], v186, 1.0 op_sel:[1,1,0]
	v_cvt_scalef32_pk_f32_fp4 v[8:9], v187, 1.0
	v_cvt_scalef32_pk_f32_fp4 v[10:11], v187, 1.0 op_sel:[1,0,0]
	v_cvt_scalef32_pk_f32_fp4 v[12:13], v187, 1.0 op_sel:[0,1,0]
	v_cvt_scalef32_pk_f32_fp4 v[14:15], v187, 1.0 op_sel:[1,1,0]
	v_readlane_b32 s54, v90, 47
	s_lshl_b32 s56, s54, 9
	s_add_u32 s56, s64, s56
	s_addc_u32 s57, s65, 0
	global_load_dwordx2 v[186:187], v227, s[56:57]
	v_pk_fma_f32 v[130:131], v[0:1], s[0:1], v[130:131] op_sel_hi:[1,0,1]
	v_pk_fma_f32 v[138:139], v[2:3], s[0:1], v[138:139] op_sel_hi:[1,0,1]
	v_pk_fma_f32 v[140:141], v[4:5], s[0:1], v[140:141] op_sel_hi:[1,0,1]
	v_pk_fma_f32 v[142:143], v[6:7], s[0:1], v[142:143] op_sel_hi:[1,0,1]
	v_pk_fma_f32 v[128:129], v[8:9], s[0:1], v[128:129] op_sel_hi:[1,0,1]
	v_pk_fma_f32 v[132:133], v[10:11], s[0:1], v[132:133] op_sel_hi:[1,0,1]
	v_pk_fma_f32 v[134:135], v[12:13], s[0:1], v[134:135] op_sel_hi:[1,0,1]
	v_pk_fma_f32 v[136:137], v[14:15], s[0:1], v[136:137] op_sel_hi:[1,0,1]
	v_readlane_b32 s0, v167, 32
	s_waitcnt vmcnt(15)
	v_cvt_scalef32_pk_f32_fp4 v[0:1], v144, 1.0
	v_cvt_scalef32_pk_f32_fp4 v[2:3], v144, 1.0 op_sel:[1,0,0]
	v_cvt_scalef32_pk_f32_fp4 v[4:5], v144, 1.0 op_sel:[0,1,0]
	v_cvt_scalef32_pk_f32_fp4 v[6:7], v144, 1.0 op_sel:[1,1,0]
	v_cvt_scalef32_pk_f32_fp4 v[8:9], v145, 1.0
	v_cvt_scalef32_pk_f32_fp4 v[10:11], v145, 1.0 op_sel:[1,0,0]
	v_cvt_scalef32_pk_f32_fp4 v[12:13], v145, 1.0 op_sel:[0,1,0]
	v_cvt_scalef32_pk_f32_fp4 v[14:15], v145, 1.0 op_sel:[1,1,0]
	v_readlane_b32 s54, v90, 48
	s_lshl_b32 s56, s54, 9
	s_add_u32 s56, s64, s56
	s_addc_u32 s57, s65, 0
	global_load_dwordx2 v[144:145], v227, s[56:57]
	v_pk_fma_f32 v[130:131], v[0:1], s[0:1], v[130:131] op_sel_hi:[1,0,1]
	v_pk_fma_f32 v[138:139], v[2:3], s[0:1], v[138:139] op_sel_hi:[1,0,1]
	v_pk_fma_f32 v[140:141], v[4:5], s[0:1], v[140:141] op_sel_hi:[1,0,1]
	v_pk_fma_f32 v[142:143], v[6:7], s[0:1], v[142:143] op_sel_hi:[1,0,1]
	v_pk_fma_f32 v[128:129], v[8:9], s[0:1], v[128:129] op_sel_hi:[1,0,1]
	v_pk_fma_f32 v[132:133], v[10:11], s[0:1], v[132:133] op_sel_hi:[1,0,1]
	v_pk_fma_f32 v[134:135], v[12:13], s[0:1], v[134:135] op_sel_hi:[1,0,1]
	v_pk_fma_f32 v[136:137], v[14:15], s[0:1], v[136:137] op_sel_hi:[1,0,1]
	v_readlane_b32 s0, v167, 33
	s_waitcnt vmcnt(15)
	v_cvt_scalef32_pk_f32_fp4 v[0:1], v146, 1.0
	v_cvt_scalef32_pk_f32_fp4 v[2:3], v146, 1.0 op_sel:[1,0,0]
	v_cvt_scalef32_pk_f32_fp4 v[4:5], v146, 1.0 op_sel:[0,1,0]
	v_cvt_scalef32_pk_f32_fp4 v[6:7], v146, 1.0 op_sel:[1,1,0]
	v_cvt_scalef32_pk_f32_fp4 v[8:9], v147, 1.0
	v_cvt_scalef32_pk_f32_fp4 v[10:11], v147, 1.0 op_sel:[1,0,0]
	v_cvt_scalef32_pk_f32_fp4 v[12:13], v147, 1.0 op_sel:[0,1,0]
	v_cvt_scalef32_pk_f32_fp4 v[14:15], v147, 1.0 op_sel:[1,1,0]
	v_readlane_b32 s54, v90, 49
	s_lshl_b32 s56, s54, 9
	s_add_u32 s56, s64, s56
	s_addc_u32 s57, s65, 0
	global_load_dwordx2 v[146:147], v227, s[56:57]
	v_pk_fma_f32 v[130:131], v[0:1], s[0:1], v[130:131] op_sel_hi:[1,0,1]
	v_pk_fma_f32 v[138:139], v[2:3], s[0:1], v[138:139] op_sel_hi:[1,0,1]
	v_pk_fma_f32 v[140:141], v[4:5], s[0:1], v[140:141] op_sel_hi:[1,0,1]
	v_pk_fma_f32 v[142:143], v[6:7], s[0:1], v[142:143] op_sel_hi:[1,0,1]
	v_pk_fma_f32 v[128:129], v[8:9], s[0:1], v[128:129] op_sel_hi:[1,0,1]
	v_pk_fma_f32 v[132:133], v[10:11], s[0:1], v[132:133] op_sel_hi:[1,0,1]
	v_pk_fma_f32 v[134:135], v[12:13], s[0:1], v[134:135] op_sel_hi:[1,0,1]
	v_pk_fma_f32 v[136:137], v[14:15], s[0:1], v[136:137] op_sel_hi:[1,0,1]
	v_readlane_b32 s0, v167, 34
	s_waitcnt vmcnt(15)
; __device__ void peer_gather_phase(const Params& P, int l, bool do_store) {
;     ...
;         v8[2 * pr] = *(const uint2*)(V + (size_t)ea * 512);
;         v8[2 * pr + 1] = *(const uint2*)(V + (size_t)eb * 512);
;     ...
;       for (int j = 0; j < 8; ++j) {
;         const float a = __builtin_bit_cast(float, __builtin_amdgcn_readlane(__builtin_bit_cast(int, avec), kb + j));
;         const f32x2 aa = f32x2{a, a};
;         y[0] += aa * __builtin_amdgcn_cvt_scalef32_pk_f32_fp4(v8[j].x, 1.0f, 0); y[1] += aa * __builtin_amdgcn_cvt_scalef32_pk_f32_fp4(v8[j].x, 1.0f, 1);
;         y[2] += aa * __builtin_amdgcn_cvt_scalef32_pk_f32_fp4(v8[j].x, 1.0f, 2); y[3] += aa * __builtin_amdgcn_cvt_scalef32_pk_f32_fp4(v8[j].x, 1.0f, 3);
;         y[4] += aa * __builtin_amdgcn_cvt_scalef32_pk_f32_fp4(v8[j].y, 1.0f, 0); y[5] += aa * __builtin_amdgcn_cvt_scalef32_pk_f32_fp4(v8[j].y, 1.0f, 1);
;         y[6] += aa * __builtin_amdgcn_cvt_scalef32_pk_f32_fp4(v8[j].y, 1.0f, 2); y[7] += aa * __builtin_amdgcn_cvt_scalef32_pk_f32_fp4(v8[j].y, 1.0f, 3);
;       }
	v_cvt_scalef32_pk_f32_fp4 v[0:1], v148, 1.0
	v_cvt_scalef32_pk_f32_fp4 v[2:3], v148, 1.0 op_sel:[1,0,0]
	v_cvt_scalef32_pk_f32_fp4 v[4:5], v148, 1.0 op_sel:[0,1,0]
	v_cvt_scalef32_pk_f32_fp4 v[6:7], v148, 1.0 op_sel:[1,1,0]
	v_cvt_scalef32_pk_f32_fp4 v[8:9], v149, 1.0
	v_cvt_scalef32_pk_f32_fp4 v[10:11], v149, 1.0 op_sel:[1,0,0]
	v_cvt_scalef32_pk_f32_fp4 v[12:13], v149, 1.0 op_sel:[0,1,0]
	v_cvt_scalef32_pk_f32_fp4 v[14:15], v149, 1.0 op_sel:[1,1,0]
	v_readlane_b32 s54, v90, 50
	s_lshl_b32 s56, s54, 9
	s_add_u32 s56, s64, s56
	s_addc_u32 s57, s65, 0
	global_load_dwordx2 v[148:149], v227, s[56:57]
	v_pk_fma_f32 v[130:131], v[0:1], s[0:1], v[130:131] op_sel_hi:[1,0,1]
	v_pk_fma_f32 v[138:139], v[2:3], s[0:1], v[138:139] op_sel_hi:[1,0,1]
	v_pk_fma_f32 v[140:141], v[4:5], s[0:1], v[140:141] op_sel_hi:[1,0,1]
	v_pk_fma_f32 v[142:143], v[6:7], s[0:1], v[142:143] op_sel_hi:[1,0,1]
	v_pk_fma_f32 v[128:129], v[8:9], s[0:1], v[128:129] op_sel_hi:[1,0,1]
	v_pk_fma_f32 v[132:133], v[10:11], s[0:1], v[132:133] op_sel_hi:[1,0,1]
	v_pk_fma_f32 v[134:135], v[12:13], s[0:1], v[134:135] op_sel_hi:[1,0,1]
	v_pk_fma_f32 v[136:137], v[14:15], s[0:1], v[136:137] op_sel_hi:[1,0,1]
	v_readlane_b32 s0, v167, 35
	s_waitcnt vmcnt(15)
	v_cvt_scalef32_pk_f32_fp4 v[0:1], v150, 1.0
	v_cvt_scalef32_pk_f32_fp4 v[2:3], v150, 1.0 op_sel:[1,0,0]
	v_cvt_scalef32_pk_f32_fp4 v[4:5], v150, 1.0 op_sel:[0,1,0]
	v_cvt_scalef32_pk_f32_fp4 v[6:7], v150, 1.0 op_sel:[1,1,0]
	v_cvt_scalef32_pk_f32_fp4 v[8:9], v151, 1.0
	v_cvt_scalef32_pk_f32_fp4 v[10:11], v151, 1.0 op_sel:[1,0,0]
	v_cvt_scalef32_pk_f32_fp4 v[12:13], v151, 1.0 op_sel:[0,1,0]
	v_cvt_scalef32_pk_f32_fp4 v[14:15], v151, 1.0 op_sel:[1,1,0]
	v_readlane_b32 s54, v90, 51
	s_lshl_b32 s56, s54, 9
	s_add_u32 s56, s64, s56
	s_addc_u32 s57, s65, 0
	global_load_dwordx2 v[150:151], v227, s[56:57]
	v_pk_fma_f32 v[130:131], v[0:1], s[0:1], v[130:131] op_sel_hi:[1,0,1]
	v_pk_fma_f32 v[138:139], v[2:3], s[0:1], v[138:139] op_sel_hi:[1,0,1]
	v_pk_fma_f32 v[140:141], v[4:5], s[0:1], v[140:141] op_sel_hi:[1,0,1]
	v_pk_fma_f32 v[142:143], v[6:7], s[0:1], v[142:143] op_sel_hi:[1,0,1]
	v_pk_fma_f32 v[128:129], v[8:9], s[0:1], v[128:129] op_sel_hi:[1,0,1]
	v_pk_fma_f32 v[132:133], v[10:11], s[0:1], v[132:133] op_sel_hi:[1,0,1]
	v_pk_fma_f32 v[134:135], v[12:13], s[0:1], v[134:135] op_sel_hi:[1,0,1]
	v_pk_fma_f32 v[136:137], v[14:15], s[0:1], v[136:137] op_sel_hi:[1,0,1]
	v_readlane_b32 s0, v167, 36
	s_waitcnt vmcnt(15)
	v_cvt_scalef32_pk_f32_fp4 v[0:1], v152, 1.0
	v_cvt_scalef32_pk_f32_fp4 v[2:3], v152, 1.0 op_sel:[1,0,0]
	v_cvt_scalef32_pk_f32_fp4 v[4:5], v152, 1.0 op_sel:[0,1,0]
	v_cvt_scalef32_pk_f32_fp4 v[6:7], v152, 1.0 op_sel:[1,1,0]
	v_cvt_scalef32_pk_f32_fp4 v[8:9], v153, 1.0
	v_cvt_scalef32_pk_f32_fp4 v[10:11], v153, 1.0 op_sel:[1,0,0]
	v_cvt_scalef32_pk_f32_fp4 v[12:13], v153, 1.0 op_sel:[0,1,0]
	v_cvt_scalef32_pk_f32_fp4 v[14:15], v153, 1.0 op_sel:[1,1,0]
	v_readlane_b32 s54, v90, 52
	s_lshl_b32 s56, s54, 9
	s_add_u32 s56, s64, s56
	s_addc_u32 s57, s65, 0
	global_load_dwordx2 v[152:153], v227, s[56:57]
	v_pk_fma_f32 v[130:131], v[0:1], s[0:1], v[130:131] op_sel_hi:[1,0,1]
	v_pk_fma_f32 v[138:139], v[2:3], s[0:1], v[138:139] op_sel_hi:[1,0,1]
	v_pk_fma_f32 v[140:141], v[4:5], s[0:1], v[140:141] op_sel_hi:[1,0,1]
	v_pk_fma_f32 v[142:143], v[6:7], s[0:1], v[142:143] op_sel_hi:[1,0,1]
	v_pk_fma_f32 v[128:129], v[8:9], s[0:1], v[128:129] op_sel_hi:[1,0,1]
	v_pk_fma_f32 v[132:133], v[10:11], s[0:1], v[132:133] op_sel_hi:[1,0,1]
	v_pk_fma_f32 v[134:135], v[12:13], s[0:1], v[134:135] op_sel_hi:[1,0,1]
	v_pk_fma_f32 v[136:137], v[14:15], s[0:1], v[136:137] op_sel_hi:[1,0,1]
	v_readlane_b32 s0, v167, 37
	s_waitcnt vmcnt(15)
	v_cvt_scalef32_pk_f32_fp4 v[0:1], v154, 1.0
	v_cvt_scalef32_pk_f32_fp4 v[2:3], v154, 1.0 op_sel:[1,0,0]
	v_cvt_scalef32_pk_f32_fp4 v[4:5], v154, 1.0 op_sel:[0,1,0]
	v_cvt_scalef32_pk_f32_fp4 v[6:7], v154, 1.0 op_sel:[1,1,0]
	v_cvt_scalef32_pk_f32_fp4 v[8:9], v155, 1.0
	v_cvt_scalef32_pk_f32_fp4 v[10:11], v155, 1.0 op_sel:[1,0,0]
	v_cvt_scalef32_pk_f32_fp4 v[12:13], v155, 1.0 op_sel:[0,1,0]
	v_cvt_scalef32_pk_f32_fp4 v[14:15], v155, 1.0 op_sel:[1,1,0]
	v_readlane_b32 s54, v90, 53
	s_lshl_b32 s56, s54, 9
	s_add_u32 s56, s64, s56
	s_addc_u32 s57, s65, 0
	global_load_dwordx2 v[154:155], v227, s[56:57]
	v_pk_fma_f32 v[130:131], v[0:1], s[0:1], v[130:131] op_sel_hi:[1,0,1]
	v_pk_fma_f32 v[138:139], v[2:3], s[0:1], v[138:139] op_sel_hi:[1,0,1]
	v_pk_fma_f32 v[140:141], v[4:5], s[0:1], v[140:141] op_sel_hi:[1,0,1]
	v_pk_fma_f32 v[142:143], v[6:7], s[0:1], v[142:143] op_sel_hi:[1,0,1]
	v_pk_fma_f32 v[128:129], v[8:9], s[0:1], v[128:129] op_sel_hi:[1,0,1]
	v_pk_fma_f32 v[132:133], v[10:11], s[0:1], v[132:133] op_sel_hi:[1,0,1]
	v_pk_fma_f32 v[134:135], v[12:13], s[0:1], v[134:135] op_sel_hi:[1,0,1]
	v_pk_fma_f32 v[136:137], v[14:15], s[0:1], v[136:137] op_sel_hi:[1,0,1]
	v_readlane_b32 s0, v167, 38
	s_waitcnt vmcnt(15)
	v_cvt_scalef32_pk_f32_fp4 v[0:1], v156, 1.0
	v_cvt_scalef32_pk_f32_fp4 v[2:3], v156, 1.0 op_sel:[1,0,0]
	v_cvt_scalef32_pk_f32_fp4 v[4:5], v156, 1.0 op_sel:[0,1,0]
	v_cvt_scalef32_pk_f32_fp4 v[6:7], v156, 1.0 op_sel:[1,1,0]
	v_cvt_scalef32_pk_f32_fp4 v[8:9], v157, 1.0
	v_cvt_scalef32_pk_f32_fp4 v[10:11], v157, 1.0 op_sel:[1,0,0]
	v_cvt_scalef32_pk_f32_fp4 v[12:13], v157, 1.0 op_sel:[0,1,0]
	v_cvt_scalef32_pk_f32_fp4 v[14:15], v157, 1.0 op_sel:[1,1,0]
	v_readlane_b32 s54, v90, 54
	s_lshl_b32 s56, s54, 9
	s_add_u32 s56, s64, s56
	s_addc_u32 s57, s65, 0
	global_load_dwordx2 v[156:157], v227, s[56:57]
	v_pk_fma_f32 v[130:131], v[0:1], s[0:1], v[130:131] op_sel_hi:[1,0,1]
	v_pk_fma_f32 v[138:139], v[2:3], s[0:1], v[138:139] op_sel_hi:[1,0,1]
	v_pk_fma_f32 v[140:141], v[4:5], s[0:1], v[140:141] op_sel_hi:[1,0,1]
	v_pk_fma_f32 v[142:143], v[6:7], s[0:1], v[142:143] op_sel_hi:[1,0,1]
	v_pk_fma_f32 v[128:129], v[8:9], s[0:1], v[128:129] op_sel_hi:[1,0,1]
	v_pk_fma_f32 v[132:133], v[10:11], s[0:1], v[132:133] op_sel_hi:[1,0,1]
	v_pk_fma_f32 v[134:135], v[12:13], s[0:1], v[134:135] op_sel_hi:[1,0,1]
	v_pk_fma_f32 v[136:137], v[14:15], s[0:1], v[136:137] op_sel_hi:[1,0,1]
	v_readlane_b32 s0, v167, 39
	s_waitcnt vmcnt(15)
; __device__ void peer_gather_phase(const Params& P, int l, bool do_store) {
;     ...
;         v8[2 * pr] = *(const uint2*)(V + (size_t)ea * 512);
;         v8[2 * pr + 1] = *(const uint2*)(V + (size_t)eb * 512);
;     ...
;       for (int j = 0; j < 8; ++j) {
;         const float a = __builtin_bit_cast(float, __builtin_amdgcn_readlane(__builtin_bit_cast(int, avec), kb + j));
;         const f32x2 aa = f32x2{a, a};
;         y[0] += aa * __builtin_amdgcn_cvt_scalef32_pk_f32_fp4(v8[j].x, 1.0f, 0); y[1] += aa * __builtin_amdgcn_cvt_scalef32_pk_f32_fp4(v8[j].x, 1.0f, 1);
;         y[2] += aa * __builtin_amdgcn_cvt_scalef32_pk_f32_fp4(v8[j].x, 1.0f, 2); y[3] += aa * __builtin_amdgcn_cvt_scalef32_pk_f32_fp4(v8[j].x, 1.0f, 3);
;         y[4] += aa * __builtin_amdgcn_cvt_scalef32_pk_f32_fp4(v8[j].y, 1.0f, 0); y[5] += aa * __builtin_amdgcn_cvt_scalef32_pk_f32_fp4(v8[j].y, 1.0f, 1);
;         y[6] += aa * __builtin_amdgcn_cvt_scalef32_pk_f32_fp4(v8[j].y, 1.0f, 2); y[7] += aa * __builtin_amdgcn_cvt_scalef32_pk_f32_fp4(v8[j].y, 1.0f, 3);
;       }
	v_cvt_scalef32_pk_f32_fp4 v[0:1], v158, 1.0
	v_cvt_scalef32_pk_f32_fp4 v[2:3], v158, 1.0 op_sel:[1,0,0]
	v_cvt_scalef32_pk_f32_fp4 v[4:5], v158, 1.0 op_sel:[0,1,0]
	v_cvt_scalef32_pk_f32_fp4 v[6:7], v158, 1.0 op_sel:[1,1,0]
	v_cvt_scalef32_pk_f32_fp4 v[8:9], v159, 1.0
	v_cvt_scalef32_pk_f32_fp4 v[10:11], v159, 1.0 op_sel:[1,0,0]
	v_cvt_scalef32_pk_f32_fp4 v[12:13], v159, 1.0 op_sel:[0,1,0]
	v_cvt_scalef32_pk_f32_fp4 v[14:15], v159, 1.0 op_sel:[1,1,0]
	v_readlane_b32 s54, v90, 55
	s_lshl_b32 s56, s54, 9
	s_add_u32 s56, s64, s56
	s_addc_u32 s57, s65, 0
	global_load_dwordx2 v[158:159], v227, s[56:57]
	v_pk_fma_f32 v[130:131], v[0:1], s[0:1], v[130:131] op_sel_hi:[1,0,1]
	v_pk_fma_f32 v[138:139], v[2:3], s[0:1], v[138:139] op_sel_hi:[1,0,1]
	v_pk_fma_f32 v[140:141], v[4:5], s[0:1], v[140:141] op_sel_hi:[1,0,1]
	v_pk_fma_f32 v[142:143], v[6:7], s[0:1], v[142:143] op_sel_hi:[1,0,1]
	v_pk_fma_f32 v[128:129], v[8:9], s[0:1], v[128:129] op_sel_hi:[1,0,1]
	v_pk_fma_f32 v[132:133], v[10:11], s[0:1], v[132:133] op_sel_hi:[1,0,1]
	v_pk_fma_f32 v[134:135], v[12:13], s[0:1], v[134:135] op_sel_hi:[1,0,1]
	v_pk_fma_f32 v[136:137], v[14:15], s[0:1], v[136:137] op_sel_hi:[1,0,1]
	v_readlane_b32 s0, v167, 40
	s_waitcnt vmcnt(15)
	v_cvt_scalef32_pk_f32_fp4 v[0:1], v168, 1.0
	v_cvt_scalef32_pk_f32_fp4 v[2:3], v168, 1.0 op_sel:[1,0,0]
	v_cvt_scalef32_pk_f32_fp4 v[4:5], v168, 1.0 op_sel:[0,1,0]
	v_cvt_scalef32_pk_f32_fp4 v[6:7], v168, 1.0 op_sel:[1,1,0]
	v_cvt_scalef32_pk_f32_fp4 v[8:9], v169, 1.0
	v_cvt_scalef32_pk_f32_fp4 v[10:11], v169, 1.0 op_sel:[1,0,0]
	v_cvt_scalef32_pk_f32_fp4 v[12:13], v169, 1.0 op_sel:[0,1,0]
	v_cvt_scalef32_pk_f32_fp4 v[14:15], v169, 1.0 op_sel:[1,1,0]
	v_readlane_b32 s54, v90, 56
	s_lshl_b32 s56, s54, 9
	s_add_u32 s56, s64, s56
	s_addc_u32 s57, s65, 0
	global_load_dwordx2 v[168:169], v227, s[56:57]
	v_pk_fma_f32 v[130:131], v[0:1], s[0:1], v[130:131] op_sel_hi:[1,0,1]
	v_pk_fma_f32 v[138:139], v[2:3], s[0:1], v[138:139] op_sel_hi:[1,0,1]
	v_pk_fma_f32 v[140:141], v[4:5], s[0:1], v[140:141] op_sel_hi:[1,0,1]
	v_pk_fma_f32 v[142:143], v[6:7], s[0:1], v[142:143] op_sel_hi:[1,0,1]
	v_pk_fma_f32 v[128:129], v[8:9], s[0:1], v[128:129] op_sel_hi:[1,0,1]
	v_pk_fma_f32 v[132:133], v[10:11], s[0:1], v[132:133] op_sel_hi:[1,0,1]
	v_pk_fma_f32 v[134:135], v[12:13], s[0:1], v[134:135] op_sel_hi:[1,0,1]
	v_pk_fma_f32 v[136:137], v[14:15], s[0:1], v[136:137] op_sel_hi:[1,0,1]
	v_readlane_b32 s0, v167, 41
	s_waitcnt vmcnt(15)
	v_cvt_scalef32_pk_f32_fp4 v[0:1], v170, 1.0
	v_cvt_scalef32_pk_f32_fp4 v[2:3], v170, 1.0 op_sel:[1,0,0]
	v_cvt_scalef32_pk_f32_fp4 v[4:5], v170, 1.0 op_sel:[0,1,0]
	v_cvt_scalef32_pk_f32_fp4 v[6:7], v170, 1.0 op_sel:[1,1,0]
	v_cvt_scalef32_pk_f32_fp4 v[8:9], v171, 1.0
	v_cvt_scalef32_pk_f32_fp4 v[10:11], v171, 1.0 op_sel:[1,0,0]
	v_cvt_scalef32_pk_f32_fp4 v[12:13], v171, 1.0 op_sel:[0,1,0]
	v_cvt_scalef32_pk_f32_fp4 v[14:15], v171, 1.0 op_sel:[1,1,0]
	v_readlane_b32 s54, v90, 57
	s_lshl_b32 s56, s54, 9
	s_add_u32 s56, s64, s56
	s_addc_u32 s57, s65, 0
	global_load_dwordx2 v[170:171], v227, s[56:57]
	v_pk_fma_f32 v[130:131], v[0:1], s[0:1], v[130:131] op_sel_hi:[1,0,1]
	v_pk_fma_f32 v[138:139], v[2:3], s[0:1], v[138:139] op_sel_hi:[1,0,1]
	v_pk_fma_f32 v[140:141], v[4:5], s[0:1], v[140:141] op_sel_hi:[1,0,1]
	v_pk_fma_f32 v[142:143], v[6:7], s[0:1], v[142:143] op_sel_hi:[1,0,1]
	v_pk_fma_f32 v[128:129], v[8:9], s[0:1], v[128:129] op_sel_hi:[1,0,1]
	v_pk_fma_f32 v[132:133], v[10:11], s[0:1], v[132:133] op_sel_hi:[1,0,1]
	v_pk_fma_f32 v[134:135], v[12:13], s[0:1], v[134:135] op_sel_hi:[1,0,1]
	v_pk_fma_f32 v[136:137], v[14:15], s[0:1], v[136:137] op_sel_hi:[1,0,1]
	v_readlane_b32 s0, v167, 42
	s_waitcnt vmcnt(15)
	v_cvt_scalef32_pk_f32_fp4 v[0:1], v172, 1.0
	v_cvt_scalef32_pk_f32_fp4 v[2:3], v172, 1.0 op_sel:[1,0,0]
	v_cvt_scalef32_pk_f32_fp4 v[4:5], v172, 1.0 op_sel:[0,1,0]
	v_cvt_scalef32_pk_f32_fp4 v[6:7], v172, 1.0 op_sel:[1,1,0]
	v_cvt_scalef32_pk_f32_fp4 v[8:9], v173, 1.0
	v_cvt_scalef32_pk_f32_fp4 v[10:11], v173, 1.0 op_sel:[1,0,0]
	v_cvt_scalef32_pk_f32_fp4 v[12:13], v173, 1.0 op_sel:[0,1,0]
	v_cvt_scalef32_pk_f32_fp4 v[14:15], v173, 1.0 op_sel:[1,1,0]
	v_readlane_b32 s54, v90, 58
	s_lshl_b32 s56, s54, 9
	s_add_u32 s56, s64, s56
	s_addc_u32 s57, s65, 0
	global_load_dwordx2 v[172:173], v227, s[56:57]
	v_pk_fma_f32 v[130:131], v[0:1], s[0:1], v[130:131] op_sel_hi:[1,0,1]
	v_pk_fma_f32 v[138:139], v[2:3], s[0:1], v[138:139] op_sel_hi:[1,0,1]
	v_pk_fma_f32 v[140:141], v[4:5], s[0:1], v[140:141] op_sel_hi:[1,0,1]
	v_pk_fma_f32 v[142:143], v[6:7], s[0:1], v[142:143] op_sel_hi:[1,0,1]
	v_pk_fma_f32 v[128:129], v[8:9], s[0:1], v[128:129] op_sel_hi:[1,0,1]
	v_pk_fma_f32 v[132:133], v[10:11], s[0:1], v[132:133] op_sel_hi:[1,0,1]
	v_pk_fma_f32 v[134:135], v[12:13], s[0:1], v[134:135] op_sel_hi:[1,0,1]
	v_pk_fma_f32 v[136:137], v[14:15], s[0:1], v[136:137] op_sel_hi:[1,0,1]
	v_readlane_b32 s0, v167, 43
	s_waitcnt vmcnt(15)
	v_cvt_scalef32_pk_f32_fp4 v[0:1], v174, 1.0
	v_cvt_scalef32_pk_f32_fp4 v[2:3], v174, 1.0 op_sel:[1,0,0]
	v_cvt_scalef32_pk_f32_fp4 v[4:5], v174, 1.0 op_sel:[0,1,0]
	v_cvt_scalef32_pk_f32_fp4 v[6:7], v174, 1.0 op_sel:[1,1,0]
	v_cvt_scalef32_pk_f32_fp4 v[8:9], v175, 1.0
	v_cvt_scalef32_pk_f32_fp4 v[10:11], v175, 1.0 op_sel:[1,0,0]
	v_cvt_scalef32_pk_f32_fp4 v[12:13], v175, 1.0 op_sel:[0,1,0]
	v_cvt_scalef32_pk_f32_fp4 v[14:15], v175, 1.0 op_sel:[1,1,0]
	v_readlane_b32 s54, v90, 59
	s_lshl_b32 s56, s54, 9
	s_add_u32 s56, s64, s56
	s_addc_u32 s57, s65, 0
	global_load_dwordx2 v[174:175], v227, s[56:57]
	v_pk_fma_f32 v[130:131], v[0:1], s[0:1], v[130:131] op_sel_hi:[1,0,1]
	v_pk_fma_f32 v[138:139], v[2:3], s[0:1], v[138:139] op_sel_hi:[1,0,1]
	v_pk_fma_f32 v[140:141], v[4:5], s[0:1], v[140:141] op_sel_hi:[1,0,1]
	v_pk_fma_f32 v[142:143], v[6:7], s[0:1], v[142:143] op_sel_hi:[1,0,1]
	v_pk_fma_f32 v[128:129], v[8:9], s[0:1], v[128:129] op_sel_hi:[1,0,1]
	v_pk_fma_f32 v[132:133], v[10:11], s[0:1], v[132:133] op_sel_hi:[1,0,1]
	v_pk_fma_f32 v[134:135], v[12:13], s[0:1], v[134:135] op_sel_hi:[1,0,1]
	v_pk_fma_f32 v[136:137], v[14:15], s[0:1], v[136:137] op_sel_hi:[1,0,1]
	v_readlane_b32 s0, v167, 44
	s_waitcnt vmcnt(15)
; __device__ void peer_gather_phase(const Params& P, int l, bool do_store) {
;     ...
;         v8[2 * pr] = *(const uint2*)(V + (size_t)ea * 512);
;         v8[2 * pr + 1] = *(const uint2*)(V + (size_t)eb * 512);
;     ...
;       for (int j = 0; j < 8; ++j) {
;         const float a = __builtin_bit_cast(float, __builtin_amdgcn_readlane(__builtin_bit_cast(int, avec), kb + j));
;         const f32x2 aa = f32x2{a, a};
;         y[0] += aa * __builtin_amdgcn_cvt_scalef32_pk_f32_fp4(v8[j].x, 1.0f, 0); y[1] += aa * __builtin_amdgcn_cvt_scalef32_pk_f32_fp4(v8[j].x, 1.0f, 1);
;         y[2] += aa * __builtin_amdgcn_cvt_scalef32_pk_f32_fp4(v8[j].x, 1.0f, 2); y[3] += aa * __builtin_amdgcn_cvt_scalef32_pk_f32_fp4(v8[j].x, 1.0f, 3);
;         y[4] += aa * __builtin_amdgcn_cvt_scalef32_pk_f32_fp4(v8[j].y, 1.0f, 0); y[5] += aa * __builtin_amdgcn_cvt_scalef32_pk_f32_fp4(v8[j].y, 1.0f, 1);
;         y[6] += aa * __builtin_amdgcn_cvt_scalef32_pk_f32_fp4(v8[j].y, 1.0f, 2); y[7] += aa * __builtin_amdgcn_cvt_scalef32_pk_f32_fp4(v8[j].y, 1.0f, 3);
;       }
	v_cvt_scalef32_pk_f32_fp4 v[0:1], v180, 1.0
	v_cvt_scalef32_pk_f32_fp4 v[2:3], v180, 1.0 op_sel:[1,0,0]
	v_cvt_scalef32_pk_f32_fp4 v[4:5], v180, 1.0 op_sel:[0,1,0]
	v_cvt_scalef32_pk_f32_fp4 v[6:7], v180, 1.0 op_sel:[1,1,0]
	v_cvt_scalef32_pk_f32_fp4 v[8:9], v181, 1.0
	v_cvt_scalef32_pk_f32_fp4 v[10:11], v181, 1.0 op_sel:[1,0,0]
	v_cvt_scalef32_pk_f32_fp4 v[12:13], v181, 1.0 op_sel:[0,1,0]
	v_cvt_scalef32_pk_f32_fp4 v[14:15], v181, 1.0 op_sel:[1,1,0]
	v_readlane_b32 s54, v90, 60
	s_lshl_b32 s56, s54, 9
	s_add_u32 s56, s64, s56
	s_addc_u32 s57, s65, 0
	global_load_dwordx2 v[180:181], v227, s[56:57]
	v_pk_fma_f32 v[130:131], v[0:1], s[0:1], v[130:131] op_sel_hi:[1,0,1]
	v_pk_fma_f32 v[138:139], v[2:3], s[0:1], v[138:139] op_sel_hi:[1,0,1]
	v_pk_fma_f32 v[140:141], v[4:5], s[0:1], v[140:141] op_sel_hi:[1,0,1]
	v_pk_fma_f32 v[142:143], v[6:7], s[0:1], v[142:143] op_sel_hi:[1,0,1]
	v_pk_fma_f32 v[128:129], v[8:9], s[0:1], v[128:129] op_sel_hi:[1,0,1]
	v_pk_fma_f32 v[132:133], v[10:11], s[0:1], v[132:133] op_sel_hi:[1,0,1]
	v_pk_fma_f32 v[134:135], v[12:13], s[0:1], v[134:135] op_sel_hi:[1,0,1]
	v_pk_fma_f32 v[136:137], v[14:15], s[0:1], v[136:137] op_sel_hi:[1,0,1]
	v_readlane_b32 s0, v167, 45
	s_waitcnt vmcnt(15)
	v_cvt_scalef32_pk_f32_fp4 v[0:1], v182, 1.0
	v_cvt_scalef32_pk_f32_fp4 v[2:3], v182, 1.0 op_sel:[1,0,0]
	v_cvt_scalef32_pk_f32_fp4 v[4:5], v182, 1.0 op_sel:[0,1,0]
	v_cvt_scalef32_pk_f32_fp4 v[6:7], v182, 1.0 op_sel:[1,1,0]
	v_cvt_scalef32_pk_f32_fp4 v[8:9], v183, 1.0
	v_cvt_scalef32_pk_f32_fp4 v[10:11], v183, 1.0 op_sel:[1,0,0]
	v_cvt_scalef32_pk_f32_fp4 v[12:13], v183, 1.0 op_sel:[0,1,0]
	v_cvt_scalef32_pk_f32_fp4 v[14:15], v183, 1.0 op_sel:[1,1,0]
	v_readlane_b32 s54, v90, 61
	s_lshl_b32 s56, s54, 9
	s_add_u32 s56, s64, s56
	s_addc_u32 s57, s65, 0
	global_load_dwordx2 v[182:183], v227, s[56:57]
	v_pk_fma_f32 v[130:131], v[0:1], s[0:1], v[130:131] op_sel_hi:[1,0,1]
	v_pk_fma_f32 v[138:139], v[2:3], s[0:1], v[138:139] op_sel_hi:[1,0,1]
	v_pk_fma_f32 v[140:141], v[4:5], s[0:1], v[140:141] op_sel_hi:[1,0,1]
	v_pk_fma_f32 v[142:143], v[6:7], s[0:1], v[142:143] op_sel_hi:[1,0,1]
	v_pk_fma_f32 v[128:129], v[8:9], s[0:1], v[128:129] op_sel_hi:[1,0,1]
	v_pk_fma_f32 v[132:133], v[10:11], s[0:1], v[132:133] op_sel_hi:[1,0,1]
	v_pk_fma_f32 v[134:135], v[12:13], s[0:1], v[134:135] op_sel_hi:[1,0,1]
	v_pk_fma_f32 v[136:137], v[14:15], s[0:1], v[136:137] op_sel_hi:[1,0,1]
	v_readlane_b32 s0, v167, 46
	s_waitcnt vmcnt(15)
	v_cvt_scalef32_pk_f32_fp4 v[0:1], v184, 1.0
	v_cvt_scalef32_pk_f32_fp4 v[2:3], v184, 1.0 op_sel:[1,0,0]
	v_cvt_scalef32_pk_f32_fp4 v[4:5], v184, 1.0 op_sel:[0,1,0]
	v_cvt_scalef32_pk_f32_fp4 v[6:7], v184, 1.0 op_sel:[1,1,0]
	v_cvt_scalef32_pk_f32_fp4 v[8:9], v185, 1.0
	v_cvt_scalef32_pk_f32_fp4 v[10:11], v185, 1.0 op_sel:[1,0,0]
	v_cvt_scalef32_pk_f32_fp4 v[12:13], v185, 1.0 op_sel:[0,1,0]
	v_cvt_scalef32_pk_f32_fp4 v[14:15], v185, 1.0 op_sel:[1,1,0]
	v_readlane_b32 s54, v90, 62
	s_lshl_b32 s56, s54, 9
	s_add_u32 s56, s64, s56
	s_addc_u32 s57, s65, 0
	global_load_dwordx2 v[184:185], v227, s[56:57]
	v_pk_fma_f32 v[130:131], v[0:1], s[0:1], v[130:131] op_sel_hi:[1,0,1]
	v_pk_fma_f32 v[138:139], v[2:3], s[0:1], v[138:139] op_sel_hi:[1,0,1]
	v_pk_fma_f32 v[140:141], v[4:5], s[0:1], v[140:141] op_sel_hi:[1,0,1]
	v_pk_fma_f32 v[142:143], v[6:7], s[0:1], v[142:143] op_sel_hi:[1,0,1]
	v_pk_fma_f32 v[128:129], v[8:9], s[0:1], v[128:129] op_sel_hi:[1,0,1]
	v_pk_fma_f32 v[132:133], v[10:11], s[0:1], v[132:133] op_sel_hi:[1,0,1]
	v_pk_fma_f32 v[134:135], v[12:13], s[0:1], v[134:135] op_sel_hi:[1,0,1]
	v_pk_fma_f32 v[136:137], v[14:15], s[0:1], v[136:137] op_sel_hi:[1,0,1]
	v_readlane_b32 s0, v167, 47
	s_waitcnt vmcnt(15)
	v_cvt_scalef32_pk_f32_fp4 v[0:1], v186, 1.0
	v_cvt_scalef32_pk_f32_fp4 v[2:3], v186, 1.0 op_sel:[1,0,0]
	v_cvt_scalef32_pk_f32_fp4 v[4:5], v186, 1.0 op_sel:[0,1,0]
	v_cvt_scalef32_pk_f32_fp4 v[6:7], v186, 1.0 op_sel:[1,1,0]
	v_cvt_scalef32_pk_f32_fp4 v[8:9], v187, 1.0
	v_cvt_scalef32_pk_f32_fp4 v[10:11], v187, 1.0 op_sel:[1,0,0]
	v_cvt_scalef32_pk_f32_fp4 v[12:13], v187, 1.0 op_sel:[0,1,0]
	v_cvt_scalef32_pk_f32_fp4 v[14:15], v187, 1.0 op_sel:[1,1,0]
	v_readlane_b32 s54, v90, 63
	s_lshl_b32 s56, s54, 9
	s_add_u32 s56, s64, s56
	s_addc_u32 s57, s65, 0
	global_load_dwordx2 v[186:187], v227, s[56:57]
	v_pk_fma_f32 v[130:131], v[0:1], s[0:1], v[130:131] op_sel_hi:[1,0,1]
	v_pk_fma_f32 v[138:139], v[2:3], s[0:1], v[138:139] op_sel_hi:[1,0,1]
	v_pk_fma_f32 v[140:141], v[4:5], s[0:1], v[140:141] op_sel_hi:[1,0,1]
	v_pk_fma_f32 v[142:143], v[6:7], s[0:1], v[142:143] op_sel_hi:[1,0,1]
	v_pk_fma_f32 v[128:129], v[8:9], s[0:1], v[128:129] op_sel_hi:[1,0,1]
	v_pk_fma_f32 v[132:133], v[10:11], s[0:1], v[132:133] op_sel_hi:[1,0,1]
	v_pk_fma_f32 v[134:135], v[12:13], s[0:1], v[134:135] op_sel_hi:[1,0,1]
	v_pk_fma_f32 v[136:137], v[14:15], s[0:1], v[136:137] op_sel_hi:[1,0,1]
	v_readlane_b32 s0, v167, 48
	s_waitcnt vmcnt(15)
	v_cvt_scalef32_pk_f32_fp4 v[0:1], v144, 1.0
	v_cvt_scalef32_pk_f32_fp4 v[2:3], v144, 1.0 op_sel:[1,0,0]
	v_cvt_scalef32_pk_f32_fp4 v[4:5], v144, 1.0 op_sel:[0,1,0]
	v_cvt_scalef32_pk_f32_fp4 v[6:7], v144, 1.0 op_sel:[1,1,0]
	v_cvt_scalef32_pk_f32_fp4 v[8:9], v145, 1.0
	v_cvt_scalef32_pk_f32_fp4 v[10:11], v145, 1.0 op_sel:[1,0,0]
	v_cvt_scalef32_pk_f32_fp4 v[12:13], v145, 1.0 op_sel:[0,1,0]
	v_cvt_scalef32_pk_f32_fp4 v[14:15], v145, 1.0 op_sel:[1,1,0]
	v_pk_fma_f32 v[130:131], v[0:1], s[0:1], v[130:131] op_sel_hi:[1,0,1]
	v_pk_fma_f32 v[138:139], v[2:3], s[0:1], v[138:139] op_sel_hi:[1,0,1]
	v_pk_fma_f32 v[140:141], v[4:5], s[0:1], v[140:141] op_sel_hi:[1,0,1]
	v_pk_fma_f32 v[142:143], v[6:7], s[0:1], v[142:143] op_sel_hi:[1,0,1]
	v_pk_fma_f32 v[128:129], v[8:9], s[0:1], v[128:129] op_sel_hi:[1,0,1]
	v_pk_fma_f32 v[132:133], v[10:11], s[0:1], v[132:133] op_sel_hi:[1,0,1]
	v_pk_fma_f32 v[134:135], v[12:13], s[0:1], v[134:135] op_sel_hi:[1,0,1]
	v_pk_fma_f32 v[136:137], v[14:15], s[0:1], v[136:137] op_sel_hi:[1,0,1]
	v_readlane_b32 s0, v167, 49
	s_waitcnt vmcnt(14)
; __device__ void peer_gather_phase(const Params& P, int l, bool do_store) {
;     ...
;       for (int j = 0; j < 8; ++j) {
;         const float a = __builtin_bit_cast(float, __builtin_amdgcn_readlane(__builtin_bit_cast(int, avec), kb + j));
;         const f32x2 aa = f32x2{a, a};
;         y[0] += aa * __builtin_amdgcn_cvt_scalef32_pk_f32_fp4(v8[j].x, 1.0f, 0); y[1] += aa * __builtin_amdgcn_cvt_scalef32_pk_f32_fp4(v8[j].x, 1.0f, 1);
;         y[2] += aa * __builtin_amdgcn_cvt_scalef32_pk_f32_fp4(v8[j].x, 1.0f, 2); y[3] += aa * __builtin_amdgcn_cvt_scalef32_pk_f32_fp4(v8[j].x, 1.0f, 3);
;         y[4] += aa * __builtin_amdgcn_cvt_scalef32_pk_f32_fp4(v8[j].y, 1.0f, 0); y[5] += aa * __builtin_amdgcn_cvt_scalef32_pk_f32_fp4(v8[j].y, 1.0f, 1);
;         y[6] += aa * __builtin_amdgcn_cvt_scalef32_pk_f32_fp4(v8[j].y, 1.0f, 2); y[7] += aa * __builtin_amdgcn_cvt_scalef32_pk_f32_fp4(v8[j].y, 1.0f, 3);
;       }
	v_cvt_scalef32_pk_f32_fp4 v[0:1], v146, 1.0
	v_cvt_scalef32_pk_f32_fp4 v[2:3], v146, 1.0 op_sel:[1,0,0]
	v_cvt_scalef32_pk_f32_fp4 v[4:5], v146, 1.0 op_sel:[0,1,0]
	v_cvt_scalef32_pk_f32_fp4 v[6:7], v146, 1.0 op_sel:[1,1,0]
	v_cvt_scalef32_pk_f32_fp4 v[8:9], v147, 1.0
	v_cvt_scalef32_pk_f32_fp4 v[10:11], v147, 1.0 op_sel:[1,0,0]
	v_cvt_scalef32_pk_f32_fp4 v[12:13], v147, 1.0 op_sel:[0,1,0]
	v_cvt_scalef32_pk_f32_fp4 v[14:15], v147, 1.0 op_sel:[1,1,0]
	v_pk_fma_f32 v[130:131], v[0:1], s[0:1], v[130:131] op_sel_hi:[1,0,1]
	v_pk_fma_f32 v[138:139], v[2:3], s[0:1], v[138:139] op_sel_hi:[1,0,1]
	v_pk_fma_f32 v[140:141], v[4:5], s[0:1], v[140:141] op_sel_hi:[1,0,1]
	v_pk_fma_f32 v[142:143], v[6:7], s[0:1], v[142:143] op_sel_hi:[1,0,1]
	v_pk_fma_f32 v[128:129], v[8:9], s[0:1], v[128:129] op_sel_hi:[1,0,1]
	v_pk_fma_f32 v[132:133], v[10:11], s[0:1], v[132:133] op_sel_hi:[1,0,1]
	v_pk_fma_f32 v[134:135], v[12:13], s[0:1], v[134:135] op_sel_hi:[1,0,1]
	v_pk_fma_f32 v[136:137], v[14:15], s[0:1], v[136:137] op_sel_hi:[1,0,1]
	v_readlane_b32 s0, v167, 50
	s_waitcnt vmcnt(13)
	v_cvt_scalef32_pk_f32_fp4 v[0:1], v148, 1.0
	v_cvt_scalef32_pk_f32_fp4 v[2:3], v148, 1.0 op_sel:[1,0,0]
	v_cvt_scalef32_pk_f32_fp4 v[4:5], v148, 1.0 op_sel:[0,1,0]
	v_cvt_scalef32_pk_f32_fp4 v[6:7], v148, 1.0 op_sel:[1,1,0]
	v_cvt_scalef32_pk_f32_fp4 v[8:9], v149, 1.0
	v_cvt_scalef32_pk_f32_fp4 v[10:11], v149, 1.0 op_sel:[1,0,0]
	v_cvt_scalef32_pk_f32_fp4 v[12:13], v149, 1.0 op_sel:[0,1,0]
	v_cvt_scalef32_pk_f32_fp4 v[14:15], v149, 1.0 op_sel:[1,1,0]
	v_pk_fma_f32 v[130:131], v[0:1], s[0:1], v[130:131] op_sel_hi:[1,0,1]
	v_pk_fma_f32 v[138:139], v[2:3], s[0:1], v[138:139] op_sel_hi:[1,0,1]
	v_pk_fma_f32 v[140:141], v[4:5], s[0:1], v[140:141] op_sel_hi:[1,0,1]
	v_pk_fma_f32 v[142:143], v[6:7], s[0:1], v[142:143] op_sel_hi:[1,0,1]
	v_pk_fma_f32 v[128:129], v[8:9], s[0:1], v[128:129] op_sel_hi:[1,0,1]
	v_pk_fma_f32 v[132:133], v[10:11], s[0:1], v[132:133] op_sel_hi:[1,0,1]
	v_pk_fma_f32 v[134:135], v[12:13], s[0:1], v[134:135] op_sel_hi:[1,0,1]
	v_pk_fma_f32 v[136:137], v[14:15], s[0:1], v[136:137] op_sel_hi:[1,0,1]
	v_readlane_b32 s0, v167, 51
	s_waitcnt vmcnt(12)
	v_cvt_scalef32_pk_f32_fp4 v[0:1], v150, 1.0
	v_cvt_scalef32_pk_f32_fp4 v[2:3], v150, 1.0 op_sel:[1,0,0]
	v_cvt_scalef32_pk_f32_fp4 v[4:5], v150, 1.0 op_sel:[0,1,0]
	v_cvt_scalef32_pk_f32_fp4 v[6:7], v150, 1.0 op_sel:[1,1,0]
	v_cvt_scalef32_pk_f32_fp4 v[8:9], v151, 1.0
	v_cvt_scalef32_pk_f32_fp4 v[10:11], v151, 1.0 op_sel:[1,0,0]
	v_cvt_scalef32_pk_f32_fp4 v[12:13], v151, 1.0 op_sel:[0,1,0]
	v_cvt_scalef32_pk_f32_fp4 v[14:15], v151, 1.0 op_sel:[1,1,0]
	v_pk_fma_f32 v[130:131], v[0:1], s[0:1], v[130:131] op_sel_hi:[1,0,1]
	v_pk_fma_f32 v[138:139], v[2:3], s[0:1], v[138:139] op_sel_hi:[1,0,1]
	v_pk_fma_f32 v[140:141], v[4:5], s[0:1], v[140:141] op_sel_hi:[1,0,1]
	v_pk_fma_f32 v[142:143], v[6:7], s[0:1], v[142:143] op_sel_hi:[1,0,1]
	v_pk_fma_f32 v[128:129], v[8:9], s[0:1], v[128:129] op_sel_hi:[1,0,1]
	v_pk_fma_f32 v[132:133], v[10:11], s[0:1], v[132:133] op_sel_hi:[1,0,1]
	v_pk_fma_f32 v[134:135], v[12:13], s[0:1], v[134:135] op_sel_hi:[1,0,1]
	v_pk_fma_f32 v[136:137], v[14:15], s[0:1], v[136:137] op_sel_hi:[1,0,1]
	v_readlane_b32 s0, v167, 52
	s_waitcnt vmcnt(11)
	v_cvt_scalef32_pk_f32_fp4 v[0:1], v152, 1.0
	v_cvt_scalef32_pk_f32_fp4 v[2:3], v152, 1.0 op_sel:[1,0,0]
	v_cvt_scalef32_pk_f32_fp4 v[4:5], v152, 1.0 op_sel:[0,1,0]
	v_cvt_scalef32_pk_f32_fp4 v[6:7], v152, 1.0 op_sel:[1,1,0]
	v_cvt_scalef32_pk_f32_fp4 v[8:9], v153, 1.0
	v_cvt_scalef32_pk_f32_fp4 v[10:11], v153, 1.0 op_sel:[1,0,0]
	v_cvt_scalef32_pk_f32_fp4 v[12:13], v153, 1.0 op_sel:[0,1,0]
	v_cvt_scalef32_pk_f32_fp4 v[14:15], v153, 1.0 op_sel:[1,1,0]
	v_pk_fma_f32 v[130:131], v[0:1], s[0:1], v[130:131] op_sel_hi:[1,0,1]
	v_pk_fma_f32 v[138:139], v[2:3], s[0:1], v[138:139] op_sel_hi:[1,0,1]
	v_pk_fma_f32 v[140:141], v[4:5], s[0:1], v[140:141] op_sel_hi:[1,0,1]
	v_pk_fma_f32 v[142:143], v[6:7], s[0:1], v[142:143] op_sel_hi:[1,0,1]
	v_pk_fma_f32 v[128:129], v[8:9], s[0:1], v[128:129] op_sel_hi:[1,0,1]
	v_pk_fma_f32 v[132:133], v[10:11], s[0:1], v[132:133] op_sel_hi:[1,0,1]
	v_pk_fma_f32 v[134:135], v[12:13], s[0:1], v[134:135] op_sel_hi:[1,0,1]
	v_pk_fma_f32 v[136:137], v[14:15], s[0:1], v[136:137] op_sel_hi:[1,0,1]
	v_readlane_b32 s0, v167, 53
	s_waitcnt vmcnt(10)
	v_cvt_scalef32_pk_f32_fp4 v[0:1], v154, 1.0
	v_cvt_scalef32_pk_f32_fp4 v[2:3], v154, 1.0 op_sel:[1,0,0]
	v_cvt_scalef32_pk_f32_fp4 v[4:5], v154, 1.0 op_sel:[0,1,0]
	v_cvt_scalef32_pk_f32_fp4 v[6:7], v154, 1.0 op_sel:[1,1,0]
	v_cvt_scalef32_pk_f32_fp4 v[8:9], v155, 1.0
	v_cvt_scalef32_pk_f32_fp4 v[10:11], v155, 1.0 op_sel:[1,0,0]
	v_cvt_scalef32_pk_f32_fp4 v[12:13], v155, 1.0 op_sel:[0,1,0]
	v_cvt_scalef32_pk_f32_fp4 v[14:15], v155, 1.0 op_sel:[1,1,0]
	v_pk_fma_f32 v[130:131], v[0:1], s[0:1], v[130:131] op_sel_hi:[1,0,1]
	v_pk_fma_f32 v[138:139], v[2:3], s[0:1], v[138:139] op_sel_hi:[1,0,1]
	v_pk_fma_f32 v[140:141], v[4:5], s[0:1], v[140:141] op_sel_hi:[1,0,1]
	v_pk_fma_f32 v[142:143], v[6:7], s[0:1], v[142:143] op_sel_hi:[1,0,1]
	v_pk_fma_f32 v[128:129], v[8:9], s[0:1], v[128:129] op_sel_hi:[1,0,1]
	v_pk_fma_f32 v[132:133], v[10:11], s[0:1], v[132:133] op_sel_hi:[1,0,1]
	v_pk_fma_f32 v[134:135], v[12:13], s[0:1], v[134:135] op_sel_hi:[1,0,1]
	v_pk_fma_f32 v[136:137], v[14:15], s[0:1], v[136:137] op_sel_hi:[1,0,1]
	v_readlane_b32 s0, v167, 54
	s_waitcnt vmcnt(9)
; __device__ void peer_gather_phase(const Params& P, int l, bool do_store) {
;     ...
;       for (int j = 0; j < 8; ++j) {
;         const float a = __builtin_bit_cast(float, __builtin_amdgcn_readlane(__builtin_bit_cast(int, avec), kb + j));
;         const f32x2 aa = f32x2{a, a};
;         y[0] += aa * __builtin_amdgcn_cvt_scalef32_pk_f32_fp4(v8[j].x, 1.0f, 0); y[1] += aa * __builtin_amdgcn_cvt_scalef32_pk_f32_fp4(v8[j].x, 1.0f, 1);
;         y[2] += aa * __builtin_amdgcn_cvt_scalef32_pk_f32_fp4(v8[j].x, 1.0f, 2); y[3] += aa * __builtin_amdgcn_cvt_scalef32_pk_f32_fp4(v8[j].x, 1.0f, 3);
;         y[4] += aa * __builtin_amdgcn_cvt_scalef32_pk_f32_fp4(v8[j].y, 1.0f, 0); y[5] += aa * __builtin_amdgcn_cvt_scalef32_pk_f32_fp4(v8[j].y, 1.0f, 1);
;         y[6] += aa * __builtin_amdgcn_cvt_scalef32_pk_f32_fp4(v8[j].y, 1.0f, 2); y[7] += aa * __builtin_amdgcn_cvt_scalef32_pk_f32_fp4(v8[j].y, 1.0f, 3);
;       }
	v_cvt_scalef32_pk_f32_fp4 v[0:1], v156, 1.0
	v_cvt_scalef32_pk_f32_fp4 v[2:3], v156, 1.0 op_sel:[1,0,0]
	v_cvt_scalef32_pk_f32_fp4 v[4:5], v156, 1.0 op_sel:[0,1,0]
	v_cvt_scalef32_pk_f32_fp4 v[6:7], v156, 1.0 op_sel:[1,1,0]
	v_cvt_scalef32_pk_f32_fp4 v[8:9], v157, 1.0
	v_cvt_scalef32_pk_f32_fp4 v[10:11], v157, 1.0 op_sel:[1,0,0]
	v_cvt_scalef32_pk_f32_fp4 v[12:13], v157, 1.0 op_sel:[0,1,0]
	v_cvt_scalef32_pk_f32_fp4 v[14:15], v157, 1.0 op_sel:[1,1,0]
	v_pk_fma_f32 v[130:131], v[0:1], s[0:1], v[130:131] op_sel_hi:[1,0,1]
	v_pk_fma_f32 v[138:139], v[2:3], s[0:1], v[138:139] op_sel_hi:[1,0,1]
	v_pk_fma_f32 v[140:141], v[4:5], s[0:1], v[140:141] op_sel_hi:[1,0,1]
	v_pk_fma_f32 v[142:143], v[6:7], s[0:1], v[142:143] op_sel_hi:[1,0,1]
	v_pk_fma_f32 v[128:129], v[8:9], s[0:1], v[128:129] op_sel_hi:[1,0,1]
	v_pk_fma_f32 v[132:133], v[10:11], s[0:1], v[132:133] op_sel_hi:[1,0,1]
	v_pk_fma_f32 v[134:135], v[12:13], s[0:1], v[134:135] op_sel_hi:[1,0,1]
	v_pk_fma_f32 v[136:137], v[14:15], s[0:1], v[136:137] op_sel_hi:[1,0,1]
	v_readlane_b32 s0, v167, 55
	s_waitcnt vmcnt(8)
	v_cvt_scalef32_pk_f32_fp4 v[0:1], v158, 1.0
	v_cvt_scalef32_pk_f32_fp4 v[2:3], v158, 1.0 op_sel:[1,0,0]
	v_cvt_scalef32_pk_f32_fp4 v[4:5], v158, 1.0 op_sel:[0,1,0]
	v_cvt_scalef32_pk_f32_fp4 v[6:7], v158, 1.0 op_sel:[1,1,0]
	v_cvt_scalef32_pk_f32_fp4 v[8:9], v159, 1.0
	v_cvt_scalef32_pk_f32_fp4 v[10:11], v159, 1.0 op_sel:[1,0,0]
	v_cvt_scalef32_pk_f32_fp4 v[12:13], v159, 1.0 op_sel:[0,1,0]
	v_cvt_scalef32_pk_f32_fp4 v[14:15], v159, 1.0 op_sel:[1,1,0]
	v_pk_fma_f32 v[130:131], v[0:1], s[0:1], v[130:131] op_sel_hi:[1,0,1]
	v_pk_fma_f32 v[138:139], v[2:3], s[0:1], v[138:139] op_sel_hi:[1,0,1]
	v_pk_fma_f32 v[140:141], v[4:5], s[0:1], v[140:141] op_sel_hi:[1,0,1]
	v_pk_fma_f32 v[142:143], v[6:7], s[0:1], v[142:143] op_sel_hi:[1,0,1]
	v_pk_fma_f32 v[128:129], v[8:9], s[0:1], v[128:129] op_sel_hi:[1,0,1]
	v_pk_fma_f32 v[132:133], v[10:11], s[0:1], v[132:133] op_sel_hi:[1,0,1]
	v_pk_fma_f32 v[134:135], v[12:13], s[0:1], v[134:135] op_sel_hi:[1,0,1]
	v_pk_fma_f32 v[136:137], v[14:15], s[0:1], v[136:137] op_sel_hi:[1,0,1]
	v_readlane_b32 s0, v167, 56
	s_waitcnt vmcnt(7)
	v_cvt_scalef32_pk_f32_fp4 v[0:1], v168, 1.0
	v_cvt_scalef32_pk_f32_fp4 v[2:3], v168, 1.0 op_sel:[1,0,0]
	v_cvt_scalef32_pk_f32_fp4 v[4:5], v168, 1.0 op_sel:[0,1,0]
	v_cvt_scalef32_pk_f32_fp4 v[6:7], v168, 1.0 op_sel:[1,1,0]
	v_cvt_scalef32_pk_f32_fp4 v[8:9], v169, 1.0
	v_cvt_scalef32_pk_f32_fp4 v[10:11], v169, 1.0 op_sel:[1,0,0]
	v_cvt_scalef32_pk_f32_fp4 v[12:13], v169, 1.0 op_sel:[0,1,0]
	v_cvt_scalef32_pk_f32_fp4 v[14:15], v169, 1.0 op_sel:[1,1,0]
	v_pk_fma_f32 v[130:131], v[0:1], s[0:1], v[130:131] op_sel_hi:[1,0,1]
	v_pk_fma_f32 v[138:139], v[2:3], s[0:1], v[138:139] op_sel_hi:[1,0,1]
	v_pk_fma_f32 v[140:141], v[4:5], s[0:1], v[140:141] op_sel_hi:[1,0,1]
	v_pk_fma_f32 v[142:143], v[6:7], s[0:1], v[142:143] op_sel_hi:[1,0,1]
	v_pk_fma_f32 v[128:129], v[8:9], s[0:1], v[128:129] op_sel_hi:[1,0,1]
	v_pk_fma_f32 v[132:133], v[10:11], s[0:1], v[132:133] op_sel_hi:[1,0,1]
	v_pk_fma_f32 v[134:135], v[12:13], s[0:1], v[134:135] op_sel_hi:[1,0,1]
	v_pk_fma_f32 v[136:137], v[14:15], s[0:1], v[136:137] op_sel_hi:[1,0,1]
	v_readlane_b32 s0, v167, 57
	s_waitcnt vmcnt(6)
	v_cvt_scalef32_pk_f32_fp4 v[0:1], v170, 1.0
	v_cvt_scalef32_pk_f32_fp4 v[2:3], v170, 1.0 op_sel:[1,0,0]
	v_cvt_scalef32_pk_f32_fp4 v[4:5], v170, 1.0 op_sel:[0,1,0]
	v_cvt_scalef32_pk_f32_fp4 v[6:7], v170, 1.0 op_sel:[1,1,0]
	v_cvt_scalef32_pk_f32_fp4 v[8:9], v171, 1.0
	v_cvt_scalef32_pk_f32_fp4 v[10:11], v171, 1.0 op_sel:[1,0,0]
	v_cvt_scalef32_pk_f32_fp4 v[12:13], v171, 1.0 op_sel:[0,1,0]
	v_cvt_scalef32_pk_f32_fp4 v[14:15], v171, 1.0 op_sel:[1,1,0]
	v_pk_fma_f32 v[130:131], v[0:1], s[0:1], v[130:131] op_sel_hi:[1,0,1]
	v_pk_fma_f32 v[138:139], v[2:3], s[0:1], v[138:139] op_sel_hi:[1,0,1]
	v_pk_fma_f32 v[140:141], v[4:5], s[0:1], v[140:141] op_sel_hi:[1,0,1]
	v_pk_fma_f32 v[142:143], v[6:7], s[0:1], v[142:143] op_sel_hi:[1,0,1]
	v_pk_fma_f32 v[128:129], v[8:9], s[0:1], v[128:129] op_sel_hi:[1,0,1]
	v_pk_fma_f32 v[132:133], v[10:11], s[0:1], v[132:133] op_sel_hi:[1,0,1]
	v_pk_fma_f32 v[134:135], v[12:13], s[0:1], v[134:135] op_sel_hi:[1,0,1]
	v_pk_fma_f32 v[136:137], v[14:15], s[0:1], v[136:137] op_sel_hi:[1,0,1]
	v_readlane_b32 s0, v167, 58
	s_waitcnt vmcnt(5)
	v_cvt_scalef32_pk_f32_fp4 v[0:1], v172, 1.0
	v_cvt_scalef32_pk_f32_fp4 v[2:3], v172, 1.0 op_sel:[1,0,0]
	v_cvt_scalef32_pk_f32_fp4 v[4:5], v172, 1.0 op_sel:[0,1,0]
	v_cvt_scalef32_pk_f32_fp4 v[6:7], v172, 1.0 op_sel:[1,1,0]
	v_cvt_scalef32_pk_f32_fp4 v[8:9], v173, 1.0
	v_cvt_scalef32_pk_f32_fp4 v[10:11], v173, 1.0 op_sel:[1,0,0]
	v_cvt_scalef32_pk_f32_fp4 v[12:13], v173, 1.0 op_sel:[0,1,0]
	v_cvt_scalef32_pk_f32_fp4 v[14:15], v173, 1.0 op_sel:[1,1,0]
	v_pk_fma_f32 v[130:131], v[0:1], s[0:1], v[130:131] op_sel_hi:[1,0,1]
	v_pk_fma_f32 v[138:139], v[2:3], s[0:1], v[138:139] op_sel_hi:[1,0,1]
	v_pk_fma_f32 v[140:141], v[4:5], s[0:1], v[140:141] op_sel_hi:[1,0,1]
	v_pk_fma_f32 v[142:143], v[6:7], s[0:1], v[142:143] op_sel_hi:[1,0,1]
	v_pk_fma_f32 v[128:129], v[8:9], s[0:1], v[128:129] op_sel_hi:[1,0,1]
	v_pk_fma_f32 v[132:133], v[10:11], s[0:1], v[132:133] op_sel_hi:[1,0,1]
	v_pk_fma_f32 v[134:135], v[12:13], s[0:1], v[134:135] op_sel_hi:[1,0,1]
	v_pk_fma_f32 v[136:137], v[14:15], s[0:1], v[136:137] op_sel_hi:[1,0,1]
	v_readlane_b32 s0, v167, 59
	s_waitcnt vmcnt(4)
; __device__ void peer_gather_phase(const Params& P, int l, bool do_store) {
;     ...
;       for (int j = 0; j < 8; ++j) {
;         const float a = __builtin_bit_cast(float, __builtin_amdgcn_readlane(__builtin_bit_cast(int, avec), kb + j));
;         const f32x2 aa = f32x2{a, a};
;         y[0] += aa * __builtin_amdgcn_cvt_scalef32_pk_f32_fp4(v8[j].x, 1.0f, 0); y[1] += aa * __builtin_amdgcn_cvt_scalef32_pk_f32_fp4(v8[j].x, 1.0f, 1);
;         y[2] += aa * __builtin_amdgcn_cvt_scalef32_pk_f32_fp4(v8[j].x, 1.0f, 2); y[3] += aa * __builtin_amdgcn_cvt_scalef32_pk_f32_fp4(v8[j].x, 1.0f, 3);
;         y[4] += aa * __builtin_amdgcn_cvt_scalef32_pk_f32_fp4(v8[j].y, 1.0f, 0); y[5] += aa * __builtin_amdgcn_cvt_scalef32_pk_f32_fp4(v8[j].y, 1.0f, 1);
;         y[6] += aa * __builtin_amdgcn_cvt_scalef32_pk_f32_fp4(v8[j].y, 1.0f, 2); y[7] += aa * __builtin_amdgcn_cvt_scalef32_pk_f32_fp4(v8[j].y, 1.0f, 3);
;       }
	v_cvt_scalef32_pk_f32_fp4 v[0:1], v174, 1.0
	v_cvt_scalef32_pk_f32_fp4 v[2:3], v174, 1.0 op_sel:[1,0,0]
	v_cvt_scalef32_pk_f32_fp4 v[4:5], v174, 1.0 op_sel:[0,1,0]
	v_cvt_scalef32_pk_f32_fp4 v[6:7], v174, 1.0 op_sel:[1,1,0]
	v_cvt_scalef32_pk_f32_fp4 v[8:9], v175, 1.0
	v_cvt_scalef32_pk_f32_fp4 v[10:11], v175, 1.0 op_sel:[1,0,0]
	v_cvt_scalef32_pk_f32_fp4 v[12:13], v175, 1.0 op_sel:[0,1,0]
	v_cvt_scalef32_pk_f32_fp4 v[14:15], v175, 1.0 op_sel:[1,1,0]
	v_pk_fma_f32 v[130:131], v[0:1], s[0:1], v[130:131] op_sel_hi:[1,0,1]
	v_pk_fma_f32 v[138:139], v[2:3], s[0:1], v[138:139] op_sel_hi:[1,0,1]
	v_pk_fma_f32 v[140:141], v[4:5], s[0:1], v[140:141] op_sel_hi:[1,0,1]
	v_pk_fma_f32 v[142:143], v[6:7], s[0:1], v[142:143] op_sel_hi:[1,0,1]
	v_pk_fma_f32 v[128:129], v[8:9], s[0:1], v[128:129] op_sel_hi:[1,0,1]
	v_pk_fma_f32 v[132:133], v[10:11], s[0:1], v[132:133] op_sel_hi:[1,0,1]
	v_pk_fma_f32 v[134:135], v[12:13], s[0:1], v[134:135] op_sel_hi:[1,0,1]
	v_pk_fma_f32 v[136:137], v[14:15], s[0:1], v[136:137] op_sel_hi:[1,0,1]
	v_readlane_b32 s0, v167, 60
	s_waitcnt vmcnt(3)
	v_cvt_scalef32_pk_f32_fp4 v[0:1], v180, 1.0
	v_cvt_scalef32_pk_f32_fp4 v[2:3], v180, 1.0 op_sel:[1,0,0]
	v_cvt_scalef32_pk_f32_fp4 v[4:5], v180, 1.0 op_sel:[0,1,0]
	v_cvt_scalef32_pk_f32_fp4 v[6:7], v180, 1.0 op_sel:[1,1,0]
	v_cvt_scalef32_pk_f32_fp4 v[8:9], v181, 1.0
	v_cvt_scalef32_pk_f32_fp4 v[10:11], v181, 1.0 op_sel:[1,0,0]
	v_cvt_scalef32_pk_f32_fp4 v[12:13], v181, 1.0 op_sel:[0,1,0]
	v_cvt_scalef32_pk_f32_fp4 v[14:15], v181, 1.0 op_sel:[1,1,0]
	v_pk_fma_f32 v[130:131], v[0:1], s[0:1], v[130:131] op_sel_hi:[1,0,1]
	v_pk_fma_f32 v[138:139], v[2:3], s[0:1], v[138:139] op_sel_hi:[1,0,1]
	v_pk_fma_f32 v[140:141], v[4:5], s[0:1], v[140:141] op_sel_hi:[1,0,1]
	v_pk_fma_f32 v[142:143], v[6:7], s[0:1], v[142:143] op_sel_hi:[1,0,1]
	v_pk_fma_f32 v[128:129], v[8:9], s[0:1], v[128:129] op_sel_hi:[1,0,1]
	v_pk_fma_f32 v[132:133], v[10:11], s[0:1], v[132:133] op_sel_hi:[1,0,1]
	v_pk_fma_f32 v[134:135], v[12:13], s[0:1], v[134:135] op_sel_hi:[1,0,1]
	v_pk_fma_f32 v[136:137], v[14:15], s[0:1], v[136:137] op_sel_hi:[1,0,1]
	v_readlane_b32 s0, v167, 61
	s_waitcnt vmcnt(2)
	v_cvt_scalef32_pk_f32_fp4 v[0:1], v182, 1.0
	v_cvt_scalef32_pk_f32_fp4 v[2:3], v182, 1.0 op_sel:[1,0,0]
	v_cvt_scalef32_pk_f32_fp4 v[4:5], v182, 1.0 op_sel:[0,1,0]
	v_cvt_scalef32_pk_f32_fp4 v[6:7], v182, 1.0 op_sel:[1,1,0]
	v_cvt_scalef32_pk_f32_fp4 v[8:9], v183, 1.0
	v_cvt_scalef32_pk_f32_fp4 v[10:11], v183, 1.0 op_sel:[1,0,0]
	v_cvt_scalef32_pk_f32_fp4 v[12:13], v183, 1.0 op_sel:[0,1,0]
	v_cvt_scalef32_pk_f32_fp4 v[14:15], v183, 1.0 op_sel:[1,1,0]
	v_pk_fma_f32 v[130:131], v[0:1], s[0:1], v[130:131] op_sel_hi:[1,0,1]
	v_pk_fma_f32 v[138:139], v[2:3], s[0:1], v[138:139] op_sel_hi:[1,0,1]
	v_pk_fma_f32 v[140:141], v[4:5], s[0:1], v[140:141] op_sel_hi:[1,0,1]
	v_pk_fma_f32 v[142:143], v[6:7], s[0:1], v[142:143] op_sel_hi:[1,0,1]
	v_pk_fma_f32 v[128:129], v[8:9], s[0:1], v[128:129] op_sel_hi:[1,0,1]
	v_pk_fma_f32 v[132:133], v[10:11], s[0:1], v[132:133] op_sel_hi:[1,0,1]
	v_pk_fma_f32 v[134:135], v[12:13], s[0:1], v[134:135] op_sel_hi:[1,0,1]
	v_pk_fma_f32 v[136:137], v[14:15], s[0:1], v[136:137] op_sel_hi:[1,0,1]
	v_readlane_b32 s0, v167, 62
	s_waitcnt vmcnt(1)
	v_cvt_scalef32_pk_f32_fp4 v[0:1], v184, 1.0
	v_cvt_scalef32_pk_f32_fp4 v[2:3], v184, 1.0 op_sel:[1,0,0]
	v_cvt_scalef32_pk_f32_fp4 v[4:5], v184, 1.0 op_sel:[0,1,0]
	v_cvt_scalef32_pk_f32_fp4 v[6:7], v184, 1.0 op_sel:[1,1,0]
	v_cvt_scalef32_pk_f32_fp4 v[8:9], v185, 1.0
	v_cvt_scalef32_pk_f32_fp4 v[10:11], v185, 1.0 op_sel:[1,0,0]
	v_cvt_scalef32_pk_f32_fp4 v[12:13], v185, 1.0 op_sel:[0,1,0]
	v_cvt_scalef32_pk_f32_fp4 v[14:15], v185, 1.0 op_sel:[1,1,0]
	v_pk_fma_f32 v[130:131], v[0:1], s[0:1], v[130:131] op_sel_hi:[1,0,1]
	v_pk_fma_f32 v[138:139], v[2:3], s[0:1], v[138:139] op_sel_hi:[1,0,1]
	v_pk_fma_f32 v[140:141], v[4:5], s[0:1], v[140:141] op_sel_hi:[1,0,1]
	v_pk_fma_f32 v[142:143], v[6:7], s[0:1], v[142:143] op_sel_hi:[1,0,1]
	v_pk_fma_f32 v[128:129], v[8:9], s[0:1], v[128:129] op_sel_hi:[1,0,1]
	v_pk_fma_f32 v[132:133], v[10:11], s[0:1], v[132:133] op_sel_hi:[1,0,1]
	v_pk_fma_f32 v[134:135], v[12:13], s[0:1], v[134:135] op_sel_hi:[1,0,1]
	v_pk_fma_f32 v[136:137], v[14:15], s[0:1], v[136:137] op_sel_hi:[1,0,1]
	v_readlane_b32 s0, v167, 63
	s_waitcnt vmcnt(0)
; __device__ void peer_gather_phase(const Params& P, int l, bool do_store) {
;     ...
;     float* xfp = P.out + (size_t)t * 1024 + lane * 16;
;     float pre[16];
; #pragma unroll
;     for (int k2 = 0; k2 < 8; ++k2) {
;       pre[2 * k2 + 0] = ALPHA_C * xf[k2].x + y[k2].x;
;       pre[2 * k2 + 1] = ALPHA_C * xf[k2].y + y[k2].y;
;     }
;     float sm = 0.f;
; #pragma unroll
;     for (int k = 0; k < 16; ++k) sm += pre[k];
;     const float mean = wave_sum(sm) * (1.f / 1024.f);
;     float vs = 0.f;
; #pragma unroll
;     for (int k = 0; k < 16; ++k) { const float dd = pre[k] - mean; vs += dd * dd; }
;     const float rstd = rsqrtf(wave_sum(vs) * (1.f / 1024.f) + EPS_C);
;     const float* g2 = P.ln2_g + l * 1024 + lane * 16;
;     const float* b2 = P.ln2_b + l * 1024 + lane * 16;
;     float o[16];
; #pragma unroll
;     for (int k4 = 0; k4 < 4; ++k4) {
;       const float4 gg = *(const float4*)(g2 + 4 * k4), bb = *(const float4*)(b2 + 4 * k4);
;       o[4 * k4 + 0] = (pre[4 * k4 + 0] - mean) * rstd * gg.x + bb.x; o[4 * k4 + 1] = (pre[4 * k4 + 1] - mean) * rstd * gg.y + bb.y;
;       o[4 * k4 + 2] = (pre[4 * k4 + 2] - mean) * rstd * gg.z + bb.z; o[4 * k4 + 3] = (pre[4 * k4 + 3] - mean) * rstd * gg.w + bb.w;
;       float4 ov; ov.x = o[4 * k4]; ov.y = o[4 * k4 + 1]; ov.z = o[4 * k4 + 2]; ov.w = o[4 * k4 + 3];
;       if (do_store && l == 1) *(float4*)(xfp + 4 * k4) = ov;
;     }
	v_cvt_scalef32_pk_f32_fp4 v[0:1], v186, 1.0
	v_cvt_scalef32_pk_f32_fp4 v[2:3], v186, 1.0 op_sel:[1,0,0]
	v_cvt_scalef32_pk_f32_fp4 v[4:5], v186, 1.0 op_sel:[0,1,0]
	v_cvt_scalef32_pk_f32_fp4 v[6:7], v186, 1.0 op_sel:[1,1,0]
	v_cvt_scalef32_pk_f32_fp4 v[8:9], v187, 1.0
	v_cvt_scalef32_pk_f32_fp4 v[10:11], v187, 1.0 op_sel:[1,0,0]
	v_cvt_scalef32_pk_f32_fp4 v[12:13], v187, 1.0 op_sel:[0,1,0]
	v_cvt_scalef32_pk_f32_fp4 v[14:15], v187, 1.0 op_sel:[1,1,0]
	v_pk_fma_f32 v[130:131], v[0:1], s[0:1], v[130:131] op_sel_hi:[1,0,1]
	v_pk_fma_f32 v[138:139], v[2:3], s[0:1], v[138:139] op_sel_hi:[1,0,1]
	v_pk_fma_f32 v[140:141], v[4:5], s[0:1], v[140:141] op_sel_hi:[1,0,1]
	v_pk_fma_f32 v[142:143], v[6:7], s[0:1], v[142:143] op_sel_hi:[1,0,1]
	v_pk_fma_f32 v[128:129], v[8:9], s[0:1], v[128:129] op_sel_hi:[1,0,1]
	v_pk_fma_f32 v[132:133], v[10:11], s[0:1], v[132:133] op_sel_hi:[1,0,1]
	v_pk_fma_f32 v[134:135], v[12:13], s[0:1], v[134:135] op_sel_hi:[1,0,1]
	v_pk_fma_f32 v[136:137], v[14:15], s[0:1], v[136:137] op_sel_hi:[1,0,1]
	v_lshlrev_b32_e32 v0, 16, v70
	v_lshlrev_b32_e32 v2, 16, v69
	v_and_b32_e32 v3, 0xffff0000, v69
	v_and_b32_e32 v1, 0xffff0000, v70
	s_mov_b32 s0, 0x3fb504f3
	v_pk_fma_f32 v[16:17], v[0:1], s[0:1], v[140:141] op_sel_hi:[1,0,1]
	v_pk_fma_f32 v[18:19], v[2:3], s[0:1], v[138:139] op_sel_hi:[1,0,1]
	global_load_dwordx4 v[0:3], v[82:83], off
	global_load_dwordx4 v[20:23], v[84:85], off
	global_load_dwordx4 v[44:47], v[82:83], off offset:16
	global_load_dwordx4 v[48:51], v[84:85], off offset:16
	global_load_dwordx4 v[52:55], v[82:83], off offset:32
	global_load_dwordx4 v[228:231], v[84:85], off offset:32
	global_load_dwordx4 v[232:235], v[82:83], off offset:48
	global_load_dwordx4 v[236:239], v[84:85], off offset:48
	v_lshlrev_b32_e32 v4, 16, v68
	v_and_b32_e32 v5, 0xffff0000, v68
	v_pk_fma_f32 v[4:5], v[4:5], s[0:1], v[130:131] op_sel_hi:[1,0,1]
	v_lshlrev_b32_e32 v10, 16, v71
	v_add_f32_e32 v24, 0, v4
	v_add_f32_e32 v24, v5, v24
	v_add_f32_e32 v24, v18, v24
	v_add_f32_e32 v24, v19, v24
	v_and_b32_e32 v11, 0xffff0000, v71
	v_add_f32_e32 v24, v16, v24
	v_pk_fma_f32 v[10:11], v[10:11], s[0:1], v[142:143] op_sel_hi:[1,0,1]
	v_add_f32_e32 v24, v17, v24
	v_lshlrev_b32_e32 v6, 16, v64
	v_lshlrev_b32_e32 v8, 16, v66
	v_lshlrev_b32_e32 v12, 16, v65
	v_lshlrev_b32_e32 v14, 16, v67
	v_and_b32_e32 v7, 0xffff0000, v64
	v_and_b32_e32 v13, 0xffff0000, v65
	v_and_b32_e32 v9, 0xffff0000, v66
	v_and_b32_e32 v15, 0xffff0000, v67
	v_add_f32_e32 v24, v10, v24
	v_add_f32_e32 v26, v11, v24
	v_pk_fma_f32 v[24:25], v[14:15], s[0:1], v[136:137] op_sel_hi:[1,0,1]
	v_pk_fma_f32 v[14:15], v[8:9], s[0:1], v[134:135] op_sel_hi:[1,0,1]
	v_pk_fma_f32 v[8:9], v[12:13], s[0:1], v[132:133] op_sel_hi:[1,0,1]
	v_pk_fma_f32 v[12:13], v[6:7], s[0:1], v[128:129] op_sel_hi:[1,0,1]
	v_mov_b32_e32 v7, v177
	v_add_f32_e32 v6, v12, v26
	v_add_f32_e32 v6, v13, v6
	v_add_f32_e32 v6, v8, v6
	v_add_f32_e32 v6, v9, v6
	v_add_f32_e32 v6, v14, v6
	v_add_f32_e32 v6, v15, v6
	v_add_f32_e32 v6, v24, v6
	v_add_f32_e32 v6, v25, v6
	s_nop 1
	v_add_f32_dpp v6, v6, v6 row_shr:1 row_mask:0xf bank_mask:0xf bound_ctrl:1
	s_nop 1
	v_add_f32_dpp v6, v6, v6 row_shr:2 row_mask:0xf bank_mask:0xf bound_ctrl:1
	s_nop 1
	v_add_f32_dpp v6, v6, v6 row_shr:4 row_mask:0xf bank_mask:0xf bound_ctrl:1
	s_nop 1
	v_add_f32_dpp v6, v6, v6 row_shr:8 row_mask:0xf bank_mask:0xf bound_ctrl:1
	s_nop 1
	v_mov_b32_dpp v7, v6 row_bcast:15 row_mask:0xa bank_mask:0xf
	v_add_f32_e32 v6, v6, v7
	v_mov_b32_e32 v7, v177
	s_nop 1
	v_mov_b32_dpp v7, v6 row_bcast:31 row_mask:0xc bank_mask:0xf
	v_add_f32_e32 v6, v6, v7
	s_nop 0
	v_readlane_b32 s0, v6, 63
	s_nop 1
	v_mul_f32_e32 v26, s0, v210
	v_pk_add_f32 v[28:29], v[4:5], v[26:27] op_sel_hi:[1,0] neg_lo:[0,1] neg_hi:[0,1]
	v_pk_add_f32 v[32:33], v[18:19], v[26:27] op_sel_hi:[1,0] neg_lo:[0,1] neg_hi:[0,1]
	v_pk_mul_f32 v[30:31], v[28:29], v[28:29]
	v_pk_mul_f32 v[18:19], v[32:33], v[32:33]
	v_pk_add_f32 v[4:5], v[16:17], v[26:27] op_sel_hi:[1,0] neg_lo:[0,1] neg_hi:[0,1]
	v_pk_add_f32 v[6:7], v[10:11], v[26:27] op_sel_hi:[1,0] neg_lo:[0,1] neg_hi:[0,1]
	v_pk_add_f32 v[10:11], v[12:13], v[26:27] op_sel_hi:[1,0] neg_lo:[0,1] neg_hi:[0,1]
	v_pk_add_f32 v[8:9], v[8:9], v[26:27] op_sel_hi:[1,0] neg_lo:[0,1] neg_hi:[0,1]
	v_pk_add_f32 v[14:15], v[14:15], v[26:27] op_sel_hi:[1,0] neg_lo:[0,1] neg_hi:[0,1]
	v_pk_add_f32 v[12:13], v[24:25], v[26:27] op_sel_hi:[1,0] neg_lo:[0,1] neg_hi:[0,1]
	v_add_f32_e32 v26, v30, v31
	v_add_f32_e32 v18, v18, v26
	v_pk_mul_f32 v[16:17], v[4:5], v[4:5]
	v_add_f32_e32 v18, v19, v18
	v_add_f32_e32 v16, v16, v18
	v_pk_mul_f32 v[34:35], v[6:7], v[6:7]
	v_add_f32_e32 v16, v17, v16
	v_add_f32_e32 v16, v34, v16
	v_pk_mul_f32 v[36:37], v[10:11], v[10:11]
	v_add_f32_e32 v16, v35, v16
	v_add_f32_e32 v16, v36, v16
	v_pk_mul_f32 v[38:39], v[8:9], v[8:9]
	v_add_f32_e32 v16, v37, v16
	v_add_f32_e32 v16, v38, v16
	v_pk_mul_f32 v[40:41], v[14:15], v[14:15]
	v_add_f32_e32 v16, v39, v16
	v_add_f32_e32 v16, v40, v16
	v_pk_mul_f32 v[24:25], v[12:13], v[12:13]
	v_add_f32_e32 v16, v41, v16
	v_add_f32_e32 v16, v24, v16
	v_add_f32_e32 v16, v25, v16
	v_mov_b32_e32 v17, v177
	s_nop 0
	v_add_f32_dpp v16, v16, v16 row_shr:1 row_mask:0xf bank_mask:0xf bound_ctrl:1
	s_nop 1
	v_add_f32_dpp v16, v16, v16 row_shr:2 row_mask:0xf bank_mask:0xf bound_ctrl:1
	s_nop 1
	v_add_f32_dpp v16, v16, v16 row_shr:4 row_mask:0xf bank_mask:0xf bound_ctrl:1
	s_nop 1
	v_add_f32_dpp v16, v16, v16 row_shr:8 row_mask:0xf bank_mask:0xf bound_ctrl:1
	s_nop 1
	v_mov_b32_dpp v17, v16 row_bcast:15 row_mask:0xa bank_mask:0xf
	v_add_f32_e32 v16, v16, v17
	v_mov_b32_e32 v17, v177
	s_nop 1
	v_mov_b32_dpp v17, v16 row_bcast:31 row_mask:0xc bank_mask:0xf
	v_add_f32_e32 v16, v16, v17
	s_nop 0
	v_readlane_b32 s0, v16, 63
	s_nop 1
	v_fma_f32 v16, s0, v210, v203
	s_mov_b32 s0, 0x800000
	v_mul_f32_e32 v17, 0x4b800000, v16
	v_cmp_gt_f32_e32 vcc, s0, v16
	s_nop 1
	v_cndmask_b32_e32 v16, v16, v17, vcc
	v_rsq_f32_e32 v18, v16
	v_lshl_add_u64 v[16:17], v[94:95], 2, v[80:81]
	v_mul_f32_e32 v19, 0x45800000, v18
	v_cndmask_b32_e32 v18, v18, v19, vcc
	v_pk_mul_f32 v[24:25], v[28:29], v[18:19] op_sel_hi:[1,0]
	s_and_b64 vcc, exec, s[38:39]
	s_waitcnt vmcnt(0)
	v_pk_fma_f32 v[0:1], v[0:1], v[24:25], v[20:21]
	v_pk_mul_f32 v[20:21], v[32:33], v[18:19] op_sel_hi:[1,0]
	s_nop 0
	v_pk_fma_f32 v[2:3], v[2:3], v[20:21], v[22:23]
	s_cbranch_vccz .LBB0_25
	global_store_dwordx4 v[16:17], v[0:3], off
